# attention fast path: three copies specialised by ring slot (K reads use immediate LDS offsets, no per-read address add; V address registers carried across tiles and stepped by a constant)
# speedup vs baseline: 1.0088x; 1.0088x over previous
.LBB0_847:
	s_cmp_gt_i32 s43, s84
	s_cbranch_scc1 .LBB0_858
	s_add_i32 s100, s43, 63
	s_cmp_le_i32 s100, s83
	s_cbranch_scc0 .Latt_slow_0
	s_cmp_eq_u32 s88, 1
	s_cbranch_scc1 .Latt_slot1_0
	s_cmp_eq_u32 s88, 2
	s_cbranch_scc1 .Latt_slot2_0
	ds_read_b128 v[206:209], v194
	ds_read_b128 v[210:213], v195
	ds_read_b128 v[214:217], v196
	ds_read_b128 v[238:241], v197
	ds_read_b128 v[242:245], v198
	ds_read_b128 v[250:253], v199
	ds_read_b128 v[222:225], v200
	ds_read_b128 v[226:229], v201
	s_cmp_lg_u32 s43, 0
	s_cbranch_scc1 .Latt_vstep_0s0
	v_bfe_u32 v246, v203, 2, 2
	v_bfe_u32 v247, v203, 5, 1
	v_lshl_or_b32 v247, v247, 2, v246
	v_and_b32_e32 v249, 3, v203
	v_and_b32_e32 v254, 16, v203
	v_lshl_or_b32 v249, v249, 2, v254
	v_lshlrev_b32_e32 v249, 1, v249
	v_lshl_add_u32 v247, v247, 9, v249
	v_add_u32_e32 v247, 0xc000, v247
	v_lshlrev_b32_e32 v246, 6, v246
	v_add_u32_e32 v205, v247, v246
	v_xor_b32_e32 v249, 64, v246
	v_add_u32_e32 v218, v247, v249
	v_xor_b32_e32 v249, 0x80, v246
	v_add_u32_e32 v219, v247, v249
	v_xor_b32_e32 v249, 0xc0, v246
	v_add_u32_e32 v221, v247, v249
	s_branch .Latt_vdone_0s0
.Latt_vstep_0s0:
	v_add_u32_e32 v205, 0xffff0000, v205
	v_add_u32_e32 v218, 0xffff0000, v218
	v_add_u32_e32 v219, 0xffff0000, v219
	v_add_u32_e32 v221, 0xffff0000, v221
.Latt_vdone_0s0:
	s_waitcnt lgkmcnt(7)
	v_mfma_f32_32x32x16_bf16 v[128:143], v[206:209], v[144:147], 0
	ds_read_b128 v[206:209], v194 offset:8192
	s_waitcnt lgkmcnt(7)
	v_mfma_f32_32x32x16_bf16 v[128:143], v[210:213], v[148:151], v[128:143]
	ds_read_b128 v[210:213], v195 offset:8192
	s_waitcnt lgkmcnt(7)
	v_mfma_f32_32x32x16_bf16 v[128:143], v[214:217], v[152:155], v[128:143]
	ds_read_b128 v[214:217], v196 offset:8192
	s_waitcnt lgkmcnt(7)
	v_mfma_f32_32x32x16_bf16 v[128:143], v[238:241], v[156:159], v[128:143]
	ds_read_b128 v[238:241], v197 offset:8192
	s_waitcnt lgkmcnt(7)
	v_mfma_f32_32x32x16_bf16 v[128:143], v[242:245], v[160:163], v[128:143]
	s_waitcnt lgkmcnt(6)
	v_mfma_f32_32x32x16_bf16 v[128:143], v[250:253], v[164:167], v[128:143]
	s_waitcnt lgkmcnt(5)
	v_mfma_f32_32x32x16_bf16 v[128:143], v[222:225], v[168:171], v[128:143]
	s_waitcnt lgkmcnt(4)
	v_mfma_f32_32x32x16_bf16 v[128:143], v[226:229], v[172:175], v[128:143]
	s_waitcnt lgkmcnt(3)
	v_mfma_f32_32x32x16_bf16 v[222:237], v[206:209], v[144:147], 0
	ds_read_b128 v[206:209], v198 offset:8192
	s_nop 8
	v_max3_f32 v246, v128, v129, v130
	v_max3_f32 v247, v131, v132, v133
	v_max3_f32 v246, v246, v134, v135
	v_max3_f32 v247, v247, v136, v137
	v_max3_f32 v246, v246, v138, v139
	v_max3_f32 v247, v247, v140, v141
	v_max3_f32 v246, v246, v142, v143
	s_waitcnt lgkmcnt(3)
	v_mfma_f32_32x32x16_bf16 v[222:237], v[210:213], v[148:151], v[222:237]
	ds_read_b128 v[210:213], v199 offset:8192
	v_max_f32_e32 v246, v246, v247
	v_mov_b32_e32 v247, v246
	v_add_f32_e32 v249, 0x41000000, v190
	s_nop 1
	v_permlane32_swap_b32_e32 v246, v247
	v_max_f32_e32 v246, v246, v247
	v_cmp_gt_f32_e32 vcc, v246, v249
	s_cbranch_vccz .Latt_nr0_0s0
	v_max_f32_e32 v246, v190, v246
	v_sub_f32_e32 v190, v190, v246
	v_exp_f32_e32 v190, v190
	s_nop 0
	v_pk_mul_f32 v[126:127], v[126:127], v[190:191] op_sel_hi:[1,0]
	v_pk_mul_f32 v[124:125], v[124:125], v[190:191] op_sel_hi:[1,0]
	v_pk_mul_f32 v[122:123], v[122:123], v[190:191] op_sel_hi:[1,0]
	v_pk_mul_f32 v[120:121], v[120:121], v[190:191] op_sel_hi:[1,0]
	v_pk_mul_f32 v[118:119], v[118:119], v[190:191] op_sel_hi:[1,0]
	v_pk_mul_f32 v[116:117], v[116:117], v[190:191] op_sel_hi:[1,0]
	v_pk_mul_f32 v[114:115], v[114:115], v[190:191] op_sel_hi:[1,0]
	v_pk_mul_f32 v[112:113], v[112:113], v[190:191] op_sel_hi:[1,0]
	v_pk_mul_f32 v[110:111], v[110:111], v[190:191] op_sel_hi:[1,0]
	v_pk_mul_f32 v[108:109], v[108:109], v[190:191] op_sel_hi:[1,0]
	v_pk_mul_f32 v[106:107], v[106:107], v[190:191] op_sel_hi:[1,0]
	v_pk_mul_f32 v[104:105], v[104:105], v[190:191] op_sel_hi:[1,0]
	v_pk_mul_f32 v[102:103], v[102:103], v[190:191] op_sel_hi:[1,0]
	v_pk_mul_f32 v[100:101], v[100:101], v[190:191] op_sel_hi:[1,0]
	v_pk_mul_f32 v[98:99], v[98:99], v[190:191] op_sel_hi:[1,0]
	v_pk_mul_f32 v[96:97], v[96:97], v[190:191] op_sel_hi:[1,0]
	v_pk_mul_f32 v[94:95], v[94:95], v[190:191] op_sel_hi:[1,0]
	v_pk_mul_f32 v[92:93], v[92:93], v[190:191] op_sel_hi:[1,0]
	v_pk_mul_f32 v[90:91], v[90:91], v[190:191] op_sel_hi:[1,0]
	v_pk_mul_f32 v[88:89], v[88:89], v[190:191] op_sel_hi:[1,0]
	v_pk_mul_f32 v[86:87], v[86:87], v[190:191] op_sel_hi:[1,0]
	v_pk_mul_f32 v[84:85], v[84:85], v[190:191] op_sel_hi:[1,0]
	v_pk_mul_f32 v[82:83], v[82:83], v[190:191] op_sel_hi:[1,0]
	v_pk_mul_f32 v[80:81], v[80:81], v[190:191] op_sel_hi:[1,0]
	v_pk_mul_f32 v[78:79], v[78:79], v[190:191] op_sel_hi:[1,0]
	v_pk_mul_f32 v[76:77], v[76:77], v[190:191] op_sel_hi:[1,0]
	v_pk_mul_f32 v[74:75], v[74:75], v[190:191] op_sel_hi:[1,0]
	v_pk_mul_f32 v[72:73], v[72:73], v[190:191] op_sel_hi:[1,0]
	v_pk_mul_f32 v[70:71], v[70:71], v[190:191] op_sel_hi:[1,0]
	v_pk_mul_f32 v[68:69], v[68:69], v[190:191] op_sel_hi:[1,0]
	v_pk_mul_f32 v[66:67], v[66:67], v[190:191] op_sel_hi:[1,0]
	v_pk_mul_f32 v[64:65], v[64:65], v[190:191] op_sel_hi:[1,0]
	v_pk_mul_f32 v[62:63], v[62:63], v[190:191] op_sel_hi:[1,0]
	v_pk_mul_f32 v[60:61], v[60:61], v[190:191] op_sel_hi:[1,0]
	v_pk_mul_f32 v[58:59], v[58:59], v[190:191] op_sel_hi:[1,0]
	v_pk_mul_f32 v[56:57], v[56:57], v[190:191] op_sel_hi:[1,0]
	v_pk_mul_f32 v[54:55], v[54:55], v[190:191] op_sel_hi:[1,0]
	v_pk_mul_f32 v[52:53], v[52:53], v[190:191] op_sel_hi:[1,0]
	v_pk_mul_f32 v[50:51], v[50:51], v[190:191] op_sel_hi:[1,0]
	v_pk_mul_f32 v[48:49], v[48:49], v[190:191] op_sel_hi:[1,0]
	v_pk_mul_f32 v[46:47], v[46:47], v[190:191] op_sel_hi:[1,0]
	v_pk_mul_f32 v[44:45], v[44:45], v[190:191] op_sel_hi:[1,0]
	v_pk_mul_f32 v[42:43], v[42:43], v[190:191] op_sel_hi:[1,0]
	v_pk_mul_f32 v[40:41], v[40:41], v[190:191] op_sel_hi:[1,0]
	v_pk_mul_f32 v[38:39], v[38:39], v[190:191] op_sel_hi:[1,0]
	v_pk_mul_f32 v[36:37], v[36:37], v[190:191] op_sel_hi:[1,0]
	v_pk_mul_f32 v[34:35], v[34:35], v[190:191] op_sel_hi:[1,0]
	v_pk_mul_f32 v[32:33], v[32:33], v[190:191] op_sel_hi:[1,0]
	v_pk_mul_f32 v[30:31], v[30:31], v[190:191] op_sel_hi:[1,0]
	v_pk_mul_f32 v[28:29], v[28:29], v[190:191] op_sel_hi:[1,0]
	v_pk_mul_f32 v[26:27], v[26:27], v[190:191] op_sel_hi:[1,0]
	v_pk_mul_f32 v[24:25], v[24:25], v[190:191] op_sel_hi:[1,0]
	v_pk_mul_f32 v[22:23], v[22:23], v[190:191] op_sel_hi:[1,0]
	v_pk_mul_f32 v[20:21], v[20:21], v[190:191] op_sel_hi:[1,0]
	v_pk_mul_f32 v[18:19], v[18:19], v[190:191] op_sel_hi:[1,0]
	v_pk_mul_f32 v[16:17], v[16:17], v[190:191] op_sel_hi:[1,0]
	v_pk_mul_f32 v[14:15], v[14:15], v[190:191] op_sel_hi:[1,0]
	v_pk_mul_f32 v[12:13], v[12:13], v[190:191] op_sel_hi:[1,0]
	v_pk_mul_f32 v[10:11], v[10:11], v[190:191] op_sel_hi:[1,0]
	v_pk_mul_f32 v[8:9], v[8:9], v[190:191] op_sel_hi:[1,0]
	v_pk_mul_f32 v[6:7], v[6:7], v[190:191] op_sel_hi:[1,0]
	v_pk_mul_f32 v[4:5], v[4:5], v[190:191] op_sel_hi:[1,0]
	v_pk_mul_f32 v[2:3], v[2:3], v[190:191] op_sel_hi:[1,0]
	v_pk_mul_f32 v[0:1], v[0:1], v[190:191] op_sel_hi:[1,0]
	v_mul_f32_e32 v202, v202, v190
	v_mov_b32_e32 v190, v246
.Latt_nr0_0s0:
	s_waitcnt lgkmcnt(3)
	v_mfma_f32_32x32x16_bf16 v[222:237], v[214:217], v[152:155], v[222:237]
	ds_read_b128 v[214:217], v200 offset:8192
	v_sub_f32_e32 v128, v128, v190
	v_exp_f32_e32 v128, v128
	v_sub_f32_e32 v129, v129, v190
	v_exp_f32_e32 v129, v129
	v_sub_f32_e32 v130, v130, v190
	s_waitcnt lgkmcnt(3)
	v_mfma_f32_32x32x16_bf16 v[222:237], v[238:241], v[156:159], v[222:237]
	ds_read_b128 v[238:241], v201 offset:8192
	v_add_f32_e32 v254, 0, v128
	v_exp_f32_e32 v130, v130
	v_sub_f32_e32 v131, v131, v190
	v_add_f32_e32 v254, v129, v254
	v_exp_f32_e32 v131, v131
	s_waitcnt lgkmcnt(3)
	v_mfma_f32_32x32x16_bf16 v[222:237], v[206:209], v[160:163], v[222:237]
	ds_read_b64_tr_b16 v[206:207], v205
	ds_read_b64_tr_b16 v[208:209], v205 offset:4096
	v_sub_f32_e32 v132, v132, v190
	v_add_f32_e32 v254, v130, v254
	v_exp_f32_e32 v132, v132
	v_sub_f32_e32 v133, v133, v190
	v_add_f32_e32 v254, v131, v254
	s_waitcnt lgkmcnt(4)
	v_mfma_f32_32x32x16_bf16 v[222:237], v[210:213], v[164:167], v[222:237]
	ds_read_b64_tr_b16 v[210:211], v218
	ds_read_b64_tr_b16 v[212:213], v218 offset:4096
	v_exp_f32_e32 v133, v133
	v_sub_f32_e32 v134, v134, v190
	v_add_f32_e32 v254, v132, v254
	v_exp_f32_e32 v134, v134
	s_waitcnt lgkmcnt(5)
	v_mfma_f32_32x32x16_bf16 v[222:237], v[214:217], v[168:171], v[222:237]
	ds_read_b64_tr_b16 v[214:215], v219
	ds_read_b64_tr_b16 v[216:217], v219 offset:4096
	v_sub_f32_e32 v135, v135, v190
	v_add_f32_e32 v254, v133, v254
	v_exp_f32_e32 v135, v135
	s_nop 0
	s_waitcnt lgkmcnt(6)
	v_mfma_f32_32x32x16_bf16 v[222:237], v[238:241], v[172:175], v[222:237]
	ds_read_b64_tr_b16 v[238:239], v221
	ds_read_b64_tr_b16 v[240:241], v221 offset:4096
	v_cvt_pk_bf16_f32 v242, v128, v129
	v_cvt_pk_bf16_f32 v243, v130, v131
	v_cvt_pk_bf16_f32 v244, v132, v133
	v_cvt_pk_bf16_f32 v245, v134, v135
	s_nop 1
	s_waitcnt lgkmcnt(6)
	v_mfma_f32_32x32x16_bf16 v[112:127], v[206:209], v[242:245], v[112:127]
	ds_read_b64_tr_b16 v[206:207], v205 offset:256
	ds_read_b64_tr_b16 v[208:209], v205 offset:4352
	v_sub_f32_e32 v136, v136, v190
	v_add_f32_e32 v254, v134, v254
	v_exp_f32_e32 v136, v136
	v_sub_f32_e32 v137, v137, v190
	v_add_f32_e32 v254, v135, v254
	s_waitcnt lgkmcnt(6)
	v_mfma_f32_32x32x16_bf16 v[96:111], v[210:213], v[242:245], v[96:111]
	ds_read_b64_tr_b16 v[210:211], v218 offset:256
	ds_read_b64_tr_b16 v[212:213], v218 offset:4352
	v_exp_f32_e32 v137, v137
	v_sub_f32_e32 v138, v138, v190
	v_add_f32_e32 v254, v136, v254
	v_exp_f32_e32 v138, v138
	v_sub_f32_e32 v139, v139, v190
	s_waitcnt lgkmcnt(6)
	v_mfma_f32_32x32x16_bf16 v[80:95], v[214:217], v[242:245], v[80:95]
	ds_read_b64_tr_b16 v[214:215], v219 offset:256
	ds_read_b64_tr_b16 v[216:217], v219 offset:4352
	v_add_f32_e32 v254, v137, v254
	v_exp_f32_e32 v139, v139
	v_sub_f32_e32 v140, v140, v190
	v_add_f32_e32 v254, v138, v254
	s_waitcnt lgkmcnt(6)
	v_mfma_f32_32x32x16_bf16 v[64:79], v[238:241], v[242:245], v[64:79]
	ds_read_b64_tr_b16 v[238:239], v221 offset:256
	ds_read_b64_tr_b16 v[240:241], v221 offset:4352
	v_exp_f32_e32 v140, v140
	v_sub_f32_e32 v141, v141, v190
	v_add_f32_e32 v254, v139, v254
	v_exp_f32_e32 v141, v141
	s_waitcnt lgkmcnt(6)
	v_mfma_f32_32x32x16_bf16 v[48:63], v[206:209], v[242:245], v[48:63]
	ds_read_b64_tr_b16 v[206:207], v205 offset:8192
	ds_read_b64_tr_b16 v[208:209], v205 offset:12288
	v_sub_f32_e32 v142, v142, v190
	v_add_f32_e32 v254, v140, v254
	v_exp_f32_e32 v142, v142
	v_sub_f32_e32 v143, v143, v190
	s_waitcnt lgkmcnt(6)
	v_mfma_f32_32x32x16_bf16 v[32:47], v[210:213], v[242:245], v[32:47]
	ds_read_b64_tr_b16 v[210:211], v218 offset:8192
	ds_read_b64_tr_b16 v[212:213], v218 offset:12288
	v_add_f32_e32 v254, v141, v254
	v_exp_f32_e32 v143, v143
	v_add_f32_e32 v254, v142, v254
	v_add_f32_e32 v254, v143, v254
	s_waitcnt lgkmcnt(6)
	v_mfma_f32_32x32x16_bf16 v[16:31], v[214:217], v[242:245], v[16:31]
	ds_read_b64_tr_b16 v[214:215], v219 offset:8192
	ds_read_b64_tr_b16 v[216:217], v219 offset:12288
	v_cvt_pk_bf16_f32 v250, v136, v137
	v_cvt_pk_bf16_f32 v251, v138, v139
	v_cvt_pk_bf16_f32 v252, v140, v141
	v_cvt_pk_bf16_f32 v253, v142, v143
	v_add_f32_e32 v202, v202, v254
	s_waitcnt lgkmcnt(6)
	v_mfma_f32_32x32x16_bf16 v[0:15], v[238:241], v[242:245], v[0:15]
	ds_read_b64_tr_b16 v[238:239], v221 offset:8192
	ds_read_b64_tr_b16 v[240:241], v221 offset:12288
	ds_read_b64_tr_b16 v[128:129], v205 offset:8448
	ds_read_b64_tr_b16 v[130:131], v205 offset:12544
	s_waitcnt lgkmcnt(8)
	v_mfma_f32_32x32x16_bf16 v[112:127], v[206:209], v[250:253], v[112:127]
	ds_read_b64_tr_b16 v[206:207], v218 offset:8448
	ds_read_b64_tr_b16 v[208:209], v218 offset:12544
	v_max3_f32 v246, v222, v223, v224
	v_max3_f32 v247, v225, v226, v227
	v_max3_f32 v246, v246, v228, v229
	v_max3_f32 v247, v247, v230, v231
	v_max3_f32 v246, v246, v232, v233
	s_waitcnt lgkmcnt(8)
	v_mfma_f32_32x32x16_bf16 v[96:111], v[210:213], v[250:253], v[96:111]
	ds_read_b64_tr_b16 v[210:211], v219 offset:8448
	ds_read_b64_tr_b16 v[212:213], v219 offset:12544
	v_max3_f32 v247, v247, v234, v235
	v_max3_f32 v246, v246, v236, v237
	v_max_f32_e32 v246, v246, v247
	v_mov_b32_e32 v247, v246
	v_add_f32_e32 v249, 0x41000000, v190
	s_waitcnt lgkmcnt(8)
	v_mfma_f32_32x32x16_bf16 v[80:95], v[214:217], v[250:253], v[80:95]
	ds_read_b64_tr_b16 v[214:215], v221 offset:8448
	ds_read_b64_tr_b16 v[216:217], v221 offset:12544
	s_nop 1
	v_permlane32_swap_b32_e32 v246, v247
	v_max_f32_e32 v246, v246, v247
	v_cmp_gt_f32_e32 vcc, v246, v249
	s_cbranch_vccnz .Latt_rs1_0s0
	s_waitcnt lgkmcnt(8)
	v_mfma_f32_32x32x16_bf16 v[64:79], v[238:241], v[250:253], v[64:79]
	ds_read_b64_tr_b16 v[238:239], v205 offset:16384
	ds_read_b64_tr_b16 v[240:241], v205 offset:20480
	v_sub_f32_e32 v222, v222, v190
	v_exp_f32_e32 v222, v222
	v_sub_f32_e32 v223, v223, v190
	v_exp_f32_e32 v223, v223
	v_sub_f32_e32 v224, v224, v190
	v_add_f32_e32 v254, 0, v222
	s_waitcnt lgkmcnt(8)
	v_mfma_f32_32x32x16_bf16 v[48:63], v[128:131], v[250:253], v[48:63]
	ds_read_b64_tr_b16 v[128:129], v218 offset:16384
	ds_read_b64_tr_b16 v[130:131], v218 offset:20480
	v_exp_f32_e32 v224, v224
	v_sub_f32_e32 v225, v225, v190
	v_add_f32_e32 v254, v223, v254
	v_exp_f32_e32 v225, v225
	v_sub_f32_e32 v226, v226, v190
	v_add_f32_e32 v254, v224, v254
	s_waitcnt lgkmcnt(8)
	v_mfma_f32_32x32x16_bf16 v[32:47], v[206:209], v[250:253], v[32:47]
	ds_read_b64_tr_b16 v[206:207], v219 offset:16384
	ds_read_b64_tr_b16 v[208:209], v219 offset:20480
	v_exp_f32_e32 v226, v226
	v_sub_f32_e32 v227, v227, v190
	v_add_f32_e32 v254, v225, v254
	v_exp_f32_e32 v227, v227
	v_sub_f32_e32 v228, v228, v190
	s_waitcnt lgkmcnt(8)
	v_mfma_f32_32x32x16_bf16 v[16:31], v[210:213], v[250:253], v[16:31]
	ds_read_b64_tr_b16 v[210:211], v221 offset:16384
	ds_read_b64_tr_b16 v[212:213], v221 offset:20480
	v_add_f32_e32 v254, v226, v254
	v_exp_f32_e32 v228, v228
	v_sub_f32_e32 v229, v229, v190
	v_add_f32_e32 v254, v227, v254
	v_exp_f32_e32 v229, v229
	s_waitcnt lgkmcnt(8)
	v_mfma_f32_32x32x16_bf16 v[0:15], v[214:217], v[250:253], v[0:15]
	ds_read_b64_tr_b16 v[214:215], v205 offset:16640
	ds_read_b64_tr_b16 v[216:217], v205 offset:20736
	s_nop 0
	v_cvt_pk_bf16_f32 v242, v222, v223
	v_cvt_pk_bf16_f32 v243, v224, v225
	v_cvt_pk_bf16_f32 v244, v226, v227
	v_cvt_pk_bf16_f32 v245, v228, v229
	s_nop 1
	s_waitcnt lgkmcnt(8)
	v_mfma_f32_32x32x16_bf16 v[112:127], v[238:241], v[242:245], v[112:127]
	ds_read_b64_tr_b16 v[238:239], v218 offset:16640
	ds_read_b64_tr_b16 v[240:241], v218 offset:20736
	v_sub_f32_e32 v230, v230, v190
	v_add_f32_e32 v254, v228, v254
	v_exp_f32_e32 v230, v230
	v_sub_f32_e32 v231, v231, v190
	v_add_f32_e32 v254, v229, v254
	s_waitcnt lgkmcnt(8)
	v_mfma_f32_32x32x16_bf16 v[96:111], v[128:131], v[242:245], v[96:111]
	ds_read_b64_tr_b16 v[128:129], v219 offset:16640
	ds_read_b64_tr_b16 v[130:131], v219 offset:20736
	v_exp_f32_e32 v231, v231
	v_sub_f32_e32 v232, v232, v190
	v_add_f32_e32 v254, v230, v254
	v_exp_f32_e32 v232, v232
	v_sub_f32_e32 v233, v233, v190
	s_cmp_lg_u64 s[18:19], 0
	s_cbranch_scc1 .Latt_nd0_0s0
	s_sub_i32 s100, s88, 1
	s_cmp_eq_u32 s88, 0
	s_cselect_b32 s100, 2, s100
	s_lshl_b32 s101, s100, 14
	s_add_i32 m0, s85, s101
	s_nop 0
	global_load_lds_dwordx4 v178, s[14:15]

.Latt_slow_0s0:
.Latt_slot1_0:
	ds_read_b128 v[206:209], v194 offset:16384
	ds_read_b128 v[210:213], v195 offset:16384
	ds_read_b128 v[214:217], v196 offset:16384
	ds_read_b128 v[238:241], v197 offset:16384
	ds_read_b128 v[242:245], v198 offset:16384
	ds_read_b128 v[250:253], v199 offset:16384
	ds_read_b128 v[222:225], v200 offset:16384
	ds_read_b128 v[226:229], v201 offset:16384
	v_add_u32_e32 v205, 0x8000, v205
	v_add_u32_e32 v218, 0x8000, v218
	v_add_u32_e32 v219, 0x8000, v219
	v_add_u32_e32 v221, 0x8000, v221
	s_waitcnt lgkmcnt(7)
	v_mfma_f32_32x32x16_bf16 v[128:143], v[206:209], v[144:147], 0
	ds_read_b128 v[206:209], v194 offset:24576
	s_waitcnt lgkmcnt(7)
	v_mfma_f32_32x32x16_bf16 v[128:143], v[210:213], v[148:151], v[128:143]
	ds_read_b128 v[210:213], v195 offset:24576
	s_waitcnt lgkmcnt(7)
	v_mfma_f32_32x32x16_bf16 v[128:143], v[214:217], v[152:155], v[128:143]
	ds_read_b128 v[214:217], v196 offset:24576
	s_waitcnt lgkmcnt(7)
	v_mfma_f32_32x32x16_bf16 v[128:143], v[238:241], v[156:159], v[128:143]
	ds_read_b128 v[238:241], v197 offset:24576
	s_waitcnt lgkmcnt(7)
	v_mfma_f32_32x32x16_bf16 v[128:143], v[242:245], v[160:163], v[128:143]
	s_waitcnt lgkmcnt(6)
	v_mfma_f32_32x32x16_bf16 v[128:143], v[250:253], v[164:167], v[128:143]
	s_waitcnt lgkmcnt(5)
	v_mfma_f32_32x32x16_bf16 v[128:143], v[222:225], v[168:171], v[128:143]
	s_waitcnt lgkmcnt(4)
	v_mfma_f32_32x32x16_bf16 v[128:143], v[226:229], v[172:175], v[128:143]
	s_waitcnt lgkmcnt(3)
	v_mfma_f32_32x32x16_bf16 v[222:237], v[206:209], v[144:147], 0
	ds_read_b128 v[206:209], v198 offset:24576
	s_nop 8
	v_max3_f32 v246, v128, v129, v130
	v_max3_f32 v247, v131, v132, v133
	v_max3_f32 v246, v246, v134, v135
	v_max3_f32 v247, v247, v136, v137
	v_max3_f32 v246, v246, v138, v139
	v_max3_f32 v247, v247, v140, v141
	v_max3_f32 v246, v246, v142, v143
	s_waitcnt lgkmcnt(3)
	v_mfma_f32_32x32x16_bf16 v[222:237], v[210:213], v[148:151], v[222:237]
	ds_read_b128 v[210:213], v199 offset:24576
	v_max_f32_e32 v246, v246, v247
	v_mov_b32_e32 v247, v246
	v_add_f32_e32 v249, 0x41000000, v190
	s_nop 1
	v_permlane32_swap_b32_e32 v246, v247
	v_max_f32_e32 v246, v246, v247
	v_cmp_gt_f32_e32 vcc, v246, v249
	s_cbranch_vccz .Latt_nr0_0s1
	v_max_f32_e32 v246, v190, v246
	v_sub_f32_e32 v190, v190, v246
	v_exp_f32_e32 v190, v190
	s_nop 0
	v_pk_mul_f32 v[126:127], v[126:127], v[190:191] op_sel_hi:[1,0]
	v_pk_mul_f32 v[124:125], v[124:125], v[190:191] op_sel_hi:[1,0]
	v_pk_mul_f32 v[122:123], v[122:123], v[190:191] op_sel_hi:[1,0]
	v_pk_mul_f32 v[120:121], v[120:121], v[190:191] op_sel_hi:[1,0]
	v_pk_mul_f32 v[118:119], v[118:119], v[190:191] op_sel_hi:[1,0]
	v_pk_mul_f32 v[116:117], v[116:117], v[190:191] op_sel_hi:[1,0]
	v_pk_mul_f32 v[114:115], v[114:115], v[190:191] op_sel_hi:[1,0]
	v_pk_mul_f32 v[112:113], v[112:113], v[190:191] op_sel_hi:[1,0]
	v_pk_mul_f32 v[110:111], v[110:111], v[190:191] op_sel_hi:[1,0]
	v_pk_mul_f32 v[108:109], v[108:109], v[190:191] op_sel_hi:[1,0]
	v_pk_mul_f32 v[106:107], v[106:107], v[190:191] op_sel_hi:[1,0]
	v_pk_mul_f32 v[104:105], v[104:105], v[190:191] op_sel_hi:[1,0]
	v_pk_mul_f32 v[102:103], v[102:103], v[190:191] op_sel_hi:[1,0]
	v_pk_mul_f32 v[100:101], v[100:101], v[190:191] op_sel_hi:[1,0]
	v_pk_mul_f32 v[98:99], v[98:99], v[190:191] op_sel_hi:[1,0]
	v_pk_mul_f32 v[96:97], v[96:97], v[190:191] op_sel_hi:[1,0]
	v_pk_mul_f32 v[94:95], v[94:95], v[190:191] op_sel_hi:[1,0]
	v_pk_mul_f32 v[92:93], v[92:93], v[190:191] op_sel_hi:[1,0]
	v_pk_mul_f32 v[90:91], v[90:91], v[190:191] op_sel_hi:[1,0]
	v_pk_mul_f32 v[88:89], v[88:89], v[190:191] op_sel_hi:[1,0]
	v_pk_mul_f32 v[86:87], v[86:87], v[190:191] op_sel_hi:[1,0]
	v_pk_mul_f32 v[84:85], v[84:85], v[190:191] op_sel_hi:[1,0]
	v_pk_mul_f32 v[82:83], v[82:83], v[190:191] op_sel_hi:[1,0]
	v_pk_mul_f32 v[80:81], v[80:81], v[190:191] op_sel_hi:[1,0]
	v_pk_mul_f32 v[78:79], v[78:79], v[190:191] op_sel_hi:[1,0]
	v_pk_mul_f32 v[76:77], v[76:77], v[190:191] op_sel_hi:[1,0]
	v_pk_mul_f32 v[74:75], v[74:75], v[190:191] op_sel_hi:[1,0]
	v_pk_mul_f32 v[72:73], v[72:73], v[190:191] op_sel_hi:[1,0]
	v_pk_mul_f32 v[70:71], v[70:71], v[190:191] op_sel_hi:[1,0]
	v_pk_mul_f32 v[68:69], v[68:69], v[190:191] op_sel_hi:[1,0]
	v_pk_mul_f32 v[66:67], v[66:67], v[190:191] op_sel_hi:[1,0]
	v_pk_mul_f32 v[64:65], v[64:65], v[190:191] op_sel_hi:[1,0]
	v_pk_mul_f32 v[62:63], v[62:63], v[190:191] op_sel_hi:[1,0]
	v_pk_mul_f32 v[60:61], v[60:61], v[190:191] op_sel_hi:[1,0]
	v_pk_mul_f32 v[58:59], v[58:59], v[190:191] op_sel_hi:[1,0]
	v_pk_mul_f32 v[56:57], v[56:57], v[190:191] op_sel_hi:[1,0]
	v_pk_mul_f32 v[54:55], v[54:55], v[190:191] op_sel_hi:[1,0]
	v_pk_mul_f32 v[52:53], v[52:53], v[190:191] op_sel_hi:[1,0]
	v_pk_mul_f32 v[50:51], v[50:51], v[190:191] op_sel_hi:[1,0]
	v_pk_mul_f32 v[48:49], v[48:49], v[190:191] op_sel_hi:[1,0]
	v_pk_mul_f32 v[46:47], v[46:47], v[190:191] op_sel_hi:[1,0]
	v_pk_mul_f32 v[44:45], v[44:45], v[190:191] op_sel_hi:[1,0]
	v_pk_mul_f32 v[42:43], v[42:43], v[190:191] op_sel_hi:[1,0]
	v_pk_mul_f32 v[40:41], v[40:41], v[190:191] op_sel_hi:[1,0]
	v_pk_mul_f32 v[38:39], v[38:39], v[190:191] op_sel_hi:[1,0]
	v_pk_mul_f32 v[36:37], v[36:37], v[190:191] op_sel_hi:[1,0]
	v_pk_mul_f32 v[34:35], v[34:35], v[190:191] op_sel_hi:[1,0]
	v_pk_mul_f32 v[32:33], v[32:33], v[190:191] op_sel_hi:[1,0]
	v_pk_mul_f32 v[30:31], v[30:31], v[190:191] op_sel_hi:[1,0]
	v_pk_mul_f32 v[28:29], v[28:29], v[190:191] op_sel_hi:[1,0]
	v_pk_mul_f32 v[26:27], v[26:27], v[190:191] op_sel_hi:[1,0]
	v_pk_mul_f32 v[24:25], v[24:25], v[190:191] op_sel_hi:[1,0]
	v_pk_mul_f32 v[22:23], v[22:23], v[190:191] op_sel_hi:[1,0]
	v_pk_mul_f32 v[20:21], v[20:21], v[190:191] op_sel_hi:[1,0]
	v_pk_mul_f32 v[18:19], v[18:19], v[190:191] op_sel_hi:[1,0]
	v_pk_mul_f32 v[16:17], v[16:17], v[190:191] op_sel_hi:[1,0]
	v_pk_mul_f32 v[14:15], v[14:15], v[190:191] op_sel_hi:[1,0]
	v_pk_mul_f32 v[12:13], v[12:13], v[190:191] op_sel_hi:[1,0]
	v_pk_mul_f32 v[10:11], v[10:11], v[190:191] op_sel_hi:[1,0]
	v_pk_mul_f32 v[8:9], v[8:9], v[190:191] op_sel_hi:[1,0]
	v_pk_mul_f32 v[6:7], v[6:7], v[190:191] op_sel_hi:[1,0]
	v_pk_mul_f32 v[4:5], v[4:5], v[190:191] op_sel_hi:[1,0]
	v_pk_mul_f32 v[2:3], v[2:3], v[190:191] op_sel_hi:[1,0]
	v_pk_mul_f32 v[0:1], v[0:1], v[190:191] op_sel_hi:[1,0]
	v_mul_f32_e32 v202, v202, v190
	v_mov_b32_e32 v190, v246
.Latt_nr0_0s1:
	s_waitcnt lgkmcnt(3)
	v_mfma_f32_32x32x16_bf16 v[222:237], v[214:217], v[152:155], v[222:237]
	ds_read_b128 v[214:217], v200 offset:24576
	v_sub_f32_e32 v128, v128, v190
	v_exp_f32_e32 v128, v128
	v_sub_f32_e32 v129, v129, v190
	v_exp_f32_e32 v129, v129
	v_sub_f32_e32 v130, v130, v190
	s_waitcnt lgkmcnt(3)
	v_mfma_f32_32x32x16_bf16 v[222:237], v[238:241], v[156:159], v[222:237]
	ds_read_b128 v[238:241], v201 offset:24576
	v_add_f32_e32 v254, 0, v128
	v_exp_f32_e32 v130, v130
	v_sub_f32_e32 v131, v131, v190
	v_add_f32_e32 v254, v129, v254
	v_exp_f32_e32 v131, v131
	s_waitcnt lgkmcnt(3)
	v_mfma_f32_32x32x16_bf16 v[222:237], v[206:209], v[160:163], v[222:237]
	ds_read_b64_tr_b16 v[206:207], v205
	ds_read_b64_tr_b16 v[208:209], v205 offset:4096
	v_sub_f32_e32 v132, v132, v190
	v_add_f32_e32 v254, v130, v254
	v_exp_f32_e32 v132, v132
	v_sub_f32_e32 v133, v133, v190
	v_add_f32_e32 v254, v131, v254
	s_waitcnt lgkmcnt(4)
	v_mfma_f32_32x32x16_bf16 v[222:237], v[210:213], v[164:167], v[222:237]
	ds_read_b64_tr_b16 v[210:211], v218
	ds_read_b64_tr_b16 v[212:213], v218 offset:4096
	v_exp_f32_e32 v133, v133
	v_sub_f32_e32 v134, v134, v190
	v_add_f32_e32 v254, v132, v254
	v_exp_f32_e32 v134, v134
	s_waitcnt lgkmcnt(5)
	v_mfma_f32_32x32x16_bf16 v[222:237], v[214:217], v[168:171], v[222:237]
	ds_read_b64_tr_b16 v[214:215], v219
	ds_read_b64_tr_b16 v[216:217], v219 offset:4096
	v_sub_f32_e32 v135, v135, v190
	v_add_f32_e32 v254, v133, v254
	v_exp_f32_e32 v135, v135
	s_nop 0
	s_waitcnt lgkmcnt(6)
	v_mfma_f32_32x32x16_bf16 v[222:237], v[238:241], v[172:175], v[222:237]
	ds_read_b64_tr_b16 v[238:239], v221
	ds_read_b64_tr_b16 v[240:241], v221 offset:4096
	v_cvt_pk_bf16_f32 v242, v128, v129
	v_cvt_pk_bf16_f32 v243, v130, v131
	v_cvt_pk_bf16_f32 v244, v132, v133
	v_cvt_pk_bf16_f32 v245, v134, v135
	s_nop 1
	s_waitcnt lgkmcnt(6)
	v_mfma_f32_32x32x16_bf16 v[112:127], v[206:209], v[242:245], v[112:127]
	ds_read_b64_tr_b16 v[206:207], v205 offset:256
	ds_read_b64_tr_b16 v[208:209], v205 offset:4352
	v_sub_f32_e32 v136, v136, v190
	v_add_f32_e32 v254, v134, v254
	v_exp_f32_e32 v136, v136
	v_sub_f32_e32 v137, v137, v190
	v_add_f32_e32 v254, v135, v254
	s_waitcnt lgkmcnt(6)
	v_mfma_f32_32x32x16_bf16 v[96:111], v[210:213], v[242:245], v[96:111]
	ds_read_b64_tr_b16 v[210:211], v218 offset:256
	ds_read_b64_tr_b16 v[212:213], v218 offset:4352
	v_exp_f32_e32 v137, v137
	v_sub_f32_e32 v138, v138, v190
	v_add_f32_e32 v254, v136, v254
	v_exp_f32_e32 v138, v138
	v_sub_f32_e32 v139, v139, v190
	s_waitcnt lgkmcnt(6)
	v_mfma_f32_32x32x16_bf16 v[80:95], v[214:217], v[242:245], v[80:95]
	ds_read_b64_tr_b16 v[214:215], v219 offset:256
	ds_read_b64_tr_b16 v[216:217], v219 offset:4352
	v_add_f32_e32 v254, v137, v254
	v_exp_f32_e32 v139, v139
	v_sub_f32_e32 v140, v140, v190
	v_add_f32_e32 v254, v138, v254
	s_waitcnt lgkmcnt(6)
	v_mfma_f32_32x32x16_bf16 v[64:79], v[238:241], v[242:245], v[64:79]
	ds_read_b64_tr_b16 v[238:239], v221 offset:256
	ds_read_b64_tr_b16 v[240:241], v221 offset:4352
	v_exp_f32_e32 v140, v140
	v_sub_f32_e32 v141, v141, v190
	v_add_f32_e32 v254, v139, v254
	v_exp_f32_e32 v141, v141
	s_waitcnt lgkmcnt(6)
	v_mfma_f32_32x32x16_bf16 v[48:63], v[206:209], v[242:245], v[48:63]
	ds_read_b64_tr_b16 v[206:207], v205 offset:8192
	ds_read_b64_tr_b16 v[208:209], v205 offset:12288
	v_sub_f32_e32 v142, v142, v190
	v_add_f32_e32 v254, v140, v254
	v_exp_f32_e32 v142, v142
	v_sub_f32_e32 v143, v143, v190
	s_waitcnt lgkmcnt(6)
	v_mfma_f32_32x32x16_bf16 v[32:47], v[210:213], v[242:245], v[32:47]
	ds_read_b64_tr_b16 v[210:211], v218 offset:8192
	ds_read_b64_tr_b16 v[212:213], v218 offset:12288
	v_add_f32_e32 v254, v141, v254
	v_exp_f32_e32 v143, v143
	v_add_f32_e32 v254, v142, v254
	v_add_f32_e32 v254, v143, v254
	s_waitcnt lgkmcnt(6)
	v_mfma_f32_32x32x16_bf16 v[16:31], v[214:217], v[242:245], v[16:31]
	ds_read_b64_tr_b16 v[214:215], v219 offset:8192
	ds_read_b64_tr_b16 v[216:217], v219 offset:12288
	v_cvt_pk_bf16_f32 v250, v136, v137
	v_cvt_pk_bf16_f32 v251, v138, v139
	v_cvt_pk_bf16_f32 v252, v140, v141
	v_cvt_pk_bf16_f32 v253, v142, v143
	v_add_f32_e32 v202, v202, v254
	s_waitcnt lgkmcnt(6)
	v_mfma_f32_32x32x16_bf16 v[0:15], v[238:241], v[242:245], v[0:15]
	ds_read_b64_tr_b16 v[238:239], v221 offset:8192
	ds_read_b64_tr_b16 v[240:241], v221 offset:12288
	ds_read_b64_tr_b16 v[128:129], v205 offset:8448
	ds_read_b64_tr_b16 v[130:131], v205 offset:12544
	s_waitcnt lgkmcnt(8)
	v_mfma_f32_32x32x16_bf16 v[112:127], v[206:209], v[250:253], v[112:127]
	ds_read_b64_tr_b16 v[206:207], v218 offset:8448
	ds_read_b64_tr_b16 v[208:209], v218 offset:12544
	v_max3_f32 v246, v222, v223, v224
	v_max3_f32 v247, v225, v226, v227
	v_max3_f32 v246, v246, v228, v229
	v_max3_f32 v247, v247, v230, v231
	v_max3_f32 v246, v246, v232, v233
	s_waitcnt lgkmcnt(8)
	v_mfma_f32_32x32x16_bf16 v[96:111], v[210:213], v[250:253], v[96:111]
	ds_read_b64_tr_b16 v[210:211], v219 offset:8448
	ds_read_b64_tr_b16 v[212:213], v219 offset:12544
	v_max3_f32 v247, v247, v234, v235
	v_max3_f32 v246, v246, v236, v237
	v_max_f32_e32 v246, v246, v247
	v_mov_b32_e32 v247, v246
	v_add_f32_e32 v249, 0x41000000, v190
	s_waitcnt lgkmcnt(8)
	v_mfma_f32_32x32x16_bf16 v[80:95], v[214:217], v[250:253], v[80:95]
	ds_read_b64_tr_b16 v[214:215], v221 offset:8448
	ds_read_b64_tr_b16 v[216:217], v221 offset:12544
	s_nop 1
	v_permlane32_swap_b32_e32 v246, v247
	v_max_f32_e32 v246, v246, v247
	v_cmp_gt_f32_e32 vcc, v246, v249
	s_cbranch_vccnz .Latt_rs1_0s1
	s_waitcnt lgkmcnt(8)
	v_mfma_f32_32x32x16_bf16 v[64:79], v[238:241], v[250:253], v[64:79]
	ds_read_b64_tr_b16 v[238:239], v205 offset:16384
	ds_read_b64_tr_b16 v[240:241], v205 offset:20480
	v_sub_f32_e32 v222, v222, v190
	v_exp_f32_e32 v222, v222
	v_sub_f32_e32 v223, v223, v190
	v_exp_f32_e32 v223, v223
	v_sub_f32_e32 v224, v224, v190
	v_add_f32_e32 v254, 0, v222
	s_waitcnt lgkmcnt(8)
	v_mfma_f32_32x32x16_bf16 v[48:63], v[128:131], v[250:253], v[48:63]
	ds_read_b64_tr_b16 v[128:129], v218 offset:16384
	ds_read_b64_tr_b16 v[130:131], v218 offset:20480
	v_exp_f32_e32 v224, v224
	v_sub_f32_e32 v225, v225, v190
	v_add_f32_e32 v254, v223, v254
	v_exp_f32_e32 v225, v225
	v_sub_f32_e32 v226, v226, v190
	v_add_f32_e32 v254, v224, v254
	s_waitcnt lgkmcnt(8)
	v_mfma_f32_32x32x16_bf16 v[32:47], v[206:209], v[250:253], v[32:47]
	ds_read_b64_tr_b16 v[206:207], v219 offset:16384
	ds_read_b64_tr_b16 v[208:209], v219 offset:20480
	v_exp_f32_e32 v226, v226
	v_sub_f32_e32 v227, v227, v190
	v_add_f32_e32 v254, v225, v254
	v_exp_f32_e32 v227, v227
	v_sub_f32_e32 v228, v228, v190
	s_waitcnt lgkmcnt(8)
	v_mfma_f32_32x32x16_bf16 v[16:31], v[210:213], v[250:253], v[16:31]
	ds_read_b64_tr_b16 v[210:211], v221 offset:16384
	ds_read_b64_tr_b16 v[212:213], v221 offset:20480
	v_add_f32_e32 v254, v226, v254
	v_exp_f32_e32 v228, v228
	v_sub_f32_e32 v229, v229, v190
	v_add_f32_e32 v254, v227, v254
	v_exp_f32_e32 v229, v229
	s_waitcnt lgkmcnt(8)
	v_mfma_f32_32x32x16_bf16 v[0:15], v[214:217], v[250:253], v[0:15]
	ds_read_b64_tr_b16 v[214:215], v205 offset:16640
	ds_read_b64_tr_b16 v[216:217], v205 offset:20736
	s_nop 0
	v_cvt_pk_bf16_f32 v242, v222, v223
	v_cvt_pk_bf16_f32 v243, v224, v225
	v_cvt_pk_bf16_f32 v244, v226, v227
	v_cvt_pk_bf16_f32 v245, v228, v229
	s_nop 1
	s_waitcnt lgkmcnt(8)
	v_mfma_f32_32x32x16_bf16 v[112:127], v[238:241], v[242:245], v[112:127]
	ds_read_b64_tr_b16 v[238:239], v218 offset:16640
	ds_read_b64_tr_b16 v[240:241], v218 offset:20736
	v_sub_f32_e32 v230, v230, v190
	v_add_f32_e32 v254, v228, v254
	v_exp_f32_e32 v230, v230
	v_sub_f32_e32 v231, v231, v190
	v_add_f32_e32 v254, v229, v254
	s_waitcnt lgkmcnt(8)
	v_mfma_f32_32x32x16_bf16 v[96:111], v[128:131], v[242:245], v[96:111]
	ds_read_b64_tr_b16 v[128:129], v219 offset:16640
	ds_read_b64_tr_b16 v[130:131], v219 offset:20736
	v_exp_f32_e32 v231, v231
	v_sub_f32_e32 v232, v232, v190
	v_add_f32_e32 v254, v230, v254
	v_exp_f32_e32 v232, v232
	v_sub_f32_e32 v233, v233, v190
	s_cmp_lg_u64 s[18:19], 0
	s_cbranch_scc1 .Latt_nd0_0s1
	s_sub_i32 s100, s88, 1
	s_cmp_eq_u32 s88, 0
	s_cselect_b32 s100, 2, s100
	s_lshl_b32 s101, s100, 14
	s_add_i32 m0, s85, s101
	s_nop 0
	global_load_lds_dwordx4 v178, s[14:15]

.Latt_slow_0s1:
.Latt_slot2_0:
	ds_read_b128 v[206:209], v194 offset:32768
	ds_read_b128 v[210:213], v195 offset:32768
	ds_read_b128 v[214:217], v196 offset:32768
	ds_read_b128 v[238:241], v197 offset:32768
	ds_read_b128 v[242:245], v198 offset:32768
	ds_read_b128 v[250:253], v199 offset:32768
	ds_read_b128 v[222:225], v200 offset:32768
	ds_read_b128 v[226:229], v201 offset:32768
	v_add_u32_e32 v205, 0x8000, v205
	v_add_u32_e32 v218, 0x8000, v218
	v_add_u32_e32 v219, 0x8000, v219
	v_add_u32_e32 v221, 0x8000, v221
	s_waitcnt lgkmcnt(7)
	v_mfma_f32_32x32x16_bf16 v[128:143], v[206:209], v[144:147], 0
	ds_read_b128 v[206:209], v194 offset:40960
	s_waitcnt lgkmcnt(7)
	v_mfma_f32_32x32x16_bf16 v[128:143], v[210:213], v[148:151], v[128:143]
	ds_read_b128 v[210:213], v195 offset:40960
	s_waitcnt lgkmcnt(7)
	v_mfma_f32_32x32x16_bf16 v[128:143], v[214:217], v[152:155], v[128:143]
	ds_read_b128 v[214:217], v196 offset:40960
	s_waitcnt lgkmcnt(7)
	v_mfma_f32_32x32x16_bf16 v[128:143], v[238:241], v[156:159], v[128:143]
	ds_read_b128 v[238:241], v197 offset:40960
	s_waitcnt lgkmcnt(7)
	v_mfma_f32_32x32x16_bf16 v[128:143], v[242:245], v[160:163], v[128:143]
	s_waitcnt lgkmcnt(6)
	v_mfma_f32_32x32x16_bf16 v[128:143], v[250:253], v[164:167], v[128:143]
	s_waitcnt lgkmcnt(5)
	v_mfma_f32_32x32x16_bf16 v[128:143], v[222:225], v[168:171], v[128:143]
	s_waitcnt lgkmcnt(4)
	v_mfma_f32_32x32x16_bf16 v[128:143], v[226:229], v[172:175], v[128:143]
	s_waitcnt lgkmcnt(3)
	v_mfma_f32_32x32x16_bf16 v[222:237], v[206:209], v[144:147], 0
	ds_read_b128 v[206:209], v198 offset:40960
	s_nop 8
	v_max3_f32 v246, v128, v129, v130
	v_max3_f32 v247, v131, v132, v133
	v_max3_f32 v246, v246, v134, v135
	v_max3_f32 v247, v247, v136, v137
	v_max3_f32 v246, v246, v138, v139
	v_max3_f32 v247, v247, v140, v141
	v_max3_f32 v246, v246, v142, v143
	s_waitcnt lgkmcnt(3)
	v_mfma_f32_32x32x16_bf16 v[222:237], v[210:213], v[148:151], v[222:237]
	ds_read_b128 v[210:213], v199 offset:40960
	v_max_f32_e32 v246, v246, v247
	v_mov_b32_e32 v247, v246
	v_add_f32_e32 v249, 0x41000000, v190
	s_nop 1
	v_permlane32_swap_b32_e32 v246, v247
	v_max_f32_e32 v246, v246, v247
	v_cmp_gt_f32_e32 vcc, v246, v249
	s_cbranch_vccz .Latt_nr0_0s2
	v_max_f32_e32 v246, v190, v246
	v_sub_f32_e32 v190, v190, v246
	v_exp_f32_e32 v190, v190
	s_nop 0
	v_pk_mul_f32 v[126:127], v[126:127], v[190:191] op_sel_hi:[1,0]
	v_pk_mul_f32 v[124:125], v[124:125], v[190:191] op_sel_hi:[1,0]
	v_pk_mul_f32 v[122:123], v[122:123], v[190:191] op_sel_hi:[1,0]
	v_pk_mul_f32 v[120:121], v[120:121], v[190:191] op_sel_hi:[1,0]
	v_pk_mul_f32 v[118:119], v[118:119], v[190:191] op_sel_hi:[1,0]
	v_pk_mul_f32 v[116:117], v[116:117], v[190:191] op_sel_hi:[1,0]
	v_pk_mul_f32 v[114:115], v[114:115], v[190:191] op_sel_hi:[1,0]
	v_pk_mul_f32 v[112:113], v[112:113], v[190:191] op_sel_hi:[1,0]
	v_pk_mul_f32 v[110:111], v[110:111], v[190:191] op_sel_hi:[1,0]
	v_pk_mul_f32 v[108:109], v[108:109], v[190:191] op_sel_hi:[1,0]
	v_pk_mul_f32 v[106:107], v[106:107], v[190:191] op_sel_hi:[1,0]
	v_pk_mul_f32 v[104:105], v[104:105], v[190:191] op_sel_hi:[1,0]
	v_pk_mul_f32 v[102:103], v[102:103], v[190:191] op_sel_hi:[1,0]
	v_pk_mul_f32 v[100:101], v[100:101], v[190:191] op_sel_hi:[1,0]
	v_pk_mul_f32 v[98:99], v[98:99], v[190:191] op_sel_hi:[1,0]
	v_pk_mul_f32 v[96:97], v[96:97], v[190:191] op_sel_hi:[1,0]
	v_pk_mul_f32 v[94:95], v[94:95], v[190:191] op_sel_hi:[1,0]
	v_pk_mul_f32 v[92:93], v[92:93], v[190:191] op_sel_hi:[1,0]
	v_pk_mul_f32 v[90:91], v[90:91], v[190:191] op_sel_hi:[1,0]
	v_pk_mul_f32 v[88:89], v[88:89], v[190:191] op_sel_hi:[1,0]
	v_pk_mul_f32 v[86:87], v[86:87], v[190:191] op_sel_hi:[1,0]
	v_pk_mul_f32 v[84:85], v[84:85], v[190:191] op_sel_hi:[1,0]
	v_pk_mul_f32 v[82:83], v[82:83], v[190:191] op_sel_hi:[1,0]
	v_pk_mul_f32 v[80:81], v[80:81], v[190:191] op_sel_hi:[1,0]
	v_pk_mul_f32 v[78:79], v[78:79], v[190:191] op_sel_hi:[1,0]
	v_pk_mul_f32 v[76:77], v[76:77], v[190:191] op_sel_hi:[1,0]
	v_pk_mul_f32 v[74:75], v[74:75], v[190:191] op_sel_hi:[1,0]
	v_pk_mul_f32 v[72:73], v[72:73], v[190:191] op_sel_hi:[1,0]
	v_pk_mul_f32 v[70:71], v[70:71], v[190:191] op_sel_hi:[1,0]
	v_pk_mul_f32 v[68:69], v[68:69], v[190:191] op_sel_hi:[1,0]
	v_pk_mul_f32 v[66:67], v[66:67], v[190:191] op_sel_hi:[1,0]
	v_pk_mul_f32 v[64:65], v[64:65], v[190:191] op_sel_hi:[1,0]
	v_pk_mul_f32 v[62:63], v[62:63], v[190:191] op_sel_hi:[1,0]
	v_pk_mul_f32 v[60:61], v[60:61], v[190:191] op_sel_hi:[1,0]
	v_pk_mul_f32 v[58:59], v[58:59], v[190:191] op_sel_hi:[1,0]
	v_pk_mul_f32 v[56:57], v[56:57], v[190:191] op_sel_hi:[1,0]
	v_pk_mul_f32 v[54:55], v[54:55], v[190:191] op_sel_hi:[1,0]
	v_pk_mul_f32 v[52:53], v[52:53], v[190:191] op_sel_hi:[1,0]
	v_pk_mul_f32 v[50:51], v[50:51], v[190:191] op_sel_hi:[1,0]
	v_pk_mul_f32 v[48:49], v[48:49], v[190:191] op_sel_hi:[1,0]
	v_pk_mul_f32 v[46:47], v[46:47], v[190:191] op_sel_hi:[1,0]
	v_pk_mul_f32 v[44:45], v[44:45], v[190:191] op_sel_hi:[1,0]
	v_pk_mul_f32 v[42:43], v[42:43], v[190:191] op_sel_hi:[1,0]
	v_pk_mul_f32 v[40:41], v[40:41], v[190:191] op_sel_hi:[1,0]
	v_pk_mul_f32 v[38:39], v[38:39], v[190:191] op_sel_hi:[1,0]
	v_pk_mul_f32 v[36:37], v[36:37], v[190:191] op_sel_hi:[1,0]
	v_pk_mul_f32 v[34:35], v[34:35], v[190:191] op_sel_hi:[1,0]
	v_pk_mul_f32 v[32:33], v[32:33], v[190:191] op_sel_hi:[1,0]
	v_pk_mul_f32 v[30:31], v[30:31], v[190:191] op_sel_hi:[1,0]
	v_pk_mul_f32 v[28:29], v[28:29], v[190:191] op_sel_hi:[1,0]
	v_pk_mul_f32 v[26:27], v[26:27], v[190:191] op_sel_hi:[1,0]
	v_pk_mul_f32 v[24:25], v[24:25], v[190:191] op_sel_hi:[1,0]
	v_pk_mul_f32 v[22:23], v[22:23], v[190:191] op_sel_hi:[1,0]
	v_pk_mul_f32 v[20:21], v[20:21], v[190:191] op_sel_hi:[1,0]
	v_pk_mul_f32 v[18:19], v[18:19], v[190:191] op_sel_hi:[1,0]
	v_pk_mul_f32 v[16:17], v[16:17], v[190:191] op_sel_hi:[1,0]
	v_pk_mul_f32 v[14:15], v[14:15], v[190:191] op_sel_hi:[1,0]
	v_pk_mul_f32 v[12:13], v[12:13], v[190:191] op_sel_hi:[1,0]
	v_pk_mul_f32 v[10:11], v[10:11], v[190:191] op_sel_hi:[1,0]
	v_pk_mul_f32 v[8:9], v[8:9], v[190:191] op_sel_hi:[1,0]
	v_pk_mul_f32 v[6:7], v[6:7], v[190:191] op_sel_hi:[1,0]
	v_pk_mul_f32 v[4:5], v[4:5], v[190:191] op_sel_hi:[1,0]
	v_pk_mul_f32 v[2:3], v[2:3], v[190:191] op_sel_hi:[1,0]
	v_pk_mul_f32 v[0:1], v[0:1], v[190:191] op_sel_hi:[1,0]
	v_mul_f32_e32 v202, v202, v190
	v_mov_b32_e32 v190, v246
.Latt_nr0_0s2:
	s_waitcnt lgkmcnt(3)
	v_mfma_f32_32x32x16_bf16 v[222:237], v[214:217], v[152:155], v[222:237]
	ds_read_b128 v[214:217], v200 offset:40960
	v_sub_f32_e32 v128, v128, v190
	v_exp_f32_e32 v128, v128
	v_sub_f32_e32 v129, v129, v190
	v_exp_f32_e32 v129, v129
	v_sub_f32_e32 v130, v130, v190
	s_waitcnt lgkmcnt(3)
	v_mfma_f32_32x32x16_bf16 v[222:237], v[238:241], v[156:159], v[222:237]
	ds_read_b128 v[238:241], v201 offset:40960
	v_add_f32_e32 v254, 0, v128
	v_exp_f32_e32 v130, v130
	v_sub_f32_e32 v131, v131, v190
	v_add_f32_e32 v254, v129, v254
	v_exp_f32_e32 v131, v131
	s_waitcnt lgkmcnt(3)
	v_mfma_f32_32x32x16_bf16 v[222:237], v[206:209], v[160:163], v[222:237]
	ds_read_b64_tr_b16 v[206:207], v205
	ds_read_b64_tr_b16 v[208:209], v205 offset:4096
	v_sub_f32_e32 v132, v132, v190
	v_add_f32_e32 v254, v130, v254
	v_exp_f32_e32 v132, v132
	v_sub_f32_e32 v133, v133, v190
	v_add_f32_e32 v254, v131, v254
	s_waitcnt lgkmcnt(4)
	v_mfma_f32_32x32x16_bf16 v[222:237], v[210:213], v[164:167], v[222:237]
	ds_read_b64_tr_b16 v[210:211], v218
	ds_read_b64_tr_b16 v[212:213], v218 offset:4096
	v_exp_f32_e32 v133, v133
	v_sub_f32_e32 v134, v134, v190
	v_add_f32_e32 v254, v132, v254
	v_exp_f32_e32 v134, v134
	s_waitcnt lgkmcnt(5)
	v_mfma_f32_32x32x16_bf16 v[222:237], v[214:217], v[168:171], v[222:237]
	ds_read_b64_tr_b16 v[214:215], v219
	ds_read_b64_tr_b16 v[216:217], v219 offset:4096
	v_sub_f32_e32 v135, v135, v190
	v_add_f32_e32 v254, v133, v254
	v_exp_f32_e32 v135, v135
	s_nop 0
	s_waitcnt lgkmcnt(6)
	v_mfma_f32_32x32x16_bf16 v[222:237], v[238:241], v[172:175], v[222:237]
	ds_read_b64_tr_b16 v[238:239], v221
	ds_read_b64_tr_b16 v[240:241], v221 offset:4096
	v_cvt_pk_bf16_f32 v242, v128, v129
	v_cvt_pk_bf16_f32 v243, v130, v131
	v_cvt_pk_bf16_f32 v244, v132, v133
	v_cvt_pk_bf16_f32 v245, v134, v135
	s_nop 1
	s_waitcnt lgkmcnt(6)
	v_mfma_f32_32x32x16_bf16 v[112:127], v[206:209], v[242:245], v[112:127]
	ds_read_b64_tr_b16 v[206:207], v205 offset:256
	ds_read_b64_tr_b16 v[208:209], v205 offset:4352
	v_sub_f32_e32 v136, v136, v190
	v_add_f32_e32 v254, v134, v254
	v_exp_f32_e32 v136, v136
	v_sub_f32_e32 v137, v137, v190
	v_add_f32_e32 v254, v135, v254
	s_waitcnt lgkmcnt(6)
	v_mfma_f32_32x32x16_bf16 v[96:111], v[210:213], v[242:245], v[96:111]
	ds_read_b64_tr_b16 v[210:211], v218 offset:256
	ds_read_b64_tr_b16 v[212:213], v218 offset:4352
	v_exp_f32_e32 v137, v137
	v_sub_f32_e32 v138, v138, v190
	v_add_f32_e32 v254, v136, v254
	v_exp_f32_e32 v138, v138
	v_sub_f32_e32 v139, v139, v190
	s_waitcnt lgkmcnt(6)
	v_mfma_f32_32x32x16_bf16 v[80:95], v[214:217], v[242:245], v[80:95]
	ds_read_b64_tr_b16 v[214:215], v219 offset:256
	ds_read_b64_tr_b16 v[216:217], v219 offset:4352
	v_add_f32_e32 v254, v137, v254
	v_exp_f32_e32 v139, v139
	v_sub_f32_e32 v140, v140, v190
	v_add_f32_e32 v254, v138, v254
	s_waitcnt lgkmcnt(6)
	v_mfma_f32_32x32x16_bf16 v[64:79], v[238:241], v[242:245], v[64:79]
	ds_read_b64_tr_b16 v[238:239], v221 offset:256
	ds_read_b64_tr_b16 v[240:241], v221 offset:4352
	v_exp_f32_e32 v140, v140
	v_sub_f32_e32 v141, v141, v190
	v_add_f32_e32 v254, v139, v254
	v_exp_f32_e32 v141, v141
	s_waitcnt lgkmcnt(6)
	v_mfma_f32_32x32x16_bf16 v[48:63], v[206:209], v[242:245], v[48:63]
	ds_read_b64_tr_b16 v[206:207], v205 offset:8192
	ds_read_b64_tr_b16 v[208:209], v205 offset:12288
	v_sub_f32_e32 v142, v142, v190
	v_add_f32_e32 v254, v140, v254
	v_exp_f32_e32 v142, v142
	v_sub_f32_e32 v143, v143, v190
	s_waitcnt lgkmcnt(6)
	v_mfma_f32_32x32x16_bf16 v[32:47], v[210:213], v[242:245], v[32:47]
	ds_read_b64_tr_b16 v[210:211], v218 offset:8192
	ds_read_b64_tr_b16 v[212:213], v218 offset:12288
	v_add_f32_e32 v254, v141, v254
	v_exp_f32_e32 v143, v143
	v_add_f32_e32 v254, v142, v254
	v_add_f32_e32 v254, v143, v254
	s_waitcnt lgkmcnt(6)
	v_mfma_f32_32x32x16_bf16 v[16:31], v[214:217], v[242:245], v[16:31]
	ds_read_b64_tr_b16 v[214:215], v219 offset:8192
	ds_read_b64_tr_b16 v[216:217], v219 offset:12288
	v_cvt_pk_bf16_f32 v250, v136, v137
	v_cvt_pk_bf16_f32 v251, v138, v139
	v_cvt_pk_bf16_f32 v252, v140, v141
	v_cvt_pk_bf16_f32 v253, v142, v143
	v_add_f32_e32 v202, v202, v254
	s_waitcnt lgkmcnt(6)
	v_mfma_f32_32x32x16_bf16 v[0:15], v[238:241], v[242:245], v[0:15]
	ds_read_b64_tr_b16 v[238:239], v221 offset:8192
	ds_read_b64_tr_b16 v[240:241], v221 offset:12288
	ds_read_b64_tr_b16 v[128:129], v205 offset:8448
	ds_read_b64_tr_b16 v[130:131], v205 offset:12544
	s_waitcnt lgkmcnt(8)
	v_mfma_f32_32x32x16_bf16 v[112:127], v[206:209], v[250:253], v[112:127]
	ds_read_b64_tr_b16 v[206:207], v218 offset:8448
	ds_read_b64_tr_b16 v[208:209], v218 offset:12544
	v_max3_f32 v246, v222, v223, v224
	v_max3_f32 v247, v225, v226, v227
	v_max3_f32 v246, v246, v228, v229
	v_max3_f32 v247, v247, v230, v231
	v_max3_f32 v246, v246, v232, v233
	s_waitcnt lgkmcnt(8)
	v_mfma_f32_32x32x16_bf16 v[96:111], v[210:213], v[250:253], v[96:111]
	ds_read_b64_tr_b16 v[210:211], v219 offset:8448
	ds_read_b64_tr_b16 v[212:213], v219 offset:12544
	v_max3_f32 v247, v247, v234, v235
	v_max3_f32 v246, v246, v236, v237
	v_max_f32_e32 v246, v246, v247
	v_mov_b32_e32 v247, v246
	v_add_f32_e32 v249, 0x41000000, v190
	s_waitcnt lgkmcnt(8)
	v_mfma_f32_32x32x16_bf16 v[80:95], v[214:217], v[250:253], v[80:95]
	ds_read_b64_tr_b16 v[214:215], v221 offset:8448
	ds_read_b64_tr_b16 v[216:217], v221 offset:12544
	s_nop 1
	v_permlane32_swap_b32_e32 v246, v247
	v_max_f32_e32 v246, v246, v247
	v_cmp_gt_f32_e32 vcc, v246, v249
	s_cbranch_vccnz .Latt_rs1_0s2
	s_waitcnt lgkmcnt(8)
	v_mfma_f32_32x32x16_bf16 v[64:79], v[238:241], v[250:253], v[64:79]
	ds_read_b64_tr_b16 v[238:239], v205 offset:16384
	ds_read_b64_tr_b16 v[240:241], v205 offset:20480
	v_sub_f32_e32 v222, v222, v190
	v_exp_f32_e32 v222, v222
	v_sub_f32_e32 v223, v223, v190
	v_exp_f32_e32 v223, v223
	v_sub_f32_e32 v224, v224, v190
	v_add_f32_e32 v254, 0, v222
	s_waitcnt lgkmcnt(8)
	v_mfma_f32_32x32x16_bf16 v[48:63], v[128:131], v[250:253], v[48:63]
	ds_read_b64_tr_b16 v[128:129], v218 offset:16384
	ds_read_b64_tr_b16 v[130:131], v218 offset:20480
	v_exp_f32_e32 v224, v224
	v_sub_f32_e32 v225, v225, v190
	v_add_f32_e32 v254, v223, v254
	v_exp_f32_e32 v225, v225
	v_sub_f32_e32 v226, v226, v190
	v_add_f32_e32 v254, v224, v254
	s_waitcnt lgkmcnt(8)
	v_mfma_f32_32x32x16_bf16 v[32:47], v[206:209], v[250:253], v[32:47]
	ds_read_b64_tr_b16 v[206:207], v219 offset:16384
	ds_read_b64_tr_b16 v[208:209], v219 offset:20480
	v_exp_f32_e32 v226, v226
	v_sub_f32_e32 v227, v227, v190
	v_add_f32_e32 v254, v225, v254
	v_exp_f32_e32 v227, v227
	v_sub_f32_e32 v228, v228, v190
	s_waitcnt lgkmcnt(8)
	v_mfma_f32_32x32x16_bf16 v[16:31], v[210:213], v[250:253], v[16:31]
	ds_read_b64_tr_b16 v[210:211], v221 offset:16384
	ds_read_b64_tr_b16 v[212:213], v221 offset:20480
	v_add_f32_e32 v254, v226, v254
	v_exp_f32_e32 v228, v228
	v_sub_f32_e32 v229, v229, v190
	v_add_f32_e32 v254, v227, v254
	v_exp_f32_e32 v229, v229
	s_waitcnt lgkmcnt(8)
	v_mfma_f32_32x32x16_bf16 v[0:15], v[214:217], v[250:253], v[0:15]
	ds_read_b64_tr_b16 v[214:215], v205 offset:16640
	ds_read_b64_tr_b16 v[216:217], v205 offset:20736
	s_nop 0
	v_cvt_pk_bf16_f32 v242, v222, v223
	v_cvt_pk_bf16_f32 v243, v224, v225
	v_cvt_pk_bf16_f32 v244, v226, v227
	v_cvt_pk_bf16_f32 v245, v228, v229
	s_nop 1
	s_waitcnt lgkmcnt(8)
	v_mfma_f32_32x32x16_bf16 v[112:127], v[238:241], v[242:245], v[112:127]
	ds_read_b64_tr_b16 v[238:239], v218 offset:16640
	ds_read_b64_tr_b16 v[240:241], v218 offset:20736
	v_sub_f32_e32 v230, v230, v190
	v_add_f32_e32 v254, v228, v254
	v_exp_f32_e32 v230, v230
	v_sub_f32_e32 v231, v231, v190
	v_add_f32_e32 v254, v229, v254
	s_waitcnt lgkmcnt(8)
	v_mfma_f32_32x32x16_bf16 v[96:111], v[128:131], v[242:245], v[96:111]
	ds_read_b64_tr_b16 v[128:129], v219 offset:16640
	ds_read_b64_tr_b16 v[130:131], v219 offset:20736
	v_exp_f32_e32 v231, v231
	v_sub_f32_e32 v232, v232, v190
	v_add_f32_e32 v254, v230, v254
	v_exp_f32_e32 v232, v232
	v_sub_f32_e32 v233, v233, v190
	s_cmp_lg_u64 s[18:19], 0
	s_cbranch_scc1 .Latt_nd0_0s2
	s_sub_i32 s100, s88, 1
	s_cmp_eq_u32 s88, 0
	s_cselect_b32 s100, 2, s100
	s_lshl_b32 s101, s100, 14
	s_add_i32 m0, s85, s101
	s_nop 0
	global_load_lds_dwordx4 v178, s[14:15]

.Latt_slow_0s2:
.Latt_slow_0:
	s_lshl_b32 s34, s88, 14
	s_add_i32 s35, s34, 0
	v_add_u32_e32 v206, s35, v194
	ds_read_b128 v[128:131], v206
	v_add_u32_e32 v207, s35, v195
	ds_read_b128 v[210:213], v207
	v_add_u32_e32 v208, s35, v196
	v_add_u32_e32 v209, s35, v197
	v_lshrrev_b32_e32 v204, 3, v203
	s_add_i32 s89, s43, 31
	v_and_or_b32 v205, v203, 31, s83
	s_cmp_le_i32 s89, s83
	s_waitcnt lgkmcnt(1)
	v_mfma_f32_32x32x16_bf16 v[128:143], v[128:131], v[144:147], 0
	ds_read_b128 v[214:217], v209
	s_waitcnt lgkmcnt(1)
	v_mfma_f32_32x32x16_bf16 v[128:143], v[210:213], v[148:151], v[128:143]
	ds_read_b128 v[210:213], v208
	s_waitcnt lgkmcnt(0)
	v_mfma_f32_32x32x16_bf16 v[128:143], v[210:213], v[152:155], v[128:143]
	v_add_u32_e32 v210, s35, v198
	v_add_u32_e32 v212, s35, v199
	v_add_u32_e32 v213, s35, v200
	v_and_b32_e32 v211, 4, v204
	ds_read_b128 v[222:225], v212
	v_mfma_f32_32x32x16_bf16 v[128:143], v[214:217], v[156:159], v[128:143]
	ds_read_b128 v[214:217], v210
	s_waitcnt lgkmcnt(0)
	v_mfma_f32_32x32x16_bf16 v[128:143], v[214:217], v[160:163], v[128:143]
	ds_read_b128 v[216:219], v213
	v_add_u32_e32 v214, s35, v201
	v_mfma_f32_32x32x16_bf16 v[128:143], v[222:225], v[164:167], v[128:143]
	ds_read_b128 v[222:225], v214
	s_waitcnt lgkmcnt(1)
	v_mfma_f32_32x32x16_bf16 v[128:143], v[216:219], v[168:171], v[128:143]
	s_waitcnt lgkmcnt(0)
	v_mfma_f32_32x32x16_bf16 v[128:143], v[222:225], v[172:175], v[128:143]
	s_cbranch_scc1 .LBB0_850
	v_add_u32_e32 v204, s43, v211
	v_cmp_lt_i32_e32 vcc, v204, v205
	v_add_u32_e32 v215, 2, v204
	s_nop 7
	v_cndmask_b32_e32 v129, v192, v129, vcc
	v_cmp_le_i32_e32 vcc, v204, v205
	s_nop 1
	v_cndmask_b32_e32 v128, v192, v128, vcc
	v_cmp_le_i32_e32 vcc, v215, v205
	v_add_u32_e32 v215, 3, v204
	s_nop 0
	v_cndmask_b32_e32 v130, v192, v130, vcc
	v_cmp_le_i32_e32 vcc, v215, v205
	v_add_u32_e32 v215, 8, v204
	s_nop 0
	v_cndmask_b32_e32 v131, v192, v131, vcc
	v_cmp_le_i32_e32 vcc, v215, v205
	v_add_u32_e32 v215, 9, v204
	s_nop 0
	v_cndmask_b32_e32 v132, v192, v132, vcc
	v_cmp_le_i32_e32 vcc, v215, v205
	v_add_u32_e32 v215, 10, v204
	s_nop 0
	v_cndmask_b32_e32 v133, v192, v133, vcc
	v_cmp_le_i32_e32 vcc, v215, v205
	v_add_u32_e32 v215, 11, v204
	s_nop 0
	v_cndmask_b32_e32 v134, v192, v134, vcc
	v_cmp_le_i32_e32 vcc, v215, v205
	v_add_u32_e32 v215, 16, v204
	s_nop 0
	v_cndmask_b32_e32 v135, v192, v135, vcc
	v_cmp_le_i32_e32 vcc, v215, v205
	v_add_u32_e32 v215, 17, v204
	s_nop 0
	v_cndmask_b32_e32 v136, v192, v136, vcc
	v_cmp_le_i32_e32 vcc, v215, v205
	v_add_u32_e32 v215, 18, v204
	s_nop 0
	v_cndmask_b32_e32 v137, v192, v137, vcc
	v_cmp_le_i32_e32 vcc, v215, v205
	v_add_u32_e32 v215, 19, v204
	s_nop 0
	v_cndmask_b32_e32 v138, v192, v138, vcc
	v_cmp_le_i32_e32 vcc, v215, v205
	v_add_u32_e32 v215, 24, v204
	s_nop 0
	v_cndmask_b32_e32 v139, v192, v139, vcc
	v_cmp_le_i32_e32 vcc, v215, v205
	v_add_u32_e32 v215, 25, v204
	s_nop 0
	v_cndmask_b32_e32 v140, v192, v140, vcc
	v_cmp_le_i32_e32 vcc, v215, v205
	v_add_u32_e32 v215, 26, v204
	v_add_u32_e32 v204, 27, v204
	v_cndmask_b32_e32 v141, v192, v141, vcc
	v_cmp_le_i32_e32 vcc, v215, v205
	s_nop 1
	v_cndmask_b32_e32 v142, v192, v142, vcc
	v_cmp_le_i32_e32 vcc, v204, v205
	s_nop 1
	v_cndmask_b32_e32 v143, v192, v143, vcc

.LBB0_866:
	s_cmp_gt_i32 s4, s84
	s_cbranch_scc1 .LBB0_877
	s_add_i32 s100, s4, 63
	s_cmp_le_i32 s100, s83
	s_cbranch_scc0 .Latt_slow_1
	s_cmp_eq_u32 s33, 1
	s_cbranch_scc1 .Latt_slot1_1
	s_cmp_eq_u32 s33, 2
	s_cbranch_scc1 .Latt_slot2_1
	ds_read_b128 v[206:209], v196
	ds_read_b128 v[210:213], v197
	ds_read_b128 v[214:217], v198
	ds_read_b128 v[238:241], v199
	ds_read_b128 v[242:245], v200
	ds_read_b128 v[250:253], v201
	ds_read_b128 v[222:225], v202
	ds_read_b128 v[226:229], v203
	s_cmp_lg_u32 s4, 0
	s_cbranch_scc1 .Latt_vstep_1s0
	v_bfe_u32 v246, v204, 2, 2
	v_bfe_u32 v247, v204, 5, 1
	v_lshl_or_b32 v247, v247, 2, v246
	v_and_b32_e32 v249, 3, v204
	v_and_b32_e32 v254, 16, v204
	v_lshl_or_b32 v249, v249, 2, v254
	v_lshlrev_b32_e32 v249, 1, v249
	v_lshl_add_u32 v247, v247, 9, v249
	v_add_u32_e32 v247, 0xc000, v247
	v_lshlrev_b32_e32 v246, 6, v246
	v_add_u32_e32 v205, v247, v246
	v_xor_b32_e32 v249, 64, v246
	v_add_u32_e32 v218, v247, v249
	v_xor_b32_e32 v249, 0x80, v246
	v_add_u32_e32 v219, v247, v249
	v_xor_b32_e32 v249, 0xc0, v246
	v_add_u32_e32 v221, v247, v249
	s_branch .Latt_vdone_1s0

.Latt_vdone_1s0:
	s_waitcnt lgkmcnt(7)
	v_mfma_f32_32x32x16_bf16 v[128:143], v[206:209], v[144:147], 0
	ds_read_b128 v[206:209], v196 offset:8192
	s_waitcnt lgkmcnt(7)
	v_mfma_f32_32x32x16_bf16 v[128:143], v[210:213], v[148:151], v[128:143]
	ds_read_b128 v[210:213], v197 offset:8192
	s_waitcnt lgkmcnt(7)
	v_mfma_f32_32x32x16_bf16 v[128:143], v[214:217], v[152:155], v[128:143]
	ds_read_b128 v[214:217], v198 offset:8192
	s_waitcnt lgkmcnt(7)
	v_mfma_f32_32x32x16_bf16 v[128:143], v[238:241], v[156:159], v[128:143]
	ds_read_b128 v[238:241], v199 offset:8192
	s_waitcnt lgkmcnt(7)
	v_mfma_f32_32x32x16_bf16 v[128:143], v[242:245], v[160:163], v[128:143]
	s_waitcnt lgkmcnt(6)
	v_mfma_f32_32x32x16_bf16 v[128:143], v[250:253], v[164:167], v[128:143]
	s_waitcnt lgkmcnt(5)
	v_mfma_f32_32x32x16_bf16 v[128:143], v[222:225], v[168:171], v[128:143]
	s_waitcnt lgkmcnt(4)
	v_mfma_f32_32x32x16_bf16 v[128:143], v[226:229], v[172:175], v[128:143]
	s_waitcnt lgkmcnt(3)
	v_mfma_f32_32x32x16_bf16 v[222:237], v[206:209], v[144:147], 0
	ds_read_b128 v[206:209], v200 offset:8192
	s_nop 8
	v_max3_f32 v246, v128, v129, v130
	v_max3_f32 v247, v131, v132, v133
	v_max3_f32 v246, v246, v134, v135
	v_max3_f32 v247, v247, v136, v137
	v_max3_f32 v246, v246, v138, v139
	v_max3_f32 v247, v247, v140, v141
	v_max3_f32 v246, v246, v142, v143
	s_waitcnt lgkmcnt(3)
	v_mfma_f32_32x32x16_bf16 v[222:237], v[210:213], v[148:151], v[222:237]
	ds_read_b128 v[210:213], v201 offset:8192
	v_max_f32_e32 v246, v246, v247
	v_mov_b32_e32 v247, v246
	v_add_f32_e32 v249, 0x41000000, v190
	s_nop 1
	v_permlane32_swap_b32_e32 v246, v247
	v_max_f32_e32 v246, v246, v247
	v_cmp_gt_f32_e32 vcc, v246, v249
	s_cbranch_vccz .Latt_nr0_1s0
	v_max_f32_e32 v246, v190, v246
	v_sub_f32_e32 v190, v190, v246
	v_exp_f32_e32 v190, v190
	s_nop 0
	v_pk_mul_f32 v[126:127], v[126:127], v[190:191] op_sel_hi:[1,0]
	v_pk_mul_f32 v[124:125], v[124:125], v[190:191] op_sel_hi:[1,0]
	v_pk_mul_f32 v[122:123], v[122:123], v[190:191] op_sel_hi:[1,0]
	v_pk_mul_f32 v[120:121], v[120:121], v[190:191] op_sel_hi:[1,0]
	v_pk_mul_f32 v[118:119], v[118:119], v[190:191] op_sel_hi:[1,0]
	v_pk_mul_f32 v[116:117], v[116:117], v[190:191] op_sel_hi:[1,0]
	v_pk_mul_f32 v[114:115], v[114:115], v[190:191] op_sel_hi:[1,0]
	v_pk_mul_f32 v[112:113], v[112:113], v[190:191] op_sel_hi:[1,0]
	v_pk_mul_f32 v[110:111], v[110:111], v[190:191] op_sel_hi:[1,0]
	v_pk_mul_f32 v[108:109], v[108:109], v[190:191] op_sel_hi:[1,0]
	v_pk_mul_f32 v[106:107], v[106:107], v[190:191] op_sel_hi:[1,0]
	v_pk_mul_f32 v[104:105], v[104:105], v[190:191] op_sel_hi:[1,0]
	v_pk_mul_f32 v[102:103], v[102:103], v[190:191] op_sel_hi:[1,0]
	v_pk_mul_f32 v[100:101], v[100:101], v[190:191] op_sel_hi:[1,0]
	v_pk_mul_f32 v[98:99], v[98:99], v[190:191] op_sel_hi:[1,0]
	v_pk_mul_f32 v[96:97], v[96:97], v[190:191] op_sel_hi:[1,0]
	v_pk_mul_f32 v[94:95], v[94:95], v[190:191] op_sel_hi:[1,0]
	v_pk_mul_f32 v[92:93], v[92:93], v[190:191] op_sel_hi:[1,0]
	v_pk_mul_f32 v[90:91], v[90:91], v[190:191] op_sel_hi:[1,0]
	v_pk_mul_f32 v[88:89], v[88:89], v[190:191] op_sel_hi:[1,0]
	v_pk_mul_f32 v[86:87], v[86:87], v[190:191] op_sel_hi:[1,0]
	v_pk_mul_f32 v[84:85], v[84:85], v[190:191] op_sel_hi:[1,0]
	v_pk_mul_f32 v[82:83], v[82:83], v[190:191] op_sel_hi:[1,0]
	v_pk_mul_f32 v[80:81], v[80:81], v[190:191] op_sel_hi:[1,0]
	v_pk_mul_f32 v[78:79], v[78:79], v[190:191] op_sel_hi:[1,0]
	v_pk_mul_f32 v[76:77], v[76:77], v[190:191] op_sel_hi:[1,0]
	v_pk_mul_f32 v[74:75], v[74:75], v[190:191] op_sel_hi:[1,0]
	v_pk_mul_f32 v[72:73], v[72:73], v[190:191] op_sel_hi:[1,0]
	v_pk_mul_f32 v[70:71], v[70:71], v[190:191] op_sel_hi:[1,0]
	v_pk_mul_f32 v[68:69], v[68:69], v[190:191] op_sel_hi:[1,0]
	v_pk_mul_f32 v[66:67], v[66:67], v[190:191] op_sel_hi:[1,0]
	v_pk_mul_f32 v[64:65], v[64:65], v[190:191] op_sel_hi:[1,0]
	v_pk_mul_f32 v[62:63], v[62:63], v[190:191] op_sel_hi:[1,0]
	v_pk_mul_f32 v[60:61], v[60:61], v[190:191] op_sel_hi:[1,0]
	v_pk_mul_f32 v[58:59], v[58:59], v[190:191] op_sel_hi:[1,0]
	v_pk_mul_f32 v[56:57], v[56:57], v[190:191] op_sel_hi:[1,0]
	v_pk_mul_f32 v[54:55], v[54:55], v[190:191] op_sel_hi:[1,0]
	v_pk_mul_f32 v[52:53], v[52:53], v[190:191] op_sel_hi:[1,0]
	v_pk_mul_f32 v[50:51], v[50:51], v[190:191] op_sel_hi:[1,0]
	v_pk_mul_f32 v[48:49], v[48:49], v[190:191] op_sel_hi:[1,0]
	v_pk_mul_f32 v[46:47], v[46:47], v[190:191] op_sel_hi:[1,0]
	v_pk_mul_f32 v[44:45], v[44:45], v[190:191] op_sel_hi:[1,0]
	v_pk_mul_f32 v[42:43], v[42:43], v[190:191] op_sel_hi:[1,0]
	v_pk_mul_f32 v[40:41], v[40:41], v[190:191] op_sel_hi:[1,0]
	v_pk_mul_f32 v[38:39], v[38:39], v[190:191] op_sel_hi:[1,0]
	v_pk_mul_f32 v[36:37], v[36:37], v[190:191] op_sel_hi:[1,0]
	v_pk_mul_f32 v[34:35], v[34:35], v[190:191] op_sel_hi:[1,0]
	v_pk_mul_f32 v[32:33], v[32:33], v[190:191] op_sel_hi:[1,0]
	v_pk_mul_f32 v[30:31], v[30:31], v[190:191] op_sel_hi:[1,0]
	v_pk_mul_f32 v[28:29], v[28:29], v[190:191] op_sel_hi:[1,0]
	v_pk_mul_f32 v[26:27], v[26:27], v[190:191] op_sel_hi:[1,0]
	v_pk_mul_f32 v[24:25], v[24:25], v[190:191] op_sel_hi:[1,0]
	v_pk_mul_f32 v[22:23], v[22:23], v[190:191] op_sel_hi:[1,0]
	v_pk_mul_f32 v[20:21], v[20:21], v[190:191] op_sel_hi:[1,0]
	v_pk_mul_f32 v[18:19], v[18:19], v[190:191] op_sel_hi:[1,0]
	v_pk_mul_f32 v[16:17], v[16:17], v[190:191] op_sel_hi:[1,0]
	v_pk_mul_f32 v[14:15], v[14:15], v[190:191] op_sel_hi:[1,0]
	v_pk_mul_f32 v[12:13], v[12:13], v[190:191] op_sel_hi:[1,0]
	v_pk_mul_f32 v[10:11], v[10:11], v[190:191] op_sel_hi:[1,0]
	v_pk_mul_f32 v[8:9], v[8:9], v[190:191] op_sel_hi:[1,0]
	v_pk_mul_f32 v[6:7], v[6:7], v[190:191] op_sel_hi:[1,0]
	v_pk_mul_f32 v[4:5], v[4:5], v[190:191] op_sel_hi:[1,0]
	v_pk_mul_f32 v[2:3], v[2:3], v[190:191] op_sel_hi:[1,0]
	v_pk_mul_f32 v[0:1], v[0:1], v[190:191] op_sel_hi:[1,0]
	v_mul_f32_e32 v195, v195, v190
	v_mov_b32_e32 v190, v246
.Latt_nr0_1s0:
	s_waitcnt lgkmcnt(3)
	v_mfma_f32_32x32x16_bf16 v[222:237], v[214:217], v[152:155], v[222:237]
	ds_read_b128 v[214:217], v202 offset:8192
	v_sub_f32_e32 v128, v128, v190
	v_exp_f32_e32 v128, v128
	v_sub_f32_e32 v129, v129, v190
	v_exp_f32_e32 v129, v129
	v_sub_f32_e32 v130, v130, v190
	s_waitcnt lgkmcnt(3)
	v_mfma_f32_32x32x16_bf16 v[222:237], v[238:241], v[156:159], v[222:237]
	ds_read_b128 v[238:241], v203 offset:8192
	v_add_f32_e32 v254, 0, v128
	v_exp_f32_e32 v130, v130
	v_sub_f32_e32 v131, v131, v190
	v_add_f32_e32 v254, v129, v254
	v_exp_f32_e32 v131, v131
	s_waitcnt lgkmcnt(3)
	v_mfma_f32_32x32x16_bf16 v[222:237], v[206:209], v[160:163], v[222:237]
	ds_read_b64_tr_b16 v[206:207], v205
	ds_read_b64_tr_b16 v[208:209], v205 offset:4096
	v_sub_f32_e32 v132, v132, v190
	v_add_f32_e32 v254, v130, v254
	v_exp_f32_e32 v132, v132
	v_sub_f32_e32 v133, v133, v190
	v_add_f32_e32 v254, v131, v254
	s_waitcnt lgkmcnt(4)
	v_mfma_f32_32x32x16_bf16 v[222:237], v[210:213], v[164:167], v[222:237]
	ds_read_b64_tr_b16 v[210:211], v218
	ds_read_b64_tr_b16 v[212:213], v218 offset:4096
	v_exp_f32_e32 v133, v133
	v_sub_f32_e32 v134, v134, v190
	v_add_f32_e32 v254, v132, v254
	v_exp_f32_e32 v134, v134
	s_waitcnt lgkmcnt(5)
	v_mfma_f32_32x32x16_bf16 v[222:237], v[214:217], v[168:171], v[222:237]
	ds_read_b64_tr_b16 v[214:215], v219
	ds_read_b64_tr_b16 v[216:217], v219 offset:4096
	v_sub_f32_e32 v135, v135, v190
	v_add_f32_e32 v254, v133, v254
	v_exp_f32_e32 v135, v135
	s_nop 0
	s_waitcnt lgkmcnt(6)
	v_mfma_f32_32x32x16_bf16 v[222:237], v[238:241], v[172:175], v[222:237]
	ds_read_b64_tr_b16 v[238:239], v221
	ds_read_b64_tr_b16 v[240:241], v221 offset:4096
	v_cvt_pk_bf16_f32 v242, v128, v129
	v_cvt_pk_bf16_f32 v243, v130, v131
	v_cvt_pk_bf16_f32 v244, v132, v133
	v_cvt_pk_bf16_f32 v245, v134, v135
	s_nop 1
	s_waitcnt lgkmcnt(6)
	v_mfma_f32_32x32x16_bf16 v[112:127], v[206:209], v[242:245], v[112:127]
	ds_read_b64_tr_b16 v[206:207], v205 offset:256
	ds_read_b64_tr_b16 v[208:209], v205 offset:4352
	v_sub_f32_e32 v136, v136, v190
	v_add_f32_e32 v254, v134, v254
	v_exp_f32_e32 v136, v136
	v_sub_f32_e32 v137, v137, v190
	v_add_f32_e32 v254, v135, v254
	s_waitcnt lgkmcnt(6)
	v_mfma_f32_32x32x16_bf16 v[96:111], v[210:213], v[242:245], v[96:111]
	ds_read_b64_tr_b16 v[210:211], v218 offset:256
	ds_read_b64_tr_b16 v[212:213], v218 offset:4352
	v_exp_f32_e32 v137, v137
	v_sub_f32_e32 v138, v138, v190
	v_add_f32_e32 v254, v136, v254
	v_exp_f32_e32 v138, v138
	v_sub_f32_e32 v139, v139, v190
	s_waitcnt lgkmcnt(6)
	v_mfma_f32_32x32x16_bf16 v[80:95], v[214:217], v[242:245], v[80:95]
	ds_read_b64_tr_b16 v[214:215], v219 offset:256
	ds_read_b64_tr_b16 v[216:217], v219 offset:4352
	v_add_f32_e32 v254, v137, v254
	v_exp_f32_e32 v139, v139
	v_sub_f32_e32 v140, v140, v190
	v_add_f32_e32 v254, v138, v254
	s_waitcnt lgkmcnt(6)
	v_mfma_f32_32x32x16_bf16 v[64:79], v[238:241], v[242:245], v[64:79]
	ds_read_b64_tr_b16 v[238:239], v221 offset:256
	ds_read_b64_tr_b16 v[240:241], v221 offset:4352
	v_exp_f32_e32 v140, v140
	v_sub_f32_e32 v141, v141, v190
	v_add_f32_e32 v254, v139, v254
	v_exp_f32_e32 v141, v141
	s_waitcnt lgkmcnt(6)
	v_mfma_f32_32x32x16_bf16 v[48:63], v[206:209], v[242:245], v[48:63]
	ds_read_b64_tr_b16 v[206:207], v205 offset:8192
	ds_read_b64_tr_b16 v[208:209], v205 offset:12288
	v_sub_f32_e32 v142, v142, v190
	v_add_f32_e32 v254, v140, v254
	v_exp_f32_e32 v142, v142
	v_sub_f32_e32 v143, v143, v190
	s_waitcnt lgkmcnt(6)
	v_mfma_f32_32x32x16_bf16 v[32:47], v[210:213], v[242:245], v[32:47]
	ds_read_b64_tr_b16 v[210:211], v218 offset:8192
	ds_read_b64_tr_b16 v[212:213], v218 offset:12288
	v_add_f32_e32 v254, v141, v254
	v_exp_f32_e32 v143, v143
	v_add_f32_e32 v254, v142, v254
	v_add_f32_e32 v254, v143, v254
	s_waitcnt lgkmcnt(6)
	v_mfma_f32_32x32x16_bf16 v[16:31], v[214:217], v[242:245], v[16:31]
	ds_read_b64_tr_b16 v[214:215], v219 offset:8192
	ds_read_b64_tr_b16 v[216:217], v219 offset:12288
	v_cvt_pk_bf16_f32 v250, v136, v137
	v_cvt_pk_bf16_f32 v251, v138, v139
	v_cvt_pk_bf16_f32 v252, v140, v141
	v_cvt_pk_bf16_f32 v253, v142, v143
	v_add_f32_e32 v195, v195, v254
	s_waitcnt lgkmcnt(6)
	v_mfma_f32_32x32x16_bf16 v[0:15], v[238:241], v[242:245], v[0:15]
	ds_read_b64_tr_b16 v[238:239], v221 offset:8192
	ds_read_b64_tr_b16 v[240:241], v221 offset:12288
	ds_read_b64_tr_b16 v[128:129], v205 offset:8448
	ds_read_b64_tr_b16 v[130:131], v205 offset:12544
	s_waitcnt lgkmcnt(8)
	v_mfma_f32_32x32x16_bf16 v[112:127], v[206:209], v[250:253], v[112:127]
	ds_read_b64_tr_b16 v[206:207], v218 offset:8448
	ds_read_b64_tr_b16 v[208:209], v218 offset:12544
	v_max3_f32 v246, v222, v223, v224
	v_max3_f32 v247, v225, v226, v227
	v_max3_f32 v246, v246, v228, v229
	v_max3_f32 v247, v247, v230, v231
	v_max3_f32 v246, v246, v232, v233
	s_waitcnt lgkmcnt(8)
	v_mfma_f32_32x32x16_bf16 v[96:111], v[210:213], v[250:253], v[96:111]
	ds_read_b64_tr_b16 v[210:211], v219 offset:8448
	ds_read_b64_tr_b16 v[212:213], v219 offset:12544
	v_max3_f32 v247, v247, v234, v235
	v_max3_f32 v246, v246, v236, v237
	v_max_f32_e32 v246, v246, v247
	v_mov_b32_e32 v247, v246
	v_add_f32_e32 v249, 0x41000000, v190
	s_waitcnt lgkmcnt(8)
	v_mfma_f32_32x32x16_bf16 v[80:95], v[214:217], v[250:253], v[80:95]
	ds_read_b64_tr_b16 v[214:215], v221 offset:8448
	ds_read_b64_tr_b16 v[216:217], v221 offset:12544
	s_nop 1
	v_permlane32_swap_b32_e32 v246, v247
	v_max_f32_e32 v246, v246, v247
	v_cmp_gt_f32_e32 vcc, v246, v249
	s_cbranch_vccnz .Latt_rs1_1s0
	s_waitcnt lgkmcnt(8)
	v_mfma_f32_32x32x16_bf16 v[64:79], v[238:241], v[250:253], v[64:79]
	ds_read_b64_tr_b16 v[238:239], v205 offset:16384
	ds_read_b64_tr_b16 v[240:241], v205 offset:20480
	v_sub_f32_e32 v222, v222, v190
	v_exp_f32_e32 v222, v222
	v_sub_f32_e32 v223, v223, v190
	v_exp_f32_e32 v223, v223
	v_sub_f32_e32 v224, v224, v190
	v_add_f32_e32 v254, 0, v222
	s_waitcnt lgkmcnt(8)
	v_mfma_f32_32x32x16_bf16 v[48:63], v[128:131], v[250:253], v[48:63]
	ds_read_b64_tr_b16 v[128:129], v218 offset:16384
	ds_read_b64_tr_b16 v[130:131], v218 offset:20480
	v_exp_f32_e32 v224, v224
	v_sub_f32_e32 v225, v225, v190
	v_add_f32_e32 v254, v223, v254
	v_exp_f32_e32 v225, v225
	v_sub_f32_e32 v226, v226, v190
	v_add_f32_e32 v254, v224, v254
	s_waitcnt lgkmcnt(8)
	v_mfma_f32_32x32x16_bf16 v[32:47], v[206:209], v[250:253], v[32:47]
	ds_read_b64_tr_b16 v[206:207], v219 offset:16384
	ds_read_b64_tr_b16 v[208:209], v219 offset:20480
	v_exp_f32_e32 v226, v226
	v_sub_f32_e32 v227, v227, v190
	v_add_f32_e32 v254, v225, v254
	v_exp_f32_e32 v227, v227
	v_sub_f32_e32 v228, v228, v190
	s_waitcnt lgkmcnt(8)
	v_mfma_f32_32x32x16_bf16 v[16:31], v[210:213], v[250:253], v[16:31]
	ds_read_b64_tr_b16 v[210:211], v221 offset:16384
	ds_read_b64_tr_b16 v[212:213], v221 offset:20480
	v_add_f32_e32 v254, v226, v254
	v_exp_f32_e32 v228, v228
	v_sub_f32_e32 v229, v229, v190
	v_add_f32_e32 v254, v227, v254
	v_exp_f32_e32 v229, v229
	s_waitcnt lgkmcnt(8)
	v_mfma_f32_32x32x16_bf16 v[0:15], v[214:217], v[250:253], v[0:15]
	ds_read_b64_tr_b16 v[214:215], v205 offset:16640
	ds_read_b64_tr_b16 v[216:217], v205 offset:20736
	s_nop 0
	v_cvt_pk_bf16_f32 v242, v222, v223
	v_cvt_pk_bf16_f32 v243, v224, v225
	v_cvt_pk_bf16_f32 v244, v226, v227
	v_cvt_pk_bf16_f32 v245, v228, v229
	s_nop 1
	s_waitcnt lgkmcnt(8)
	v_mfma_f32_32x32x16_bf16 v[112:127], v[238:241], v[242:245], v[112:127]
	ds_read_b64_tr_b16 v[238:239], v218 offset:16640
	ds_read_b64_tr_b16 v[240:241], v218 offset:20736
	v_sub_f32_e32 v230, v230, v190
	v_add_f32_e32 v254, v228, v254
	v_exp_f32_e32 v230, v230
	v_sub_f32_e32 v231, v231, v190
	v_add_f32_e32 v254, v229, v254
	s_waitcnt lgkmcnt(8)
	v_mfma_f32_32x32x16_bf16 v[96:111], v[128:131], v[242:245], v[96:111]
	ds_read_b64_tr_b16 v[128:129], v219 offset:16640
	ds_read_b64_tr_b16 v[130:131], v219 offset:20736
	v_exp_f32_e32 v231, v231
	v_sub_f32_e32 v232, v232, v190
	v_add_f32_e32 v254, v230, v254
	v_exp_f32_e32 v232, v232
	v_sub_f32_e32 v233, v233, v190
	s_cmp_lg_u64 s[18:19], 0
	s_cbranch_scc1 .Latt_nd0_1s0
	s_sub_i32 s100, s33, 1
	s_cmp_eq_u32 s33, 0
	s_cselect_b32 s100, 2, s100
	s_lshl_b32 s101, s100, 14
	s_add_i32 m0, s85, s101
	s_nop 0
	global_load_lds_dwordx4 v178, s[12:13]

.Latt_slow_1s0:
.Latt_slot1_1:
	ds_read_b128 v[206:209], v196 offset:16384
	ds_read_b128 v[210:213], v197 offset:16384
	ds_read_b128 v[214:217], v198 offset:16384
	ds_read_b128 v[238:241], v199 offset:16384
	ds_read_b128 v[242:245], v200 offset:16384
	ds_read_b128 v[250:253], v201 offset:16384
	ds_read_b128 v[222:225], v202 offset:16384
	ds_read_b128 v[226:229], v203 offset:16384
	v_add_u32_e32 v205, 0x8000, v205
	v_add_u32_e32 v218, 0x8000, v218
	v_add_u32_e32 v219, 0x8000, v219
	v_add_u32_e32 v221, 0x8000, v221
	s_waitcnt lgkmcnt(7)
	v_mfma_f32_32x32x16_bf16 v[128:143], v[206:209], v[144:147], 0
	ds_read_b128 v[206:209], v196 offset:24576
	s_waitcnt lgkmcnt(7)
	v_mfma_f32_32x32x16_bf16 v[128:143], v[210:213], v[148:151], v[128:143]
	ds_read_b128 v[210:213], v197 offset:24576
	s_waitcnt lgkmcnt(7)
	v_mfma_f32_32x32x16_bf16 v[128:143], v[214:217], v[152:155], v[128:143]
	ds_read_b128 v[214:217], v198 offset:24576
	s_waitcnt lgkmcnt(7)
	v_mfma_f32_32x32x16_bf16 v[128:143], v[238:241], v[156:159], v[128:143]
	ds_read_b128 v[238:241], v199 offset:24576
	s_waitcnt lgkmcnt(7)
	v_mfma_f32_32x32x16_bf16 v[128:143], v[242:245], v[160:163], v[128:143]
	s_waitcnt lgkmcnt(6)
	v_mfma_f32_32x32x16_bf16 v[128:143], v[250:253], v[164:167], v[128:143]
	s_waitcnt lgkmcnt(5)
	v_mfma_f32_32x32x16_bf16 v[128:143], v[222:225], v[168:171], v[128:143]
	s_waitcnt lgkmcnt(4)
	v_mfma_f32_32x32x16_bf16 v[128:143], v[226:229], v[172:175], v[128:143]
	s_waitcnt lgkmcnt(3)
	v_mfma_f32_32x32x16_bf16 v[222:237], v[206:209], v[144:147], 0
	ds_read_b128 v[206:209], v200 offset:24576
	s_nop 8
	v_max3_f32 v246, v128, v129, v130
	v_max3_f32 v247, v131, v132, v133
	v_max3_f32 v246, v246, v134, v135
	v_max3_f32 v247, v247, v136, v137
	v_max3_f32 v246, v246, v138, v139
	v_max3_f32 v247, v247, v140, v141
	v_max3_f32 v246, v246, v142, v143
	s_waitcnt lgkmcnt(3)
	v_mfma_f32_32x32x16_bf16 v[222:237], v[210:213], v[148:151], v[222:237]
	ds_read_b128 v[210:213], v201 offset:24576
	v_max_f32_e32 v246, v246, v247
	v_mov_b32_e32 v247, v246
	v_add_f32_e32 v249, 0x41000000, v190
	s_nop 1
	v_permlane32_swap_b32_e32 v246, v247
	v_max_f32_e32 v246, v246, v247
	v_cmp_gt_f32_e32 vcc, v246, v249
	s_cbranch_vccz .Latt_nr0_1s1
	v_max_f32_e32 v246, v190, v246
	v_sub_f32_e32 v190, v190, v246
	v_exp_f32_e32 v190, v190
	s_nop 0
	v_pk_mul_f32 v[126:127], v[126:127], v[190:191] op_sel_hi:[1,0]
	v_pk_mul_f32 v[124:125], v[124:125], v[190:191] op_sel_hi:[1,0]
	v_pk_mul_f32 v[122:123], v[122:123], v[190:191] op_sel_hi:[1,0]
	v_pk_mul_f32 v[120:121], v[120:121], v[190:191] op_sel_hi:[1,0]
	v_pk_mul_f32 v[118:119], v[118:119], v[190:191] op_sel_hi:[1,0]
	v_pk_mul_f32 v[116:117], v[116:117], v[190:191] op_sel_hi:[1,0]
	v_pk_mul_f32 v[114:115], v[114:115], v[190:191] op_sel_hi:[1,0]
	v_pk_mul_f32 v[112:113], v[112:113], v[190:191] op_sel_hi:[1,0]
	v_pk_mul_f32 v[110:111], v[110:111], v[190:191] op_sel_hi:[1,0]
	v_pk_mul_f32 v[108:109], v[108:109], v[190:191] op_sel_hi:[1,0]
	v_pk_mul_f32 v[106:107], v[106:107], v[190:191] op_sel_hi:[1,0]
	v_pk_mul_f32 v[104:105], v[104:105], v[190:191] op_sel_hi:[1,0]
	v_pk_mul_f32 v[102:103], v[102:103], v[190:191] op_sel_hi:[1,0]
	v_pk_mul_f32 v[100:101], v[100:101], v[190:191] op_sel_hi:[1,0]
	v_pk_mul_f32 v[98:99], v[98:99], v[190:191] op_sel_hi:[1,0]
	v_pk_mul_f32 v[96:97], v[96:97], v[190:191] op_sel_hi:[1,0]
	v_pk_mul_f32 v[94:95], v[94:95], v[190:191] op_sel_hi:[1,0]
	v_pk_mul_f32 v[92:93], v[92:93], v[190:191] op_sel_hi:[1,0]
	v_pk_mul_f32 v[90:91], v[90:91], v[190:191] op_sel_hi:[1,0]
	v_pk_mul_f32 v[88:89], v[88:89], v[190:191] op_sel_hi:[1,0]
	v_pk_mul_f32 v[86:87], v[86:87], v[190:191] op_sel_hi:[1,0]
	v_pk_mul_f32 v[84:85], v[84:85], v[190:191] op_sel_hi:[1,0]
	v_pk_mul_f32 v[82:83], v[82:83], v[190:191] op_sel_hi:[1,0]
	v_pk_mul_f32 v[80:81], v[80:81], v[190:191] op_sel_hi:[1,0]
	v_pk_mul_f32 v[78:79], v[78:79], v[190:191] op_sel_hi:[1,0]
	v_pk_mul_f32 v[76:77], v[76:77], v[190:191] op_sel_hi:[1,0]
	v_pk_mul_f32 v[74:75], v[74:75], v[190:191] op_sel_hi:[1,0]
	v_pk_mul_f32 v[72:73], v[72:73], v[190:191] op_sel_hi:[1,0]
	v_pk_mul_f32 v[70:71], v[70:71], v[190:191] op_sel_hi:[1,0]
	v_pk_mul_f32 v[68:69], v[68:69], v[190:191] op_sel_hi:[1,0]
	v_pk_mul_f32 v[66:67], v[66:67], v[190:191] op_sel_hi:[1,0]
	v_pk_mul_f32 v[64:65], v[64:65], v[190:191] op_sel_hi:[1,0]
	v_pk_mul_f32 v[62:63], v[62:63], v[190:191] op_sel_hi:[1,0]
	v_pk_mul_f32 v[60:61], v[60:61], v[190:191] op_sel_hi:[1,0]
	v_pk_mul_f32 v[58:59], v[58:59], v[190:191] op_sel_hi:[1,0]
	v_pk_mul_f32 v[56:57], v[56:57], v[190:191] op_sel_hi:[1,0]
	v_pk_mul_f32 v[54:55], v[54:55], v[190:191] op_sel_hi:[1,0]
	v_pk_mul_f32 v[52:53], v[52:53], v[190:191] op_sel_hi:[1,0]
	v_pk_mul_f32 v[50:51], v[50:51], v[190:191] op_sel_hi:[1,0]
	v_pk_mul_f32 v[48:49], v[48:49], v[190:191] op_sel_hi:[1,0]
	v_pk_mul_f32 v[46:47], v[46:47], v[190:191] op_sel_hi:[1,0]
	v_pk_mul_f32 v[44:45], v[44:45], v[190:191] op_sel_hi:[1,0]
	v_pk_mul_f32 v[42:43], v[42:43], v[190:191] op_sel_hi:[1,0]
	v_pk_mul_f32 v[40:41], v[40:41], v[190:191] op_sel_hi:[1,0]
	v_pk_mul_f32 v[38:39], v[38:39], v[190:191] op_sel_hi:[1,0]
	v_pk_mul_f32 v[36:37], v[36:37], v[190:191] op_sel_hi:[1,0]
	v_pk_mul_f32 v[34:35], v[34:35], v[190:191] op_sel_hi:[1,0]
	v_pk_mul_f32 v[32:33], v[32:33], v[190:191] op_sel_hi:[1,0]
	v_pk_mul_f32 v[30:31], v[30:31], v[190:191] op_sel_hi:[1,0]
	v_pk_mul_f32 v[28:29], v[28:29], v[190:191] op_sel_hi:[1,0]
	v_pk_mul_f32 v[26:27], v[26:27], v[190:191] op_sel_hi:[1,0]
	v_pk_mul_f32 v[24:25], v[24:25], v[190:191] op_sel_hi:[1,0]
	v_pk_mul_f32 v[22:23], v[22:23], v[190:191] op_sel_hi:[1,0]
	v_pk_mul_f32 v[20:21], v[20:21], v[190:191] op_sel_hi:[1,0]
	v_pk_mul_f32 v[18:19], v[18:19], v[190:191] op_sel_hi:[1,0]
	v_pk_mul_f32 v[16:17], v[16:17], v[190:191] op_sel_hi:[1,0]
	v_pk_mul_f32 v[14:15], v[14:15], v[190:191] op_sel_hi:[1,0]
	v_pk_mul_f32 v[12:13], v[12:13], v[190:191] op_sel_hi:[1,0]
	v_pk_mul_f32 v[10:11], v[10:11], v[190:191] op_sel_hi:[1,0]
	v_pk_mul_f32 v[8:9], v[8:9], v[190:191] op_sel_hi:[1,0]
	v_pk_mul_f32 v[6:7], v[6:7], v[190:191] op_sel_hi:[1,0]
	v_pk_mul_f32 v[4:5], v[4:5], v[190:191] op_sel_hi:[1,0]
	v_pk_mul_f32 v[2:3], v[2:3], v[190:191] op_sel_hi:[1,0]
	v_pk_mul_f32 v[0:1], v[0:1], v[190:191] op_sel_hi:[1,0]
	v_mul_f32_e32 v195, v195, v190
	v_mov_b32_e32 v190, v246
.Latt_nr0_1s1:
	s_waitcnt lgkmcnt(3)
	v_mfma_f32_32x32x16_bf16 v[222:237], v[214:217], v[152:155], v[222:237]
	ds_read_b128 v[214:217], v202 offset:24576
	v_sub_f32_e32 v128, v128, v190
	v_exp_f32_e32 v128, v128
	v_sub_f32_e32 v129, v129, v190
	v_exp_f32_e32 v129, v129
	v_sub_f32_e32 v130, v130, v190
	s_waitcnt lgkmcnt(3)
	v_mfma_f32_32x32x16_bf16 v[222:237], v[238:241], v[156:159], v[222:237]
	ds_read_b128 v[238:241], v203 offset:24576
	v_add_f32_e32 v254, 0, v128
	v_exp_f32_e32 v130, v130
	v_sub_f32_e32 v131, v131, v190
	v_add_f32_e32 v254, v129, v254
	v_exp_f32_e32 v131, v131
	s_waitcnt lgkmcnt(3)
	v_mfma_f32_32x32x16_bf16 v[222:237], v[206:209], v[160:163], v[222:237]
	ds_read_b64_tr_b16 v[206:207], v205
	ds_read_b64_tr_b16 v[208:209], v205 offset:4096
	v_sub_f32_e32 v132, v132, v190
	v_add_f32_e32 v254, v130, v254
	v_exp_f32_e32 v132, v132
	v_sub_f32_e32 v133, v133, v190
	v_add_f32_e32 v254, v131, v254
	s_waitcnt lgkmcnt(4)
	v_mfma_f32_32x32x16_bf16 v[222:237], v[210:213], v[164:167], v[222:237]
	ds_read_b64_tr_b16 v[210:211], v218
	ds_read_b64_tr_b16 v[212:213], v218 offset:4096
	v_exp_f32_e32 v133, v133
	v_sub_f32_e32 v134, v134, v190
	v_add_f32_e32 v254, v132, v254
	v_exp_f32_e32 v134, v134
	s_waitcnt lgkmcnt(5)
	v_mfma_f32_32x32x16_bf16 v[222:237], v[214:217], v[168:171], v[222:237]
	ds_read_b64_tr_b16 v[214:215], v219
	ds_read_b64_tr_b16 v[216:217], v219 offset:4096
	v_sub_f32_e32 v135, v135, v190
	v_add_f32_e32 v254, v133, v254
	v_exp_f32_e32 v135, v135
	s_nop 0
	s_waitcnt lgkmcnt(6)
	v_mfma_f32_32x32x16_bf16 v[222:237], v[238:241], v[172:175], v[222:237]
	ds_read_b64_tr_b16 v[238:239], v221
	ds_read_b64_tr_b16 v[240:241], v221 offset:4096
	v_cvt_pk_bf16_f32 v242, v128, v129
	v_cvt_pk_bf16_f32 v243, v130, v131
	v_cvt_pk_bf16_f32 v244, v132, v133
	v_cvt_pk_bf16_f32 v245, v134, v135
	s_nop 1
	s_waitcnt lgkmcnt(6)
	v_mfma_f32_32x32x16_bf16 v[112:127], v[206:209], v[242:245], v[112:127]
	ds_read_b64_tr_b16 v[206:207], v205 offset:256
	ds_read_b64_tr_b16 v[208:209], v205 offset:4352
	v_sub_f32_e32 v136, v136, v190
	v_add_f32_e32 v254, v134, v254
	v_exp_f32_e32 v136, v136
	v_sub_f32_e32 v137, v137, v190
	v_add_f32_e32 v254, v135, v254
	s_waitcnt lgkmcnt(6)
	v_mfma_f32_32x32x16_bf16 v[96:111], v[210:213], v[242:245], v[96:111]
	ds_read_b64_tr_b16 v[210:211], v218 offset:256
	ds_read_b64_tr_b16 v[212:213], v218 offset:4352
	v_exp_f32_e32 v137, v137
	v_sub_f32_e32 v138, v138, v190
	v_add_f32_e32 v254, v136, v254
	v_exp_f32_e32 v138, v138
	v_sub_f32_e32 v139, v139, v190
	s_waitcnt lgkmcnt(6)
	v_mfma_f32_32x32x16_bf16 v[80:95], v[214:217], v[242:245], v[80:95]
	ds_read_b64_tr_b16 v[214:215], v219 offset:256
	ds_read_b64_tr_b16 v[216:217], v219 offset:4352
	v_add_f32_e32 v254, v137, v254
	v_exp_f32_e32 v139, v139
	v_sub_f32_e32 v140, v140, v190
	v_add_f32_e32 v254, v138, v254
	s_waitcnt lgkmcnt(6)
	v_mfma_f32_32x32x16_bf16 v[64:79], v[238:241], v[242:245], v[64:79]
	ds_read_b64_tr_b16 v[238:239], v221 offset:256
	ds_read_b64_tr_b16 v[240:241], v221 offset:4352
	v_exp_f32_e32 v140, v140
	v_sub_f32_e32 v141, v141, v190
	v_add_f32_e32 v254, v139, v254
	v_exp_f32_e32 v141, v141
	s_waitcnt lgkmcnt(6)
	v_mfma_f32_32x32x16_bf16 v[48:63], v[206:209], v[242:245], v[48:63]
	ds_read_b64_tr_b16 v[206:207], v205 offset:8192
	ds_read_b64_tr_b16 v[208:209], v205 offset:12288
	v_sub_f32_e32 v142, v142, v190
	v_add_f32_e32 v254, v140, v254
	v_exp_f32_e32 v142, v142
	v_sub_f32_e32 v143, v143, v190
	s_waitcnt lgkmcnt(6)
	v_mfma_f32_32x32x16_bf16 v[32:47], v[210:213], v[242:245], v[32:47]
	ds_read_b64_tr_b16 v[210:211], v218 offset:8192
	ds_read_b64_tr_b16 v[212:213], v218 offset:12288
	v_add_f32_e32 v254, v141, v254
	v_exp_f32_e32 v143, v143
	v_add_f32_e32 v254, v142, v254
	v_add_f32_e32 v254, v143, v254
	s_waitcnt lgkmcnt(6)
	v_mfma_f32_32x32x16_bf16 v[16:31], v[214:217], v[242:245], v[16:31]
	ds_read_b64_tr_b16 v[214:215], v219 offset:8192
	ds_read_b64_tr_b16 v[216:217], v219 offset:12288
	v_cvt_pk_bf16_f32 v250, v136, v137
	v_cvt_pk_bf16_f32 v251, v138, v139
	v_cvt_pk_bf16_f32 v252, v140, v141
	v_cvt_pk_bf16_f32 v253, v142, v143
	v_add_f32_e32 v195, v195, v254
	s_waitcnt lgkmcnt(6)
	v_mfma_f32_32x32x16_bf16 v[0:15], v[238:241], v[242:245], v[0:15]
	ds_read_b64_tr_b16 v[238:239], v221 offset:8192
	ds_read_b64_tr_b16 v[240:241], v221 offset:12288
	ds_read_b64_tr_b16 v[128:129], v205 offset:8448
	ds_read_b64_tr_b16 v[130:131], v205 offset:12544
	s_waitcnt lgkmcnt(8)
	v_mfma_f32_32x32x16_bf16 v[112:127], v[206:209], v[250:253], v[112:127]
	ds_read_b64_tr_b16 v[206:207], v218 offset:8448
	ds_read_b64_tr_b16 v[208:209], v218 offset:12544
	v_max3_f32 v246, v222, v223, v224
	v_max3_f32 v247, v225, v226, v227
	v_max3_f32 v246, v246, v228, v229
	v_max3_f32 v247, v247, v230, v231
	v_max3_f32 v246, v246, v232, v233
	s_waitcnt lgkmcnt(8)
	v_mfma_f32_32x32x16_bf16 v[96:111], v[210:213], v[250:253], v[96:111]
	ds_read_b64_tr_b16 v[210:211], v219 offset:8448
	ds_read_b64_tr_b16 v[212:213], v219 offset:12544
	v_max3_f32 v247, v247, v234, v235
	v_max3_f32 v246, v246, v236, v237
	v_max_f32_e32 v246, v246, v247
	v_mov_b32_e32 v247, v246
	v_add_f32_e32 v249, 0x41000000, v190
	s_waitcnt lgkmcnt(8)
	v_mfma_f32_32x32x16_bf16 v[80:95], v[214:217], v[250:253], v[80:95]
	ds_read_b64_tr_b16 v[214:215], v221 offset:8448
	ds_read_b64_tr_b16 v[216:217], v221 offset:12544
	s_nop 1
	v_permlane32_swap_b32_e32 v246, v247
	v_max_f32_e32 v246, v246, v247
	v_cmp_gt_f32_e32 vcc, v246, v249
	s_cbranch_vccnz .Latt_rs1_1s1
	s_waitcnt lgkmcnt(8)
	v_mfma_f32_32x32x16_bf16 v[64:79], v[238:241], v[250:253], v[64:79]
	ds_read_b64_tr_b16 v[238:239], v205 offset:16384
	ds_read_b64_tr_b16 v[240:241], v205 offset:20480
	v_sub_f32_e32 v222, v222, v190
	v_exp_f32_e32 v222, v222
	v_sub_f32_e32 v223, v223, v190
	v_exp_f32_e32 v223, v223
	v_sub_f32_e32 v224, v224, v190
	v_add_f32_e32 v254, 0, v222
	s_waitcnt lgkmcnt(8)
	v_mfma_f32_32x32x16_bf16 v[48:63], v[128:131], v[250:253], v[48:63]
	ds_read_b64_tr_b16 v[128:129], v218 offset:16384
	ds_read_b64_tr_b16 v[130:131], v218 offset:20480
	v_exp_f32_e32 v224, v224
	v_sub_f32_e32 v225, v225, v190
	v_add_f32_e32 v254, v223, v254
	v_exp_f32_e32 v225, v225
	v_sub_f32_e32 v226, v226, v190
	v_add_f32_e32 v254, v224, v254
	s_waitcnt lgkmcnt(8)
	v_mfma_f32_32x32x16_bf16 v[32:47], v[206:209], v[250:253], v[32:47]
	ds_read_b64_tr_b16 v[206:207], v219 offset:16384
	ds_read_b64_tr_b16 v[208:209], v219 offset:20480
	v_exp_f32_e32 v226, v226
	v_sub_f32_e32 v227, v227, v190
	v_add_f32_e32 v254, v225, v254
	v_exp_f32_e32 v227, v227
	v_sub_f32_e32 v228, v228, v190
	s_waitcnt lgkmcnt(8)
	v_mfma_f32_32x32x16_bf16 v[16:31], v[210:213], v[250:253], v[16:31]
	ds_read_b64_tr_b16 v[210:211], v221 offset:16384
	ds_read_b64_tr_b16 v[212:213], v221 offset:20480
	v_add_f32_e32 v254, v226, v254
	v_exp_f32_e32 v228, v228
	v_sub_f32_e32 v229, v229, v190
	v_add_f32_e32 v254, v227, v254
	v_exp_f32_e32 v229, v229
	s_waitcnt lgkmcnt(8)
	v_mfma_f32_32x32x16_bf16 v[0:15], v[214:217], v[250:253], v[0:15]
	ds_read_b64_tr_b16 v[214:215], v205 offset:16640
	ds_read_b64_tr_b16 v[216:217], v205 offset:20736
	s_nop 0
	v_cvt_pk_bf16_f32 v242, v222, v223
	v_cvt_pk_bf16_f32 v243, v224, v225
	v_cvt_pk_bf16_f32 v244, v226, v227
	v_cvt_pk_bf16_f32 v245, v228, v229
	s_nop 1
	s_waitcnt lgkmcnt(8)
	v_mfma_f32_32x32x16_bf16 v[112:127], v[238:241], v[242:245], v[112:127]
	ds_read_b64_tr_b16 v[238:239], v218 offset:16640
	ds_read_b64_tr_b16 v[240:241], v218 offset:20736
	v_sub_f32_e32 v230, v230, v190
	v_add_f32_e32 v254, v228, v254
	v_exp_f32_e32 v230, v230
	v_sub_f32_e32 v231, v231, v190
	v_add_f32_e32 v254, v229, v254
	s_waitcnt lgkmcnt(8)
	v_mfma_f32_32x32x16_bf16 v[96:111], v[128:131], v[242:245], v[96:111]
	ds_read_b64_tr_b16 v[128:129], v219 offset:16640
	ds_read_b64_tr_b16 v[130:131], v219 offset:20736
	v_exp_f32_e32 v231, v231
	v_sub_f32_e32 v232, v232, v190
	v_add_f32_e32 v254, v230, v254
	v_exp_f32_e32 v232, v232
	v_sub_f32_e32 v233, v233, v190
	s_cmp_lg_u64 s[18:19], 0
	s_cbranch_scc1 .Latt_nd0_1s1
	s_sub_i32 s100, s33, 1
	s_cmp_eq_u32 s33, 0
	s_cselect_b32 s100, 2, s100
	s_lshl_b32 s101, s100, 14
	s_add_i32 m0, s85, s101
	s_nop 0
	global_load_lds_dwordx4 v178, s[12:13]

.Latt_slow_1s1:
.Latt_slot2_1:
	ds_read_b128 v[206:209], v196 offset:32768
	ds_read_b128 v[210:213], v197 offset:32768
	ds_read_b128 v[214:217], v198 offset:32768
	ds_read_b128 v[238:241], v199 offset:32768
	ds_read_b128 v[242:245], v200 offset:32768
	ds_read_b128 v[250:253], v201 offset:32768
	ds_read_b128 v[222:225], v202 offset:32768
	ds_read_b128 v[226:229], v203 offset:32768
	v_add_u32_e32 v205, 0x8000, v205
	v_add_u32_e32 v218, 0x8000, v218
	v_add_u32_e32 v219, 0x8000, v219
	v_add_u32_e32 v221, 0x8000, v221
	s_waitcnt lgkmcnt(7)
	v_mfma_f32_32x32x16_bf16 v[128:143], v[206:209], v[144:147], 0
	ds_read_b128 v[206:209], v196 offset:40960
	s_waitcnt lgkmcnt(7)
	v_mfma_f32_32x32x16_bf16 v[128:143], v[210:213], v[148:151], v[128:143]
	ds_read_b128 v[210:213], v197 offset:40960
	s_waitcnt lgkmcnt(7)
	v_mfma_f32_32x32x16_bf16 v[128:143], v[214:217], v[152:155], v[128:143]
	ds_read_b128 v[214:217], v198 offset:40960
	s_waitcnt lgkmcnt(7)
	v_mfma_f32_32x32x16_bf16 v[128:143], v[238:241], v[156:159], v[128:143]
	ds_read_b128 v[238:241], v199 offset:40960
	s_waitcnt lgkmcnt(7)
	v_mfma_f32_32x32x16_bf16 v[128:143], v[242:245], v[160:163], v[128:143]
	s_waitcnt lgkmcnt(6)
	v_mfma_f32_32x32x16_bf16 v[128:143], v[250:253], v[164:167], v[128:143]
	s_waitcnt lgkmcnt(5)
	v_mfma_f32_32x32x16_bf16 v[128:143], v[222:225], v[168:171], v[128:143]
	s_waitcnt lgkmcnt(4)
	v_mfma_f32_32x32x16_bf16 v[128:143], v[226:229], v[172:175], v[128:143]
	s_waitcnt lgkmcnt(3)
	v_mfma_f32_32x32x16_bf16 v[222:237], v[206:209], v[144:147], 0
	ds_read_b128 v[206:209], v200 offset:40960
	s_nop 8
	v_max3_f32 v246, v128, v129, v130
	v_max3_f32 v247, v131, v132, v133
	v_max3_f32 v246, v246, v134, v135
	v_max3_f32 v247, v247, v136, v137
	v_max3_f32 v246, v246, v138, v139
	v_max3_f32 v247, v247, v140, v141
	v_max3_f32 v246, v246, v142, v143
	s_waitcnt lgkmcnt(3)
	v_mfma_f32_32x32x16_bf16 v[222:237], v[210:213], v[148:151], v[222:237]
	ds_read_b128 v[210:213], v201 offset:40960
	v_max_f32_e32 v246, v246, v247
	v_mov_b32_e32 v247, v246
	v_add_f32_e32 v249, 0x41000000, v190
	s_nop 1
	v_permlane32_swap_b32_e32 v246, v247
	v_max_f32_e32 v246, v246, v247
	v_cmp_gt_f32_e32 vcc, v246, v249
	s_cbranch_vccz .Latt_nr0_1s2
	v_max_f32_e32 v246, v190, v246
	v_sub_f32_e32 v190, v190, v246
	v_exp_f32_e32 v190, v190
	s_nop 0
	v_pk_mul_f32 v[126:127], v[126:127], v[190:191] op_sel_hi:[1,0]
	v_pk_mul_f32 v[124:125], v[124:125], v[190:191] op_sel_hi:[1,0]
	v_pk_mul_f32 v[122:123], v[122:123], v[190:191] op_sel_hi:[1,0]
	v_pk_mul_f32 v[120:121], v[120:121], v[190:191] op_sel_hi:[1,0]
	v_pk_mul_f32 v[118:119], v[118:119], v[190:191] op_sel_hi:[1,0]
	v_pk_mul_f32 v[116:117], v[116:117], v[190:191] op_sel_hi:[1,0]
	v_pk_mul_f32 v[114:115], v[114:115], v[190:191] op_sel_hi:[1,0]
	v_pk_mul_f32 v[112:113], v[112:113], v[190:191] op_sel_hi:[1,0]
	v_pk_mul_f32 v[110:111], v[110:111], v[190:191] op_sel_hi:[1,0]
	v_pk_mul_f32 v[108:109], v[108:109], v[190:191] op_sel_hi:[1,0]
	v_pk_mul_f32 v[106:107], v[106:107], v[190:191] op_sel_hi:[1,0]
	v_pk_mul_f32 v[104:105], v[104:105], v[190:191] op_sel_hi:[1,0]
	v_pk_mul_f32 v[102:103], v[102:103], v[190:191] op_sel_hi:[1,0]
	v_pk_mul_f32 v[100:101], v[100:101], v[190:191] op_sel_hi:[1,0]
	v_pk_mul_f32 v[98:99], v[98:99], v[190:191] op_sel_hi:[1,0]
	v_pk_mul_f32 v[96:97], v[96:97], v[190:191] op_sel_hi:[1,0]
	v_pk_mul_f32 v[94:95], v[94:95], v[190:191] op_sel_hi:[1,0]
	v_pk_mul_f32 v[92:93], v[92:93], v[190:191] op_sel_hi:[1,0]
	v_pk_mul_f32 v[90:91], v[90:91], v[190:191] op_sel_hi:[1,0]
	v_pk_mul_f32 v[88:89], v[88:89], v[190:191] op_sel_hi:[1,0]
	v_pk_mul_f32 v[86:87], v[86:87], v[190:191] op_sel_hi:[1,0]
	v_pk_mul_f32 v[84:85], v[84:85], v[190:191] op_sel_hi:[1,0]
	v_pk_mul_f32 v[82:83], v[82:83], v[190:191] op_sel_hi:[1,0]
	v_pk_mul_f32 v[80:81], v[80:81], v[190:191] op_sel_hi:[1,0]
	v_pk_mul_f32 v[78:79], v[78:79], v[190:191] op_sel_hi:[1,0]
	v_pk_mul_f32 v[76:77], v[76:77], v[190:191] op_sel_hi:[1,0]
	v_pk_mul_f32 v[74:75], v[74:75], v[190:191] op_sel_hi:[1,0]
	v_pk_mul_f32 v[72:73], v[72:73], v[190:191] op_sel_hi:[1,0]
	v_pk_mul_f32 v[70:71], v[70:71], v[190:191] op_sel_hi:[1,0]
	v_pk_mul_f32 v[68:69], v[68:69], v[190:191] op_sel_hi:[1,0]
	v_pk_mul_f32 v[66:67], v[66:67], v[190:191] op_sel_hi:[1,0]
	v_pk_mul_f32 v[64:65], v[64:65], v[190:191] op_sel_hi:[1,0]
	v_pk_mul_f32 v[62:63], v[62:63], v[190:191] op_sel_hi:[1,0]
	v_pk_mul_f32 v[60:61], v[60:61], v[190:191] op_sel_hi:[1,0]
	v_pk_mul_f32 v[58:59], v[58:59], v[190:191] op_sel_hi:[1,0]
	v_pk_mul_f32 v[56:57], v[56:57], v[190:191] op_sel_hi:[1,0]
	v_pk_mul_f32 v[54:55], v[54:55], v[190:191] op_sel_hi:[1,0]
	v_pk_mul_f32 v[52:53], v[52:53], v[190:191] op_sel_hi:[1,0]
	v_pk_mul_f32 v[50:51], v[50:51], v[190:191] op_sel_hi:[1,0]
	v_pk_mul_f32 v[48:49], v[48:49], v[190:191] op_sel_hi:[1,0]
	v_pk_mul_f32 v[46:47], v[46:47], v[190:191] op_sel_hi:[1,0]
	v_pk_mul_f32 v[44:45], v[44:45], v[190:191] op_sel_hi:[1,0]
	v_pk_mul_f32 v[42:43], v[42:43], v[190:191] op_sel_hi:[1,0]
	v_pk_mul_f32 v[40:41], v[40:41], v[190:191] op_sel_hi:[1,0]
	v_pk_mul_f32 v[38:39], v[38:39], v[190:191] op_sel_hi:[1,0]
	v_pk_mul_f32 v[36:37], v[36:37], v[190:191] op_sel_hi:[1,0]
	v_pk_mul_f32 v[34:35], v[34:35], v[190:191] op_sel_hi:[1,0]
	v_pk_mul_f32 v[32:33], v[32:33], v[190:191] op_sel_hi:[1,0]
	v_pk_mul_f32 v[30:31], v[30:31], v[190:191] op_sel_hi:[1,0]
	v_pk_mul_f32 v[28:29], v[28:29], v[190:191] op_sel_hi:[1,0]
	v_pk_mul_f32 v[26:27], v[26:27], v[190:191] op_sel_hi:[1,0]
	v_pk_mul_f32 v[24:25], v[24:25], v[190:191] op_sel_hi:[1,0]
	v_pk_mul_f32 v[22:23], v[22:23], v[190:191] op_sel_hi:[1,0]
	v_pk_mul_f32 v[20:21], v[20:21], v[190:191] op_sel_hi:[1,0]
	v_pk_mul_f32 v[18:19], v[18:19], v[190:191] op_sel_hi:[1,0]
	v_pk_mul_f32 v[16:17], v[16:17], v[190:191] op_sel_hi:[1,0]
	v_pk_mul_f32 v[14:15], v[14:15], v[190:191] op_sel_hi:[1,0]
	v_pk_mul_f32 v[12:13], v[12:13], v[190:191] op_sel_hi:[1,0]
	v_pk_mul_f32 v[10:11], v[10:11], v[190:191] op_sel_hi:[1,0]
	v_pk_mul_f32 v[8:9], v[8:9], v[190:191] op_sel_hi:[1,0]
	v_pk_mul_f32 v[6:7], v[6:7], v[190:191] op_sel_hi:[1,0]
	v_pk_mul_f32 v[4:5], v[4:5], v[190:191] op_sel_hi:[1,0]
	v_pk_mul_f32 v[2:3], v[2:3], v[190:191] op_sel_hi:[1,0]
	v_pk_mul_f32 v[0:1], v[0:1], v[190:191] op_sel_hi:[1,0]
	v_mul_f32_e32 v195, v195, v190
	v_mov_b32_e32 v190, v246
.Latt_nr0_1s2:
	s_waitcnt lgkmcnt(3)
	v_mfma_f32_32x32x16_bf16 v[222:237], v[214:217], v[152:155], v[222:237]
	ds_read_b128 v[214:217], v202 offset:40960
	v_sub_f32_e32 v128, v128, v190
	v_exp_f32_e32 v128, v128
	v_sub_f32_e32 v129, v129, v190
	v_exp_f32_e32 v129, v129
	v_sub_f32_e32 v130, v130, v190
	s_waitcnt lgkmcnt(3)
	v_mfma_f32_32x32x16_bf16 v[222:237], v[238:241], v[156:159], v[222:237]
	ds_read_b128 v[238:241], v203 offset:40960
	v_add_f32_e32 v254, 0, v128
	v_exp_f32_e32 v130, v130
	v_sub_f32_e32 v131, v131, v190
	v_add_f32_e32 v254, v129, v254
	v_exp_f32_e32 v131, v131
	s_waitcnt lgkmcnt(3)
	v_mfma_f32_32x32x16_bf16 v[222:237], v[206:209], v[160:163], v[222:237]
	ds_read_b64_tr_b16 v[206:207], v205
	ds_read_b64_tr_b16 v[208:209], v205 offset:4096
	v_sub_f32_e32 v132, v132, v190
	v_add_f32_e32 v254, v130, v254
	v_exp_f32_e32 v132, v132
	v_sub_f32_e32 v133, v133, v190
	v_add_f32_e32 v254, v131, v254
	s_waitcnt lgkmcnt(4)
	v_mfma_f32_32x32x16_bf16 v[222:237], v[210:213], v[164:167], v[222:237]
	ds_read_b64_tr_b16 v[210:211], v218
	ds_read_b64_tr_b16 v[212:213], v218 offset:4096
	v_exp_f32_e32 v133, v133
	v_sub_f32_e32 v134, v134, v190
	v_add_f32_e32 v254, v132, v254
	v_exp_f32_e32 v134, v134
	s_waitcnt lgkmcnt(5)
	v_mfma_f32_32x32x16_bf16 v[222:237], v[214:217], v[168:171], v[222:237]
	ds_read_b64_tr_b16 v[214:215], v219
	ds_read_b64_tr_b16 v[216:217], v219 offset:4096
	v_sub_f32_e32 v135, v135, v190
	v_add_f32_e32 v254, v133, v254
	v_exp_f32_e32 v135, v135
	s_nop 0
	s_waitcnt lgkmcnt(6)
	v_mfma_f32_32x32x16_bf16 v[222:237], v[238:241], v[172:175], v[222:237]
	ds_read_b64_tr_b16 v[238:239], v221
	ds_read_b64_tr_b16 v[240:241], v221 offset:4096
	v_cvt_pk_bf16_f32 v242, v128, v129
	v_cvt_pk_bf16_f32 v243, v130, v131
	v_cvt_pk_bf16_f32 v244, v132, v133
	v_cvt_pk_bf16_f32 v245, v134, v135
	s_nop 1
	s_waitcnt lgkmcnt(6)
	v_mfma_f32_32x32x16_bf16 v[112:127], v[206:209], v[242:245], v[112:127]
	ds_read_b64_tr_b16 v[206:207], v205 offset:256
	ds_read_b64_tr_b16 v[208:209], v205 offset:4352
	v_sub_f32_e32 v136, v136, v190
	v_add_f32_e32 v254, v134, v254
	v_exp_f32_e32 v136, v136
	v_sub_f32_e32 v137, v137, v190
	v_add_f32_e32 v254, v135, v254
	s_waitcnt lgkmcnt(6)
	v_mfma_f32_32x32x16_bf16 v[96:111], v[210:213], v[242:245], v[96:111]
	ds_read_b64_tr_b16 v[210:211], v218 offset:256
	ds_read_b64_tr_b16 v[212:213], v218 offset:4352
	v_exp_f32_e32 v137, v137
	v_sub_f32_e32 v138, v138, v190
	v_add_f32_e32 v254, v136, v254
	v_exp_f32_e32 v138, v138
	v_sub_f32_e32 v139, v139, v190
	s_waitcnt lgkmcnt(6)
	v_mfma_f32_32x32x16_bf16 v[80:95], v[214:217], v[242:245], v[80:95]
	ds_read_b64_tr_b16 v[214:215], v219 offset:256
	ds_read_b64_tr_b16 v[216:217], v219 offset:4352
	v_add_f32_e32 v254, v137, v254
	v_exp_f32_e32 v139, v139
	v_sub_f32_e32 v140, v140, v190
	v_add_f32_e32 v254, v138, v254
	s_waitcnt lgkmcnt(6)
	v_mfma_f32_32x32x16_bf16 v[64:79], v[238:241], v[242:245], v[64:79]
	ds_read_b64_tr_b16 v[238:239], v221 offset:256
	ds_read_b64_tr_b16 v[240:241], v221 offset:4352
	v_exp_f32_e32 v140, v140
	v_sub_f32_e32 v141, v141, v190
	v_add_f32_e32 v254, v139, v254
	v_exp_f32_e32 v141, v141
	s_waitcnt lgkmcnt(6)
	v_mfma_f32_32x32x16_bf16 v[48:63], v[206:209], v[242:245], v[48:63]
	ds_read_b64_tr_b16 v[206:207], v205 offset:8192
	ds_read_b64_tr_b16 v[208:209], v205 offset:12288
	v_sub_f32_e32 v142, v142, v190
	v_add_f32_e32 v254, v140, v254
	v_exp_f32_e32 v142, v142
	v_sub_f32_e32 v143, v143, v190
	s_waitcnt lgkmcnt(6)
	v_mfma_f32_32x32x16_bf16 v[32:47], v[210:213], v[242:245], v[32:47]
	ds_read_b64_tr_b16 v[210:211], v218 offset:8192
	ds_read_b64_tr_b16 v[212:213], v218 offset:12288
	v_add_f32_e32 v254, v141, v254
	v_exp_f32_e32 v143, v143
	v_add_f32_e32 v254, v142, v254
	v_add_f32_e32 v254, v143, v254
	s_waitcnt lgkmcnt(6)
	v_mfma_f32_32x32x16_bf16 v[16:31], v[214:217], v[242:245], v[16:31]
	ds_read_b64_tr_b16 v[214:215], v219 offset:8192
	ds_read_b64_tr_b16 v[216:217], v219 offset:12288
	v_cvt_pk_bf16_f32 v250, v136, v137
	v_cvt_pk_bf16_f32 v251, v138, v139
	v_cvt_pk_bf16_f32 v252, v140, v141
	v_cvt_pk_bf16_f32 v253, v142, v143
	v_add_f32_e32 v195, v195, v254
	s_waitcnt lgkmcnt(6)
	v_mfma_f32_32x32x16_bf16 v[0:15], v[238:241], v[242:245], v[0:15]
	ds_read_b64_tr_b16 v[238:239], v221 offset:8192
	ds_read_b64_tr_b16 v[240:241], v221 offset:12288
	ds_read_b64_tr_b16 v[128:129], v205 offset:8448
	ds_read_b64_tr_b16 v[130:131], v205 offset:12544
	s_waitcnt lgkmcnt(8)
	v_mfma_f32_32x32x16_bf16 v[112:127], v[206:209], v[250:253], v[112:127]
	ds_read_b64_tr_b16 v[206:207], v218 offset:8448
	ds_read_b64_tr_b16 v[208:209], v218 offset:12544
	v_max3_f32 v246, v222, v223, v224
	v_max3_f32 v247, v225, v226, v227
	v_max3_f32 v246, v246, v228, v229
	v_max3_f32 v247, v247, v230, v231
	v_max3_f32 v246, v246, v232, v233
	s_waitcnt lgkmcnt(8)
	v_mfma_f32_32x32x16_bf16 v[96:111], v[210:213], v[250:253], v[96:111]
	ds_read_b64_tr_b16 v[210:211], v219 offset:8448
	ds_read_b64_tr_b16 v[212:213], v219 offset:12544
	v_max3_f32 v247, v247, v234, v235
	v_max3_f32 v246, v246, v236, v237
	v_max_f32_e32 v246, v246, v247
	v_mov_b32_e32 v247, v246
	v_add_f32_e32 v249, 0x41000000, v190
	s_waitcnt lgkmcnt(8)
	v_mfma_f32_32x32x16_bf16 v[80:95], v[214:217], v[250:253], v[80:95]
	ds_read_b64_tr_b16 v[214:215], v221 offset:8448
	ds_read_b64_tr_b16 v[216:217], v221 offset:12544
	s_nop 1
	v_permlane32_swap_b32_e32 v246, v247
	v_max_f32_e32 v246, v246, v247
	v_cmp_gt_f32_e32 vcc, v246, v249
	s_cbranch_vccnz .Latt_rs1_1s2
	s_waitcnt lgkmcnt(8)
	v_mfma_f32_32x32x16_bf16 v[64:79], v[238:241], v[250:253], v[64:79]
	ds_read_b64_tr_b16 v[238:239], v205 offset:16384
	ds_read_b64_tr_b16 v[240:241], v205 offset:20480
	v_sub_f32_e32 v222, v222, v190
	v_exp_f32_e32 v222, v222
	v_sub_f32_e32 v223, v223, v190
	v_exp_f32_e32 v223, v223
	v_sub_f32_e32 v224, v224, v190
	v_add_f32_e32 v254, 0, v222
	s_waitcnt lgkmcnt(8)
	v_mfma_f32_32x32x16_bf16 v[48:63], v[128:131], v[250:253], v[48:63]
	ds_read_b64_tr_b16 v[128:129], v218 offset:16384
	ds_read_b64_tr_b16 v[130:131], v218 offset:20480
	v_exp_f32_e32 v224, v224
	v_sub_f32_e32 v225, v225, v190
	v_add_f32_e32 v254, v223, v254
	v_exp_f32_e32 v225, v225
	v_sub_f32_e32 v226, v226, v190
	v_add_f32_e32 v254, v224, v254
	s_waitcnt lgkmcnt(8)
	v_mfma_f32_32x32x16_bf16 v[32:47], v[206:209], v[250:253], v[32:47]
	ds_read_b64_tr_b16 v[206:207], v219 offset:16384
	ds_read_b64_tr_b16 v[208:209], v219 offset:20480
	v_exp_f32_e32 v226, v226
	v_sub_f32_e32 v227, v227, v190
	v_add_f32_e32 v254, v225, v254
	v_exp_f32_e32 v227, v227
	v_sub_f32_e32 v228, v228, v190
	s_waitcnt lgkmcnt(8)
	v_mfma_f32_32x32x16_bf16 v[16:31], v[210:213], v[250:253], v[16:31]
	ds_read_b64_tr_b16 v[210:211], v221 offset:16384
	ds_read_b64_tr_b16 v[212:213], v221 offset:20480
	v_add_f32_e32 v254, v226, v254
	v_exp_f32_e32 v228, v228
	v_sub_f32_e32 v229, v229, v190
	v_add_f32_e32 v254, v227, v254
	v_exp_f32_e32 v229, v229
	s_waitcnt lgkmcnt(8)
	v_mfma_f32_32x32x16_bf16 v[0:15], v[214:217], v[250:253], v[0:15]
	ds_read_b64_tr_b16 v[214:215], v205 offset:16640
	ds_read_b64_tr_b16 v[216:217], v205 offset:20736
	s_nop 0
	v_cvt_pk_bf16_f32 v242, v222, v223
	v_cvt_pk_bf16_f32 v243, v224, v225
	v_cvt_pk_bf16_f32 v244, v226, v227
	v_cvt_pk_bf16_f32 v245, v228, v229
	s_nop 1
	s_waitcnt lgkmcnt(8)
	v_mfma_f32_32x32x16_bf16 v[112:127], v[238:241], v[242:245], v[112:127]
	ds_read_b64_tr_b16 v[238:239], v218 offset:16640
	ds_read_b64_tr_b16 v[240:241], v218 offset:20736
	v_sub_f32_e32 v230, v230, v190
	v_add_f32_e32 v254, v228, v254
	v_exp_f32_e32 v230, v230
	v_sub_f32_e32 v231, v231, v190
	v_add_f32_e32 v254, v229, v254
	s_waitcnt lgkmcnt(8)
	v_mfma_f32_32x32x16_bf16 v[96:111], v[128:131], v[242:245], v[96:111]
	ds_read_b64_tr_b16 v[128:129], v219 offset:16640
	ds_read_b64_tr_b16 v[130:131], v219 offset:20736
	v_exp_f32_e32 v231, v231
	v_sub_f32_e32 v232, v232, v190
	v_add_f32_e32 v254, v230, v254
	v_exp_f32_e32 v232, v232
	v_sub_f32_e32 v233, v233, v190
	s_cmp_lg_u64 s[18:19], 0
	s_cbranch_scc1 .Latt_nd0_1s2
	s_sub_i32 s100, s33, 1
	s_cmp_eq_u32 s33, 0
	s_cselect_b32 s100, 2, s100
	s_lshl_b32 s101, s100, 14
	s_add_i32 m0, s85, s101
	s_nop 0
	global_load_lds_dwordx4 v178, s[12:13]

.Latt_slow_1s2:
.Latt_slow_1:
	s_lshl_b32 s89, s33, 14
	s_add_i32 s90, s89, 0
	v_add_u32_e32 v207, s90, v196
	ds_read_b128 v[128:131], v207
	v_add_u32_e32 v208, s90, v197
	ds_read_b128 v[210:213], v208
	v_add_u32_e32 v209, s90, v198
	v_lshrrev_b32_e32 v205, 3, v204
	s_add_i32 s91, s4, 31
	v_and_or_b32 v206, v204, 31, s83
	s_cmp_le_i32 s91, s83
	s_waitcnt lgkmcnt(1)
	v_mfma_f32_32x32x16_bf16 v[128:143], v[128:131], v[144:147], 0
	s_waitcnt lgkmcnt(0)
	v_mfma_f32_32x32x16_bf16 v[128:143], v[210:213], v[148:151], v[128:143]
	ds_read_b128 v[212:215], v209
	v_add_u32_e32 v210, s90, v199
	v_add_u32_e32 v211, s90, v200
	s_waitcnt lgkmcnt(0)
	v_mfma_f32_32x32x16_bf16 v[128:143], v[212:215], v[152:155], v[128:143]
	ds_read_b128 v[212:215], v210
	s_waitcnt lgkmcnt(0)
	v_mfma_f32_32x32x16_bf16 v[128:143], v[212:215], v[156:159], v[128:143]
	ds_read_b128 v[214:217], v211
	v_add_u32_e32 v212, s90, v201
	v_add_u32_e32 v213, s90, v202
	s_waitcnt lgkmcnt(0)
	v_mfma_f32_32x32x16_bf16 v[128:143], v[214:217], v[160:163], v[128:143]
	ds_read_b128 v[214:217], v212
	s_waitcnt lgkmcnt(0)
	v_mfma_f32_32x32x16_bf16 v[128:143], v[214:217], v[164:167], v[128:143]
	ds_read_b128 v[216:219], v213
	v_add_u32_e32 v215, s90, v203
	v_and_b32_e32 v214, 4, v205
	s_waitcnt lgkmcnt(0)
	v_mfma_f32_32x32x16_bf16 v[128:143], v[216:219], v[168:171], v[128:143]
	ds_read_b128 v[216:219], v215
	s_waitcnt lgkmcnt(0)
	v_mfma_f32_32x32x16_bf16 v[128:143], v[216:219], v[172:175], v[128:143]
	s_cbranch_scc1 .LBB0_869
	v_add_u32_e32 v205, s4, v214
	v_cmp_lt_i32_e32 vcc, v205, v206
	v_add_u32_e32 v216, 2, v205
	s_nop 7
	v_cndmask_b32_e32 v129, v192, v129, vcc
	v_cmp_le_i32_e32 vcc, v205, v206
	s_nop 1
	v_cndmask_b32_e32 v128, v192, v128, vcc
	v_cmp_le_i32_e32 vcc, v216, v206
	v_add_u32_e32 v216, 3, v205
	s_nop 0
	v_cndmask_b32_e32 v130, v192, v130, vcc
	v_cmp_le_i32_e32 vcc, v216, v206
	v_add_u32_e32 v216, 8, v205
	s_nop 0
	v_cndmask_b32_e32 v131, v192, v131, vcc
	v_cmp_le_i32_e32 vcc, v216, v206
	v_add_u32_e32 v216, 9, v205
	s_nop 0
	v_cndmask_b32_e32 v132, v192, v132, vcc
	v_cmp_le_i32_e32 vcc, v216, v206
	v_add_u32_e32 v216, 10, v205
	s_nop 0
	v_cndmask_b32_e32 v133, v192, v133, vcc
	v_cmp_le_i32_e32 vcc, v216, v206
	v_add_u32_e32 v216, 11, v205
	s_nop 0
	v_cndmask_b32_e32 v134, v192, v134, vcc
	v_cmp_le_i32_e32 vcc, v216, v206
	v_add_u32_e32 v216, 16, v205
	s_nop 0
	v_cndmask_b32_e32 v135, v192, v135, vcc
	v_cmp_le_i32_e32 vcc, v216, v206
	v_add_u32_e32 v216, 17, v205
	s_nop 0
	v_cndmask_b32_e32 v136, v192, v136, vcc
	v_cmp_le_i32_e32 vcc, v216, v206
	v_add_u32_e32 v216, 18, v205
	s_nop 0
	v_cndmask_b32_e32 v137, v192, v137, vcc
	v_cmp_le_i32_e32 vcc, v216, v206
	v_add_u32_e32 v216, 19, v205
	s_nop 0
	v_cndmask_b32_e32 v138, v192, v138, vcc
	v_cmp_le_i32_e32 vcc, v216, v206
	v_add_u32_e32 v216, 24, v205
	s_nop 0
	v_cndmask_b32_e32 v139, v192, v139, vcc
	v_cmp_le_i32_e32 vcc, v216, v206
	v_add_u32_e32 v216, 25, v205
	s_nop 0
	v_cndmask_b32_e32 v140, v192, v140, vcc
	v_cmp_le_i32_e32 vcc, v216, v206
	v_add_u32_e32 v216, 26, v205
	v_add_u32_e32 v205, 27, v205
	v_cndmask_b32_e32 v141, v192, v141, vcc
	v_cmp_le_i32_e32 vcc, v216, v206
	s_nop 1
	v_cndmask_b32_e32 v142, v192, v142, vcc
	v_cmp_le_i32_e32 vcc, v205, v206
	s_nop 1
	v_cndmask_b32_e32 v143, v192, v143, vcc

.LBB0_885:
	s_cmp_gt_i32 s84, s81
	s_cbranch_scc1 .LBB0_896
	s_add_i32 s100, s84, 63
	s_cmp_le_i32 s100, s80
	s_cbranch_scc0 .Latt_slow_2
	s_cmp_eq_u32 s38, 1
	s_cbranch_scc1 .Latt_slot1_2
	s_cmp_eq_u32 s38, 2
	s_cbranch_scc1 .Latt_slot2_2
	ds_read_b128 v[206:209], v195
	ds_read_b128 v[210:213], v196
	ds_read_b128 v[214:217], v197
	ds_read_b128 v[238:241], v198
	ds_read_b128 v[242:245], v199
	ds_read_b128 v[250:253], v200
	ds_read_b128 v[222:225], v201
	ds_read_b128 v[226:229], v202
	s_cmp_lg_u32 s84, 0
	s_cbranch_scc1 .Latt_vstep_2s0
	v_bfe_u32 v246, v204, 2, 2
	v_bfe_u32 v247, v204, 5, 1
	v_lshl_or_b32 v247, v247, 2, v246
	v_and_b32_e32 v249, 3, v204
	v_and_b32_e32 v254, 16, v204
	v_lshl_or_b32 v249, v249, 2, v254
	v_lshlrev_b32_e32 v249, 1, v249
	v_lshl_add_u32 v247, v247, 9, v249
	v_add_u32_e32 v247, 0xc000, v247
	v_lshlrev_b32_e32 v246, 6, v246
	v_add_u32_e32 v205, v247, v246
	v_xor_b32_e32 v249, 64, v246
	v_add_u32_e32 v218, v247, v249
	v_xor_b32_e32 v249, 0x80, v246
	v_add_u32_e32 v219, v247, v249
	v_xor_b32_e32 v249, 0xc0, v246
	v_add_u32_e32 v221, v247, v249
	s_branch .Latt_vdone_2s0

.Latt_vdone_2s0:
	s_waitcnt lgkmcnt(7)
	v_mfma_f32_32x32x16_bf16 v[128:143], v[206:209], v[144:147], 0
	ds_read_b128 v[206:209], v195 offset:8192
	s_waitcnt lgkmcnt(7)
	v_mfma_f32_32x32x16_bf16 v[128:143], v[210:213], v[148:151], v[128:143]
	ds_read_b128 v[210:213], v196 offset:8192
	s_waitcnt lgkmcnt(7)
	v_mfma_f32_32x32x16_bf16 v[128:143], v[214:217], v[152:155], v[128:143]
	ds_read_b128 v[214:217], v197 offset:8192
	s_waitcnt lgkmcnt(7)
	v_mfma_f32_32x32x16_bf16 v[128:143], v[238:241], v[156:159], v[128:143]
	ds_read_b128 v[238:241], v198 offset:8192
	s_waitcnt lgkmcnt(7)
	v_mfma_f32_32x32x16_bf16 v[128:143], v[242:245], v[160:163], v[128:143]
	s_waitcnt lgkmcnt(6)
	v_mfma_f32_32x32x16_bf16 v[128:143], v[250:253], v[164:167], v[128:143]
	s_waitcnt lgkmcnt(5)
	v_mfma_f32_32x32x16_bf16 v[128:143], v[222:225], v[168:171], v[128:143]
	s_waitcnt lgkmcnt(4)
	v_mfma_f32_32x32x16_bf16 v[128:143], v[226:229], v[172:175], v[128:143]
	s_waitcnt lgkmcnt(3)
	v_mfma_f32_32x32x16_bf16 v[222:237], v[206:209], v[144:147], 0
	ds_read_b128 v[206:209], v199 offset:8192
	s_nop 8
	v_max3_f32 v246, v128, v129, v130
	v_max3_f32 v247, v131, v132, v133
	v_max3_f32 v246, v246, v134, v135
	v_max3_f32 v247, v247, v136, v137
	v_max3_f32 v246, v246, v138, v139
	v_max3_f32 v247, v247, v140, v141
	v_max3_f32 v246, v246, v142, v143
	s_waitcnt lgkmcnt(3)
	v_mfma_f32_32x32x16_bf16 v[222:237], v[210:213], v[148:151], v[222:237]
	ds_read_b128 v[210:213], v200 offset:8192
	v_max_f32_e32 v246, v246, v247
	v_mov_b32_e32 v247, v246
	v_add_f32_e32 v249, 0x41000000, v190
	s_nop 1
	v_permlane32_swap_b32_e32 v246, v247
	v_max_f32_e32 v246, v246, v247
	v_cmp_gt_f32_e32 vcc, v246, v249
	s_cbranch_vccz .Latt_nr0_2s0
	v_max_f32_e32 v246, v190, v246
	v_sub_f32_e32 v190, v190, v246
	v_exp_f32_e32 v190, v190
	s_nop 0
	v_pk_mul_f32 v[126:127], v[126:127], v[190:191] op_sel_hi:[1,0]
	v_pk_mul_f32 v[124:125], v[124:125], v[190:191] op_sel_hi:[1,0]
	v_pk_mul_f32 v[122:123], v[122:123], v[190:191] op_sel_hi:[1,0]
	v_pk_mul_f32 v[120:121], v[120:121], v[190:191] op_sel_hi:[1,0]
	v_pk_mul_f32 v[118:119], v[118:119], v[190:191] op_sel_hi:[1,0]
	v_pk_mul_f32 v[116:117], v[116:117], v[190:191] op_sel_hi:[1,0]
	v_pk_mul_f32 v[114:115], v[114:115], v[190:191] op_sel_hi:[1,0]
	v_pk_mul_f32 v[112:113], v[112:113], v[190:191] op_sel_hi:[1,0]
	v_pk_mul_f32 v[110:111], v[110:111], v[190:191] op_sel_hi:[1,0]
	v_pk_mul_f32 v[108:109], v[108:109], v[190:191] op_sel_hi:[1,0]
	v_pk_mul_f32 v[106:107], v[106:107], v[190:191] op_sel_hi:[1,0]
	v_pk_mul_f32 v[104:105], v[104:105], v[190:191] op_sel_hi:[1,0]
	v_pk_mul_f32 v[102:103], v[102:103], v[190:191] op_sel_hi:[1,0]
	v_pk_mul_f32 v[100:101], v[100:101], v[190:191] op_sel_hi:[1,0]
	v_pk_mul_f32 v[98:99], v[98:99], v[190:191] op_sel_hi:[1,0]
	v_pk_mul_f32 v[96:97], v[96:97], v[190:191] op_sel_hi:[1,0]
	v_pk_mul_f32 v[94:95], v[94:95], v[190:191] op_sel_hi:[1,0]
	v_pk_mul_f32 v[92:93], v[92:93], v[190:191] op_sel_hi:[1,0]
	v_pk_mul_f32 v[90:91], v[90:91], v[190:191] op_sel_hi:[1,0]
	v_pk_mul_f32 v[88:89], v[88:89], v[190:191] op_sel_hi:[1,0]
	v_pk_mul_f32 v[86:87], v[86:87], v[190:191] op_sel_hi:[1,0]
	v_pk_mul_f32 v[84:85], v[84:85], v[190:191] op_sel_hi:[1,0]
	v_pk_mul_f32 v[82:83], v[82:83], v[190:191] op_sel_hi:[1,0]
	v_pk_mul_f32 v[80:81], v[80:81], v[190:191] op_sel_hi:[1,0]
	v_pk_mul_f32 v[78:79], v[78:79], v[190:191] op_sel_hi:[1,0]
	v_pk_mul_f32 v[76:77], v[76:77], v[190:191] op_sel_hi:[1,0]
	v_pk_mul_f32 v[74:75], v[74:75], v[190:191] op_sel_hi:[1,0]
	v_pk_mul_f32 v[72:73], v[72:73], v[190:191] op_sel_hi:[1,0]
	v_pk_mul_f32 v[70:71], v[70:71], v[190:191] op_sel_hi:[1,0]
	v_pk_mul_f32 v[68:69], v[68:69], v[190:191] op_sel_hi:[1,0]
	v_pk_mul_f32 v[66:67], v[66:67], v[190:191] op_sel_hi:[1,0]
	v_pk_mul_f32 v[64:65], v[64:65], v[190:191] op_sel_hi:[1,0]
	v_pk_mul_f32 v[62:63], v[62:63], v[190:191] op_sel_hi:[1,0]
	v_pk_mul_f32 v[60:61], v[60:61], v[190:191] op_sel_hi:[1,0]
	v_pk_mul_f32 v[58:59], v[58:59], v[190:191] op_sel_hi:[1,0]
	v_pk_mul_f32 v[56:57], v[56:57], v[190:191] op_sel_hi:[1,0]
	v_pk_mul_f32 v[54:55], v[54:55], v[190:191] op_sel_hi:[1,0]
	v_pk_mul_f32 v[52:53], v[52:53], v[190:191] op_sel_hi:[1,0]
	v_pk_mul_f32 v[50:51], v[50:51], v[190:191] op_sel_hi:[1,0]
	v_pk_mul_f32 v[48:49], v[48:49], v[190:191] op_sel_hi:[1,0]
	v_pk_mul_f32 v[46:47], v[46:47], v[190:191] op_sel_hi:[1,0]
	v_pk_mul_f32 v[44:45], v[44:45], v[190:191] op_sel_hi:[1,0]
	v_pk_mul_f32 v[42:43], v[42:43], v[190:191] op_sel_hi:[1,0]
	v_pk_mul_f32 v[40:41], v[40:41], v[190:191] op_sel_hi:[1,0]
	v_pk_mul_f32 v[38:39], v[38:39], v[190:191] op_sel_hi:[1,0]
	v_pk_mul_f32 v[36:37], v[36:37], v[190:191] op_sel_hi:[1,0]
	v_pk_mul_f32 v[34:35], v[34:35], v[190:191] op_sel_hi:[1,0]
	v_pk_mul_f32 v[32:33], v[32:33], v[190:191] op_sel_hi:[1,0]
	v_pk_mul_f32 v[30:31], v[30:31], v[190:191] op_sel_hi:[1,0]
	v_pk_mul_f32 v[28:29], v[28:29], v[190:191] op_sel_hi:[1,0]
	v_pk_mul_f32 v[26:27], v[26:27], v[190:191] op_sel_hi:[1,0]
	v_pk_mul_f32 v[24:25], v[24:25], v[190:191] op_sel_hi:[1,0]
	v_pk_mul_f32 v[22:23], v[22:23], v[190:191] op_sel_hi:[1,0]
	v_pk_mul_f32 v[20:21], v[20:21], v[190:191] op_sel_hi:[1,0]
	v_pk_mul_f32 v[18:19], v[18:19], v[190:191] op_sel_hi:[1,0]
	v_pk_mul_f32 v[16:17], v[16:17], v[190:191] op_sel_hi:[1,0]
	v_pk_mul_f32 v[14:15], v[14:15], v[190:191] op_sel_hi:[1,0]
	v_pk_mul_f32 v[12:13], v[12:13], v[190:191] op_sel_hi:[1,0]
	v_pk_mul_f32 v[10:11], v[10:11], v[190:191] op_sel_hi:[1,0]
	v_pk_mul_f32 v[8:9], v[8:9], v[190:191] op_sel_hi:[1,0]
	v_pk_mul_f32 v[6:7], v[6:7], v[190:191] op_sel_hi:[1,0]
	v_pk_mul_f32 v[4:5], v[4:5], v[190:191] op_sel_hi:[1,0]
	v_pk_mul_f32 v[2:3], v[2:3], v[190:191] op_sel_hi:[1,0]
	v_pk_mul_f32 v[0:1], v[0:1], v[190:191] op_sel_hi:[1,0]
	v_mul_f32_e32 v203, v203, v190
	v_mov_b32_e32 v190, v246
.Latt_nr0_2s0:
	s_waitcnt lgkmcnt(3)
	v_mfma_f32_32x32x16_bf16 v[222:237], v[214:217], v[152:155], v[222:237]
	ds_read_b128 v[214:217], v201 offset:8192
	v_sub_f32_e32 v128, v128, v190
	v_exp_f32_e32 v128, v128
	v_sub_f32_e32 v129, v129, v190
	v_exp_f32_e32 v129, v129
	v_sub_f32_e32 v130, v130, v190
	s_waitcnt lgkmcnt(3)
	v_mfma_f32_32x32x16_bf16 v[222:237], v[238:241], v[156:159], v[222:237]
	ds_read_b128 v[238:241], v202 offset:8192
	v_add_f32_e32 v254, 0, v128
	v_exp_f32_e32 v130, v130
	v_sub_f32_e32 v131, v131, v190
	v_add_f32_e32 v254, v129, v254
	v_exp_f32_e32 v131, v131
	s_waitcnt lgkmcnt(3)
	v_mfma_f32_32x32x16_bf16 v[222:237], v[206:209], v[160:163], v[222:237]
	ds_read_b64_tr_b16 v[206:207], v205
	ds_read_b64_tr_b16 v[208:209], v205 offset:4096
	v_sub_f32_e32 v132, v132, v190
	v_add_f32_e32 v254, v130, v254
	v_exp_f32_e32 v132, v132
	v_sub_f32_e32 v133, v133, v190
	v_add_f32_e32 v254, v131, v254
	s_waitcnt lgkmcnt(4)
	v_mfma_f32_32x32x16_bf16 v[222:237], v[210:213], v[164:167], v[222:237]
	ds_read_b64_tr_b16 v[210:211], v218
	ds_read_b64_tr_b16 v[212:213], v218 offset:4096
	v_exp_f32_e32 v133, v133
	v_sub_f32_e32 v134, v134, v190
	v_add_f32_e32 v254, v132, v254
	v_exp_f32_e32 v134, v134
	s_waitcnt lgkmcnt(5)
	v_mfma_f32_32x32x16_bf16 v[222:237], v[214:217], v[168:171], v[222:237]
	ds_read_b64_tr_b16 v[214:215], v219
	ds_read_b64_tr_b16 v[216:217], v219 offset:4096
	v_sub_f32_e32 v135, v135, v190
	v_add_f32_e32 v254, v133, v254
	v_exp_f32_e32 v135, v135
	s_nop 0
	s_waitcnt lgkmcnt(6)
	v_mfma_f32_32x32x16_bf16 v[222:237], v[238:241], v[172:175], v[222:237]
	ds_read_b64_tr_b16 v[238:239], v221
	ds_read_b64_tr_b16 v[240:241], v221 offset:4096
	v_cvt_pk_bf16_f32 v242, v128, v129
	v_cvt_pk_bf16_f32 v243, v130, v131
	v_cvt_pk_bf16_f32 v244, v132, v133
	v_cvt_pk_bf16_f32 v245, v134, v135
	s_nop 1
	s_waitcnt lgkmcnt(6)
	v_mfma_f32_32x32x16_bf16 v[112:127], v[206:209], v[242:245], v[112:127]
	ds_read_b64_tr_b16 v[206:207], v205 offset:256
	ds_read_b64_tr_b16 v[208:209], v205 offset:4352
	v_sub_f32_e32 v136, v136, v190
	v_add_f32_e32 v254, v134, v254
	v_exp_f32_e32 v136, v136
	v_sub_f32_e32 v137, v137, v190
	v_add_f32_e32 v254, v135, v254
	s_waitcnt lgkmcnt(6)
	v_mfma_f32_32x32x16_bf16 v[96:111], v[210:213], v[242:245], v[96:111]
	ds_read_b64_tr_b16 v[210:211], v218 offset:256
	ds_read_b64_tr_b16 v[212:213], v218 offset:4352
	v_exp_f32_e32 v137, v137
	v_sub_f32_e32 v138, v138, v190
	v_add_f32_e32 v254, v136, v254
	v_exp_f32_e32 v138, v138
	v_sub_f32_e32 v139, v139, v190
	s_waitcnt lgkmcnt(6)
	v_mfma_f32_32x32x16_bf16 v[80:95], v[214:217], v[242:245], v[80:95]
	ds_read_b64_tr_b16 v[214:215], v219 offset:256
	ds_read_b64_tr_b16 v[216:217], v219 offset:4352
	v_add_f32_e32 v254, v137, v254
	v_exp_f32_e32 v139, v139
	v_sub_f32_e32 v140, v140, v190
	v_add_f32_e32 v254, v138, v254
	s_waitcnt lgkmcnt(6)
	v_mfma_f32_32x32x16_bf16 v[64:79], v[238:241], v[242:245], v[64:79]
	ds_read_b64_tr_b16 v[238:239], v221 offset:256
	ds_read_b64_tr_b16 v[240:241], v221 offset:4352
	v_exp_f32_e32 v140, v140
	v_sub_f32_e32 v141, v141, v190
	v_add_f32_e32 v254, v139, v254
	v_exp_f32_e32 v141, v141
	s_waitcnt lgkmcnt(6)
	v_mfma_f32_32x32x16_bf16 v[48:63], v[206:209], v[242:245], v[48:63]
	ds_read_b64_tr_b16 v[206:207], v205 offset:8192
	ds_read_b64_tr_b16 v[208:209], v205 offset:12288
	v_sub_f32_e32 v142, v142, v190
	v_add_f32_e32 v254, v140, v254
	v_exp_f32_e32 v142, v142
	v_sub_f32_e32 v143, v143, v190
	s_waitcnt lgkmcnt(6)
	v_mfma_f32_32x32x16_bf16 v[32:47], v[210:213], v[242:245], v[32:47]
	ds_read_b64_tr_b16 v[210:211], v218 offset:8192
	ds_read_b64_tr_b16 v[212:213], v218 offset:12288
	v_add_f32_e32 v254, v141, v254
	v_exp_f32_e32 v143, v143
	v_add_f32_e32 v254, v142, v254
	v_add_f32_e32 v254, v143, v254
	s_waitcnt lgkmcnt(6)
	v_mfma_f32_32x32x16_bf16 v[16:31], v[214:217], v[242:245], v[16:31]
	ds_read_b64_tr_b16 v[214:215], v219 offset:8192
	ds_read_b64_tr_b16 v[216:217], v219 offset:12288
	v_cvt_pk_bf16_f32 v250, v136, v137
	v_cvt_pk_bf16_f32 v251, v138, v139
	v_cvt_pk_bf16_f32 v252, v140, v141
	v_cvt_pk_bf16_f32 v253, v142, v143
	v_add_f32_e32 v203, v203, v254
	s_waitcnt lgkmcnt(6)
	v_mfma_f32_32x32x16_bf16 v[0:15], v[238:241], v[242:245], v[0:15]
	ds_read_b64_tr_b16 v[238:239], v221 offset:8192
	ds_read_b64_tr_b16 v[240:241], v221 offset:12288
	ds_read_b64_tr_b16 v[128:129], v205 offset:8448
	ds_read_b64_tr_b16 v[130:131], v205 offset:12544
	s_waitcnt lgkmcnt(8)
	v_mfma_f32_32x32x16_bf16 v[112:127], v[206:209], v[250:253], v[112:127]
	ds_read_b64_tr_b16 v[206:207], v218 offset:8448
	ds_read_b64_tr_b16 v[208:209], v218 offset:12544
	v_max3_f32 v246, v222, v223, v224
	v_max3_f32 v247, v225, v226, v227
	v_max3_f32 v246, v246, v228, v229
	v_max3_f32 v247, v247, v230, v231
	v_max3_f32 v246, v246, v232, v233
	s_waitcnt lgkmcnt(8)
	v_mfma_f32_32x32x16_bf16 v[96:111], v[210:213], v[250:253], v[96:111]
	ds_read_b64_tr_b16 v[210:211], v219 offset:8448
	ds_read_b64_tr_b16 v[212:213], v219 offset:12544
	v_max3_f32 v247, v247, v234, v235
	v_max3_f32 v246, v246, v236, v237
	v_max_f32_e32 v246, v246, v247
	v_mov_b32_e32 v247, v246
	v_add_f32_e32 v249, 0x41000000, v190
	s_waitcnt lgkmcnt(8)
	v_mfma_f32_32x32x16_bf16 v[80:95], v[214:217], v[250:253], v[80:95]
	ds_read_b64_tr_b16 v[214:215], v221 offset:8448
	ds_read_b64_tr_b16 v[216:217], v221 offset:12544
	s_nop 1
	v_permlane32_swap_b32_e32 v246, v247
	v_max_f32_e32 v246, v246, v247
	v_cmp_gt_f32_e32 vcc, v246, v249
	s_cbranch_vccnz .Latt_rs1_2s0
	s_waitcnt lgkmcnt(8)
	v_mfma_f32_32x32x16_bf16 v[64:79], v[238:241], v[250:253], v[64:79]
	ds_read_b64_tr_b16 v[238:239], v205 offset:16384
	ds_read_b64_tr_b16 v[240:241], v205 offset:20480
	v_sub_f32_e32 v222, v222, v190
	v_exp_f32_e32 v222, v222
	v_sub_f32_e32 v223, v223, v190
	v_exp_f32_e32 v223, v223
	v_sub_f32_e32 v224, v224, v190
	v_add_f32_e32 v254, 0, v222
	s_waitcnt lgkmcnt(8)
	v_mfma_f32_32x32x16_bf16 v[48:63], v[128:131], v[250:253], v[48:63]
	ds_read_b64_tr_b16 v[128:129], v218 offset:16384
	ds_read_b64_tr_b16 v[130:131], v218 offset:20480
	v_exp_f32_e32 v224, v224
	v_sub_f32_e32 v225, v225, v190
	v_add_f32_e32 v254, v223, v254
	v_exp_f32_e32 v225, v225
	v_sub_f32_e32 v226, v226, v190
	v_add_f32_e32 v254, v224, v254
	s_waitcnt lgkmcnt(8)
	v_mfma_f32_32x32x16_bf16 v[32:47], v[206:209], v[250:253], v[32:47]
	ds_read_b64_tr_b16 v[206:207], v219 offset:16384
	ds_read_b64_tr_b16 v[208:209], v219 offset:20480
	v_exp_f32_e32 v226, v226
	v_sub_f32_e32 v227, v227, v190
	v_add_f32_e32 v254, v225, v254
	v_exp_f32_e32 v227, v227
	v_sub_f32_e32 v228, v228, v190
	s_waitcnt lgkmcnt(8)
	v_mfma_f32_32x32x16_bf16 v[16:31], v[210:213], v[250:253], v[16:31]
	ds_read_b64_tr_b16 v[210:211], v221 offset:16384
	ds_read_b64_tr_b16 v[212:213], v221 offset:20480
	v_add_f32_e32 v254, v226, v254
	v_exp_f32_e32 v228, v228
	v_sub_f32_e32 v229, v229, v190
	v_add_f32_e32 v254, v227, v254
	v_exp_f32_e32 v229, v229
	s_waitcnt lgkmcnt(8)
	v_mfma_f32_32x32x16_bf16 v[0:15], v[214:217], v[250:253], v[0:15]
	ds_read_b64_tr_b16 v[214:215], v205 offset:16640
	ds_read_b64_tr_b16 v[216:217], v205 offset:20736
	s_nop 0
	v_cvt_pk_bf16_f32 v242, v222, v223
	v_cvt_pk_bf16_f32 v243, v224, v225
	v_cvt_pk_bf16_f32 v244, v226, v227
	v_cvt_pk_bf16_f32 v245, v228, v229
	s_nop 1
	s_waitcnt lgkmcnt(8)
	v_mfma_f32_32x32x16_bf16 v[112:127], v[238:241], v[242:245], v[112:127]
	ds_read_b64_tr_b16 v[238:239], v218 offset:16640
	ds_read_b64_tr_b16 v[240:241], v218 offset:20736
	v_sub_f32_e32 v230, v230, v190
	v_add_f32_e32 v254, v228, v254
	v_exp_f32_e32 v230, v230
	v_sub_f32_e32 v231, v231, v190
	v_add_f32_e32 v254, v229, v254
	s_waitcnt lgkmcnt(8)
	v_mfma_f32_32x32x16_bf16 v[96:111], v[128:131], v[242:245], v[96:111]
	ds_read_b64_tr_b16 v[128:129], v219 offset:16640
	ds_read_b64_tr_b16 v[130:131], v219 offset:20736
	v_exp_f32_e32 v231, v231
	v_sub_f32_e32 v232, v232, v190
	v_add_f32_e32 v254, v230, v254
	v_exp_f32_e32 v232, v232
	v_sub_f32_e32 v233, v233, v190
	s_cmp_lg_u64 s[12:13], 0
	s_cbranch_scc1 .Latt_nd0_2s0
	s_sub_i32 s100, s38, 1
	s_cmp_eq_u32 s38, 0
	s_cselect_b32 s100, 2, s100
	s_lshl_b32 s101, s100, 14
	s_add_i32 m0, s40, s101
	s_nop 0
	global_load_lds_dwordx4 v178, s[22:23]

.Latt_slow_2s0:
.Latt_slot1_2:
	ds_read_b128 v[206:209], v195 offset:16384
	ds_read_b128 v[210:213], v196 offset:16384
	ds_read_b128 v[214:217], v197 offset:16384
	ds_read_b128 v[238:241], v198 offset:16384
	ds_read_b128 v[242:245], v199 offset:16384
	ds_read_b128 v[250:253], v200 offset:16384
	ds_read_b128 v[222:225], v201 offset:16384
	ds_read_b128 v[226:229], v202 offset:16384
	v_add_u32_e32 v205, 0x8000, v205
	v_add_u32_e32 v218, 0x8000, v218
	v_add_u32_e32 v219, 0x8000, v219
	v_add_u32_e32 v221, 0x8000, v221
	s_waitcnt lgkmcnt(7)
	v_mfma_f32_32x32x16_bf16 v[128:143], v[206:209], v[144:147], 0
	ds_read_b128 v[206:209], v195 offset:24576
	s_waitcnt lgkmcnt(7)
	v_mfma_f32_32x32x16_bf16 v[128:143], v[210:213], v[148:151], v[128:143]
	ds_read_b128 v[210:213], v196 offset:24576
	s_waitcnt lgkmcnt(7)
	v_mfma_f32_32x32x16_bf16 v[128:143], v[214:217], v[152:155], v[128:143]
	ds_read_b128 v[214:217], v197 offset:24576
	s_waitcnt lgkmcnt(7)
	v_mfma_f32_32x32x16_bf16 v[128:143], v[238:241], v[156:159], v[128:143]
	ds_read_b128 v[238:241], v198 offset:24576
	s_waitcnt lgkmcnt(7)
	v_mfma_f32_32x32x16_bf16 v[128:143], v[242:245], v[160:163], v[128:143]
	s_waitcnt lgkmcnt(6)
	v_mfma_f32_32x32x16_bf16 v[128:143], v[250:253], v[164:167], v[128:143]
	s_waitcnt lgkmcnt(5)
	v_mfma_f32_32x32x16_bf16 v[128:143], v[222:225], v[168:171], v[128:143]
	s_waitcnt lgkmcnt(4)
	v_mfma_f32_32x32x16_bf16 v[128:143], v[226:229], v[172:175], v[128:143]
	s_waitcnt lgkmcnt(3)
	v_mfma_f32_32x32x16_bf16 v[222:237], v[206:209], v[144:147], 0
	ds_read_b128 v[206:209], v199 offset:24576
	s_nop 8
	v_max3_f32 v246, v128, v129, v130
	v_max3_f32 v247, v131, v132, v133
	v_max3_f32 v246, v246, v134, v135
	v_max3_f32 v247, v247, v136, v137
	v_max3_f32 v246, v246, v138, v139
	v_max3_f32 v247, v247, v140, v141
	v_max3_f32 v246, v246, v142, v143
	s_waitcnt lgkmcnt(3)
	v_mfma_f32_32x32x16_bf16 v[222:237], v[210:213], v[148:151], v[222:237]
	ds_read_b128 v[210:213], v200 offset:24576
	v_max_f32_e32 v246, v246, v247
	v_mov_b32_e32 v247, v246
	v_add_f32_e32 v249, 0x41000000, v190
	s_nop 1
	v_permlane32_swap_b32_e32 v246, v247
	v_max_f32_e32 v246, v246, v247
	v_cmp_gt_f32_e32 vcc, v246, v249
	s_cbranch_vccz .Latt_nr0_2s1
	v_max_f32_e32 v246, v190, v246
	v_sub_f32_e32 v190, v190, v246
	v_exp_f32_e32 v190, v190
	s_nop 0
	v_pk_mul_f32 v[126:127], v[126:127], v[190:191] op_sel_hi:[1,0]
	v_pk_mul_f32 v[124:125], v[124:125], v[190:191] op_sel_hi:[1,0]
	v_pk_mul_f32 v[122:123], v[122:123], v[190:191] op_sel_hi:[1,0]
	v_pk_mul_f32 v[120:121], v[120:121], v[190:191] op_sel_hi:[1,0]
	v_pk_mul_f32 v[118:119], v[118:119], v[190:191] op_sel_hi:[1,0]
	v_pk_mul_f32 v[116:117], v[116:117], v[190:191] op_sel_hi:[1,0]
	v_pk_mul_f32 v[114:115], v[114:115], v[190:191] op_sel_hi:[1,0]
	v_pk_mul_f32 v[112:113], v[112:113], v[190:191] op_sel_hi:[1,0]
	v_pk_mul_f32 v[110:111], v[110:111], v[190:191] op_sel_hi:[1,0]
	v_pk_mul_f32 v[108:109], v[108:109], v[190:191] op_sel_hi:[1,0]
	v_pk_mul_f32 v[106:107], v[106:107], v[190:191] op_sel_hi:[1,0]
	v_pk_mul_f32 v[104:105], v[104:105], v[190:191] op_sel_hi:[1,0]
	v_pk_mul_f32 v[102:103], v[102:103], v[190:191] op_sel_hi:[1,0]
	v_pk_mul_f32 v[100:101], v[100:101], v[190:191] op_sel_hi:[1,0]
	v_pk_mul_f32 v[98:99], v[98:99], v[190:191] op_sel_hi:[1,0]
	v_pk_mul_f32 v[96:97], v[96:97], v[190:191] op_sel_hi:[1,0]
	v_pk_mul_f32 v[94:95], v[94:95], v[190:191] op_sel_hi:[1,0]
	v_pk_mul_f32 v[92:93], v[92:93], v[190:191] op_sel_hi:[1,0]
	v_pk_mul_f32 v[90:91], v[90:91], v[190:191] op_sel_hi:[1,0]
	v_pk_mul_f32 v[88:89], v[88:89], v[190:191] op_sel_hi:[1,0]
	v_pk_mul_f32 v[86:87], v[86:87], v[190:191] op_sel_hi:[1,0]
	v_pk_mul_f32 v[84:85], v[84:85], v[190:191] op_sel_hi:[1,0]
	v_pk_mul_f32 v[82:83], v[82:83], v[190:191] op_sel_hi:[1,0]
	v_pk_mul_f32 v[80:81], v[80:81], v[190:191] op_sel_hi:[1,0]
	v_pk_mul_f32 v[78:79], v[78:79], v[190:191] op_sel_hi:[1,0]
	v_pk_mul_f32 v[76:77], v[76:77], v[190:191] op_sel_hi:[1,0]
	v_pk_mul_f32 v[74:75], v[74:75], v[190:191] op_sel_hi:[1,0]
	v_pk_mul_f32 v[72:73], v[72:73], v[190:191] op_sel_hi:[1,0]
	v_pk_mul_f32 v[70:71], v[70:71], v[190:191] op_sel_hi:[1,0]
	v_pk_mul_f32 v[68:69], v[68:69], v[190:191] op_sel_hi:[1,0]
	v_pk_mul_f32 v[66:67], v[66:67], v[190:191] op_sel_hi:[1,0]
	v_pk_mul_f32 v[64:65], v[64:65], v[190:191] op_sel_hi:[1,0]
	v_pk_mul_f32 v[62:63], v[62:63], v[190:191] op_sel_hi:[1,0]
	v_pk_mul_f32 v[60:61], v[60:61], v[190:191] op_sel_hi:[1,0]
	v_pk_mul_f32 v[58:59], v[58:59], v[190:191] op_sel_hi:[1,0]
	v_pk_mul_f32 v[56:57], v[56:57], v[190:191] op_sel_hi:[1,0]
	v_pk_mul_f32 v[54:55], v[54:55], v[190:191] op_sel_hi:[1,0]
	v_pk_mul_f32 v[52:53], v[52:53], v[190:191] op_sel_hi:[1,0]
	v_pk_mul_f32 v[50:51], v[50:51], v[190:191] op_sel_hi:[1,0]
	v_pk_mul_f32 v[48:49], v[48:49], v[190:191] op_sel_hi:[1,0]
	v_pk_mul_f32 v[46:47], v[46:47], v[190:191] op_sel_hi:[1,0]
	v_pk_mul_f32 v[44:45], v[44:45], v[190:191] op_sel_hi:[1,0]
	v_pk_mul_f32 v[42:43], v[42:43], v[190:191] op_sel_hi:[1,0]
	v_pk_mul_f32 v[40:41], v[40:41], v[190:191] op_sel_hi:[1,0]
	v_pk_mul_f32 v[38:39], v[38:39], v[190:191] op_sel_hi:[1,0]
	v_pk_mul_f32 v[36:37], v[36:37], v[190:191] op_sel_hi:[1,0]
	v_pk_mul_f32 v[34:35], v[34:35], v[190:191] op_sel_hi:[1,0]
	v_pk_mul_f32 v[32:33], v[32:33], v[190:191] op_sel_hi:[1,0]
	v_pk_mul_f32 v[30:31], v[30:31], v[190:191] op_sel_hi:[1,0]
	v_pk_mul_f32 v[28:29], v[28:29], v[190:191] op_sel_hi:[1,0]
	v_pk_mul_f32 v[26:27], v[26:27], v[190:191] op_sel_hi:[1,0]
	v_pk_mul_f32 v[24:25], v[24:25], v[190:191] op_sel_hi:[1,0]
	v_pk_mul_f32 v[22:23], v[22:23], v[190:191] op_sel_hi:[1,0]
	v_pk_mul_f32 v[20:21], v[20:21], v[190:191] op_sel_hi:[1,0]
	v_pk_mul_f32 v[18:19], v[18:19], v[190:191] op_sel_hi:[1,0]
	v_pk_mul_f32 v[16:17], v[16:17], v[190:191] op_sel_hi:[1,0]
	v_pk_mul_f32 v[14:15], v[14:15], v[190:191] op_sel_hi:[1,0]
	v_pk_mul_f32 v[12:13], v[12:13], v[190:191] op_sel_hi:[1,0]
	v_pk_mul_f32 v[10:11], v[10:11], v[190:191] op_sel_hi:[1,0]
	v_pk_mul_f32 v[8:9], v[8:9], v[190:191] op_sel_hi:[1,0]
	v_pk_mul_f32 v[6:7], v[6:7], v[190:191] op_sel_hi:[1,0]
	v_pk_mul_f32 v[4:5], v[4:5], v[190:191] op_sel_hi:[1,0]
	v_pk_mul_f32 v[2:3], v[2:3], v[190:191] op_sel_hi:[1,0]
	v_pk_mul_f32 v[0:1], v[0:1], v[190:191] op_sel_hi:[1,0]
	v_mul_f32_e32 v203, v203, v190
	v_mov_b32_e32 v190, v246
.Latt_nr0_2s1:
	s_waitcnt lgkmcnt(3)
	v_mfma_f32_32x32x16_bf16 v[222:237], v[214:217], v[152:155], v[222:237]
	ds_read_b128 v[214:217], v201 offset:24576
	v_sub_f32_e32 v128, v128, v190
	v_exp_f32_e32 v128, v128
	v_sub_f32_e32 v129, v129, v190
	v_exp_f32_e32 v129, v129
	v_sub_f32_e32 v130, v130, v190
	s_waitcnt lgkmcnt(3)
	v_mfma_f32_32x32x16_bf16 v[222:237], v[238:241], v[156:159], v[222:237]
	ds_read_b128 v[238:241], v202 offset:24576
	v_add_f32_e32 v254, 0, v128
	v_exp_f32_e32 v130, v130
	v_sub_f32_e32 v131, v131, v190
	v_add_f32_e32 v254, v129, v254
	v_exp_f32_e32 v131, v131
	s_waitcnt lgkmcnt(3)
	v_mfma_f32_32x32x16_bf16 v[222:237], v[206:209], v[160:163], v[222:237]
	ds_read_b64_tr_b16 v[206:207], v205
	ds_read_b64_tr_b16 v[208:209], v205 offset:4096
	v_sub_f32_e32 v132, v132, v190
	v_add_f32_e32 v254, v130, v254
	v_exp_f32_e32 v132, v132
	v_sub_f32_e32 v133, v133, v190
	v_add_f32_e32 v254, v131, v254
	s_waitcnt lgkmcnt(4)
	v_mfma_f32_32x32x16_bf16 v[222:237], v[210:213], v[164:167], v[222:237]
	ds_read_b64_tr_b16 v[210:211], v218
	ds_read_b64_tr_b16 v[212:213], v218 offset:4096
	v_exp_f32_e32 v133, v133
	v_sub_f32_e32 v134, v134, v190
	v_add_f32_e32 v254, v132, v254
	v_exp_f32_e32 v134, v134
	s_waitcnt lgkmcnt(5)
	v_mfma_f32_32x32x16_bf16 v[222:237], v[214:217], v[168:171], v[222:237]
	ds_read_b64_tr_b16 v[214:215], v219
	ds_read_b64_tr_b16 v[216:217], v219 offset:4096
	v_sub_f32_e32 v135, v135, v190
	v_add_f32_e32 v254, v133, v254
	v_exp_f32_e32 v135, v135
	s_nop 0
	s_waitcnt lgkmcnt(6)
	v_mfma_f32_32x32x16_bf16 v[222:237], v[238:241], v[172:175], v[222:237]
	ds_read_b64_tr_b16 v[238:239], v221
	ds_read_b64_tr_b16 v[240:241], v221 offset:4096
	v_cvt_pk_bf16_f32 v242, v128, v129
	v_cvt_pk_bf16_f32 v243, v130, v131
	v_cvt_pk_bf16_f32 v244, v132, v133
	v_cvt_pk_bf16_f32 v245, v134, v135
	s_nop 1
	s_waitcnt lgkmcnt(6)
	v_mfma_f32_32x32x16_bf16 v[112:127], v[206:209], v[242:245], v[112:127]
	ds_read_b64_tr_b16 v[206:207], v205 offset:256
	ds_read_b64_tr_b16 v[208:209], v205 offset:4352
	v_sub_f32_e32 v136, v136, v190
	v_add_f32_e32 v254, v134, v254
	v_exp_f32_e32 v136, v136
	v_sub_f32_e32 v137, v137, v190
	v_add_f32_e32 v254, v135, v254
	s_waitcnt lgkmcnt(6)
	v_mfma_f32_32x32x16_bf16 v[96:111], v[210:213], v[242:245], v[96:111]
	ds_read_b64_tr_b16 v[210:211], v218 offset:256
	ds_read_b64_tr_b16 v[212:213], v218 offset:4352
	v_exp_f32_e32 v137, v137
	v_sub_f32_e32 v138, v138, v190
	v_add_f32_e32 v254, v136, v254
	v_exp_f32_e32 v138, v138
	v_sub_f32_e32 v139, v139, v190
	s_waitcnt lgkmcnt(6)
	v_mfma_f32_32x32x16_bf16 v[80:95], v[214:217], v[242:245], v[80:95]
	ds_read_b64_tr_b16 v[214:215], v219 offset:256
	ds_read_b64_tr_b16 v[216:217], v219 offset:4352
	v_add_f32_e32 v254, v137, v254
	v_exp_f32_e32 v139, v139
	v_sub_f32_e32 v140, v140, v190
	v_add_f32_e32 v254, v138, v254
	s_waitcnt lgkmcnt(6)
	v_mfma_f32_32x32x16_bf16 v[64:79], v[238:241], v[242:245], v[64:79]
	ds_read_b64_tr_b16 v[238:239], v221 offset:256
	ds_read_b64_tr_b16 v[240:241], v221 offset:4352
	v_exp_f32_e32 v140, v140
	v_sub_f32_e32 v141, v141, v190
	v_add_f32_e32 v254, v139, v254
	v_exp_f32_e32 v141, v141
	s_waitcnt lgkmcnt(6)
	v_mfma_f32_32x32x16_bf16 v[48:63], v[206:209], v[242:245], v[48:63]
	ds_read_b64_tr_b16 v[206:207], v205 offset:8192
	ds_read_b64_tr_b16 v[208:209], v205 offset:12288
	v_sub_f32_e32 v142, v142, v190
	v_add_f32_e32 v254, v140, v254
	v_exp_f32_e32 v142, v142
	v_sub_f32_e32 v143, v143, v190
	s_waitcnt lgkmcnt(6)
	v_mfma_f32_32x32x16_bf16 v[32:47], v[210:213], v[242:245], v[32:47]
	ds_read_b64_tr_b16 v[210:211], v218 offset:8192
	ds_read_b64_tr_b16 v[212:213], v218 offset:12288
	v_add_f32_e32 v254, v141, v254
	v_exp_f32_e32 v143, v143
	v_add_f32_e32 v254, v142, v254
	v_add_f32_e32 v254, v143, v254
	s_waitcnt lgkmcnt(6)
	v_mfma_f32_32x32x16_bf16 v[16:31], v[214:217], v[242:245], v[16:31]
	ds_read_b64_tr_b16 v[214:215], v219 offset:8192
	ds_read_b64_tr_b16 v[216:217], v219 offset:12288
	v_cvt_pk_bf16_f32 v250, v136, v137
	v_cvt_pk_bf16_f32 v251, v138, v139
	v_cvt_pk_bf16_f32 v252, v140, v141
	v_cvt_pk_bf16_f32 v253, v142, v143
	v_add_f32_e32 v203, v203, v254
	s_waitcnt lgkmcnt(6)
	v_mfma_f32_32x32x16_bf16 v[0:15], v[238:241], v[242:245], v[0:15]
	ds_read_b64_tr_b16 v[238:239], v221 offset:8192
	ds_read_b64_tr_b16 v[240:241], v221 offset:12288
	ds_read_b64_tr_b16 v[128:129], v205 offset:8448
	ds_read_b64_tr_b16 v[130:131], v205 offset:12544
	s_waitcnt lgkmcnt(8)
	v_mfma_f32_32x32x16_bf16 v[112:127], v[206:209], v[250:253], v[112:127]
	ds_read_b64_tr_b16 v[206:207], v218 offset:8448
	ds_read_b64_tr_b16 v[208:209], v218 offset:12544
	v_max3_f32 v246, v222, v223, v224
	v_max3_f32 v247, v225, v226, v227
	v_max3_f32 v246, v246, v228, v229
	v_max3_f32 v247, v247, v230, v231
	v_max3_f32 v246, v246, v232, v233
	s_waitcnt lgkmcnt(8)
	v_mfma_f32_32x32x16_bf16 v[96:111], v[210:213], v[250:253], v[96:111]
	ds_read_b64_tr_b16 v[210:211], v219 offset:8448
	ds_read_b64_tr_b16 v[212:213], v219 offset:12544
	v_max3_f32 v247, v247, v234, v235
	v_max3_f32 v246, v246, v236, v237
	v_max_f32_e32 v246, v246, v247
	v_mov_b32_e32 v247, v246
	v_add_f32_e32 v249, 0x41000000, v190
	s_waitcnt lgkmcnt(8)
	v_mfma_f32_32x32x16_bf16 v[80:95], v[214:217], v[250:253], v[80:95]
	ds_read_b64_tr_b16 v[214:215], v221 offset:8448
	ds_read_b64_tr_b16 v[216:217], v221 offset:12544
	s_nop 1
	v_permlane32_swap_b32_e32 v246, v247
	v_max_f32_e32 v246, v246, v247
	v_cmp_gt_f32_e32 vcc, v246, v249
	s_cbranch_vccnz .Latt_rs1_2s1
	s_waitcnt lgkmcnt(8)
	v_mfma_f32_32x32x16_bf16 v[64:79], v[238:241], v[250:253], v[64:79]
	ds_read_b64_tr_b16 v[238:239], v205 offset:16384
	ds_read_b64_tr_b16 v[240:241], v205 offset:20480
	v_sub_f32_e32 v222, v222, v190
	v_exp_f32_e32 v222, v222
	v_sub_f32_e32 v223, v223, v190
	v_exp_f32_e32 v223, v223
	v_sub_f32_e32 v224, v224, v190
	v_add_f32_e32 v254, 0, v222
	s_waitcnt lgkmcnt(8)
	v_mfma_f32_32x32x16_bf16 v[48:63], v[128:131], v[250:253], v[48:63]
	ds_read_b64_tr_b16 v[128:129], v218 offset:16384
	ds_read_b64_tr_b16 v[130:131], v218 offset:20480
	v_exp_f32_e32 v224, v224
	v_sub_f32_e32 v225, v225, v190
	v_add_f32_e32 v254, v223, v254
	v_exp_f32_e32 v225, v225
	v_sub_f32_e32 v226, v226, v190
	v_add_f32_e32 v254, v224, v254
	s_waitcnt lgkmcnt(8)
	v_mfma_f32_32x32x16_bf16 v[32:47], v[206:209], v[250:253], v[32:47]
	ds_read_b64_tr_b16 v[206:207], v219 offset:16384
	ds_read_b64_tr_b16 v[208:209], v219 offset:20480
	v_exp_f32_e32 v226, v226
	v_sub_f32_e32 v227, v227, v190
	v_add_f32_e32 v254, v225, v254
	v_exp_f32_e32 v227, v227
	v_sub_f32_e32 v228, v228, v190
	s_waitcnt lgkmcnt(8)
	v_mfma_f32_32x32x16_bf16 v[16:31], v[210:213], v[250:253], v[16:31]
	ds_read_b64_tr_b16 v[210:211], v221 offset:16384
	ds_read_b64_tr_b16 v[212:213], v221 offset:20480
	v_add_f32_e32 v254, v226, v254
	v_exp_f32_e32 v228, v228
	v_sub_f32_e32 v229, v229, v190
	v_add_f32_e32 v254, v227, v254
	v_exp_f32_e32 v229, v229
	s_waitcnt lgkmcnt(8)
	v_mfma_f32_32x32x16_bf16 v[0:15], v[214:217], v[250:253], v[0:15]
	ds_read_b64_tr_b16 v[214:215], v205 offset:16640
	ds_read_b64_tr_b16 v[216:217], v205 offset:20736
	s_nop 0
	v_cvt_pk_bf16_f32 v242, v222, v223
	v_cvt_pk_bf16_f32 v243, v224, v225
	v_cvt_pk_bf16_f32 v244, v226, v227
	v_cvt_pk_bf16_f32 v245, v228, v229
	s_nop 1
	s_waitcnt lgkmcnt(8)
	v_mfma_f32_32x32x16_bf16 v[112:127], v[238:241], v[242:245], v[112:127]
	ds_read_b64_tr_b16 v[238:239], v218 offset:16640
	ds_read_b64_tr_b16 v[240:241], v218 offset:20736
	v_sub_f32_e32 v230, v230, v190
	v_add_f32_e32 v254, v228, v254
	v_exp_f32_e32 v230, v230
	v_sub_f32_e32 v231, v231, v190
	v_add_f32_e32 v254, v229, v254
	s_waitcnt lgkmcnt(8)
	v_mfma_f32_32x32x16_bf16 v[96:111], v[128:131], v[242:245], v[96:111]
	ds_read_b64_tr_b16 v[128:129], v219 offset:16640
	ds_read_b64_tr_b16 v[130:131], v219 offset:20736
	v_exp_f32_e32 v231, v231
	v_sub_f32_e32 v232, v232, v190
	v_add_f32_e32 v254, v230, v254
	v_exp_f32_e32 v232, v232
	v_sub_f32_e32 v233, v233, v190
	s_cmp_lg_u64 s[12:13], 0
	s_cbranch_scc1 .Latt_nd0_2s1
	s_sub_i32 s100, s38, 1
	s_cmp_eq_u32 s38, 0
	s_cselect_b32 s100, 2, s100
	s_lshl_b32 s101, s100, 14
	s_add_i32 m0, s40, s101
	s_nop 0
	global_load_lds_dwordx4 v178, s[22:23]

.Latt_slow_2s1:
.Latt_slot2_2:
	ds_read_b128 v[206:209], v195 offset:32768
	ds_read_b128 v[210:213], v196 offset:32768
	ds_read_b128 v[214:217], v197 offset:32768
	ds_read_b128 v[238:241], v198 offset:32768
	ds_read_b128 v[242:245], v199 offset:32768
	ds_read_b128 v[250:253], v200 offset:32768
	ds_read_b128 v[222:225], v201 offset:32768
	ds_read_b128 v[226:229], v202 offset:32768
	v_add_u32_e32 v205, 0x8000, v205
	v_add_u32_e32 v218, 0x8000, v218
	v_add_u32_e32 v219, 0x8000, v219
	v_add_u32_e32 v221, 0x8000, v221
	s_waitcnt lgkmcnt(7)
	v_mfma_f32_32x32x16_bf16 v[128:143], v[206:209], v[144:147], 0
	ds_read_b128 v[206:209], v195 offset:40960
	s_waitcnt lgkmcnt(7)
	v_mfma_f32_32x32x16_bf16 v[128:143], v[210:213], v[148:151], v[128:143]
	ds_read_b128 v[210:213], v196 offset:40960
	s_waitcnt lgkmcnt(7)
	v_mfma_f32_32x32x16_bf16 v[128:143], v[214:217], v[152:155], v[128:143]
	ds_read_b128 v[214:217], v197 offset:40960
	s_waitcnt lgkmcnt(7)
	v_mfma_f32_32x32x16_bf16 v[128:143], v[238:241], v[156:159], v[128:143]
	ds_read_b128 v[238:241], v198 offset:40960
	s_waitcnt lgkmcnt(7)
	v_mfma_f32_32x32x16_bf16 v[128:143], v[242:245], v[160:163], v[128:143]
	s_waitcnt lgkmcnt(6)
	v_mfma_f32_32x32x16_bf16 v[128:143], v[250:253], v[164:167], v[128:143]
	s_waitcnt lgkmcnt(5)
	v_mfma_f32_32x32x16_bf16 v[128:143], v[222:225], v[168:171], v[128:143]
	s_waitcnt lgkmcnt(4)
	v_mfma_f32_32x32x16_bf16 v[128:143], v[226:229], v[172:175], v[128:143]
	s_waitcnt lgkmcnt(3)
	v_mfma_f32_32x32x16_bf16 v[222:237], v[206:209], v[144:147], 0
	ds_read_b128 v[206:209], v199 offset:40960
	s_nop 8
	v_max3_f32 v246, v128, v129, v130
	v_max3_f32 v247, v131, v132, v133
	v_max3_f32 v246, v246, v134, v135
	v_max3_f32 v247, v247, v136, v137
	v_max3_f32 v246, v246, v138, v139
	v_max3_f32 v247, v247, v140, v141
	v_max3_f32 v246, v246, v142, v143
	s_waitcnt lgkmcnt(3)
	v_mfma_f32_32x32x16_bf16 v[222:237], v[210:213], v[148:151], v[222:237]
	ds_read_b128 v[210:213], v200 offset:40960
	v_max_f32_e32 v246, v246, v247
	v_mov_b32_e32 v247, v246
	v_add_f32_e32 v249, 0x41000000, v190
	s_nop 1
	v_permlane32_swap_b32_e32 v246, v247
	v_max_f32_e32 v246, v246, v247
	v_cmp_gt_f32_e32 vcc, v246, v249
	s_cbranch_vccz .Latt_nr0_2s2
	v_max_f32_e32 v246, v190, v246
	v_sub_f32_e32 v190, v190, v246
	v_exp_f32_e32 v190, v190
	s_nop 0
	v_pk_mul_f32 v[126:127], v[126:127], v[190:191] op_sel_hi:[1,0]
	v_pk_mul_f32 v[124:125], v[124:125], v[190:191] op_sel_hi:[1,0]
	v_pk_mul_f32 v[122:123], v[122:123], v[190:191] op_sel_hi:[1,0]
	v_pk_mul_f32 v[120:121], v[120:121], v[190:191] op_sel_hi:[1,0]
	v_pk_mul_f32 v[118:119], v[118:119], v[190:191] op_sel_hi:[1,0]
	v_pk_mul_f32 v[116:117], v[116:117], v[190:191] op_sel_hi:[1,0]
	v_pk_mul_f32 v[114:115], v[114:115], v[190:191] op_sel_hi:[1,0]
	v_pk_mul_f32 v[112:113], v[112:113], v[190:191] op_sel_hi:[1,0]
	v_pk_mul_f32 v[110:111], v[110:111], v[190:191] op_sel_hi:[1,0]
	v_pk_mul_f32 v[108:109], v[108:109], v[190:191] op_sel_hi:[1,0]
	v_pk_mul_f32 v[106:107], v[106:107], v[190:191] op_sel_hi:[1,0]
	v_pk_mul_f32 v[104:105], v[104:105], v[190:191] op_sel_hi:[1,0]
	v_pk_mul_f32 v[102:103], v[102:103], v[190:191] op_sel_hi:[1,0]
	v_pk_mul_f32 v[100:101], v[100:101], v[190:191] op_sel_hi:[1,0]
	v_pk_mul_f32 v[98:99], v[98:99], v[190:191] op_sel_hi:[1,0]
	v_pk_mul_f32 v[96:97], v[96:97], v[190:191] op_sel_hi:[1,0]
	v_pk_mul_f32 v[94:95], v[94:95], v[190:191] op_sel_hi:[1,0]
	v_pk_mul_f32 v[92:93], v[92:93], v[190:191] op_sel_hi:[1,0]
	v_pk_mul_f32 v[90:91], v[90:91], v[190:191] op_sel_hi:[1,0]
	v_pk_mul_f32 v[88:89], v[88:89], v[190:191] op_sel_hi:[1,0]
	v_pk_mul_f32 v[86:87], v[86:87], v[190:191] op_sel_hi:[1,0]
	v_pk_mul_f32 v[84:85], v[84:85], v[190:191] op_sel_hi:[1,0]
	v_pk_mul_f32 v[82:83], v[82:83], v[190:191] op_sel_hi:[1,0]
	v_pk_mul_f32 v[80:81], v[80:81], v[190:191] op_sel_hi:[1,0]
	v_pk_mul_f32 v[78:79], v[78:79], v[190:191] op_sel_hi:[1,0]
	v_pk_mul_f32 v[76:77], v[76:77], v[190:191] op_sel_hi:[1,0]
	v_pk_mul_f32 v[74:75], v[74:75], v[190:191] op_sel_hi:[1,0]
	v_pk_mul_f32 v[72:73], v[72:73], v[190:191] op_sel_hi:[1,0]
	v_pk_mul_f32 v[70:71], v[70:71], v[190:191] op_sel_hi:[1,0]
	v_pk_mul_f32 v[68:69], v[68:69], v[190:191] op_sel_hi:[1,0]
	v_pk_mul_f32 v[66:67], v[66:67], v[190:191] op_sel_hi:[1,0]
	v_pk_mul_f32 v[64:65], v[64:65], v[190:191] op_sel_hi:[1,0]
	v_pk_mul_f32 v[62:63], v[62:63], v[190:191] op_sel_hi:[1,0]
	v_pk_mul_f32 v[60:61], v[60:61], v[190:191] op_sel_hi:[1,0]
	v_pk_mul_f32 v[58:59], v[58:59], v[190:191] op_sel_hi:[1,0]
	v_pk_mul_f32 v[56:57], v[56:57], v[190:191] op_sel_hi:[1,0]
	v_pk_mul_f32 v[54:55], v[54:55], v[190:191] op_sel_hi:[1,0]
	v_pk_mul_f32 v[52:53], v[52:53], v[190:191] op_sel_hi:[1,0]
	v_pk_mul_f32 v[50:51], v[50:51], v[190:191] op_sel_hi:[1,0]
	v_pk_mul_f32 v[48:49], v[48:49], v[190:191] op_sel_hi:[1,0]
	v_pk_mul_f32 v[46:47], v[46:47], v[190:191] op_sel_hi:[1,0]
	v_pk_mul_f32 v[44:45], v[44:45], v[190:191] op_sel_hi:[1,0]
	v_pk_mul_f32 v[42:43], v[42:43], v[190:191] op_sel_hi:[1,0]
	v_pk_mul_f32 v[40:41], v[40:41], v[190:191] op_sel_hi:[1,0]
	v_pk_mul_f32 v[38:39], v[38:39], v[190:191] op_sel_hi:[1,0]
	v_pk_mul_f32 v[36:37], v[36:37], v[190:191] op_sel_hi:[1,0]
	v_pk_mul_f32 v[34:35], v[34:35], v[190:191] op_sel_hi:[1,0]
	v_pk_mul_f32 v[32:33], v[32:33], v[190:191] op_sel_hi:[1,0]
	v_pk_mul_f32 v[30:31], v[30:31], v[190:191] op_sel_hi:[1,0]
	v_pk_mul_f32 v[28:29], v[28:29], v[190:191] op_sel_hi:[1,0]
	v_pk_mul_f32 v[26:27], v[26:27], v[190:191] op_sel_hi:[1,0]
	v_pk_mul_f32 v[24:25], v[24:25], v[190:191] op_sel_hi:[1,0]
	v_pk_mul_f32 v[22:23], v[22:23], v[190:191] op_sel_hi:[1,0]
	v_pk_mul_f32 v[20:21], v[20:21], v[190:191] op_sel_hi:[1,0]
	v_pk_mul_f32 v[18:19], v[18:19], v[190:191] op_sel_hi:[1,0]
	v_pk_mul_f32 v[16:17], v[16:17], v[190:191] op_sel_hi:[1,0]
	v_pk_mul_f32 v[14:15], v[14:15], v[190:191] op_sel_hi:[1,0]
	v_pk_mul_f32 v[12:13], v[12:13], v[190:191] op_sel_hi:[1,0]
	v_pk_mul_f32 v[10:11], v[10:11], v[190:191] op_sel_hi:[1,0]
	v_pk_mul_f32 v[8:9], v[8:9], v[190:191] op_sel_hi:[1,0]
	v_pk_mul_f32 v[6:7], v[6:7], v[190:191] op_sel_hi:[1,0]
	v_pk_mul_f32 v[4:5], v[4:5], v[190:191] op_sel_hi:[1,0]
	v_pk_mul_f32 v[2:3], v[2:3], v[190:191] op_sel_hi:[1,0]
	v_pk_mul_f32 v[0:1], v[0:1], v[190:191] op_sel_hi:[1,0]
	v_mul_f32_e32 v203, v203, v190
	v_mov_b32_e32 v190, v246
.Latt_nr0_2s2:
	s_waitcnt lgkmcnt(3)
	v_mfma_f32_32x32x16_bf16 v[222:237], v[214:217], v[152:155], v[222:237]
	ds_read_b128 v[214:217], v201 offset:40960
	v_sub_f32_e32 v128, v128, v190
	v_exp_f32_e32 v128, v128
	v_sub_f32_e32 v129, v129, v190
	v_exp_f32_e32 v129, v129
	v_sub_f32_e32 v130, v130, v190
	s_waitcnt lgkmcnt(3)
	v_mfma_f32_32x32x16_bf16 v[222:237], v[238:241], v[156:159], v[222:237]
	ds_read_b128 v[238:241], v202 offset:40960
	v_add_f32_e32 v254, 0, v128
	v_exp_f32_e32 v130, v130
	v_sub_f32_e32 v131, v131, v190
	v_add_f32_e32 v254, v129, v254
	v_exp_f32_e32 v131, v131
	s_waitcnt lgkmcnt(3)
	v_mfma_f32_32x32x16_bf16 v[222:237], v[206:209], v[160:163], v[222:237]
	ds_read_b64_tr_b16 v[206:207], v205
	ds_read_b64_tr_b16 v[208:209], v205 offset:4096
	v_sub_f32_e32 v132, v132, v190
	v_add_f32_e32 v254, v130, v254
	v_exp_f32_e32 v132, v132
	v_sub_f32_e32 v133, v133, v190
	v_add_f32_e32 v254, v131, v254
	s_waitcnt lgkmcnt(4)
	v_mfma_f32_32x32x16_bf16 v[222:237], v[210:213], v[164:167], v[222:237]
	ds_read_b64_tr_b16 v[210:211], v218
	ds_read_b64_tr_b16 v[212:213], v218 offset:4096
	v_exp_f32_e32 v133, v133
	v_sub_f32_e32 v134, v134, v190
	v_add_f32_e32 v254, v132, v254
	v_exp_f32_e32 v134, v134
	s_waitcnt lgkmcnt(5)
	v_mfma_f32_32x32x16_bf16 v[222:237], v[214:217], v[168:171], v[222:237]
	ds_read_b64_tr_b16 v[214:215], v219
	ds_read_b64_tr_b16 v[216:217], v219 offset:4096
	v_sub_f32_e32 v135, v135, v190
	v_add_f32_e32 v254, v133, v254
	v_exp_f32_e32 v135, v135
	s_nop 0
	s_waitcnt lgkmcnt(6)
	v_mfma_f32_32x32x16_bf16 v[222:237], v[238:241], v[172:175], v[222:237]
	ds_read_b64_tr_b16 v[238:239], v221
	ds_read_b64_tr_b16 v[240:241], v221 offset:4096
	v_cvt_pk_bf16_f32 v242, v128, v129
	v_cvt_pk_bf16_f32 v243, v130, v131
	v_cvt_pk_bf16_f32 v244, v132, v133
	v_cvt_pk_bf16_f32 v245, v134, v135
	s_nop 1
	s_waitcnt lgkmcnt(6)
	v_mfma_f32_32x32x16_bf16 v[112:127], v[206:209], v[242:245], v[112:127]
	ds_read_b64_tr_b16 v[206:207], v205 offset:256
	ds_read_b64_tr_b16 v[208:209], v205 offset:4352
	v_sub_f32_e32 v136, v136, v190
	v_add_f32_e32 v254, v134, v254
	v_exp_f32_e32 v136, v136
	v_sub_f32_e32 v137, v137, v190
	v_add_f32_e32 v254, v135, v254
	s_waitcnt lgkmcnt(6)
	v_mfma_f32_32x32x16_bf16 v[96:111], v[210:213], v[242:245], v[96:111]
	ds_read_b64_tr_b16 v[210:211], v218 offset:256
	ds_read_b64_tr_b16 v[212:213], v218 offset:4352
	v_exp_f32_e32 v137, v137
	v_sub_f32_e32 v138, v138, v190
	v_add_f32_e32 v254, v136, v254
	v_exp_f32_e32 v138, v138
	v_sub_f32_e32 v139, v139, v190
	s_waitcnt lgkmcnt(6)
	v_mfma_f32_32x32x16_bf16 v[80:95], v[214:217], v[242:245], v[80:95]
	ds_read_b64_tr_b16 v[214:215], v219 offset:256
	ds_read_b64_tr_b16 v[216:217], v219 offset:4352
	v_add_f32_e32 v254, v137, v254
	v_exp_f32_e32 v139, v139
	v_sub_f32_e32 v140, v140, v190
	v_add_f32_e32 v254, v138, v254
	s_waitcnt lgkmcnt(6)
	v_mfma_f32_32x32x16_bf16 v[64:79], v[238:241], v[242:245], v[64:79]
	ds_read_b64_tr_b16 v[238:239], v221 offset:256
	ds_read_b64_tr_b16 v[240:241], v221 offset:4352
	v_exp_f32_e32 v140, v140
	v_sub_f32_e32 v141, v141, v190
	v_add_f32_e32 v254, v139, v254
	v_exp_f32_e32 v141, v141
	s_waitcnt lgkmcnt(6)
	v_mfma_f32_32x32x16_bf16 v[48:63], v[206:209], v[242:245], v[48:63]
	ds_read_b64_tr_b16 v[206:207], v205 offset:8192
	ds_read_b64_tr_b16 v[208:209], v205 offset:12288
	v_sub_f32_e32 v142, v142, v190
	v_add_f32_e32 v254, v140, v254
	v_exp_f32_e32 v142, v142
	v_sub_f32_e32 v143, v143, v190
	s_waitcnt lgkmcnt(6)
	v_mfma_f32_32x32x16_bf16 v[32:47], v[210:213], v[242:245], v[32:47]
	ds_read_b64_tr_b16 v[210:211], v218 offset:8192
	ds_read_b64_tr_b16 v[212:213], v218 offset:12288
	v_add_f32_e32 v254, v141, v254
	v_exp_f32_e32 v143, v143
	v_add_f32_e32 v254, v142, v254
	v_add_f32_e32 v254, v143, v254
	s_waitcnt lgkmcnt(6)
	v_mfma_f32_32x32x16_bf16 v[16:31], v[214:217], v[242:245], v[16:31]
	ds_read_b64_tr_b16 v[214:215], v219 offset:8192
	ds_read_b64_tr_b16 v[216:217], v219 offset:12288
	v_cvt_pk_bf16_f32 v250, v136, v137
	v_cvt_pk_bf16_f32 v251, v138, v139
	v_cvt_pk_bf16_f32 v252, v140, v141
	v_cvt_pk_bf16_f32 v253, v142, v143
	v_add_f32_e32 v203, v203, v254
	s_waitcnt lgkmcnt(6)
	v_mfma_f32_32x32x16_bf16 v[0:15], v[238:241], v[242:245], v[0:15]
	ds_read_b64_tr_b16 v[238:239], v221 offset:8192
	ds_read_b64_tr_b16 v[240:241], v221 offset:12288
	ds_read_b64_tr_b16 v[128:129], v205 offset:8448
	ds_read_b64_tr_b16 v[130:131], v205 offset:12544
	s_waitcnt lgkmcnt(8)
	v_mfma_f32_32x32x16_bf16 v[112:127], v[206:209], v[250:253], v[112:127]
	ds_read_b64_tr_b16 v[206:207], v218 offset:8448
	ds_read_b64_tr_b16 v[208:209], v218 offset:12544
	v_max3_f32 v246, v222, v223, v224
	v_max3_f32 v247, v225, v226, v227
	v_max3_f32 v246, v246, v228, v229
	v_max3_f32 v247, v247, v230, v231
	v_max3_f32 v246, v246, v232, v233
	s_waitcnt lgkmcnt(8)
	v_mfma_f32_32x32x16_bf16 v[96:111], v[210:213], v[250:253], v[96:111]
	ds_read_b64_tr_b16 v[210:211], v219 offset:8448
	ds_read_b64_tr_b16 v[212:213], v219 offset:12544
	v_max3_f32 v247, v247, v234, v235
	v_max3_f32 v246, v246, v236, v237
	v_max_f32_e32 v246, v246, v247
	v_mov_b32_e32 v247, v246
	v_add_f32_e32 v249, 0x41000000, v190
	s_waitcnt lgkmcnt(8)
	v_mfma_f32_32x32x16_bf16 v[80:95], v[214:217], v[250:253], v[80:95]
	ds_read_b64_tr_b16 v[214:215], v221 offset:8448
	ds_read_b64_tr_b16 v[216:217], v221 offset:12544
	s_nop 1
	v_permlane32_swap_b32_e32 v246, v247
	v_max_f32_e32 v246, v246, v247
	v_cmp_gt_f32_e32 vcc, v246, v249
	s_cbranch_vccnz .Latt_rs1_2s2
	s_waitcnt lgkmcnt(8)
	v_mfma_f32_32x32x16_bf16 v[64:79], v[238:241], v[250:253], v[64:79]
	ds_read_b64_tr_b16 v[238:239], v205 offset:16384
	ds_read_b64_tr_b16 v[240:241], v205 offset:20480
	v_sub_f32_e32 v222, v222, v190
	v_exp_f32_e32 v222, v222
	v_sub_f32_e32 v223, v223, v190
	v_exp_f32_e32 v223, v223
	v_sub_f32_e32 v224, v224, v190
	v_add_f32_e32 v254, 0, v222
	s_waitcnt lgkmcnt(8)
	v_mfma_f32_32x32x16_bf16 v[48:63], v[128:131], v[250:253], v[48:63]
	ds_read_b64_tr_b16 v[128:129], v218 offset:16384
	ds_read_b64_tr_b16 v[130:131], v218 offset:20480
	v_exp_f32_e32 v224, v224
	v_sub_f32_e32 v225, v225, v190
	v_add_f32_e32 v254, v223, v254
	v_exp_f32_e32 v225, v225
	v_sub_f32_e32 v226, v226, v190
	v_add_f32_e32 v254, v224, v254
	s_waitcnt lgkmcnt(8)
	v_mfma_f32_32x32x16_bf16 v[32:47], v[206:209], v[250:253], v[32:47]
	ds_read_b64_tr_b16 v[206:207], v219 offset:16384
	ds_read_b64_tr_b16 v[208:209], v219 offset:20480
	v_exp_f32_e32 v226, v226
	v_sub_f32_e32 v227, v227, v190
	v_add_f32_e32 v254, v225, v254
	v_exp_f32_e32 v227, v227
	v_sub_f32_e32 v228, v228, v190
	s_waitcnt lgkmcnt(8)
	v_mfma_f32_32x32x16_bf16 v[16:31], v[210:213], v[250:253], v[16:31]
	ds_read_b64_tr_b16 v[210:211], v221 offset:16384
	ds_read_b64_tr_b16 v[212:213], v221 offset:20480
	v_add_f32_e32 v254, v226, v254
	v_exp_f32_e32 v228, v228
	v_sub_f32_e32 v229, v229, v190
	v_add_f32_e32 v254, v227, v254
	v_exp_f32_e32 v229, v229
	s_waitcnt lgkmcnt(8)
	v_mfma_f32_32x32x16_bf16 v[0:15], v[214:217], v[250:253], v[0:15]
	ds_read_b64_tr_b16 v[214:215], v205 offset:16640
	ds_read_b64_tr_b16 v[216:217], v205 offset:20736
	s_nop 0
	v_cvt_pk_bf16_f32 v242, v222, v223
	v_cvt_pk_bf16_f32 v243, v224, v225
	v_cvt_pk_bf16_f32 v244, v226, v227
	v_cvt_pk_bf16_f32 v245, v228, v229
	s_nop 1
	s_waitcnt lgkmcnt(8)
	v_mfma_f32_32x32x16_bf16 v[112:127], v[238:241], v[242:245], v[112:127]
	ds_read_b64_tr_b16 v[238:239], v218 offset:16640
	ds_read_b64_tr_b16 v[240:241], v218 offset:20736
	v_sub_f32_e32 v230, v230, v190
	v_add_f32_e32 v254, v228, v254
	v_exp_f32_e32 v230, v230
	v_sub_f32_e32 v231, v231, v190
	v_add_f32_e32 v254, v229, v254
	s_waitcnt lgkmcnt(8)
	v_mfma_f32_32x32x16_bf16 v[96:111], v[128:131], v[242:245], v[96:111]
	ds_read_b64_tr_b16 v[128:129], v219 offset:16640
	ds_read_b64_tr_b16 v[130:131], v219 offset:20736
	v_exp_f32_e32 v231, v231
	v_sub_f32_e32 v232, v232, v190
	v_add_f32_e32 v254, v230, v254
	v_exp_f32_e32 v232, v232
	v_sub_f32_e32 v233, v233, v190
	s_cmp_lg_u64 s[12:13], 0
	s_cbranch_scc1 .Latt_nd0_2s2
	s_sub_i32 s100, s38, 1
	s_cmp_eq_u32 s38, 0
	s_cselect_b32 s100, 2, s100
	s_lshl_b32 s101, s100, 14
	s_add_i32 m0, s40, s101
	s_nop 0
	global_load_lds_dwordx4 v178, s[22:23]

.Latt_slow_2s2:
.Latt_slow_2:
	s_lshl_b32 s14, s38, 14
	s_add_i32 s15, s14, 0
	v_add_u32_e32 v207, s15, v195
	ds_read_b128 v[128:131], v207
	v_add_u32_e32 v208, s15, v196
	ds_read_b128 v[210:213], v208
	v_add_u32_e32 v209, s15, v197
	v_lshrrev_b32_e32 v205, 3, v204
	s_add_i32 s39, s84, 31
	v_and_or_b32 v206, v204, 31, s80
	s_cmp_le_i32 s39, s80
	s_waitcnt lgkmcnt(1)
	v_mfma_f32_32x32x16_bf16 v[128:143], v[128:131], v[144:147], 0
	s_waitcnt lgkmcnt(0)
	v_mfma_f32_32x32x16_bf16 v[128:143], v[210:213], v[148:151], v[128:143]
	ds_read_b128 v[212:215], v209
	v_add_u32_e32 v210, s15, v198
	ds_read_b128 v[216:219], v210
	v_add_u32_e32 v211, s15, v199
	s_waitcnt lgkmcnt(1)
	v_mfma_f32_32x32x16_bf16 v[128:143], v[212:215], v[152:155], v[128:143]
	v_add_u32_e32 v213, s15, v200
	v_and_b32_e32 v212, 4, v205
	ds_read_b128 v[222:225], v213
	s_waitcnt lgkmcnt(1)
	v_mfma_f32_32x32x16_bf16 v[128:143], v[216:219], v[156:159], v[128:143]
	ds_read_b128 v[214:217], v211
	s_waitcnt lgkmcnt(0)
	v_mfma_f32_32x32x16_bf16 v[128:143], v[214:217], v[160:163], v[128:143]
	v_add_u32_e32 v214, s15, v201
	ds_read_b128 v[216:219], v214
	v_add_u32_e32 v215, s15, v202
	v_mfma_f32_32x32x16_bf16 v[128:143], v[222:225], v[164:167], v[128:143]
	ds_read_b128 v[222:225], v215
	s_waitcnt lgkmcnt(1)
	v_mfma_f32_32x32x16_bf16 v[128:143], v[216:219], v[168:171], v[128:143]
	s_waitcnt lgkmcnt(0)
	v_mfma_f32_32x32x16_bf16 v[128:143], v[222:225], v[172:175], v[128:143]
	s_cbranch_scc1 .LBB0_888
	v_add_u32_e32 v205, s84, v212
	v_cmp_lt_i32_e32 vcc, v205, v206
	v_add_u32_e32 v216, 2, v205
	s_nop 7
	v_cndmask_b32_e32 v129, v192, v129, vcc
	v_cmp_le_i32_e32 vcc, v205, v206
	s_nop 1
	v_cndmask_b32_e32 v128, v192, v128, vcc
	v_cmp_le_i32_e32 vcc, v216, v206
	v_add_u32_e32 v216, 3, v205
	s_nop 0
	v_cndmask_b32_e32 v130, v192, v130, vcc
	v_cmp_le_i32_e32 vcc, v216, v206
	v_add_u32_e32 v216, 8, v205
	s_nop 0
	v_cndmask_b32_e32 v131, v192, v131, vcc
	v_cmp_le_i32_e32 vcc, v216, v206
	v_add_u32_e32 v216, 9, v205
	s_nop 0
	v_cndmask_b32_e32 v132, v192, v132, vcc
	v_cmp_le_i32_e32 vcc, v216, v206
	v_add_u32_e32 v216, 10, v205
	s_nop 0
	v_cndmask_b32_e32 v133, v192, v133, vcc
	v_cmp_le_i32_e32 vcc, v216, v206
	v_add_u32_e32 v216, 11, v205
	s_nop 0
	v_cndmask_b32_e32 v134, v192, v134, vcc
	v_cmp_le_i32_e32 vcc, v216, v206
	v_add_u32_e32 v216, 16, v205
	s_nop 0
	v_cndmask_b32_e32 v135, v192, v135, vcc
	v_cmp_le_i32_e32 vcc, v216, v206
	v_add_u32_e32 v216, 17, v205
	s_nop 0
	v_cndmask_b32_e32 v136, v192, v136, vcc
	v_cmp_le_i32_e32 vcc, v216, v206
	v_add_u32_e32 v216, 18, v205
	s_nop 0
	v_cndmask_b32_e32 v137, v192, v137, vcc
	v_cmp_le_i32_e32 vcc, v216, v206
	v_add_u32_e32 v216, 19, v205
	s_nop 0
	v_cndmask_b32_e32 v138, v192, v138, vcc
	v_cmp_le_i32_e32 vcc, v216, v206
	v_add_u32_e32 v216, 24, v205
	s_nop 0
	v_cndmask_b32_e32 v139, v192, v139, vcc
	v_cmp_le_i32_e32 vcc, v216, v206
	v_add_u32_e32 v216, 25, v205
	s_nop 0
	v_cndmask_b32_e32 v140, v192, v140, vcc
	v_cmp_le_i32_e32 vcc, v216, v206
	v_add_u32_e32 v216, 26, v205
	v_add_u32_e32 v205, 27, v205
	v_cndmask_b32_e32 v141, v192, v141, vcc
	v_cmp_le_i32_e32 vcc, v216, v206
	s_nop 1
	v_cndmask_b32_e32 v142, v192, v142, vcc
	v_cmp_le_i32_e32 vcc, v205, v206
	s_nop 1
	v_cndmask_b32_e32 v143, v192, v143, vcc

.LBB0_904:
	s_cmp_gt_i32 s14, s81
	s_cbranch_scc1 .LBB0_915
	s_add_i32 s100, s14, 63
	s_cmp_le_i32 s100, s80
	s_cbranch_scc0 .Latt_slow_3
	s_cmp_eq_u32 s11, 1
	s_cbranch_scc1 .Latt_slot1_3
	s_cmp_eq_u32 s11, 2
	s_cbranch_scc1 .Latt_slot2_3
	ds_read_b128 v[206:209], v196
	ds_read_b128 v[210:213], v197
	ds_read_b128 v[214:217], v198
	ds_read_b128 v[238:241], v199
	ds_read_b128 v[242:245], v200
	ds_read_b128 v[250:253], v201
	ds_read_b128 v[222:225], v202
	ds_read_b128 v[226:229], v203
	s_cmp_lg_u32 s14, 0
	s_cbranch_scc1 .Latt_vstep_3s0
	v_bfe_u32 v246, v204, 2, 2
	v_bfe_u32 v247, v204, 5, 1
	v_lshl_or_b32 v247, v247, 2, v246
	v_and_b32_e32 v249, 3, v204
	v_and_b32_e32 v254, 16, v204
	v_lshl_or_b32 v249, v249, 2, v254
	v_lshlrev_b32_e32 v249, 1, v249
	v_lshl_add_u32 v247, v247, 9, v249
	v_add_u32_e32 v247, 0xc000, v247
	v_lshlrev_b32_e32 v246, 6, v246
	v_add_u32_e32 v205, v247, v246
	v_xor_b32_e32 v249, 64, v246
	v_add_u32_e32 v218, v247, v249
	v_xor_b32_e32 v249, 0x80, v246
	v_add_u32_e32 v219, v247, v249
	v_xor_b32_e32 v249, 0xc0, v246
	v_add_u32_e32 v221, v247, v249
	s_branch .Latt_vdone_3s0

.Latt_nr0_3s0:
	s_waitcnt lgkmcnt(3)
	v_mfma_f32_32x32x16_bf16 v[222:237], v[214:217], v[152:155], v[222:237]
	ds_read_b128 v[214:217], v202 offset:8192
	v_sub_f32_e32 v128, v128, v190
	v_exp_f32_e32 v128, v128
	v_sub_f32_e32 v129, v129, v190
	v_exp_f32_e32 v129, v129
	v_sub_f32_e32 v130, v130, v190
	s_waitcnt lgkmcnt(3)
	v_mfma_f32_32x32x16_bf16 v[222:237], v[238:241], v[156:159], v[222:237]
	ds_read_b128 v[238:241], v203 offset:8192
	v_add_f32_e32 v254, 0, v128
	v_exp_f32_e32 v130, v130
	v_sub_f32_e32 v131, v131, v190
	v_add_f32_e32 v254, v129, v254
	v_exp_f32_e32 v131, v131
	s_waitcnt lgkmcnt(3)
	v_mfma_f32_32x32x16_bf16 v[222:237], v[206:209], v[160:163], v[222:237]
	ds_read_b64_tr_b16 v[206:207], v205
	ds_read_b64_tr_b16 v[208:209], v205 offset:4096
	v_sub_f32_e32 v132, v132, v190
	v_add_f32_e32 v254, v130, v254
	v_exp_f32_e32 v132, v132
	v_sub_f32_e32 v133, v133, v190
	v_add_f32_e32 v254, v131, v254
	s_waitcnt lgkmcnt(4)
	v_mfma_f32_32x32x16_bf16 v[222:237], v[210:213], v[164:167], v[222:237]
	ds_read_b64_tr_b16 v[210:211], v218
	ds_read_b64_tr_b16 v[212:213], v218 offset:4096
	v_exp_f32_e32 v133, v133
	v_sub_f32_e32 v134, v134, v190
	v_add_f32_e32 v254, v132, v254
	v_exp_f32_e32 v134, v134
	s_waitcnt lgkmcnt(5)
	v_mfma_f32_32x32x16_bf16 v[222:237], v[214:217], v[168:171], v[222:237]
	ds_read_b64_tr_b16 v[214:215], v219
	ds_read_b64_tr_b16 v[216:217], v219 offset:4096
	v_sub_f32_e32 v135, v135, v190
	v_add_f32_e32 v254, v133, v254
	v_exp_f32_e32 v135, v135
	s_nop 0
	s_waitcnt lgkmcnt(6)
	v_mfma_f32_32x32x16_bf16 v[222:237], v[238:241], v[172:175], v[222:237]
	ds_read_b64_tr_b16 v[238:239], v221
	ds_read_b64_tr_b16 v[240:241], v221 offset:4096
	v_cvt_pk_bf16_f32 v242, v128, v129
	v_cvt_pk_bf16_f32 v243, v130, v131
	v_cvt_pk_bf16_f32 v244, v132, v133
	v_cvt_pk_bf16_f32 v245, v134, v135
	s_nop 1
	s_waitcnt lgkmcnt(6)
	v_mfma_f32_32x32x16_bf16 v[112:127], v[206:209], v[242:245], v[112:127]
	ds_read_b64_tr_b16 v[206:207], v205 offset:256
	ds_read_b64_tr_b16 v[208:209], v205 offset:4352
	v_sub_f32_e32 v136, v136, v190
	v_add_f32_e32 v254, v134, v254
	v_exp_f32_e32 v136, v136
	v_sub_f32_e32 v137, v137, v190
	v_add_f32_e32 v254, v135, v254
	s_waitcnt lgkmcnt(6)
	v_mfma_f32_32x32x16_bf16 v[96:111], v[210:213], v[242:245], v[96:111]
	ds_read_b64_tr_b16 v[210:211], v218 offset:256
	ds_read_b64_tr_b16 v[212:213], v218 offset:4352
	v_exp_f32_e32 v137, v137
	v_sub_f32_e32 v138, v138, v190
	v_add_f32_e32 v254, v136, v254
	v_exp_f32_e32 v138, v138
	v_sub_f32_e32 v139, v139, v190
	s_waitcnt lgkmcnt(6)
	v_mfma_f32_32x32x16_bf16 v[80:95], v[214:217], v[242:245], v[80:95]
	ds_read_b64_tr_b16 v[214:215], v219 offset:256
	ds_read_b64_tr_b16 v[216:217], v219 offset:4352
	v_add_f32_e32 v254, v137, v254
	v_exp_f32_e32 v139, v139
	v_sub_f32_e32 v140, v140, v190
	v_add_f32_e32 v254, v138, v254
	s_waitcnt lgkmcnt(6)
	v_mfma_f32_32x32x16_bf16 v[64:79], v[238:241], v[242:245], v[64:79]
	ds_read_b64_tr_b16 v[238:239], v221 offset:256
	ds_read_b64_tr_b16 v[240:241], v221 offset:4352
	v_exp_f32_e32 v140, v140
	v_sub_f32_e32 v141, v141, v190
	v_add_f32_e32 v254, v139, v254
	v_exp_f32_e32 v141, v141
	s_waitcnt lgkmcnt(6)
	v_mfma_f32_32x32x16_bf16 v[48:63], v[206:209], v[242:245], v[48:63]
	ds_read_b64_tr_b16 v[206:207], v205 offset:8192
	ds_read_b64_tr_b16 v[208:209], v205 offset:12288
	v_sub_f32_e32 v142, v142, v190
	v_add_f32_e32 v254, v140, v254
	v_exp_f32_e32 v142, v142
	v_sub_f32_e32 v143, v143, v190
	s_waitcnt lgkmcnt(6)
	v_mfma_f32_32x32x16_bf16 v[32:47], v[210:213], v[242:245], v[32:47]
	ds_read_b64_tr_b16 v[210:211], v218 offset:8192
	ds_read_b64_tr_b16 v[212:213], v218 offset:12288
	v_add_f32_e32 v254, v141, v254
	v_exp_f32_e32 v143, v143
	v_add_f32_e32 v254, v142, v254
	v_add_f32_e32 v254, v143, v254
	s_waitcnt lgkmcnt(6)
	v_mfma_f32_32x32x16_bf16 v[16:31], v[214:217], v[242:245], v[16:31]
	ds_read_b64_tr_b16 v[214:215], v219 offset:8192
	ds_read_b64_tr_b16 v[216:217], v219 offset:12288
	v_cvt_pk_bf16_f32 v250, v136, v137
	v_cvt_pk_bf16_f32 v251, v138, v139
	v_cvt_pk_bf16_f32 v252, v140, v141
	v_cvt_pk_bf16_f32 v253, v142, v143
	v_add_f32_e32 v195, v195, v254
	s_waitcnt lgkmcnt(6)
	v_mfma_f32_32x32x16_bf16 v[0:15], v[238:241], v[242:245], v[0:15]
	ds_read_b64_tr_b16 v[238:239], v221 offset:8192
	ds_read_b64_tr_b16 v[240:241], v221 offset:12288
	ds_read_b64_tr_b16 v[128:129], v205 offset:8448
	ds_read_b64_tr_b16 v[130:131], v205 offset:12544
	s_waitcnt lgkmcnt(8)
	v_mfma_f32_32x32x16_bf16 v[112:127], v[206:209], v[250:253], v[112:127]
	ds_read_b64_tr_b16 v[206:207], v218 offset:8448
	ds_read_b64_tr_b16 v[208:209], v218 offset:12544
	v_max3_f32 v246, v222, v223, v224
	v_max3_f32 v247, v225, v226, v227
	v_max3_f32 v246, v246, v228, v229
	v_max3_f32 v247, v247, v230, v231
	v_max3_f32 v246, v246, v232, v233
	s_waitcnt lgkmcnt(8)
	v_mfma_f32_32x32x16_bf16 v[96:111], v[210:213], v[250:253], v[96:111]
	ds_read_b64_tr_b16 v[210:211], v219 offset:8448
	ds_read_b64_tr_b16 v[212:213], v219 offset:12544
	v_max3_f32 v247, v247, v234, v235
	v_max3_f32 v246, v246, v236, v237
	v_max_f32_e32 v246, v246, v247
	v_mov_b32_e32 v247, v246
	v_add_f32_e32 v249, 0x41000000, v190
	s_waitcnt lgkmcnt(8)
	v_mfma_f32_32x32x16_bf16 v[80:95], v[214:217], v[250:253], v[80:95]
	ds_read_b64_tr_b16 v[214:215], v221 offset:8448
	ds_read_b64_tr_b16 v[216:217], v221 offset:12544
	s_nop 1
	v_permlane32_swap_b32_e32 v246, v247
	v_max_f32_e32 v246, v246, v247
	v_cmp_gt_f32_e32 vcc, v246, v249
	s_cbranch_vccnz .Latt_rs1_3s0
	s_waitcnt lgkmcnt(8)
	v_mfma_f32_32x32x16_bf16 v[64:79], v[238:241], v[250:253], v[64:79]
	ds_read_b64_tr_b16 v[238:239], v205 offset:16384
	ds_read_b64_tr_b16 v[240:241], v205 offset:20480
	v_sub_f32_e32 v222, v222, v190
	v_exp_f32_e32 v222, v222
	v_sub_f32_e32 v223, v223, v190
	v_exp_f32_e32 v223, v223
	v_sub_f32_e32 v224, v224, v190
	v_add_f32_e32 v254, 0, v222
	s_waitcnt lgkmcnt(8)
	v_mfma_f32_32x32x16_bf16 v[48:63], v[128:131], v[250:253], v[48:63]
	ds_read_b64_tr_b16 v[128:129], v218 offset:16384
	ds_read_b64_tr_b16 v[130:131], v218 offset:20480
	v_exp_f32_e32 v224, v224
	v_sub_f32_e32 v225, v225, v190
	v_add_f32_e32 v254, v223, v254
	v_exp_f32_e32 v225, v225
	v_sub_f32_e32 v226, v226, v190
	v_add_f32_e32 v254, v224, v254
	s_waitcnt lgkmcnt(8)
	v_mfma_f32_32x32x16_bf16 v[32:47], v[206:209], v[250:253], v[32:47]
	ds_read_b64_tr_b16 v[206:207], v219 offset:16384
	ds_read_b64_tr_b16 v[208:209], v219 offset:20480
	v_exp_f32_e32 v226, v226
	v_sub_f32_e32 v227, v227, v190
	v_add_f32_e32 v254, v225, v254
	v_exp_f32_e32 v227, v227
	v_sub_f32_e32 v228, v228, v190
	s_waitcnt lgkmcnt(8)
	v_mfma_f32_32x32x16_bf16 v[16:31], v[210:213], v[250:253], v[16:31]
	ds_read_b64_tr_b16 v[210:211], v221 offset:16384
	ds_read_b64_tr_b16 v[212:213], v221 offset:20480
	v_add_f32_e32 v254, v226, v254
	v_exp_f32_e32 v228, v228
	v_sub_f32_e32 v229, v229, v190
	v_add_f32_e32 v254, v227, v254
	v_exp_f32_e32 v229, v229
	s_waitcnt lgkmcnt(8)
	v_mfma_f32_32x32x16_bf16 v[0:15], v[214:217], v[250:253], v[0:15]
	ds_read_b64_tr_b16 v[214:215], v205 offset:16640
	ds_read_b64_tr_b16 v[216:217], v205 offset:20736
	s_nop 0
	v_cvt_pk_bf16_f32 v242, v222, v223
	v_cvt_pk_bf16_f32 v243, v224, v225
	v_cvt_pk_bf16_f32 v244, v226, v227
	v_cvt_pk_bf16_f32 v245, v228, v229
	s_nop 1
	s_waitcnt lgkmcnt(8)
	v_mfma_f32_32x32x16_bf16 v[112:127], v[238:241], v[242:245], v[112:127]
	ds_read_b64_tr_b16 v[238:239], v218 offset:16640
	ds_read_b64_tr_b16 v[240:241], v218 offset:20736
	v_sub_f32_e32 v230, v230, v190
	v_add_f32_e32 v254, v228, v254
	v_exp_f32_e32 v230, v230
	v_sub_f32_e32 v231, v231, v190
	v_add_f32_e32 v254, v229, v254
	s_waitcnt lgkmcnt(8)
	v_mfma_f32_32x32x16_bf16 v[96:111], v[128:131], v[242:245], v[96:111]
	ds_read_b64_tr_b16 v[128:129], v219 offset:16640
	ds_read_b64_tr_b16 v[130:131], v219 offset:20736
	v_exp_f32_e32 v231, v231
	v_sub_f32_e32 v232, v232, v190
	v_add_f32_e32 v254, v230, v254
	v_exp_f32_e32 v232, v232
	v_sub_f32_e32 v233, v233, v190
	s_cmp_lg_u64 s[8:9], 0
	s_cbranch_scc1 .Latt_nd0_3s0
	s_sub_i32 s100, s11, 1
	s_cmp_eq_u32 s11, 0
	s_cselect_b32 s100, 2, s100
	s_lshl_b32 s101, s100, 14
	s_add_i32 m0, s40, s101
	s_nop 0
	global_load_lds_dwordx4 v178, s[34:35]

.Latt_nr0_3s1:
	s_waitcnt lgkmcnt(3)
	v_mfma_f32_32x32x16_bf16 v[222:237], v[214:217], v[152:155], v[222:237]
	ds_read_b128 v[214:217], v202 offset:24576
	v_sub_f32_e32 v128, v128, v190
	v_exp_f32_e32 v128, v128
	v_sub_f32_e32 v129, v129, v190
	v_exp_f32_e32 v129, v129
	v_sub_f32_e32 v130, v130, v190
	s_waitcnt lgkmcnt(3)
	v_mfma_f32_32x32x16_bf16 v[222:237], v[238:241], v[156:159], v[222:237]
	ds_read_b128 v[238:241], v203 offset:24576
	v_add_f32_e32 v254, 0, v128
	v_exp_f32_e32 v130, v130
	v_sub_f32_e32 v131, v131, v190
	v_add_f32_e32 v254, v129, v254
	v_exp_f32_e32 v131, v131
	s_waitcnt lgkmcnt(3)
	v_mfma_f32_32x32x16_bf16 v[222:237], v[206:209], v[160:163], v[222:237]
	ds_read_b64_tr_b16 v[206:207], v205
	ds_read_b64_tr_b16 v[208:209], v205 offset:4096
	v_sub_f32_e32 v132, v132, v190
	v_add_f32_e32 v254, v130, v254
	v_exp_f32_e32 v132, v132
	v_sub_f32_e32 v133, v133, v190
	v_add_f32_e32 v254, v131, v254
	s_waitcnt lgkmcnt(4)
	v_mfma_f32_32x32x16_bf16 v[222:237], v[210:213], v[164:167], v[222:237]
	ds_read_b64_tr_b16 v[210:211], v218
	ds_read_b64_tr_b16 v[212:213], v218 offset:4096
	v_exp_f32_e32 v133, v133
	v_sub_f32_e32 v134, v134, v190
	v_add_f32_e32 v254, v132, v254
	v_exp_f32_e32 v134, v134
	s_waitcnt lgkmcnt(5)
	v_mfma_f32_32x32x16_bf16 v[222:237], v[214:217], v[168:171], v[222:237]
	ds_read_b64_tr_b16 v[214:215], v219
	ds_read_b64_tr_b16 v[216:217], v219 offset:4096
	v_sub_f32_e32 v135, v135, v190
	v_add_f32_e32 v254, v133, v254
	v_exp_f32_e32 v135, v135
	s_nop 0
	s_waitcnt lgkmcnt(6)
	v_mfma_f32_32x32x16_bf16 v[222:237], v[238:241], v[172:175], v[222:237]
	ds_read_b64_tr_b16 v[238:239], v221
	ds_read_b64_tr_b16 v[240:241], v221 offset:4096
	v_cvt_pk_bf16_f32 v242, v128, v129
	v_cvt_pk_bf16_f32 v243, v130, v131
	v_cvt_pk_bf16_f32 v244, v132, v133
	v_cvt_pk_bf16_f32 v245, v134, v135
	s_nop 1
	s_waitcnt lgkmcnt(6)
	v_mfma_f32_32x32x16_bf16 v[112:127], v[206:209], v[242:245], v[112:127]
	ds_read_b64_tr_b16 v[206:207], v205 offset:256
	ds_read_b64_tr_b16 v[208:209], v205 offset:4352
	v_sub_f32_e32 v136, v136, v190
	v_add_f32_e32 v254, v134, v254
	v_exp_f32_e32 v136, v136
	v_sub_f32_e32 v137, v137, v190
	v_add_f32_e32 v254, v135, v254
	s_waitcnt lgkmcnt(6)
	v_mfma_f32_32x32x16_bf16 v[96:111], v[210:213], v[242:245], v[96:111]
	ds_read_b64_tr_b16 v[210:211], v218 offset:256
	ds_read_b64_tr_b16 v[212:213], v218 offset:4352
	v_exp_f32_e32 v137, v137
	v_sub_f32_e32 v138, v138, v190
	v_add_f32_e32 v254, v136, v254
	v_exp_f32_e32 v138, v138
	v_sub_f32_e32 v139, v139, v190
	s_waitcnt lgkmcnt(6)
	v_mfma_f32_32x32x16_bf16 v[80:95], v[214:217], v[242:245], v[80:95]
	ds_read_b64_tr_b16 v[214:215], v219 offset:256
	ds_read_b64_tr_b16 v[216:217], v219 offset:4352
	v_add_f32_e32 v254, v137, v254
	v_exp_f32_e32 v139, v139
	v_sub_f32_e32 v140, v140, v190
	v_add_f32_e32 v254, v138, v254
	s_waitcnt lgkmcnt(6)
	v_mfma_f32_32x32x16_bf16 v[64:79], v[238:241], v[242:245], v[64:79]
	ds_read_b64_tr_b16 v[238:239], v221 offset:256
	ds_read_b64_tr_b16 v[240:241], v221 offset:4352
	v_exp_f32_e32 v140, v140
	v_sub_f32_e32 v141, v141, v190
	v_add_f32_e32 v254, v139, v254
	v_exp_f32_e32 v141, v141
	s_waitcnt lgkmcnt(6)
	v_mfma_f32_32x32x16_bf16 v[48:63], v[206:209], v[242:245], v[48:63]
	ds_read_b64_tr_b16 v[206:207], v205 offset:8192
	ds_read_b64_tr_b16 v[208:209], v205 offset:12288
	v_sub_f32_e32 v142, v142, v190
	v_add_f32_e32 v254, v140, v254
	v_exp_f32_e32 v142, v142
	v_sub_f32_e32 v143, v143, v190
	s_waitcnt lgkmcnt(6)
	v_mfma_f32_32x32x16_bf16 v[32:47], v[210:213], v[242:245], v[32:47]
	ds_read_b64_tr_b16 v[210:211], v218 offset:8192
	ds_read_b64_tr_b16 v[212:213], v218 offset:12288
	v_add_f32_e32 v254, v141, v254
	v_exp_f32_e32 v143, v143
	v_add_f32_e32 v254, v142, v254
	v_add_f32_e32 v254, v143, v254
	s_waitcnt lgkmcnt(6)
	v_mfma_f32_32x32x16_bf16 v[16:31], v[214:217], v[242:245], v[16:31]
	ds_read_b64_tr_b16 v[214:215], v219 offset:8192
	ds_read_b64_tr_b16 v[216:217], v219 offset:12288
	v_cvt_pk_bf16_f32 v250, v136, v137
	v_cvt_pk_bf16_f32 v251, v138, v139
	v_cvt_pk_bf16_f32 v252, v140, v141
	v_cvt_pk_bf16_f32 v253, v142, v143
	v_add_f32_e32 v195, v195, v254
	s_waitcnt lgkmcnt(6)
	v_mfma_f32_32x32x16_bf16 v[0:15], v[238:241], v[242:245], v[0:15]
	ds_read_b64_tr_b16 v[238:239], v221 offset:8192
	ds_read_b64_tr_b16 v[240:241], v221 offset:12288
	ds_read_b64_tr_b16 v[128:129], v205 offset:8448
	ds_read_b64_tr_b16 v[130:131], v205 offset:12544
	s_waitcnt lgkmcnt(8)
	v_mfma_f32_32x32x16_bf16 v[112:127], v[206:209], v[250:253], v[112:127]
	ds_read_b64_tr_b16 v[206:207], v218 offset:8448
	ds_read_b64_tr_b16 v[208:209], v218 offset:12544
	v_max3_f32 v246, v222, v223, v224
	v_max3_f32 v247, v225, v226, v227
	v_max3_f32 v246, v246, v228, v229
	v_max3_f32 v247, v247, v230, v231
	v_max3_f32 v246, v246, v232, v233
	s_waitcnt lgkmcnt(8)
	v_mfma_f32_32x32x16_bf16 v[96:111], v[210:213], v[250:253], v[96:111]
	ds_read_b64_tr_b16 v[210:211], v219 offset:8448
	ds_read_b64_tr_b16 v[212:213], v219 offset:12544
	v_max3_f32 v247, v247, v234, v235
	v_max3_f32 v246, v246, v236, v237
	v_max_f32_e32 v246, v246, v247
	v_mov_b32_e32 v247, v246
	v_add_f32_e32 v249, 0x41000000, v190
	s_waitcnt lgkmcnt(8)
	v_mfma_f32_32x32x16_bf16 v[80:95], v[214:217], v[250:253], v[80:95]
	ds_read_b64_tr_b16 v[214:215], v221 offset:8448
	ds_read_b64_tr_b16 v[216:217], v221 offset:12544
	s_nop 1
	v_permlane32_swap_b32_e32 v246, v247
	v_max_f32_e32 v246, v246, v247
	v_cmp_gt_f32_e32 vcc, v246, v249
	s_cbranch_vccnz .Latt_rs1_3s1
	s_waitcnt lgkmcnt(8)
	v_mfma_f32_32x32x16_bf16 v[64:79], v[238:241], v[250:253], v[64:79]
	ds_read_b64_tr_b16 v[238:239], v205 offset:16384
	ds_read_b64_tr_b16 v[240:241], v205 offset:20480
	v_sub_f32_e32 v222, v222, v190
	v_exp_f32_e32 v222, v222
	v_sub_f32_e32 v223, v223, v190
	v_exp_f32_e32 v223, v223
	v_sub_f32_e32 v224, v224, v190
	v_add_f32_e32 v254, 0, v222
	s_waitcnt lgkmcnt(8)
	v_mfma_f32_32x32x16_bf16 v[48:63], v[128:131], v[250:253], v[48:63]
	ds_read_b64_tr_b16 v[128:129], v218 offset:16384
	ds_read_b64_tr_b16 v[130:131], v218 offset:20480
	v_exp_f32_e32 v224, v224
	v_sub_f32_e32 v225, v225, v190
	v_add_f32_e32 v254, v223, v254
	v_exp_f32_e32 v225, v225
	v_sub_f32_e32 v226, v226, v190
	v_add_f32_e32 v254, v224, v254
	s_waitcnt lgkmcnt(8)
	v_mfma_f32_32x32x16_bf16 v[32:47], v[206:209], v[250:253], v[32:47]
	ds_read_b64_tr_b16 v[206:207], v219 offset:16384
	ds_read_b64_tr_b16 v[208:209], v219 offset:20480
	v_exp_f32_e32 v226, v226
	v_sub_f32_e32 v227, v227, v190
	v_add_f32_e32 v254, v225, v254
	v_exp_f32_e32 v227, v227
	v_sub_f32_e32 v228, v228, v190
	s_waitcnt lgkmcnt(8)
	v_mfma_f32_32x32x16_bf16 v[16:31], v[210:213], v[250:253], v[16:31]
	ds_read_b64_tr_b16 v[210:211], v221 offset:16384
	ds_read_b64_tr_b16 v[212:213], v221 offset:20480
	v_add_f32_e32 v254, v226, v254
	v_exp_f32_e32 v228, v228
	v_sub_f32_e32 v229, v229, v190
	v_add_f32_e32 v254, v227, v254
	v_exp_f32_e32 v229, v229
	s_waitcnt lgkmcnt(8)
	v_mfma_f32_32x32x16_bf16 v[0:15], v[214:217], v[250:253], v[0:15]
	ds_read_b64_tr_b16 v[214:215], v205 offset:16640
	ds_read_b64_tr_b16 v[216:217], v205 offset:20736
	s_nop 0
	v_cvt_pk_bf16_f32 v242, v222, v223
	v_cvt_pk_bf16_f32 v243, v224, v225
	v_cvt_pk_bf16_f32 v244, v226, v227
	v_cvt_pk_bf16_f32 v245, v228, v229
	s_nop 1
	s_waitcnt lgkmcnt(8)
	v_mfma_f32_32x32x16_bf16 v[112:127], v[238:241], v[242:245], v[112:127]
	ds_read_b64_tr_b16 v[238:239], v218 offset:16640
	ds_read_b64_tr_b16 v[240:241], v218 offset:20736
	v_sub_f32_e32 v230, v230, v190
	v_add_f32_e32 v254, v228, v254
	v_exp_f32_e32 v230, v230
	v_sub_f32_e32 v231, v231, v190
	v_add_f32_e32 v254, v229, v254
	s_waitcnt lgkmcnt(8)
	v_mfma_f32_32x32x16_bf16 v[96:111], v[128:131], v[242:245], v[96:111]
	ds_read_b64_tr_b16 v[128:129], v219 offset:16640
	ds_read_b64_tr_b16 v[130:131], v219 offset:20736
	v_exp_f32_e32 v231, v231
	v_sub_f32_e32 v232, v232, v190
	v_add_f32_e32 v254, v230, v254
	v_exp_f32_e32 v232, v232
	v_sub_f32_e32 v233, v233, v190
	s_cmp_lg_u64 s[8:9], 0
	s_cbranch_scc1 .Latt_nd0_3s1
	s_sub_i32 s100, s11, 1
	s_cmp_eq_u32 s11, 0
	s_cselect_b32 s100, 2, s100
	s_lshl_b32 s101, s100, 14
	s_add_i32 m0, s40, s101
	s_nop 0
	global_load_lds_dwordx4 v178, s[34:35]

.Latt_nr0_3s2:
	s_waitcnt lgkmcnt(3)
	v_mfma_f32_32x32x16_bf16 v[222:237], v[214:217], v[152:155], v[222:237]
	ds_read_b128 v[214:217], v202 offset:40960
	v_sub_f32_e32 v128, v128, v190
	v_exp_f32_e32 v128, v128
	v_sub_f32_e32 v129, v129, v190
	v_exp_f32_e32 v129, v129
	v_sub_f32_e32 v130, v130, v190
	s_waitcnt lgkmcnt(3)
	v_mfma_f32_32x32x16_bf16 v[222:237], v[238:241], v[156:159], v[222:237]
	ds_read_b128 v[238:241], v203 offset:40960
	v_add_f32_e32 v254, 0, v128
	v_exp_f32_e32 v130, v130
	v_sub_f32_e32 v131, v131, v190
	v_add_f32_e32 v254, v129, v254
	v_exp_f32_e32 v131, v131
	s_waitcnt lgkmcnt(3)
	v_mfma_f32_32x32x16_bf16 v[222:237], v[206:209], v[160:163], v[222:237]
	ds_read_b64_tr_b16 v[206:207], v205
	ds_read_b64_tr_b16 v[208:209], v205 offset:4096
	v_sub_f32_e32 v132, v132, v190
	v_add_f32_e32 v254, v130, v254
	v_exp_f32_e32 v132, v132
	v_sub_f32_e32 v133, v133, v190
	v_add_f32_e32 v254, v131, v254
	s_waitcnt lgkmcnt(4)
	v_mfma_f32_32x32x16_bf16 v[222:237], v[210:213], v[164:167], v[222:237]
	ds_read_b64_tr_b16 v[210:211], v218
	ds_read_b64_tr_b16 v[212:213], v218 offset:4096
	v_exp_f32_e32 v133, v133
	v_sub_f32_e32 v134, v134, v190
	v_add_f32_e32 v254, v132, v254
	v_exp_f32_e32 v134, v134
	s_waitcnt lgkmcnt(5)
	v_mfma_f32_32x32x16_bf16 v[222:237], v[214:217], v[168:171], v[222:237]
	ds_read_b64_tr_b16 v[214:215], v219
	ds_read_b64_tr_b16 v[216:217], v219 offset:4096
	v_sub_f32_e32 v135, v135, v190
	v_add_f32_e32 v254, v133, v254
	v_exp_f32_e32 v135, v135
	s_nop 0
	s_waitcnt lgkmcnt(6)
	v_mfma_f32_32x32x16_bf16 v[222:237], v[238:241], v[172:175], v[222:237]
	ds_read_b64_tr_b16 v[238:239], v221
	ds_read_b64_tr_b16 v[240:241], v221 offset:4096
	v_cvt_pk_bf16_f32 v242, v128, v129
	v_cvt_pk_bf16_f32 v243, v130, v131
	v_cvt_pk_bf16_f32 v244, v132, v133
	v_cvt_pk_bf16_f32 v245, v134, v135
	s_nop 1
	s_waitcnt lgkmcnt(6)
	v_mfma_f32_32x32x16_bf16 v[112:127], v[206:209], v[242:245], v[112:127]
	ds_read_b64_tr_b16 v[206:207], v205 offset:256
	ds_read_b64_tr_b16 v[208:209], v205 offset:4352
	v_sub_f32_e32 v136, v136, v190
	v_add_f32_e32 v254, v134, v254
	v_exp_f32_e32 v136, v136
	v_sub_f32_e32 v137, v137, v190
	v_add_f32_e32 v254, v135, v254
	s_waitcnt lgkmcnt(6)
	v_mfma_f32_32x32x16_bf16 v[96:111], v[210:213], v[242:245], v[96:111]
	ds_read_b64_tr_b16 v[210:211], v218 offset:256
	ds_read_b64_tr_b16 v[212:213], v218 offset:4352
	v_exp_f32_e32 v137, v137
	v_sub_f32_e32 v138, v138, v190
	v_add_f32_e32 v254, v136, v254
	v_exp_f32_e32 v138, v138
	v_sub_f32_e32 v139, v139, v190
	s_waitcnt lgkmcnt(6)
	v_mfma_f32_32x32x16_bf16 v[80:95], v[214:217], v[242:245], v[80:95]
	ds_read_b64_tr_b16 v[214:215], v219 offset:256
	ds_read_b64_tr_b16 v[216:217], v219 offset:4352
	v_add_f32_e32 v254, v137, v254
	v_exp_f32_e32 v139, v139
	v_sub_f32_e32 v140, v140, v190
	v_add_f32_e32 v254, v138, v254
	s_waitcnt lgkmcnt(6)
	v_mfma_f32_32x32x16_bf16 v[64:79], v[238:241], v[242:245], v[64:79]
	ds_read_b64_tr_b16 v[238:239], v221 offset:256
	ds_read_b64_tr_b16 v[240:241], v221 offset:4352
	v_exp_f32_e32 v140, v140
	v_sub_f32_e32 v141, v141, v190
	v_add_f32_e32 v254, v139, v254
	v_exp_f32_e32 v141, v141
	s_waitcnt lgkmcnt(6)
	v_mfma_f32_32x32x16_bf16 v[48:63], v[206:209], v[242:245], v[48:63]
	ds_read_b64_tr_b16 v[206:207], v205 offset:8192
	ds_read_b64_tr_b16 v[208:209], v205 offset:12288
	v_sub_f32_e32 v142, v142, v190
	v_add_f32_e32 v254, v140, v254
	v_exp_f32_e32 v142, v142
	v_sub_f32_e32 v143, v143, v190
	s_waitcnt lgkmcnt(6)
	v_mfma_f32_32x32x16_bf16 v[32:47], v[210:213], v[242:245], v[32:47]
	ds_read_b64_tr_b16 v[210:211], v218 offset:8192
	ds_read_b64_tr_b16 v[212:213], v218 offset:12288
	v_add_f32_e32 v254, v141, v254
	v_exp_f32_e32 v143, v143
	v_add_f32_e32 v254, v142, v254
	v_add_f32_e32 v254, v143, v254
	s_waitcnt lgkmcnt(6)
	v_mfma_f32_32x32x16_bf16 v[16:31], v[214:217], v[242:245], v[16:31]
	ds_read_b64_tr_b16 v[214:215], v219 offset:8192
	ds_read_b64_tr_b16 v[216:217], v219 offset:12288
	v_cvt_pk_bf16_f32 v250, v136, v137
	v_cvt_pk_bf16_f32 v251, v138, v139
	v_cvt_pk_bf16_f32 v252, v140, v141
	v_cvt_pk_bf16_f32 v253, v142, v143
	v_add_f32_e32 v195, v195, v254
	s_waitcnt lgkmcnt(6)
	v_mfma_f32_32x32x16_bf16 v[0:15], v[238:241], v[242:245], v[0:15]
	ds_read_b64_tr_b16 v[238:239], v221 offset:8192
	ds_read_b64_tr_b16 v[240:241], v221 offset:12288
	ds_read_b64_tr_b16 v[128:129], v205 offset:8448
	ds_read_b64_tr_b16 v[130:131], v205 offset:12544
	s_waitcnt lgkmcnt(8)
	v_mfma_f32_32x32x16_bf16 v[112:127], v[206:209], v[250:253], v[112:127]
	ds_read_b64_tr_b16 v[206:207], v218 offset:8448
	ds_read_b64_tr_b16 v[208:209], v218 offset:12544
	v_max3_f32 v246, v222, v223, v224
	v_max3_f32 v247, v225, v226, v227
	v_max3_f32 v246, v246, v228, v229
	v_max3_f32 v247, v247, v230, v231
	v_max3_f32 v246, v246, v232, v233
	s_waitcnt lgkmcnt(8)
	v_mfma_f32_32x32x16_bf16 v[96:111], v[210:213], v[250:253], v[96:111]
	ds_read_b64_tr_b16 v[210:211], v219 offset:8448
	ds_read_b64_tr_b16 v[212:213], v219 offset:12544
	v_max3_f32 v247, v247, v234, v235
	v_max3_f32 v246, v246, v236, v237
	v_max_f32_e32 v246, v246, v247
	v_mov_b32_e32 v247, v246
	v_add_f32_e32 v249, 0x41000000, v190
	s_waitcnt lgkmcnt(8)
	v_mfma_f32_32x32x16_bf16 v[80:95], v[214:217], v[250:253], v[80:95]
	ds_read_b64_tr_b16 v[214:215], v221 offset:8448
	ds_read_b64_tr_b16 v[216:217], v221 offset:12544
	s_nop 1
	v_permlane32_swap_b32_e32 v246, v247
	v_max_f32_e32 v246, v246, v247
	v_cmp_gt_f32_e32 vcc, v246, v249
	s_cbranch_vccnz .Latt_rs1_3s2
	s_waitcnt lgkmcnt(8)
	v_mfma_f32_32x32x16_bf16 v[64:79], v[238:241], v[250:253], v[64:79]
	ds_read_b64_tr_b16 v[238:239], v205 offset:16384
	ds_read_b64_tr_b16 v[240:241], v205 offset:20480
	v_sub_f32_e32 v222, v222, v190
	v_exp_f32_e32 v222, v222
	v_sub_f32_e32 v223, v223, v190
	v_exp_f32_e32 v223, v223
	v_sub_f32_e32 v224, v224, v190
	v_add_f32_e32 v254, 0, v222
	s_waitcnt lgkmcnt(8)
	v_mfma_f32_32x32x16_bf16 v[48:63], v[128:131], v[250:253], v[48:63]
	ds_read_b64_tr_b16 v[128:129], v218 offset:16384
	ds_read_b64_tr_b16 v[130:131], v218 offset:20480
	v_exp_f32_e32 v224, v224
	v_sub_f32_e32 v225, v225, v190
	v_add_f32_e32 v254, v223, v254
	v_exp_f32_e32 v225, v225
	v_sub_f32_e32 v226, v226, v190
	v_add_f32_e32 v254, v224, v254
	s_waitcnt lgkmcnt(8)
	v_mfma_f32_32x32x16_bf16 v[32:47], v[206:209], v[250:253], v[32:47]
	ds_read_b64_tr_b16 v[206:207], v219 offset:16384
	ds_read_b64_tr_b16 v[208:209], v219 offset:20480
	v_exp_f32_e32 v226, v226
	v_sub_f32_e32 v227, v227, v190
	v_add_f32_e32 v254, v225, v254
	v_exp_f32_e32 v227, v227
	v_sub_f32_e32 v228, v228, v190
	s_waitcnt lgkmcnt(8)
	v_mfma_f32_32x32x16_bf16 v[16:31], v[210:213], v[250:253], v[16:31]
	ds_read_b64_tr_b16 v[210:211], v221 offset:16384
	ds_read_b64_tr_b16 v[212:213], v221 offset:20480
	v_add_f32_e32 v254, v226, v254
	v_exp_f32_e32 v228, v228
	v_sub_f32_e32 v229, v229, v190
	v_add_f32_e32 v254, v227, v254
	v_exp_f32_e32 v229, v229
	s_waitcnt lgkmcnt(8)
	v_mfma_f32_32x32x16_bf16 v[0:15], v[214:217], v[250:253], v[0:15]
	ds_read_b64_tr_b16 v[214:215], v205 offset:16640
	ds_read_b64_tr_b16 v[216:217], v205 offset:20736
	s_nop 0
	v_cvt_pk_bf16_f32 v242, v222, v223
	v_cvt_pk_bf16_f32 v243, v224, v225
	v_cvt_pk_bf16_f32 v244, v226, v227
	v_cvt_pk_bf16_f32 v245, v228, v229
	s_nop 1
	s_waitcnt lgkmcnt(8)
	v_mfma_f32_32x32x16_bf16 v[112:127], v[238:241], v[242:245], v[112:127]
	ds_read_b64_tr_b16 v[238:239], v218 offset:16640
	ds_read_b64_tr_b16 v[240:241], v218 offset:20736
	v_sub_f32_e32 v230, v230, v190
	v_add_f32_e32 v254, v228, v254
	v_exp_f32_e32 v230, v230
	v_sub_f32_e32 v231, v231, v190
	v_add_f32_e32 v254, v229, v254
	s_waitcnt lgkmcnt(8)
	v_mfma_f32_32x32x16_bf16 v[96:111], v[128:131], v[242:245], v[96:111]
	ds_read_b64_tr_b16 v[128:129], v219 offset:16640
	ds_read_b64_tr_b16 v[130:131], v219 offset:20736
	v_exp_f32_e32 v231, v231
	v_sub_f32_e32 v232, v232, v190
	v_add_f32_e32 v254, v230, v254
	v_exp_f32_e32 v232, v232
	v_sub_f32_e32 v233, v233, v190
	s_cmp_lg_u64 s[8:9], 0
	s_cbranch_scc1 .Latt_nd0_3s2
	s_sub_i32 s100, s11, 1
	s_cmp_eq_u32 s11, 0
	s_cselect_b32 s100, 2, s100
	s_lshl_b32 s101, s100, 14
	s_add_i32 m0, s40, s101
	s_nop 0
	global_load_lds_dwordx4 v178, s[34:35]

.Latt_slow_3s2:
.Latt_slow_3:
	s_lshl_b32 s15, s11, 14
	s_add_i32 s16, s15, 0
	v_add_u32_e32 v207, s16, v196
	ds_read_b128 v[128:131], v207
	v_add_u32_e32 v208, s16, v197
	ds_read_b128 v[210:213], v208
	v_add_u32_e32 v209, s16, v198
	v_lshrrev_b32_e32 v205, 3, v204
	s_add_i32 s17, s14, 31
	v_and_or_b32 v206, v204, 31, s80
	s_cmp_le_i32 s17, s80
	s_waitcnt lgkmcnt(1)
	v_mfma_f32_32x32x16_bf16 v[128:143], v[128:131], v[144:147], 0
	s_waitcnt lgkmcnt(0)
	v_mfma_f32_32x32x16_bf16 v[128:143], v[210:213], v[148:151], v[128:143]
	ds_read_b128 v[212:215], v209
	v_add_u32_e32 v210, s16, v199
	ds_read_b128 v[216:219], v210
	v_add_u32_e32 v211, s16, v200
	s_waitcnt lgkmcnt(1)
	v_mfma_f32_32x32x16_bf16 v[128:143], v[212:215], v[152:155], v[128:143]
	v_add_u32_e32 v213, s16, v201
	v_and_b32_e32 v212, 4, v205
	ds_read_b128 v[222:225], v213
	s_waitcnt lgkmcnt(1)
	v_mfma_f32_32x32x16_bf16 v[128:143], v[216:219], v[156:159], v[128:143]
	ds_read_b128 v[214:217], v211
	s_waitcnt lgkmcnt(0)
	v_mfma_f32_32x32x16_bf16 v[128:143], v[214:217], v[160:163], v[128:143]
	v_add_u32_e32 v214, s16, v202
	ds_read_b128 v[216:219], v214
	v_add_u32_e32 v215, s16, v203
	v_mfma_f32_32x32x16_bf16 v[128:143], v[222:225], v[164:167], v[128:143]
	ds_read_b128 v[222:225], v215
	s_waitcnt lgkmcnt(1)
	v_mfma_f32_32x32x16_bf16 v[128:143], v[216:219], v[168:171], v[128:143]
	s_waitcnt lgkmcnt(0)
	v_mfma_f32_32x32x16_bf16 v[128:143], v[222:225], v[172:175], v[128:143]
	s_cbranch_scc1 .LBB0_907
	v_add_u32_e32 v205, s14, v212
	v_cmp_lt_i32_e32 vcc, v205, v206
	v_add_u32_e32 v216, 2, v205
	s_nop 7
	v_cndmask_b32_e32 v129, v192, v129, vcc
	v_cmp_le_i32_e32 vcc, v205, v206
	s_nop 1
	v_cndmask_b32_e32 v128, v192, v128, vcc
	v_cmp_le_i32_e32 vcc, v216, v206
	v_add_u32_e32 v216, 3, v205
	s_nop 0
	v_cndmask_b32_e32 v130, v192, v130, vcc
	v_cmp_le_i32_e32 vcc, v216, v206
	v_add_u32_e32 v216, 8, v205
	s_nop 0
	v_cndmask_b32_e32 v131, v192, v131, vcc
	v_cmp_le_i32_e32 vcc, v216, v206
	v_add_u32_e32 v216, 9, v205
	s_nop 0
	v_cndmask_b32_e32 v132, v192, v132, vcc
	v_cmp_le_i32_e32 vcc, v216, v206
	v_add_u32_e32 v216, 10, v205
	s_nop 0
	v_cndmask_b32_e32 v133, v192, v133, vcc
	v_cmp_le_i32_e32 vcc, v216, v206
	v_add_u32_e32 v216, 11, v205
	s_nop 0
	v_cndmask_b32_e32 v134, v192, v134, vcc
	v_cmp_le_i32_e32 vcc, v216, v206
	v_add_u32_e32 v216, 16, v205
	s_nop 0
	v_cndmask_b32_e32 v135, v192, v135, vcc
	v_cmp_le_i32_e32 vcc, v216, v206
	v_add_u32_e32 v216, 17, v205
	s_nop 0
	v_cndmask_b32_e32 v136, v192, v136, vcc
	v_cmp_le_i32_e32 vcc, v216, v206
	v_add_u32_e32 v216, 18, v205
	s_nop 0
	v_cndmask_b32_e32 v137, v192, v137, vcc
	v_cmp_le_i32_e32 vcc, v216, v206
	v_add_u32_e32 v216, 19, v205
	s_nop 0
	v_cndmask_b32_e32 v138, v192, v138, vcc
	v_cmp_le_i32_e32 vcc, v216, v206
	v_add_u32_e32 v216, 24, v205
	s_nop 0
	v_cndmask_b32_e32 v139, v192, v139, vcc
	v_cmp_le_i32_e32 vcc, v216, v206
	v_add_u32_e32 v216, 25, v205
	s_nop 0
	v_cndmask_b32_e32 v140, v192, v140, vcc
	v_cmp_le_i32_e32 vcc, v216, v206
	v_add_u32_e32 v216, 26, v205
	v_add_u32_e32 v205, 27, v205
	v_cndmask_b32_e32 v141, v192, v141, vcc
	v_cmp_le_i32_e32 vcc, v216, v206
	s_nop 1
	v_cndmask_b32_e32 v142, v192, v142, vcc
	v_cmp_le_i32_e32 vcc, v205, v206
	s_nop 1
	v_cndmask_b32_e32 v143, v192, v143, vcc

.LBB0_1801:
	s_cmp_gt_i32 s39, s72
	s_cbranch_scc1 .LBB0_1812
	s_add_i32 s100, s39, 63
	s_cmp_le_i32 s100, s71
	s_cbranch_scc0 .Latt_slow_4
	s_cmp_eq_u32 s76, 1
	s_cbranch_scc1 .Latt_slot1_4
	s_cmp_eq_u32 s76, 2
	s_cbranch_scc1 .Latt_slot2_4
	ds_read_b128 v[206:209], v194
	ds_read_b128 v[210:213], v195
	ds_read_b128 v[214:217], v196
	ds_read_b128 v[238:241], v197
	ds_read_b128 v[242:245], v198
	ds_read_b128 v[250:253], v199
	ds_read_b128 v[222:225], v200
	ds_read_b128 v[226:229], v201
	s_cmp_lg_u32 s39, 0
	s_cbranch_scc1 .Latt_vstep_4s0
	v_bfe_u32 v246, v203, 2, 2
	v_bfe_u32 v247, v203, 5, 1
	v_lshl_or_b32 v247, v247, 2, v246
	v_and_b32_e32 v249, 3, v203
	v_and_b32_e32 v254, 16, v203
	v_lshl_or_b32 v249, v249, 2, v254
	v_lshlrev_b32_e32 v249, 1, v249
	v_lshl_add_u32 v247, v247, 9, v249
	v_add_u32_e32 v247, 0xc000, v247
	v_lshlrev_b32_e32 v246, 6, v246
	v_add_u32_e32 v205, v247, v246
	v_xor_b32_e32 v249, 64, v246
	v_add_u32_e32 v218, v247, v249
	v_xor_b32_e32 v249, 0x80, v246
	v_add_u32_e32 v219, v247, v249
	v_xor_b32_e32 v249, 0xc0, v246
	v_add_u32_e32 v221, v247, v249
	s_branch .Latt_vdone_4s0

.Latt_nr0_4s0:
	s_waitcnt lgkmcnt(3)
	v_mfma_f32_32x32x16_bf16 v[222:237], v[214:217], v[152:155], v[222:237]
	ds_read_b128 v[214:217], v200 offset:8192
	v_sub_f32_e32 v128, v128, v190
	v_exp_f32_e32 v128, v128
	v_sub_f32_e32 v129, v129, v190
	v_exp_f32_e32 v129, v129
	v_sub_f32_e32 v130, v130, v190
	s_waitcnt lgkmcnt(3)
	v_mfma_f32_32x32x16_bf16 v[222:237], v[238:241], v[156:159], v[222:237]
	ds_read_b128 v[238:241], v201 offset:8192
	v_add_f32_e32 v254, 0, v128
	v_exp_f32_e32 v130, v130
	v_sub_f32_e32 v131, v131, v190
	v_add_f32_e32 v254, v129, v254
	v_exp_f32_e32 v131, v131
	s_waitcnt lgkmcnt(3)
	v_mfma_f32_32x32x16_bf16 v[222:237], v[206:209], v[160:163], v[222:237]
	ds_read_b64_tr_b16 v[206:207], v205
	ds_read_b64_tr_b16 v[208:209], v205 offset:4096
	v_sub_f32_e32 v132, v132, v190
	v_add_f32_e32 v254, v130, v254
	v_exp_f32_e32 v132, v132
	v_sub_f32_e32 v133, v133, v190
	v_add_f32_e32 v254, v131, v254
	s_waitcnt lgkmcnt(4)
	v_mfma_f32_32x32x16_bf16 v[222:237], v[210:213], v[164:167], v[222:237]
	ds_read_b64_tr_b16 v[210:211], v218
	ds_read_b64_tr_b16 v[212:213], v218 offset:4096
	v_exp_f32_e32 v133, v133
	v_sub_f32_e32 v134, v134, v190
	v_add_f32_e32 v254, v132, v254
	v_exp_f32_e32 v134, v134
	s_waitcnt lgkmcnt(5)
	v_mfma_f32_32x32x16_bf16 v[222:237], v[214:217], v[168:171], v[222:237]
	ds_read_b64_tr_b16 v[214:215], v219
	ds_read_b64_tr_b16 v[216:217], v219 offset:4096
	v_sub_f32_e32 v135, v135, v190
	v_add_f32_e32 v254, v133, v254
	v_exp_f32_e32 v135, v135
	s_nop 0
	s_waitcnt lgkmcnt(6)
	v_mfma_f32_32x32x16_bf16 v[222:237], v[238:241], v[172:175], v[222:237]
	ds_read_b64_tr_b16 v[238:239], v221
	ds_read_b64_tr_b16 v[240:241], v221 offset:4096
	v_cvt_pk_bf16_f32 v242, v128, v129
	v_cvt_pk_bf16_f32 v243, v130, v131
	v_cvt_pk_bf16_f32 v244, v132, v133
	v_cvt_pk_bf16_f32 v245, v134, v135
	s_nop 1
	s_waitcnt lgkmcnt(6)
	v_mfma_f32_32x32x16_bf16 v[112:127], v[206:209], v[242:245], v[112:127]
	ds_read_b64_tr_b16 v[206:207], v205 offset:256
	ds_read_b64_tr_b16 v[208:209], v205 offset:4352
	v_sub_f32_e32 v136, v136, v190
	v_add_f32_e32 v254, v134, v254
	v_exp_f32_e32 v136, v136
	v_sub_f32_e32 v137, v137, v190
	v_add_f32_e32 v254, v135, v254
	s_waitcnt lgkmcnt(6)
	v_mfma_f32_32x32x16_bf16 v[96:111], v[210:213], v[242:245], v[96:111]
	ds_read_b64_tr_b16 v[210:211], v218 offset:256
	ds_read_b64_tr_b16 v[212:213], v218 offset:4352
	v_exp_f32_e32 v137, v137
	v_sub_f32_e32 v138, v138, v190
	v_add_f32_e32 v254, v136, v254
	v_exp_f32_e32 v138, v138
	v_sub_f32_e32 v139, v139, v190
	s_waitcnt lgkmcnt(6)
	v_mfma_f32_32x32x16_bf16 v[80:95], v[214:217], v[242:245], v[80:95]
	ds_read_b64_tr_b16 v[214:215], v219 offset:256
	ds_read_b64_tr_b16 v[216:217], v219 offset:4352
	v_add_f32_e32 v254, v137, v254
	v_exp_f32_e32 v139, v139
	v_sub_f32_e32 v140, v140, v190
	v_add_f32_e32 v254, v138, v254
	s_waitcnt lgkmcnt(6)
	v_mfma_f32_32x32x16_bf16 v[64:79], v[238:241], v[242:245], v[64:79]
	ds_read_b64_tr_b16 v[238:239], v221 offset:256
	ds_read_b64_tr_b16 v[240:241], v221 offset:4352
	v_exp_f32_e32 v140, v140
	v_sub_f32_e32 v141, v141, v190
	v_add_f32_e32 v254, v139, v254
	v_exp_f32_e32 v141, v141
	s_waitcnt lgkmcnt(6)
	v_mfma_f32_32x32x16_bf16 v[48:63], v[206:209], v[242:245], v[48:63]
	ds_read_b64_tr_b16 v[206:207], v205 offset:8192
	ds_read_b64_tr_b16 v[208:209], v205 offset:12288
	v_sub_f32_e32 v142, v142, v190
	v_add_f32_e32 v254, v140, v254
	v_exp_f32_e32 v142, v142
	v_sub_f32_e32 v143, v143, v190
	s_waitcnt lgkmcnt(6)
	v_mfma_f32_32x32x16_bf16 v[32:47], v[210:213], v[242:245], v[32:47]
	ds_read_b64_tr_b16 v[210:211], v218 offset:8192
	ds_read_b64_tr_b16 v[212:213], v218 offset:12288
	v_add_f32_e32 v254, v141, v254
	v_exp_f32_e32 v143, v143
	v_add_f32_e32 v254, v142, v254
	v_add_f32_e32 v254, v143, v254
	s_waitcnt lgkmcnt(6)
	v_mfma_f32_32x32x16_bf16 v[16:31], v[214:217], v[242:245], v[16:31]
	ds_read_b64_tr_b16 v[214:215], v219 offset:8192
	ds_read_b64_tr_b16 v[216:217], v219 offset:12288
	v_cvt_pk_bf16_f32 v250, v136, v137
	v_cvt_pk_bf16_f32 v251, v138, v139
	v_cvt_pk_bf16_f32 v252, v140, v141
	v_cvt_pk_bf16_f32 v253, v142, v143
	v_add_f32_e32 v202, v202, v254
	s_waitcnt lgkmcnt(6)
	v_mfma_f32_32x32x16_bf16 v[0:15], v[238:241], v[242:245], v[0:15]
	ds_read_b64_tr_b16 v[238:239], v221 offset:8192
	ds_read_b64_tr_b16 v[240:241], v221 offset:12288
	ds_read_b64_tr_b16 v[128:129], v205 offset:8448
	ds_read_b64_tr_b16 v[130:131], v205 offset:12544
	s_waitcnt lgkmcnt(8)
	v_mfma_f32_32x32x16_bf16 v[112:127], v[206:209], v[250:253], v[112:127]
	ds_read_b64_tr_b16 v[206:207], v218 offset:8448
	ds_read_b64_tr_b16 v[208:209], v218 offset:12544
	v_max3_f32 v246, v222, v223, v224
	v_max3_f32 v247, v225, v226, v227
	v_max3_f32 v246, v246, v228, v229
	v_max3_f32 v247, v247, v230, v231
	v_max3_f32 v246, v246, v232, v233
	s_waitcnt lgkmcnt(8)
	v_mfma_f32_32x32x16_bf16 v[96:111], v[210:213], v[250:253], v[96:111]
	ds_read_b64_tr_b16 v[210:211], v219 offset:8448
	ds_read_b64_tr_b16 v[212:213], v219 offset:12544
	v_max3_f32 v247, v247, v234, v235
	v_max3_f32 v246, v246, v236, v237
	v_max_f32_e32 v246, v246, v247
	v_mov_b32_e32 v247, v246
	v_add_f32_e32 v249, 0x41000000, v190
	s_waitcnt lgkmcnt(8)
	v_mfma_f32_32x32x16_bf16 v[80:95], v[214:217], v[250:253], v[80:95]
	ds_read_b64_tr_b16 v[214:215], v221 offset:8448
	ds_read_b64_tr_b16 v[216:217], v221 offset:12544
	s_nop 1
	v_permlane32_swap_b32_e32 v246, v247
	v_max_f32_e32 v246, v246, v247
	v_cmp_gt_f32_e32 vcc, v246, v249
	s_cbranch_vccnz .Latt_rs1_4s0
	s_waitcnt lgkmcnt(8)
	v_mfma_f32_32x32x16_bf16 v[64:79], v[238:241], v[250:253], v[64:79]
	ds_read_b64_tr_b16 v[238:239], v205 offset:16384
	ds_read_b64_tr_b16 v[240:241], v205 offset:20480
	v_sub_f32_e32 v222, v222, v190
	v_exp_f32_e32 v222, v222
	v_sub_f32_e32 v223, v223, v190
	v_exp_f32_e32 v223, v223
	v_sub_f32_e32 v224, v224, v190
	v_add_f32_e32 v254, 0, v222
	s_waitcnt lgkmcnt(8)
	v_mfma_f32_32x32x16_bf16 v[48:63], v[128:131], v[250:253], v[48:63]
	ds_read_b64_tr_b16 v[128:129], v218 offset:16384
	ds_read_b64_tr_b16 v[130:131], v218 offset:20480
	v_exp_f32_e32 v224, v224
	v_sub_f32_e32 v225, v225, v190
	v_add_f32_e32 v254, v223, v254
	v_exp_f32_e32 v225, v225
	v_sub_f32_e32 v226, v226, v190
	v_add_f32_e32 v254, v224, v254
	s_waitcnt lgkmcnt(8)
	v_mfma_f32_32x32x16_bf16 v[32:47], v[206:209], v[250:253], v[32:47]
	ds_read_b64_tr_b16 v[206:207], v219 offset:16384
	ds_read_b64_tr_b16 v[208:209], v219 offset:20480
	v_exp_f32_e32 v226, v226
	v_sub_f32_e32 v227, v227, v190
	v_add_f32_e32 v254, v225, v254
	v_exp_f32_e32 v227, v227
	v_sub_f32_e32 v228, v228, v190
	s_waitcnt lgkmcnt(8)
	v_mfma_f32_32x32x16_bf16 v[16:31], v[210:213], v[250:253], v[16:31]
	ds_read_b64_tr_b16 v[210:211], v221 offset:16384
	ds_read_b64_tr_b16 v[212:213], v221 offset:20480
	v_add_f32_e32 v254, v226, v254
	v_exp_f32_e32 v228, v228
	v_sub_f32_e32 v229, v229, v190
	v_add_f32_e32 v254, v227, v254
	v_exp_f32_e32 v229, v229
	s_waitcnt lgkmcnt(8)
	v_mfma_f32_32x32x16_bf16 v[0:15], v[214:217], v[250:253], v[0:15]
	ds_read_b64_tr_b16 v[214:215], v205 offset:16640
	ds_read_b64_tr_b16 v[216:217], v205 offset:20736
	s_nop 0
	v_cvt_pk_bf16_f32 v242, v222, v223
	v_cvt_pk_bf16_f32 v243, v224, v225
	v_cvt_pk_bf16_f32 v244, v226, v227
	v_cvt_pk_bf16_f32 v245, v228, v229
	s_nop 1
	s_waitcnt lgkmcnt(8)
	v_mfma_f32_32x32x16_bf16 v[112:127], v[238:241], v[242:245], v[112:127]
	ds_read_b64_tr_b16 v[238:239], v218 offset:16640
	ds_read_b64_tr_b16 v[240:241], v218 offset:20736
	v_sub_f32_e32 v230, v230, v190
	v_add_f32_e32 v254, v228, v254
	v_exp_f32_e32 v230, v230
	v_sub_f32_e32 v231, v231, v190
	v_add_f32_e32 v254, v229, v254
	s_waitcnt lgkmcnt(8)
	v_mfma_f32_32x32x16_bf16 v[96:111], v[128:131], v[242:245], v[96:111]
	ds_read_b64_tr_b16 v[128:129], v219 offset:16640
	ds_read_b64_tr_b16 v[130:131], v219 offset:20736
	v_exp_f32_e32 v231, v231
	v_sub_f32_e32 v232, v232, v190
	v_add_f32_e32 v254, v230, v254
	v_exp_f32_e32 v232, v232
	v_sub_f32_e32 v233, v233, v190
	s_cmp_lg_u64 s[18:19], 0
	s_cbranch_scc1 .Latt_nd0_4s0
	s_sub_i32 s100, s76, 1
	s_cmp_eq_u32 s76, 0
	s_cselect_b32 s100, 2, s100
	s_lshl_b32 s101, s100, 14
	s_add_i32 m0, s73, s101
	s_nop 0
	global_load_lds_dwordx4 v178, s[14:15]

.Latt_nr0_4s1:
	s_waitcnt lgkmcnt(3)
	v_mfma_f32_32x32x16_bf16 v[222:237], v[214:217], v[152:155], v[222:237]
	ds_read_b128 v[214:217], v200 offset:24576
	v_sub_f32_e32 v128, v128, v190
	v_exp_f32_e32 v128, v128
	v_sub_f32_e32 v129, v129, v190
	v_exp_f32_e32 v129, v129
	v_sub_f32_e32 v130, v130, v190
	s_waitcnt lgkmcnt(3)
	v_mfma_f32_32x32x16_bf16 v[222:237], v[238:241], v[156:159], v[222:237]
	ds_read_b128 v[238:241], v201 offset:24576
	v_add_f32_e32 v254, 0, v128
	v_exp_f32_e32 v130, v130
	v_sub_f32_e32 v131, v131, v190
	v_add_f32_e32 v254, v129, v254
	v_exp_f32_e32 v131, v131
	s_waitcnt lgkmcnt(3)
	v_mfma_f32_32x32x16_bf16 v[222:237], v[206:209], v[160:163], v[222:237]
	ds_read_b64_tr_b16 v[206:207], v205
	ds_read_b64_tr_b16 v[208:209], v205 offset:4096
	v_sub_f32_e32 v132, v132, v190
	v_add_f32_e32 v254, v130, v254
	v_exp_f32_e32 v132, v132
	v_sub_f32_e32 v133, v133, v190
	v_add_f32_e32 v254, v131, v254
	s_waitcnt lgkmcnt(4)
	v_mfma_f32_32x32x16_bf16 v[222:237], v[210:213], v[164:167], v[222:237]
	ds_read_b64_tr_b16 v[210:211], v218
	ds_read_b64_tr_b16 v[212:213], v218 offset:4096
	v_exp_f32_e32 v133, v133
	v_sub_f32_e32 v134, v134, v190
	v_add_f32_e32 v254, v132, v254
	v_exp_f32_e32 v134, v134
	s_waitcnt lgkmcnt(5)
	v_mfma_f32_32x32x16_bf16 v[222:237], v[214:217], v[168:171], v[222:237]
	ds_read_b64_tr_b16 v[214:215], v219
	ds_read_b64_tr_b16 v[216:217], v219 offset:4096
	v_sub_f32_e32 v135, v135, v190
	v_add_f32_e32 v254, v133, v254
	v_exp_f32_e32 v135, v135
	s_nop 0
	s_waitcnt lgkmcnt(6)
	v_mfma_f32_32x32x16_bf16 v[222:237], v[238:241], v[172:175], v[222:237]
	ds_read_b64_tr_b16 v[238:239], v221
	ds_read_b64_tr_b16 v[240:241], v221 offset:4096
	v_cvt_pk_bf16_f32 v242, v128, v129
	v_cvt_pk_bf16_f32 v243, v130, v131
	v_cvt_pk_bf16_f32 v244, v132, v133
	v_cvt_pk_bf16_f32 v245, v134, v135
	s_nop 1
	s_waitcnt lgkmcnt(6)
	v_mfma_f32_32x32x16_bf16 v[112:127], v[206:209], v[242:245], v[112:127]
	ds_read_b64_tr_b16 v[206:207], v205 offset:256
	ds_read_b64_tr_b16 v[208:209], v205 offset:4352
	v_sub_f32_e32 v136, v136, v190
	v_add_f32_e32 v254, v134, v254
	v_exp_f32_e32 v136, v136
	v_sub_f32_e32 v137, v137, v190
	v_add_f32_e32 v254, v135, v254
	s_waitcnt lgkmcnt(6)
	v_mfma_f32_32x32x16_bf16 v[96:111], v[210:213], v[242:245], v[96:111]
	ds_read_b64_tr_b16 v[210:211], v218 offset:256
	ds_read_b64_tr_b16 v[212:213], v218 offset:4352
	v_exp_f32_e32 v137, v137
	v_sub_f32_e32 v138, v138, v190
	v_add_f32_e32 v254, v136, v254
	v_exp_f32_e32 v138, v138
	v_sub_f32_e32 v139, v139, v190
	s_waitcnt lgkmcnt(6)
	v_mfma_f32_32x32x16_bf16 v[80:95], v[214:217], v[242:245], v[80:95]
	ds_read_b64_tr_b16 v[214:215], v219 offset:256
	ds_read_b64_tr_b16 v[216:217], v219 offset:4352
	v_add_f32_e32 v254, v137, v254
	v_exp_f32_e32 v139, v139
	v_sub_f32_e32 v140, v140, v190
	v_add_f32_e32 v254, v138, v254
	s_waitcnt lgkmcnt(6)
	v_mfma_f32_32x32x16_bf16 v[64:79], v[238:241], v[242:245], v[64:79]
	ds_read_b64_tr_b16 v[238:239], v221 offset:256
	ds_read_b64_tr_b16 v[240:241], v221 offset:4352
	v_exp_f32_e32 v140, v140
	v_sub_f32_e32 v141, v141, v190
	v_add_f32_e32 v254, v139, v254
	v_exp_f32_e32 v141, v141
	s_waitcnt lgkmcnt(6)
	v_mfma_f32_32x32x16_bf16 v[48:63], v[206:209], v[242:245], v[48:63]
	ds_read_b64_tr_b16 v[206:207], v205 offset:8192
	ds_read_b64_tr_b16 v[208:209], v205 offset:12288
	v_sub_f32_e32 v142, v142, v190
	v_add_f32_e32 v254, v140, v254
	v_exp_f32_e32 v142, v142
	v_sub_f32_e32 v143, v143, v190
	s_waitcnt lgkmcnt(6)
	v_mfma_f32_32x32x16_bf16 v[32:47], v[210:213], v[242:245], v[32:47]
	ds_read_b64_tr_b16 v[210:211], v218 offset:8192
	ds_read_b64_tr_b16 v[212:213], v218 offset:12288
	v_add_f32_e32 v254, v141, v254
	v_exp_f32_e32 v143, v143
	v_add_f32_e32 v254, v142, v254
	v_add_f32_e32 v254, v143, v254
	s_waitcnt lgkmcnt(6)
	v_mfma_f32_32x32x16_bf16 v[16:31], v[214:217], v[242:245], v[16:31]
	ds_read_b64_tr_b16 v[214:215], v219 offset:8192
	ds_read_b64_tr_b16 v[216:217], v219 offset:12288
	v_cvt_pk_bf16_f32 v250, v136, v137
	v_cvt_pk_bf16_f32 v251, v138, v139
	v_cvt_pk_bf16_f32 v252, v140, v141
	v_cvt_pk_bf16_f32 v253, v142, v143
	v_add_f32_e32 v202, v202, v254
	s_waitcnt lgkmcnt(6)
	v_mfma_f32_32x32x16_bf16 v[0:15], v[238:241], v[242:245], v[0:15]
	ds_read_b64_tr_b16 v[238:239], v221 offset:8192
	ds_read_b64_tr_b16 v[240:241], v221 offset:12288
	ds_read_b64_tr_b16 v[128:129], v205 offset:8448
	ds_read_b64_tr_b16 v[130:131], v205 offset:12544
	s_waitcnt lgkmcnt(8)
	v_mfma_f32_32x32x16_bf16 v[112:127], v[206:209], v[250:253], v[112:127]
	ds_read_b64_tr_b16 v[206:207], v218 offset:8448
	ds_read_b64_tr_b16 v[208:209], v218 offset:12544
	v_max3_f32 v246, v222, v223, v224
	v_max3_f32 v247, v225, v226, v227
	v_max3_f32 v246, v246, v228, v229
	v_max3_f32 v247, v247, v230, v231
	v_max3_f32 v246, v246, v232, v233
	s_waitcnt lgkmcnt(8)
	v_mfma_f32_32x32x16_bf16 v[96:111], v[210:213], v[250:253], v[96:111]
	ds_read_b64_tr_b16 v[210:211], v219 offset:8448
	ds_read_b64_tr_b16 v[212:213], v219 offset:12544
	v_max3_f32 v247, v247, v234, v235
	v_max3_f32 v246, v246, v236, v237
	v_max_f32_e32 v246, v246, v247
	v_mov_b32_e32 v247, v246
	v_add_f32_e32 v249, 0x41000000, v190
	s_waitcnt lgkmcnt(8)
	v_mfma_f32_32x32x16_bf16 v[80:95], v[214:217], v[250:253], v[80:95]
	ds_read_b64_tr_b16 v[214:215], v221 offset:8448
	ds_read_b64_tr_b16 v[216:217], v221 offset:12544
	s_nop 1
	v_permlane32_swap_b32_e32 v246, v247
	v_max_f32_e32 v246, v246, v247
	v_cmp_gt_f32_e32 vcc, v246, v249
	s_cbranch_vccnz .Latt_rs1_4s1
	s_waitcnt lgkmcnt(8)
	v_mfma_f32_32x32x16_bf16 v[64:79], v[238:241], v[250:253], v[64:79]
	ds_read_b64_tr_b16 v[238:239], v205 offset:16384
	ds_read_b64_tr_b16 v[240:241], v205 offset:20480
	v_sub_f32_e32 v222, v222, v190
	v_exp_f32_e32 v222, v222
	v_sub_f32_e32 v223, v223, v190
	v_exp_f32_e32 v223, v223
	v_sub_f32_e32 v224, v224, v190
	v_add_f32_e32 v254, 0, v222
	s_waitcnt lgkmcnt(8)
	v_mfma_f32_32x32x16_bf16 v[48:63], v[128:131], v[250:253], v[48:63]
	ds_read_b64_tr_b16 v[128:129], v218 offset:16384
	ds_read_b64_tr_b16 v[130:131], v218 offset:20480
	v_exp_f32_e32 v224, v224
	v_sub_f32_e32 v225, v225, v190
	v_add_f32_e32 v254, v223, v254
	v_exp_f32_e32 v225, v225
	v_sub_f32_e32 v226, v226, v190
	v_add_f32_e32 v254, v224, v254
	s_waitcnt lgkmcnt(8)
	v_mfma_f32_32x32x16_bf16 v[32:47], v[206:209], v[250:253], v[32:47]
	ds_read_b64_tr_b16 v[206:207], v219 offset:16384
	ds_read_b64_tr_b16 v[208:209], v219 offset:20480
	v_exp_f32_e32 v226, v226
	v_sub_f32_e32 v227, v227, v190
	v_add_f32_e32 v254, v225, v254
	v_exp_f32_e32 v227, v227
	v_sub_f32_e32 v228, v228, v190
	s_waitcnt lgkmcnt(8)
	v_mfma_f32_32x32x16_bf16 v[16:31], v[210:213], v[250:253], v[16:31]
	ds_read_b64_tr_b16 v[210:211], v221 offset:16384
	ds_read_b64_tr_b16 v[212:213], v221 offset:20480
	v_add_f32_e32 v254, v226, v254
	v_exp_f32_e32 v228, v228
	v_sub_f32_e32 v229, v229, v190
	v_add_f32_e32 v254, v227, v254
	v_exp_f32_e32 v229, v229
	s_waitcnt lgkmcnt(8)
	v_mfma_f32_32x32x16_bf16 v[0:15], v[214:217], v[250:253], v[0:15]
	ds_read_b64_tr_b16 v[214:215], v205 offset:16640
	ds_read_b64_tr_b16 v[216:217], v205 offset:20736
	s_nop 0
	v_cvt_pk_bf16_f32 v242, v222, v223
	v_cvt_pk_bf16_f32 v243, v224, v225
	v_cvt_pk_bf16_f32 v244, v226, v227
	v_cvt_pk_bf16_f32 v245, v228, v229
	s_nop 1
	s_waitcnt lgkmcnt(8)
	v_mfma_f32_32x32x16_bf16 v[112:127], v[238:241], v[242:245], v[112:127]
	ds_read_b64_tr_b16 v[238:239], v218 offset:16640
	ds_read_b64_tr_b16 v[240:241], v218 offset:20736
	v_sub_f32_e32 v230, v230, v190
	v_add_f32_e32 v254, v228, v254
	v_exp_f32_e32 v230, v230
	v_sub_f32_e32 v231, v231, v190
	v_add_f32_e32 v254, v229, v254
	s_waitcnt lgkmcnt(8)
	v_mfma_f32_32x32x16_bf16 v[96:111], v[128:131], v[242:245], v[96:111]
	ds_read_b64_tr_b16 v[128:129], v219 offset:16640
	ds_read_b64_tr_b16 v[130:131], v219 offset:20736
	v_exp_f32_e32 v231, v231
	v_sub_f32_e32 v232, v232, v190
	v_add_f32_e32 v254, v230, v254
	v_exp_f32_e32 v232, v232
	v_sub_f32_e32 v233, v233, v190
	s_cmp_lg_u64 s[18:19], 0
	s_cbranch_scc1 .Latt_nd0_4s1
	s_sub_i32 s100, s76, 1
	s_cmp_eq_u32 s76, 0
	s_cselect_b32 s100, 2, s100
	s_lshl_b32 s101, s100, 14
	s_add_i32 m0, s73, s101
	s_nop 0
	global_load_lds_dwordx4 v178, s[14:15]

.Latt_nr0_4s2:
	s_waitcnt lgkmcnt(3)
	v_mfma_f32_32x32x16_bf16 v[222:237], v[214:217], v[152:155], v[222:237]
	ds_read_b128 v[214:217], v200 offset:40960
	v_sub_f32_e32 v128, v128, v190
	v_exp_f32_e32 v128, v128
	v_sub_f32_e32 v129, v129, v190
	v_exp_f32_e32 v129, v129
	v_sub_f32_e32 v130, v130, v190
	s_waitcnt lgkmcnt(3)
	v_mfma_f32_32x32x16_bf16 v[222:237], v[238:241], v[156:159], v[222:237]
	ds_read_b128 v[238:241], v201 offset:40960
	v_add_f32_e32 v254, 0, v128
	v_exp_f32_e32 v130, v130
	v_sub_f32_e32 v131, v131, v190
	v_add_f32_e32 v254, v129, v254
	v_exp_f32_e32 v131, v131
	s_waitcnt lgkmcnt(3)
	v_mfma_f32_32x32x16_bf16 v[222:237], v[206:209], v[160:163], v[222:237]
	ds_read_b64_tr_b16 v[206:207], v205
	ds_read_b64_tr_b16 v[208:209], v205 offset:4096
	v_sub_f32_e32 v132, v132, v190
	v_add_f32_e32 v254, v130, v254
	v_exp_f32_e32 v132, v132
	v_sub_f32_e32 v133, v133, v190
	v_add_f32_e32 v254, v131, v254
	s_waitcnt lgkmcnt(4)
	v_mfma_f32_32x32x16_bf16 v[222:237], v[210:213], v[164:167], v[222:237]
	ds_read_b64_tr_b16 v[210:211], v218
	ds_read_b64_tr_b16 v[212:213], v218 offset:4096
	v_exp_f32_e32 v133, v133
	v_sub_f32_e32 v134, v134, v190
	v_add_f32_e32 v254, v132, v254
	v_exp_f32_e32 v134, v134
	s_waitcnt lgkmcnt(5)
	v_mfma_f32_32x32x16_bf16 v[222:237], v[214:217], v[168:171], v[222:237]
	ds_read_b64_tr_b16 v[214:215], v219
	ds_read_b64_tr_b16 v[216:217], v219 offset:4096
	v_sub_f32_e32 v135, v135, v190
	v_add_f32_e32 v254, v133, v254
	v_exp_f32_e32 v135, v135
	s_nop 0
	s_waitcnt lgkmcnt(6)
	v_mfma_f32_32x32x16_bf16 v[222:237], v[238:241], v[172:175], v[222:237]
	ds_read_b64_tr_b16 v[238:239], v221
	ds_read_b64_tr_b16 v[240:241], v221 offset:4096
	v_cvt_pk_bf16_f32 v242, v128, v129
	v_cvt_pk_bf16_f32 v243, v130, v131
	v_cvt_pk_bf16_f32 v244, v132, v133
	v_cvt_pk_bf16_f32 v245, v134, v135
	s_nop 1
	s_waitcnt lgkmcnt(6)
	v_mfma_f32_32x32x16_bf16 v[112:127], v[206:209], v[242:245], v[112:127]
	ds_read_b64_tr_b16 v[206:207], v205 offset:256
	ds_read_b64_tr_b16 v[208:209], v205 offset:4352
	v_sub_f32_e32 v136, v136, v190
	v_add_f32_e32 v254, v134, v254
	v_exp_f32_e32 v136, v136
	v_sub_f32_e32 v137, v137, v190
	v_add_f32_e32 v254, v135, v254
	s_waitcnt lgkmcnt(6)
	v_mfma_f32_32x32x16_bf16 v[96:111], v[210:213], v[242:245], v[96:111]
	ds_read_b64_tr_b16 v[210:211], v218 offset:256
	ds_read_b64_tr_b16 v[212:213], v218 offset:4352
	v_exp_f32_e32 v137, v137
	v_sub_f32_e32 v138, v138, v190
	v_add_f32_e32 v254, v136, v254
	v_exp_f32_e32 v138, v138
	v_sub_f32_e32 v139, v139, v190
	s_waitcnt lgkmcnt(6)
	v_mfma_f32_32x32x16_bf16 v[80:95], v[214:217], v[242:245], v[80:95]
	ds_read_b64_tr_b16 v[214:215], v219 offset:256
	ds_read_b64_tr_b16 v[216:217], v219 offset:4352
	v_add_f32_e32 v254, v137, v254
	v_exp_f32_e32 v139, v139
	v_sub_f32_e32 v140, v140, v190
	v_add_f32_e32 v254, v138, v254
	s_waitcnt lgkmcnt(6)
	v_mfma_f32_32x32x16_bf16 v[64:79], v[238:241], v[242:245], v[64:79]
	ds_read_b64_tr_b16 v[238:239], v221 offset:256
	ds_read_b64_tr_b16 v[240:241], v221 offset:4352
	v_exp_f32_e32 v140, v140
	v_sub_f32_e32 v141, v141, v190
	v_add_f32_e32 v254, v139, v254
	v_exp_f32_e32 v141, v141
	s_waitcnt lgkmcnt(6)
	v_mfma_f32_32x32x16_bf16 v[48:63], v[206:209], v[242:245], v[48:63]
	ds_read_b64_tr_b16 v[206:207], v205 offset:8192
	ds_read_b64_tr_b16 v[208:209], v205 offset:12288
	v_sub_f32_e32 v142, v142, v190
	v_add_f32_e32 v254, v140, v254
	v_exp_f32_e32 v142, v142
	v_sub_f32_e32 v143, v143, v190
	s_waitcnt lgkmcnt(6)
	v_mfma_f32_32x32x16_bf16 v[32:47], v[210:213], v[242:245], v[32:47]
	ds_read_b64_tr_b16 v[210:211], v218 offset:8192
	ds_read_b64_tr_b16 v[212:213], v218 offset:12288
	v_add_f32_e32 v254, v141, v254
	v_exp_f32_e32 v143, v143
	v_add_f32_e32 v254, v142, v254
	v_add_f32_e32 v254, v143, v254
	s_waitcnt lgkmcnt(6)
	v_mfma_f32_32x32x16_bf16 v[16:31], v[214:217], v[242:245], v[16:31]
	ds_read_b64_tr_b16 v[214:215], v219 offset:8192
	ds_read_b64_tr_b16 v[216:217], v219 offset:12288
	v_cvt_pk_bf16_f32 v250, v136, v137
	v_cvt_pk_bf16_f32 v251, v138, v139
	v_cvt_pk_bf16_f32 v252, v140, v141
	v_cvt_pk_bf16_f32 v253, v142, v143
	v_add_f32_e32 v202, v202, v254
	s_waitcnt lgkmcnt(6)
	v_mfma_f32_32x32x16_bf16 v[0:15], v[238:241], v[242:245], v[0:15]
	ds_read_b64_tr_b16 v[238:239], v221 offset:8192
	ds_read_b64_tr_b16 v[240:241], v221 offset:12288
	ds_read_b64_tr_b16 v[128:129], v205 offset:8448
	ds_read_b64_tr_b16 v[130:131], v205 offset:12544
	s_waitcnt lgkmcnt(8)
	v_mfma_f32_32x32x16_bf16 v[112:127], v[206:209], v[250:253], v[112:127]
	ds_read_b64_tr_b16 v[206:207], v218 offset:8448
	ds_read_b64_tr_b16 v[208:209], v218 offset:12544
	v_max3_f32 v246, v222, v223, v224
	v_max3_f32 v247, v225, v226, v227
	v_max3_f32 v246, v246, v228, v229
	v_max3_f32 v247, v247, v230, v231
	v_max3_f32 v246, v246, v232, v233
	s_waitcnt lgkmcnt(8)
	v_mfma_f32_32x32x16_bf16 v[96:111], v[210:213], v[250:253], v[96:111]
	ds_read_b64_tr_b16 v[210:211], v219 offset:8448
	ds_read_b64_tr_b16 v[212:213], v219 offset:12544
	v_max3_f32 v247, v247, v234, v235
	v_max3_f32 v246, v246, v236, v237
	v_max_f32_e32 v246, v246, v247
	v_mov_b32_e32 v247, v246
	v_add_f32_e32 v249, 0x41000000, v190
	s_waitcnt lgkmcnt(8)
	v_mfma_f32_32x32x16_bf16 v[80:95], v[214:217], v[250:253], v[80:95]
	ds_read_b64_tr_b16 v[214:215], v221 offset:8448
	ds_read_b64_tr_b16 v[216:217], v221 offset:12544
	s_nop 1
	v_permlane32_swap_b32_e32 v246, v247
	v_max_f32_e32 v246, v246, v247
	v_cmp_gt_f32_e32 vcc, v246, v249
	s_cbranch_vccnz .Latt_rs1_4s2
	s_waitcnt lgkmcnt(8)
	v_mfma_f32_32x32x16_bf16 v[64:79], v[238:241], v[250:253], v[64:79]
	ds_read_b64_tr_b16 v[238:239], v205 offset:16384
	ds_read_b64_tr_b16 v[240:241], v205 offset:20480
	v_sub_f32_e32 v222, v222, v190
	v_exp_f32_e32 v222, v222
	v_sub_f32_e32 v223, v223, v190
	v_exp_f32_e32 v223, v223
	v_sub_f32_e32 v224, v224, v190
	v_add_f32_e32 v254, 0, v222
	s_waitcnt lgkmcnt(8)
	v_mfma_f32_32x32x16_bf16 v[48:63], v[128:131], v[250:253], v[48:63]
	ds_read_b64_tr_b16 v[128:129], v218 offset:16384
	ds_read_b64_tr_b16 v[130:131], v218 offset:20480
	v_exp_f32_e32 v224, v224
	v_sub_f32_e32 v225, v225, v190
	v_add_f32_e32 v254, v223, v254
	v_exp_f32_e32 v225, v225
	v_sub_f32_e32 v226, v226, v190
	v_add_f32_e32 v254, v224, v254
	s_waitcnt lgkmcnt(8)
	v_mfma_f32_32x32x16_bf16 v[32:47], v[206:209], v[250:253], v[32:47]
	ds_read_b64_tr_b16 v[206:207], v219 offset:16384
	ds_read_b64_tr_b16 v[208:209], v219 offset:20480
	v_exp_f32_e32 v226, v226
	v_sub_f32_e32 v227, v227, v190
	v_add_f32_e32 v254, v225, v254
	v_exp_f32_e32 v227, v227
	v_sub_f32_e32 v228, v228, v190
	s_waitcnt lgkmcnt(8)
	v_mfma_f32_32x32x16_bf16 v[16:31], v[210:213], v[250:253], v[16:31]
	ds_read_b64_tr_b16 v[210:211], v221 offset:16384
	ds_read_b64_tr_b16 v[212:213], v221 offset:20480
	v_add_f32_e32 v254, v226, v254
	v_exp_f32_e32 v228, v228
	v_sub_f32_e32 v229, v229, v190
	v_add_f32_e32 v254, v227, v254
	v_exp_f32_e32 v229, v229
	s_waitcnt lgkmcnt(8)
	v_mfma_f32_32x32x16_bf16 v[0:15], v[214:217], v[250:253], v[0:15]
	ds_read_b64_tr_b16 v[214:215], v205 offset:16640
	ds_read_b64_tr_b16 v[216:217], v205 offset:20736
	s_nop 0
	v_cvt_pk_bf16_f32 v242, v222, v223
	v_cvt_pk_bf16_f32 v243, v224, v225
	v_cvt_pk_bf16_f32 v244, v226, v227
	v_cvt_pk_bf16_f32 v245, v228, v229
	s_nop 1
	s_waitcnt lgkmcnt(8)
	v_mfma_f32_32x32x16_bf16 v[112:127], v[238:241], v[242:245], v[112:127]
	ds_read_b64_tr_b16 v[238:239], v218 offset:16640
	ds_read_b64_tr_b16 v[240:241], v218 offset:20736
	v_sub_f32_e32 v230, v230, v190
	v_add_f32_e32 v254, v228, v254
	v_exp_f32_e32 v230, v230
	v_sub_f32_e32 v231, v231, v190
	v_add_f32_e32 v254, v229, v254
	s_waitcnt lgkmcnt(8)
	v_mfma_f32_32x32x16_bf16 v[96:111], v[128:131], v[242:245], v[96:111]
	ds_read_b64_tr_b16 v[128:129], v219 offset:16640
	ds_read_b64_tr_b16 v[130:131], v219 offset:20736
	v_exp_f32_e32 v231, v231
	v_sub_f32_e32 v232, v232, v190
	v_add_f32_e32 v254, v230, v254
	v_exp_f32_e32 v232, v232
	v_sub_f32_e32 v233, v233, v190
	s_cmp_lg_u64 s[18:19], 0
	s_cbranch_scc1 .Latt_nd0_4s2
	s_sub_i32 s100, s76, 1
	s_cmp_eq_u32 s76, 0
	s_cselect_b32 s100, 2, s100
	s_lshl_b32 s101, s100, 14
	s_add_i32 m0, s73, s101
	s_nop 0
	global_load_lds_dwordx4 v178, s[14:15]

.Latt_slow_4s2:
.Latt_slow_4:
	s_lshl_b32 s22, s76, 14
	s_add_i32 s23, s22, 0
	v_add_u32_e32 v206, s23, v194
	ds_read_b128 v[128:131], v206
	v_add_u32_e32 v207, s23, v195
	ds_read_b128 v[210:213], v207
	v_add_u32_e32 v208, s23, v196
	v_add_u32_e32 v209, s23, v197
	v_lshrrev_b32_e32 v204, 3, v203
	s_add_i32 s77, s39, 31
	v_and_or_b32 v205, v203, 31, s71
	s_cmp_le_i32 s77, s71
	s_waitcnt lgkmcnt(1)
	v_mfma_f32_32x32x16_bf16 v[128:143], v[128:131], v[144:147], 0
	ds_read_b128 v[214:217], v209
	s_waitcnt lgkmcnt(1)
	v_mfma_f32_32x32x16_bf16 v[128:143], v[210:213], v[148:151], v[128:143]
	ds_read_b128 v[210:213], v208
	s_waitcnt lgkmcnt(0)
	v_mfma_f32_32x32x16_bf16 v[128:143], v[210:213], v[152:155], v[128:143]
	v_add_u32_e32 v210, s23, v198
	v_add_u32_e32 v212, s23, v199
	v_add_u32_e32 v213, s23, v200
	v_and_b32_e32 v211, 4, v204
	ds_read_b128 v[222:225], v212
	v_mfma_f32_32x32x16_bf16 v[128:143], v[214:217], v[156:159], v[128:143]
	ds_read_b128 v[214:217], v210
	s_waitcnt lgkmcnt(0)
	v_mfma_f32_32x32x16_bf16 v[128:143], v[214:217], v[160:163], v[128:143]
	ds_read_b128 v[216:219], v213
	v_add_u32_e32 v214, s23, v201
	v_mfma_f32_32x32x16_bf16 v[128:143], v[222:225], v[164:167], v[128:143]
	ds_read_b128 v[222:225], v214
	s_waitcnt lgkmcnt(1)
	v_mfma_f32_32x32x16_bf16 v[128:143], v[216:219], v[168:171], v[128:143]
	s_waitcnt lgkmcnt(0)
	v_mfma_f32_32x32x16_bf16 v[128:143], v[222:225], v[172:175], v[128:143]
	s_cbranch_scc1 .LBB0_1804
	v_add_u32_e32 v204, s39, v211
	v_cmp_lt_i32_e32 vcc, v204, v205
	v_add_u32_e32 v215, 2, v204
	s_nop 7
	v_cndmask_b32_e32 v129, v192, v129, vcc
	v_cmp_le_i32_e32 vcc, v204, v205
	s_nop 1
	v_cndmask_b32_e32 v128, v192, v128, vcc
	v_cmp_le_i32_e32 vcc, v215, v205
	v_add_u32_e32 v215, 3, v204
	s_nop 0
	v_cndmask_b32_e32 v130, v192, v130, vcc
	v_cmp_le_i32_e32 vcc, v215, v205
	v_add_u32_e32 v215, 8, v204
	s_nop 0
	v_cndmask_b32_e32 v131, v192, v131, vcc
	v_cmp_le_i32_e32 vcc, v215, v205
	v_add_u32_e32 v215, 9, v204
	s_nop 0
	v_cndmask_b32_e32 v132, v192, v132, vcc
	v_cmp_le_i32_e32 vcc, v215, v205
	v_add_u32_e32 v215, 10, v204
	s_nop 0
	v_cndmask_b32_e32 v133, v192, v133, vcc
	v_cmp_le_i32_e32 vcc, v215, v205
	v_add_u32_e32 v215, 11, v204
	s_nop 0
	v_cndmask_b32_e32 v134, v192, v134, vcc
	v_cmp_le_i32_e32 vcc, v215, v205
	v_add_u32_e32 v215, 16, v204
	s_nop 0
	v_cndmask_b32_e32 v135, v192, v135, vcc
	v_cmp_le_i32_e32 vcc, v215, v205
	v_add_u32_e32 v215, 17, v204
	s_nop 0
	v_cndmask_b32_e32 v136, v192, v136, vcc
	v_cmp_le_i32_e32 vcc, v215, v205
	v_add_u32_e32 v215, 18, v204
	s_nop 0
	v_cndmask_b32_e32 v137, v192, v137, vcc
	v_cmp_le_i32_e32 vcc, v215, v205
	v_add_u32_e32 v215, 19, v204
	s_nop 0
	v_cndmask_b32_e32 v138, v192, v138, vcc
	v_cmp_le_i32_e32 vcc, v215, v205
	v_add_u32_e32 v215, 24, v204
	s_nop 0
	v_cndmask_b32_e32 v139, v192, v139, vcc
	v_cmp_le_i32_e32 vcc, v215, v205
	v_add_u32_e32 v215, 25, v204
	s_nop 0
	v_cndmask_b32_e32 v140, v192, v140, vcc
	v_cmp_le_i32_e32 vcc, v215, v205
	v_add_u32_e32 v215, 26, v204
	v_add_u32_e32 v204, 27, v204
	v_cndmask_b32_e32 v141, v192, v141, vcc
	v_cmp_le_i32_e32 vcc, v215, v205
	s_nop 1
	v_cndmask_b32_e32 v142, v192, v142, vcc
	v_cmp_le_i32_e32 vcc, v204, v205
	s_nop 1
	v_cndmask_b32_e32 v143, v192, v143, vcc

.LBB0_1820:
	s_cmp_gt_i32 s4, s72
	s_cbranch_scc1 .LBB0_1831
	s_add_i32 s100, s4, 63
	s_cmp_le_i32 s100, s71
	s_cbranch_scc0 .Latt_slow_5
	s_cmp_eq_u32 s33, 1
	s_cbranch_scc1 .Latt_slot1_5
	s_cmp_eq_u32 s33, 2
	s_cbranch_scc1 .Latt_slot2_5
	ds_read_b128 v[206:209], v196
	ds_read_b128 v[210:213], v197
	ds_read_b128 v[214:217], v198
	ds_read_b128 v[238:241], v199
	ds_read_b128 v[242:245], v200
	ds_read_b128 v[250:253], v201
	ds_read_b128 v[222:225], v202
	ds_read_b128 v[226:229], v203
	s_cmp_lg_u32 s4, 0
	s_cbranch_scc1 .Latt_vstep_5s0
	v_bfe_u32 v246, v204, 2, 2
	v_bfe_u32 v247, v204, 5, 1
	v_lshl_or_b32 v247, v247, 2, v246
	v_and_b32_e32 v249, 3, v204
	v_and_b32_e32 v254, 16, v204
	v_lshl_or_b32 v249, v249, 2, v254
	v_lshlrev_b32_e32 v249, 1, v249
	v_lshl_add_u32 v247, v247, 9, v249
	v_add_u32_e32 v247, 0xc000, v247
	v_lshlrev_b32_e32 v246, 6, v246
	v_add_u32_e32 v205, v247, v246
	v_xor_b32_e32 v249, 64, v246
	v_add_u32_e32 v218, v247, v249
	v_xor_b32_e32 v249, 0x80, v246
	v_add_u32_e32 v219, v247, v249
	v_xor_b32_e32 v249, 0xc0, v246
	v_add_u32_e32 v221, v247, v249
	s_branch .Latt_vdone_5s0

.Latt_nr0_5s0:
	s_waitcnt lgkmcnt(3)
	v_mfma_f32_32x32x16_bf16 v[222:237], v[214:217], v[152:155], v[222:237]
	ds_read_b128 v[214:217], v202 offset:8192
	v_sub_f32_e32 v128, v128, v190
	v_exp_f32_e32 v128, v128
	v_sub_f32_e32 v129, v129, v190
	v_exp_f32_e32 v129, v129
	v_sub_f32_e32 v130, v130, v190
	s_waitcnt lgkmcnt(3)
	v_mfma_f32_32x32x16_bf16 v[222:237], v[238:241], v[156:159], v[222:237]
	ds_read_b128 v[238:241], v203 offset:8192
	v_add_f32_e32 v254, 0, v128
	v_exp_f32_e32 v130, v130
	v_sub_f32_e32 v131, v131, v190
	v_add_f32_e32 v254, v129, v254
	v_exp_f32_e32 v131, v131
	s_waitcnt lgkmcnt(3)
	v_mfma_f32_32x32x16_bf16 v[222:237], v[206:209], v[160:163], v[222:237]
	ds_read_b64_tr_b16 v[206:207], v205
	ds_read_b64_tr_b16 v[208:209], v205 offset:4096
	v_sub_f32_e32 v132, v132, v190
	v_add_f32_e32 v254, v130, v254
	v_exp_f32_e32 v132, v132
	v_sub_f32_e32 v133, v133, v190
	v_add_f32_e32 v254, v131, v254
	s_waitcnt lgkmcnt(4)
	v_mfma_f32_32x32x16_bf16 v[222:237], v[210:213], v[164:167], v[222:237]
	ds_read_b64_tr_b16 v[210:211], v218
	ds_read_b64_tr_b16 v[212:213], v218 offset:4096
	v_exp_f32_e32 v133, v133
	v_sub_f32_e32 v134, v134, v190
	v_add_f32_e32 v254, v132, v254
	v_exp_f32_e32 v134, v134
	s_waitcnt lgkmcnt(5)
	v_mfma_f32_32x32x16_bf16 v[222:237], v[214:217], v[168:171], v[222:237]
	ds_read_b64_tr_b16 v[214:215], v219
	ds_read_b64_tr_b16 v[216:217], v219 offset:4096
	v_sub_f32_e32 v135, v135, v190
	v_add_f32_e32 v254, v133, v254
	v_exp_f32_e32 v135, v135
	s_nop 0
	s_waitcnt lgkmcnt(6)
	v_mfma_f32_32x32x16_bf16 v[222:237], v[238:241], v[172:175], v[222:237]
	ds_read_b64_tr_b16 v[238:239], v221
	ds_read_b64_tr_b16 v[240:241], v221 offset:4096
	v_cvt_pk_bf16_f32 v242, v128, v129
	v_cvt_pk_bf16_f32 v243, v130, v131
	v_cvt_pk_bf16_f32 v244, v132, v133
	v_cvt_pk_bf16_f32 v245, v134, v135
	s_nop 1
	s_waitcnt lgkmcnt(6)
	v_mfma_f32_32x32x16_bf16 v[112:127], v[206:209], v[242:245], v[112:127]
	ds_read_b64_tr_b16 v[206:207], v205 offset:256
	ds_read_b64_tr_b16 v[208:209], v205 offset:4352
	v_sub_f32_e32 v136, v136, v190
	v_add_f32_e32 v254, v134, v254
	v_exp_f32_e32 v136, v136
	v_sub_f32_e32 v137, v137, v190
	v_add_f32_e32 v254, v135, v254
	s_waitcnt lgkmcnt(6)
	v_mfma_f32_32x32x16_bf16 v[96:111], v[210:213], v[242:245], v[96:111]
	ds_read_b64_tr_b16 v[210:211], v218 offset:256
	ds_read_b64_tr_b16 v[212:213], v218 offset:4352
	v_exp_f32_e32 v137, v137
	v_sub_f32_e32 v138, v138, v190
	v_add_f32_e32 v254, v136, v254
	v_exp_f32_e32 v138, v138
	v_sub_f32_e32 v139, v139, v190
	s_waitcnt lgkmcnt(6)
	v_mfma_f32_32x32x16_bf16 v[80:95], v[214:217], v[242:245], v[80:95]
	ds_read_b64_tr_b16 v[214:215], v219 offset:256
	ds_read_b64_tr_b16 v[216:217], v219 offset:4352
	v_add_f32_e32 v254, v137, v254
	v_exp_f32_e32 v139, v139
	v_sub_f32_e32 v140, v140, v190
	v_add_f32_e32 v254, v138, v254
	s_waitcnt lgkmcnt(6)
	v_mfma_f32_32x32x16_bf16 v[64:79], v[238:241], v[242:245], v[64:79]
	ds_read_b64_tr_b16 v[238:239], v221 offset:256
	ds_read_b64_tr_b16 v[240:241], v221 offset:4352
	v_exp_f32_e32 v140, v140
	v_sub_f32_e32 v141, v141, v190
	v_add_f32_e32 v254, v139, v254
	v_exp_f32_e32 v141, v141
	s_waitcnt lgkmcnt(6)
	v_mfma_f32_32x32x16_bf16 v[48:63], v[206:209], v[242:245], v[48:63]
	ds_read_b64_tr_b16 v[206:207], v205 offset:8192
	ds_read_b64_tr_b16 v[208:209], v205 offset:12288
	v_sub_f32_e32 v142, v142, v190
	v_add_f32_e32 v254, v140, v254
	v_exp_f32_e32 v142, v142
	v_sub_f32_e32 v143, v143, v190
	s_waitcnt lgkmcnt(6)
	v_mfma_f32_32x32x16_bf16 v[32:47], v[210:213], v[242:245], v[32:47]
	ds_read_b64_tr_b16 v[210:211], v218 offset:8192
	ds_read_b64_tr_b16 v[212:213], v218 offset:12288
	v_add_f32_e32 v254, v141, v254
	v_exp_f32_e32 v143, v143
	v_add_f32_e32 v254, v142, v254
	v_add_f32_e32 v254, v143, v254
	s_waitcnt lgkmcnt(6)
	v_mfma_f32_32x32x16_bf16 v[16:31], v[214:217], v[242:245], v[16:31]
	ds_read_b64_tr_b16 v[214:215], v219 offset:8192
	ds_read_b64_tr_b16 v[216:217], v219 offset:12288
	v_cvt_pk_bf16_f32 v250, v136, v137
	v_cvt_pk_bf16_f32 v251, v138, v139
	v_cvt_pk_bf16_f32 v252, v140, v141
	v_cvt_pk_bf16_f32 v253, v142, v143
	v_add_f32_e32 v195, v195, v254
	s_waitcnt lgkmcnt(6)
	v_mfma_f32_32x32x16_bf16 v[0:15], v[238:241], v[242:245], v[0:15]
	ds_read_b64_tr_b16 v[238:239], v221 offset:8192
	ds_read_b64_tr_b16 v[240:241], v221 offset:12288
	ds_read_b64_tr_b16 v[128:129], v205 offset:8448
	ds_read_b64_tr_b16 v[130:131], v205 offset:12544
	s_waitcnt lgkmcnt(8)
	v_mfma_f32_32x32x16_bf16 v[112:127], v[206:209], v[250:253], v[112:127]
	ds_read_b64_tr_b16 v[206:207], v218 offset:8448
	ds_read_b64_tr_b16 v[208:209], v218 offset:12544
	v_max3_f32 v246, v222, v223, v224
	v_max3_f32 v247, v225, v226, v227
	v_max3_f32 v246, v246, v228, v229
	v_max3_f32 v247, v247, v230, v231
	v_max3_f32 v246, v246, v232, v233
	s_waitcnt lgkmcnt(8)
	v_mfma_f32_32x32x16_bf16 v[96:111], v[210:213], v[250:253], v[96:111]
	ds_read_b64_tr_b16 v[210:211], v219 offset:8448
	ds_read_b64_tr_b16 v[212:213], v219 offset:12544
	v_max3_f32 v247, v247, v234, v235
	v_max3_f32 v246, v246, v236, v237
	v_max_f32_e32 v246, v246, v247
	v_mov_b32_e32 v247, v246
	v_add_f32_e32 v249, 0x41000000, v190
	s_waitcnt lgkmcnt(8)
	v_mfma_f32_32x32x16_bf16 v[80:95], v[214:217], v[250:253], v[80:95]
	ds_read_b64_tr_b16 v[214:215], v221 offset:8448
	ds_read_b64_tr_b16 v[216:217], v221 offset:12544
	s_nop 1
	v_permlane32_swap_b32_e32 v246, v247
	v_max_f32_e32 v246, v246, v247
	v_cmp_gt_f32_e32 vcc, v246, v249
	s_cbranch_vccnz .Latt_rs1_5s0
	s_waitcnt lgkmcnt(8)
	v_mfma_f32_32x32x16_bf16 v[64:79], v[238:241], v[250:253], v[64:79]
	ds_read_b64_tr_b16 v[238:239], v205 offset:16384
	ds_read_b64_tr_b16 v[240:241], v205 offset:20480
	v_sub_f32_e32 v222, v222, v190
	v_exp_f32_e32 v222, v222
	v_sub_f32_e32 v223, v223, v190
	v_exp_f32_e32 v223, v223
	v_sub_f32_e32 v224, v224, v190
	v_add_f32_e32 v254, 0, v222
	s_waitcnt lgkmcnt(8)
	v_mfma_f32_32x32x16_bf16 v[48:63], v[128:131], v[250:253], v[48:63]
	ds_read_b64_tr_b16 v[128:129], v218 offset:16384
	ds_read_b64_tr_b16 v[130:131], v218 offset:20480
	v_exp_f32_e32 v224, v224
	v_sub_f32_e32 v225, v225, v190
	v_add_f32_e32 v254, v223, v254
	v_exp_f32_e32 v225, v225
	v_sub_f32_e32 v226, v226, v190
	v_add_f32_e32 v254, v224, v254
	s_waitcnt lgkmcnt(8)
	v_mfma_f32_32x32x16_bf16 v[32:47], v[206:209], v[250:253], v[32:47]
	ds_read_b64_tr_b16 v[206:207], v219 offset:16384
	ds_read_b64_tr_b16 v[208:209], v219 offset:20480
	v_exp_f32_e32 v226, v226
	v_sub_f32_e32 v227, v227, v190
	v_add_f32_e32 v254, v225, v254
	v_exp_f32_e32 v227, v227
	v_sub_f32_e32 v228, v228, v190
	s_waitcnt lgkmcnt(8)
	v_mfma_f32_32x32x16_bf16 v[16:31], v[210:213], v[250:253], v[16:31]
	ds_read_b64_tr_b16 v[210:211], v221 offset:16384
	ds_read_b64_tr_b16 v[212:213], v221 offset:20480
	v_add_f32_e32 v254, v226, v254
	v_exp_f32_e32 v228, v228
	v_sub_f32_e32 v229, v229, v190
	v_add_f32_e32 v254, v227, v254
	v_exp_f32_e32 v229, v229
	s_waitcnt lgkmcnt(8)
	v_mfma_f32_32x32x16_bf16 v[0:15], v[214:217], v[250:253], v[0:15]
	ds_read_b64_tr_b16 v[214:215], v205 offset:16640
	ds_read_b64_tr_b16 v[216:217], v205 offset:20736
	s_nop 0
	v_cvt_pk_bf16_f32 v242, v222, v223
	v_cvt_pk_bf16_f32 v243, v224, v225
	v_cvt_pk_bf16_f32 v244, v226, v227
	v_cvt_pk_bf16_f32 v245, v228, v229
	s_nop 1
	s_waitcnt lgkmcnt(8)
	v_mfma_f32_32x32x16_bf16 v[112:127], v[238:241], v[242:245], v[112:127]
	ds_read_b64_tr_b16 v[238:239], v218 offset:16640
	ds_read_b64_tr_b16 v[240:241], v218 offset:20736
	v_sub_f32_e32 v230, v230, v190
	v_add_f32_e32 v254, v228, v254
	v_exp_f32_e32 v230, v230
	v_sub_f32_e32 v231, v231, v190
	v_add_f32_e32 v254, v229, v254
	s_waitcnt lgkmcnt(8)
	v_mfma_f32_32x32x16_bf16 v[96:111], v[128:131], v[242:245], v[96:111]
	ds_read_b64_tr_b16 v[128:129], v219 offset:16640
	ds_read_b64_tr_b16 v[130:131], v219 offset:20736
	v_exp_f32_e32 v231, v231
	v_sub_f32_e32 v232, v232, v190
	v_add_f32_e32 v254, v230, v254
	v_exp_f32_e32 v232, v232
	v_sub_f32_e32 v233, v233, v190
	s_cmp_lg_u64 s[18:19], 0
	s_cbranch_scc1 .Latt_nd0_5s0
	s_sub_i32 s100, s33, 1
	s_cmp_eq_u32 s33, 0
	s_cselect_b32 s100, 2, s100
	s_lshl_b32 s101, s100, 14
	s_add_i32 m0, s73, s101
	s_nop 0
	global_load_lds_dwordx4 v178, s[12:13]

.Latt_nr0_5s1:
	s_waitcnt lgkmcnt(3)
	v_mfma_f32_32x32x16_bf16 v[222:237], v[214:217], v[152:155], v[222:237]
	ds_read_b128 v[214:217], v202 offset:24576
	v_sub_f32_e32 v128, v128, v190
	v_exp_f32_e32 v128, v128
	v_sub_f32_e32 v129, v129, v190
	v_exp_f32_e32 v129, v129
	v_sub_f32_e32 v130, v130, v190
	s_waitcnt lgkmcnt(3)
	v_mfma_f32_32x32x16_bf16 v[222:237], v[238:241], v[156:159], v[222:237]
	ds_read_b128 v[238:241], v203 offset:24576
	v_add_f32_e32 v254, 0, v128
	v_exp_f32_e32 v130, v130
	v_sub_f32_e32 v131, v131, v190
	v_add_f32_e32 v254, v129, v254
	v_exp_f32_e32 v131, v131
	s_waitcnt lgkmcnt(3)
	v_mfma_f32_32x32x16_bf16 v[222:237], v[206:209], v[160:163], v[222:237]
	ds_read_b64_tr_b16 v[206:207], v205
	ds_read_b64_tr_b16 v[208:209], v205 offset:4096
	v_sub_f32_e32 v132, v132, v190
	v_add_f32_e32 v254, v130, v254
	v_exp_f32_e32 v132, v132
	v_sub_f32_e32 v133, v133, v190
	v_add_f32_e32 v254, v131, v254
	s_waitcnt lgkmcnt(4)
	v_mfma_f32_32x32x16_bf16 v[222:237], v[210:213], v[164:167], v[222:237]
	ds_read_b64_tr_b16 v[210:211], v218
	ds_read_b64_tr_b16 v[212:213], v218 offset:4096
	v_exp_f32_e32 v133, v133
	v_sub_f32_e32 v134, v134, v190
	v_add_f32_e32 v254, v132, v254
	v_exp_f32_e32 v134, v134
	s_waitcnt lgkmcnt(5)
	v_mfma_f32_32x32x16_bf16 v[222:237], v[214:217], v[168:171], v[222:237]
	ds_read_b64_tr_b16 v[214:215], v219
	ds_read_b64_tr_b16 v[216:217], v219 offset:4096
	v_sub_f32_e32 v135, v135, v190
	v_add_f32_e32 v254, v133, v254
	v_exp_f32_e32 v135, v135
	s_nop 0
	s_waitcnt lgkmcnt(6)
	v_mfma_f32_32x32x16_bf16 v[222:237], v[238:241], v[172:175], v[222:237]
	ds_read_b64_tr_b16 v[238:239], v221
	ds_read_b64_tr_b16 v[240:241], v221 offset:4096
	v_cvt_pk_bf16_f32 v242, v128, v129
	v_cvt_pk_bf16_f32 v243, v130, v131
	v_cvt_pk_bf16_f32 v244, v132, v133
	v_cvt_pk_bf16_f32 v245, v134, v135
	s_nop 1
	s_waitcnt lgkmcnt(6)
	v_mfma_f32_32x32x16_bf16 v[112:127], v[206:209], v[242:245], v[112:127]
	ds_read_b64_tr_b16 v[206:207], v205 offset:256
	ds_read_b64_tr_b16 v[208:209], v205 offset:4352
	v_sub_f32_e32 v136, v136, v190
	v_add_f32_e32 v254, v134, v254
	v_exp_f32_e32 v136, v136
	v_sub_f32_e32 v137, v137, v190
	v_add_f32_e32 v254, v135, v254
	s_waitcnt lgkmcnt(6)
	v_mfma_f32_32x32x16_bf16 v[96:111], v[210:213], v[242:245], v[96:111]
	ds_read_b64_tr_b16 v[210:211], v218 offset:256
	ds_read_b64_tr_b16 v[212:213], v218 offset:4352
	v_exp_f32_e32 v137, v137
	v_sub_f32_e32 v138, v138, v190
	v_add_f32_e32 v254, v136, v254
	v_exp_f32_e32 v138, v138
	v_sub_f32_e32 v139, v139, v190
	s_waitcnt lgkmcnt(6)
	v_mfma_f32_32x32x16_bf16 v[80:95], v[214:217], v[242:245], v[80:95]
	ds_read_b64_tr_b16 v[214:215], v219 offset:256
	ds_read_b64_tr_b16 v[216:217], v219 offset:4352
	v_add_f32_e32 v254, v137, v254
	v_exp_f32_e32 v139, v139
	v_sub_f32_e32 v140, v140, v190
	v_add_f32_e32 v254, v138, v254
	s_waitcnt lgkmcnt(6)
	v_mfma_f32_32x32x16_bf16 v[64:79], v[238:241], v[242:245], v[64:79]
	ds_read_b64_tr_b16 v[238:239], v221 offset:256
	ds_read_b64_tr_b16 v[240:241], v221 offset:4352
	v_exp_f32_e32 v140, v140
	v_sub_f32_e32 v141, v141, v190
	v_add_f32_e32 v254, v139, v254
	v_exp_f32_e32 v141, v141
	s_waitcnt lgkmcnt(6)
	v_mfma_f32_32x32x16_bf16 v[48:63], v[206:209], v[242:245], v[48:63]
	ds_read_b64_tr_b16 v[206:207], v205 offset:8192
	ds_read_b64_tr_b16 v[208:209], v205 offset:12288
	v_sub_f32_e32 v142, v142, v190
	v_add_f32_e32 v254, v140, v254
	v_exp_f32_e32 v142, v142
	v_sub_f32_e32 v143, v143, v190
	s_waitcnt lgkmcnt(6)
	v_mfma_f32_32x32x16_bf16 v[32:47], v[210:213], v[242:245], v[32:47]
	ds_read_b64_tr_b16 v[210:211], v218 offset:8192
	ds_read_b64_tr_b16 v[212:213], v218 offset:12288
	v_add_f32_e32 v254, v141, v254
	v_exp_f32_e32 v143, v143
	v_add_f32_e32 v254, v142, v254
	v_add_f32_e32 v254, v143, v254
	s_waitcnt lgkmcnt(6)
	v_mfma_f32_32x32x16_bf16 v[16:31], v[214:217], v[242:245], v[16:31]
	ds_read_b64_tr_b16 v[214:215], v219 offset:8192
	ds_read_b64_tr_b16 v[216:217], v219 offset:12288
	v_cvt_pk_bf16_f32 v250, v136, v137
	v_cvt_pk_bf16_f32 v251, v138, v139
	v_cvt_pk_bf16_f32 v252, v140, v141
	v_cvt_pk_bf16_f32 v253, v142, v143
	v_add_f32_e32 v195, v195, v254
	s_waitcnt lgkmcnt(6)
	v_mfma_f32_32x32x16_bf16 v[0:15], v[238:241], v[242:245], v[0:15]
	ds_read_b64_tr_b16 v[238:239], v221 offset:8192
	ds_read_b64_tr_b16 v[240:241], v221 offset:12288
	ds_read_b64_tr_b16 v[128:129], v205 offset:8448
	ds_read_b64_tr_b16 v[130:131], v205 offset:12544
	s_waitcnt lgkmcnt(8)
	v_mfma_f32_32x32x16_bf16 v[112:127], v[206:209], v[250:253], v[112:127]
	ds_read_b64_tr_b16 v[206:207], v218 offset:8448
	ds_read_b64_tr_b16 v[208:209], v218 offset:12544
	v_max3_f32 v246, v222, v223, v224
	v_max3_f32 v247, v225, v226, v227
	v_max3_f32 v246, v246, v228, v229
	v_max3_f32 v247, v247, v230, v231
	v_max3_f32 v246, v246, v232, v233
	s_waitcnt lgkmcnt(8)
	v_mfma_f32_32x32x16_bf16 v[96:111], v[210:213], v[250:253], v[96:111]
	ds_read_b64_tr_b16 v[210:211], v219 offset:8448
	ds_read_b64_tr_b16 v[212:213], v219 offset:12544
	v_max3_f32 v247, v247, v234, v235
	v_max3_f32 v246, v246, v236, v237
	v_max_f32_e32 v246, v246, v247
	v_mov_b32_e32 v247, v246
	v_add_f32_e32 v249, 0x41000000, v190
	s_waitcnt lgkmcnt(8)
	v_mfma_f32_32x32x16_bf16 v[80:95], v[214:217], v[250:253], v[80:95]
	ds_read_b64_tr_b16 v[214:215], v221 offset:8448
	ds_read_b64_tr_b16 v[216:217], v221 offset:12544
	s_nop 1
	v_permlane32_swap_b32_e32 v246, v247
	v_max_f32_e32 v246, v246, v247
	v_cmp_gt_f32_e32 vcc, v246, v249
	s_cbranch_vccnz .Latt_rs1_5s1
	s_waitcnt lgkmcnt(8)
	v_mfma_f32_32x32x16_bf16 v[64:79], v[238:241], v[250:253], v[64:79]
	ds_read_b64_tr_b16 v[238:239], v205 offset:16384
	ds_read_b64_tr_b16 v[240:241], v205 offset:20480
	v_sub_f32_e32 v222, v222, v190
	v_exp_f32_e32 v222, v222
	v_sub_f32_e32 v223, v223, v190
	v_exp_f32_e32 v223, v223
	v_sub_f32_e32 v224, v224, v190
	v_add_f32_e32 v254, 0, v222
	s_waitcnt lgkmcnt(8)
	v_mfma_f32_32x32x16_bf16 v[48:63], v[128:131], v[250:253], v[48:63]
	ds_read_b64_tr_b16 v[128:129], v218 offset:16384
	ds_read_b64_tr_b16 v[130:131], v218 offset:20480
	v_exp_f32_e32 v224, v224
	v_sub_f32_e32 v225, v225, v190
	v_add_f32_e32 v254, v223, v254
	v_exp_f32_e32 v225, v225
	v_sub_f32_e32 v226, v226, v190
	v_add_f32_e32 v254, v224, v254
	s_waitcnt lgkmcnt(8)
	v_mfma_f32_32x32x16_bf16 v[32:47], v[206:209], v[250:253], v[32:47]
	ds_read_b64_tr_b16 v[206:207], v219 offset:16384
	ds_read_b64_tr_b16 v[208:209], v219 offset:20480
	v_exp_f32_e32 v226, v226
	v_sub_f32_e32 v227, v227, v190
	v_add_f32_e32 v254, v225, v254
	v_exp_f32_e32 v227, v227
	v_sub_f32_e32 v228, v228, v190
	s_waitcnt lgkmcnt(8)
	v_mfma_f32_32x32x16_bf16 v[16:31], v[210:213], v[250:253], v[16:31]
	ds_read_b64_tr_b16 v[210:211], v221 offset:16384
	ds_read_b64_tr_b16 v[212:213], v221 offset:20480
	v_add_f32_e32 v254, v226, v254
	v_exp_f32_e32 v228, v228
	v_sub_f32_e32 v229, v229, v190
	v_add_f32_e32 v254, v227, v254
	v_exp_f32_e32 v229, v229
	s_waitcnt lgkmcnt(8)
	v_mfma_f32_32x32x16_bf16 v[0:15], v[214:217], v[250:253], v[0:15]
	ds_read_b64_tr_b16 v[214:215], v205 offset:16640
	ds_read_b64_tr_b16 v[216:217], v205 offset:20736
	s_nop 0
	v_cvt_pk_bf16_f32 v242, v222, v223
	v_cvt_pk_bf16_f32 v243, v224, v225
	v_cvt_pk_bf16_f32 v244, v226, v227
	v_cvt_pk_bf16_f32 v245, v228, v229
	s_nop 1
	s_waitcnt lgkmcnt(8)
	v_mfma_f32_32x32x16_bf16 v[112:127], v[238:241], v[242:245], v[112:127]
	ds_read_b64_tr_b16 v[238:239], v218 offset:16640
	ds_read_b64_tr_b16 v[240:241], v218 offset:20736
	v_sub_f32_e32 v230, v230, v190
	v_add_f32_e32 v254, v228, v254
	v_exp_f32_e32 v230, v230
	v_sub_f32_e32 v231, v231, v190
	v_add_f32_e32 v254, v229, v254
	s_waitcnt lgkmcnt(8)
	v_mfma_f32_32x32x16_bf16 v[96:111], v[128:131], v[242:245], v[96:111]
	ds_read_b64_tr_b16 v[128:129], v219 offset:16640
	ds_read_b64_tr_b16 v[130:131], v219 offset:20736
	v_exp_f32_e32 v231, v231
	v_sub_f32_e32 v232, v232, v190
	v_add_f32_e32 v254, v230, v254
	v_exp_f32_e32 v232, v232
	v_sub_f32_e32 v233, v233, v190
	s_cmp_lg_u64 s[18:19], 0
	s_cbranch_scc1 .Latt_nd0_5s1
	s_sub_i32 s100, s33, 1
	s_cmp_eq_u32 s33, 0
	s_cselect_b32 s100, 2, s100
	s_lshl_b32 s101, s100, 14
	s_add_i32 m0, s73, s101
	s_nop 0
	global_load_lds_dwordx4 v178, s[12:13]

.Latt_nr0_5s2:
	s_waitcnt lgkmcnt(3)
	v_mfma_f32_32x32x16_bf16 v[222:237], v[214:217], v[152:155], v[222:237]
	ds_read_b128 v[214:217], v202 offset:40960
	v_sub_f32_e32 v128, v128, v190
	v_exp_f32_e32 v128, v128
	v_sub_f32_e32 v129, v129, v190
	v_exp_f32_e32 v129, v129
	v_sub_f32_e32 v130, v130, v190
	s_waitcnt lgkmcnt(3)
	v_mfma_f32_32x32x16_bf16 v[222:237], v[238:241], v[156:159], v[222:237]
	ds_read_b128 v[238:241], v203 offset:40960
	v_add_f32_e32 v254, 0, v128
	v_exp_f32_e32 v130, v130
	v_sub_f32_e32 v131, v131, v190
	v_add_f32_e32 v254, v129, v254
	v_exp_f32_e32 v131, v131
	s_waitcnt lgkmcnt(3)
	v_mfma_f32_32x32x16_bf16 v[222:237], v[206:209], v[160:163], v[222:237]
	ds_read_b64_tr_b16 v[206:207], v205
	ds_read_b64_tr_b16 v[208:209], v205 offset:4096
	v_sub_f32_e32 v132, v132, v190
	v_add_f32_e32 v254, v130, v254
	v_exp_f32_e32 v132, v132
	v_sub_f32_e32 v133, v133, v190
	v_add_f32_e32 v254, v131, v254
	s_waitcnt lgkmcnt(4)
	v_mfma_f32_32x32x16_bf16 v[222:237], v[210:213], v[164:167], v[222:237]
	ds_read_b64_tr_b16 v[210:211], v218
	ds_read_b64_tr_b16 v[212:213], v218 offset:4096
	v_exp_f32_e32 v133, v133
	v_sub_f32_e32 v134, v134, v190
	v_add_f32_e32 v254, v132, v254
	v_exp_f32_e32 v134, v134
	s_waitcnt lgkmcnt(5)
	v_mfma_f32_32x32x16_bf16 v[222:237], v[214:217], v[168:171], v[222:237]
	ds_read_b64_tr_b16 v[214:215], v219
	ds_read_b64_tr_b16 v[216:217], v219 offset:4096
	v_sub_f32_e32 v135, v135, v190
	v_add_f32_e32 v254, v133, v254
	v_exp_f32_e32 v135, v135
	s_nop 0
	s_waitcnt lgkmcnt(6)
	v_mfma_f32_32x32x16_bf16 v[222:237], v[238:241], v[172:175], v[222:237]
	ds_read_b64_tr_b16 v[238:239], v221
	ds_read_b64_tr_b16 v[240:241], v221 offset:4096
	v_cvt_pk_bf16_f32 v242, v128, v129
	v_cvt_pk_bf16_f32 v243, v130, v131
	v_cvt_pk_bf16_f32 v244, v132, v133
	v_cvt_pk_bf16_f32 v245, v134, v135
	s_nop 1
	s_waitcnt lgkmcnt(6)
	v_mfma_f32_32x32x16_bf16 v[112:127], v[206:209], v[242:245], v[112:127]
	ds_read_b64_tr_b16 v[206:207], v205 offset:256
	ds_read_b64_tr_b16 v[208:209], v205 offset:4352
	v_sub_f32_e32 v136, v136, v190
	v_add_f32_e32 v254, v134, v254
	v_exp_f32_e32 v136, v136
	v_sub_f32_e32 v137, v137, v190
	v_add_f32_e32 v254, v135, v254
	s_waitcnt lgkmcnt(6)
	v_mfma_f32_32x32x16_bf16 v[96:111], v[210:213], v[242:245], v[96:111]
	ds_read_b64_tr_b16 v[210:211], v218 offset:256
	ds_read_b64_tr_b16 v[212:213], v218 offset:4352
	v_exp_f32_e32 v137, v137
	v_sub_f32_e32 v138, v138, v190
	v_add_f32_e32 v254, v136, v254
	v_exp_f32_e32 v138, v138
	v_sub_f32_e32 v139, v139, v190
	s_waitcnt lgkmcnt(6)
	v_mfma_f32_32x32x16_bf16 v[80:95], v[214:217], v[242:245], v[80:95]
	ds_read_b64_tr_b16 v[214:215], v219 offset:256
	ds_read_b64_tr_b16 v[216:217], v219 offset:4352
	v_add_f32_e32 v254, v137, v254
	v_exp_f32_e32 v139, v139
	v_sub_f32_e32 v140, v140, v190
	v_add_f32_e32 v254, v138, v254
	s_waitcnt lgkmcnt(6)
	v_mfma_f32_32x32x16_bf16 v[64:79], v[238:241], v[242:245], v[64:79]
	ds_read_b64_tr_b16 v[238:239], v221 offset:256
	ds_read_b64_tr_b16 v[240:241], v221 offset:4352
	v_exp_f32_e32 v140, v140
	v_sub_f32_e32 v141, v141, v190
	v_add_f32_e32 v254, v139, v254
	v_exp_f32_e32 v141, v141
	s_waitcnt lgkmcnt(6)
	v_mfma_f32_32x32x16_bf16 v[48:63], v[206:209], v[242:245], v[48:63]
	ds_read_b64_tr_b16 v[206:207], v205 offset:8192
	ds_read_b64_tr_b16 v[208:209], v205 offset:12288
	v_sub_f32_e32 v142, v142, v190
	v_add_f32_e32 v254, v140, v254
	v_exp_f32_e32 v142, v142
	v_sub_f32_e32 v143, v143, v190
	s_waitcnt lgkmcnt(6)
	v_mfma_f32_32x32x16_bf16 v[32:47], v[210:213], v[242:245], v[32:47]
	ds_read_b64_tr_b16 v[210:211], v218 offset:8192
	ds_read_b64_tr_b16 v[212:213], v218 offset:12288
	v_add_f32_e32 v254, v141, v254
	v_exp_f32_e32 v143, v143
	v_add_f32_e32 v254, v142, v254
	v_add_f32_e32 v254, v143, v254
	s_waitcnt lgkmcnt(6)
	v_mfma_f32_32x32x16_bf16 v[16:31], v[214:217], v[242:245], v[16:31]
	ds_read_b64_tr_b16 v[214:215], v219 offset:8192
	ds_read_b64_tr_b16 v[216:217], v219 offset:12288
	v_cvt_pk_bf16_f32 v250, v136, v137
	v_cvt_pk_bf16_f32 v251, v138, v139
	v_cvt_pk_bf16_f32 v252, v140, v141
	v_cvt_pk_bf16_f32 v253, v142, v143
	v_add_f32_e32 v195, v195, v254
	s_waitcnt lgkmcnt(6)
	v_mfma_f32_32x32x16_bf16 v[0:15], v[238:241], v[242:245], v[0:15]
	ds_read_b64_tr_b16 v[238:239], v221 offset:8192
	ds_read_b64_tr_b16 v[240:241], v221 offset:12288
	ds_read_b64_tr_b16 v[128:129], v205 offset:8448
	ds_read_b64_tr_b16 v[130:131], v205 offset:12544
	s_waitcnt lgkmcnt(8)
	v_mfma_f32_32x32x16_bf16 v[112:127], v[206:209], v[250:253], v[112:127]
	ds_read_b64_tr_b16 v[206:207], v218 offset:8448
	ds_read_b64_tr_b16 v[208:209], v218 offset:12544
	v_max3_f32 v246, v222, v223, v224
	v_max3_f32 v247, v225, v226, v227
	v_max3_f32 v246, v246, v228, v229
	v_max3_f32 v247, v247, v230, v231
	v_max3_f32 v246, v246, v232, v233
	s_waitcnt lgkmcnt(8)
	v_mfma_f32_32x32x16_bf16 v[96:111], v[210:213], v[250:253], v[96:111]
	ds_read_b64_tr_b16 v[210:211], v219 offset:8448
	ds_read_b64_tr_b16 v[212:213], v219 offset:12544
	v_max3_f32 v247, v247, v234, v235
	v_max3_f32 v246, v246, v236, v237
	v_max_f32_e32 v246, v246, v247
	v_mov_b32_e32 v247, v246
	v_add_f32_e32 v249, 0x41000000, v190
	s_waitcnt lgkmcnt(8)
	v_mfma_f32_32x32x16_bf16 v[80:95], v[214:217], v[250:253], v[80:95]
	ds_read_b64_tr_b16 v[214:215], v221 offset:8448
	ds_read_b64_tr_b16 v[216:217], v221 offset:12544
	s_nop 1
	v_permlane32_swap_b32_e32 v246, v247
	v_max_f32_e32 v246, v246, v247
	v_cmp_gt_f32_e32 vcc, v246, v249
	s_cbranch_vccnz .Latt_rs1_5s2
	s_waitcnt lgkmcnt(8)
	v_mfma_f32_32x32x16_bf16 v[64:79], v[238:241], v[250:253], v[64:79]
	ds_read_b64_tr_b16 v[238:239], v205 offset:16384
	ds_read_b64_tr_b16 v[240:241], v205 offset:20480
	v_sub_f32_e32 v222, v222, v190
	v_exp_f32_e32 v222, v222
	v_sub_f32_e32 v223, v223, v190
	v_exp_f32_e32 v223, v223
	v_sub_f32_e32 v224, v224, v190
	v_add_f32_e32 v254, 0, v222
	s_waitcnt lgkmcnt(8)
	v_mfma_f32_32x32x16_bf16 v[48:63], v[128:131], v[250:253], v[48:63]
	ds_read_b64_tr_b16 v[128:129], v218 offset:16384
	ds_read_b64_tr_b16 v[130:131], v218 offset:20480
	v_exp_f32_e32 v224, v224
	v_sub_f32_e32 v225, v225, v190
	v_add_f32_e32 v254, v223, v254
	v_exp_f32_e32 v225, v225
	v_sub_f32_e32 v226, v226, v190
	v_add_f32_e32 v254, v224, v254
	s_waitcnt lgkmcnt(8)
	v_mfma_f32_32x32x16_bf16 v[32:47], v[206:209], v[250:253], v[32:47]
	ds_read_b64_tr_b16 v[206:207], v219 offset:16384
	ds_read_b64_tr_b16 v[208:209], v219 offset:20480
	v_exp_f32_e32 v226, v226
	v_sub_f32_e32 v227, v227, v190
	v_add_f32_e32 v254, v225, v254
	v_exp_f32_e32 v227, v227
	v_sub_f32_e32 v228, v228, v190
	s_waitcnt lgkmcnt(8)
	v_mfma_f32_32x32x16_bf16 v[16:31], v[210:213], v[250:253], v[16:31]
	ds_read_b64_tr_b16 v[210:211], v221 offset:16384
	ds_read_b64_tr_b16 v[212:213], v221 offset:20480
	v_add_f32_e32 v254, v226, v254
	v_exp_f32_e32 v228, v228
	v_sub_f32_e32 v229, v229, v190
	v_add_f32_e32 v254, v227, v254
	v_exp_f32_e32 v229, v229
	s_waitcnt lgkmcnt(8)
	v_mfma_f32_32x32x16_bf16 v[0:15], v[214:217], v[250:253], v[0:15]
	ds_read_b64_tr_b16 v[214:215], v205 offset:16640
	ds_read_b64_tr_b16 v[216:217], v205 offset:20736
	s_nop 0
	v_cvt_pk_bf16_f32 v242, v222, v223
	v_cvt_pk_bf16_f32 v243, v224, v225
	v_cvt_pk_bf16_f32 v244, v226, v227
	v_cvt_pk_bf16_f32 v245, v228, v229
	s_nop 1
	s_waitcnt lgkmcnt(8)
	v_mfma_f32_32x32x16_bf16 v[112:127], v[238:241], v[242:245], v[112:127]
	ds_read_b64_tr_b16 v[238:239], v218 offset:16640
	ds_read_b64_tr_b16 v[240:241], v218 offset:20736
	v_sub_f32_e32 v230, v230, v190
	v_add_f32_e32 v254, v228, v254
	v_exp_f32_e32 v230, v230
	v_sub_f32_e32 v231, v231, v190
	v_add_f32_e32 v254, v229, v254
	s_waitcnt lgkmcnt(8)
	v_mfma_f32_32x32x16_bf16 v[96:111], v[128:131], v[242:245], v[96:111]
	ds_read_b64_tr_b16 v[128:129], v219 offset:16640
	ds_read_b64_tr_b16 v[130:131], v219 offset:20736
	v_exp_f32_e32 v231, v231
	v_sub_f32_e32 v232, v232, v190
	v_add_f32_e32 v254, v230, v254
	v_exp_f32_e32 v232, v232
	v_sub_f32_e32 v233, v233, v190
	s_cmp_lg_u64 s[18:19], 0
	s_cbranch_scc1 .Latt_nd0_5s2
	s_sub_i32 s100, s33, 1
	s_cmp_eq_u32 s33, 0
	s_cselect_b32 s100, 2, s100
	s_lshl_b32 s101, s100, 14
	s_add_i32 m0, s73, s101
	s_nop 0
	global_load_lds_dwordx4 v178, s[12:13]

.Latt_slow_5s2:
.Latt_slow_5:
	s_lshl_b32 s77, s33, 14
	s_add_i32 s78, s77, 0
	v_add_u32_e32 v207, s78, v196
	ds_read_b128 v[128:131], v207
	v_add_u32_e32 v208, s78, v197
	ds_read_b128 v[210:213], v208
	v_add_u32_e32 v209, s78, v198
	v_lshrrev_b32_e32 v205, 3, v204
	s_add_i32 s79, s4, 31
	v_and_or_b32 v206, v204, 31, s71
	s_cmp_le_i32 s79, s71
	s_waitcnt lgkmcnt(1)
	v_mfma_f32_32x32x16_bf16 v[128:143], v[128:131], v[144:147], 0
	s_waitcnt lgkmcnt(0)
	v_mfma_f32_32x32x16_bf16 v[128:143], v[210:213], v[148:151], v[128:143]
	ds_read_b128 v[212:215], v209
	v_add_u32_e32 v210, s78, v199
	ds_read_b128 v[216:219], v210
	v_add_u32_e32 v211, s78, v200
	s_waitcnt lgkmcnt(1)
	v_mfma_f32_32x32x16_bf16 v[128:143], v[212:215], v[152:155], v[128:143]
	v_add_u32_e32 v213, s78, v201
	v_and_b32_e32 v212, 4, v205
	ds_read_b128 v[222:225], v213
	s_waitcnt lgkmcnt(1)
	v_mfma_f32_32x32x16_bf16 v[128:143], v[216:219], v[156:159], v[128:143]
	ds_read_b128 v[214:217], v211
	s_waitcnt lgkmcnt(0)
	v_mfma_f32_32x32x16_bf16 v[128:143], v[214:217], v[160:163], v[128:143]
	v_add_u32_e32 v214, s78, v202
	ds_read_b128 v[216:219], v214
	v_add_u32_e32 v215, s78, v203
	v_mfma_f32_32x32x16_bf16 v[128:143], v[222:225], v[164:167], v[128:143]
	ds_read_b128 v[222:225], v215
	s_waitcnt lgkmcnt(1)
	v_mfma_f32_32x32x16_bf16 v[128:143], v[216:219], v[168:171], v[128:143]
	s_waitcnt lgkmcnt(0)
	v_mfma_f32_32x32x16_bf16 v[128:143], v[222:225], v[172:175], v[128:143]
	s_cbranch_scc1 .LBB0_1823
	v_add_u32_e32 v205, s4, v212
	v_cmp_lt_i32_e32 vcc, v205, v206
	v_add_u32_e32 v216, 2, v205
	s_nop 7
	v_cndmask_b32_e32 v129, v192, v129, vcc
	v_cmp_le_i32_e32 vcc, v205, v206
	s_nop 1
	v_cndmask_b32_e32 v128, v192, v128, vcc
	v_cmp_le_i32_e32 vcc, v216, v206
	v_add_u32_e32 v216, 3, v205
	s_nop 0
	v_cndmask_b32_e32 v130, v192, v130, vcc
	v_cmp_le_i32_e32 vcc, v216, v206
	v_add_u32_e32 v216, 8, v205
	s_nop 0
	v_cndmask_b32_e32 v131, v192, v131, vcc
	v_cmp_le_i32_e32 vcc, v216, v206
	v_add_u32_e32 v216, 9, v205
	s_nop 0
	v_cndmask_b32_e32 v132, v192, v132, vcc
	v_cmp_le_i32_e32 vcc, v216, v206
	v_add_u32_e32 v216, 10, v205
	s_nop 0
	v_cndmask_b32_e32 v133, v192, v133, vcc
	v_cmp_le_i32_e32 vcc, v216, v206
	v_add_u32_e32 v216, 11, v205
	s_nop 0
	v_cndmask_b32_e32 v134, v192, v134, vcc
	v_cmp_le_i32_e32 vcc, v216, v206
	v_add_u32_e32 v216, 16, v205
	s_nop 0
	v_cndmask_b32_e32 v135, v192, v135, vcc
	v_cmp_le_i32_e32 vcc, v216, v206
	v_add_u32_e32 v216, 17, v205
	s_nop 0
	v_cndmask_b32_e32 v136, v192, v136, vcc
	v_cmp_le_i32_e32 vcc, v216, v206
	v_add_u32_e32 v216, 18, v205
	s_nop 0
	v_cndmask_b32_e32 v137, v192, v137, vcc
	v_cmp_le_i32_e32 vcc, v216, v206
	v_add_u32_e32 v216, 19, v205
	s_nop 0
	v_cndmask_b32_e32 v138, v192, v138, vcc
	v_cmp_le_i32_e32 vcc, v216, v206
	v_add_u32_e32 v216, 24, v205
	s_nop 0
	v_cndmask_b32_e32 v139, v192, v139, vcc
	v_cmp_le_i32_e32 vcc, v216, v206
	v_add_u32_e32 v216, 25, v205
	s_nop 0
	v_cndmask_b32_e32 v140, v192, v140, vcc
	v_cmp_le_i32_e32 vcc, v216, v206
	v_add_u32_e32 v216, 26, v205
	v_add_u32_e32 v205, 27, v205
	v_cndmask_b32_e32 v141, v192, v141, vcc
	v_cmp_le_i32_e32 vcc, v216, v206
	s_nop 1
	v_cndmask_b32_e32 v142, v192, v142, vcc
	v_cmp_le_i32_e32 vcc, v205, v206
	s_nop 1
	v_cndmask_b32_e32 v143, v192, v143, vcc

.LBB0_1839:
	s_cmp_gt_i32 s72, s69
	s_cbranch_scc1 .LBB0_1850
	s_add_i32 s100, s72, 63
	s_cmp_le_i32 s100, s68
	s_cbranch_scc0 .Latt_slow_6
	s_cmp_eq_u32 s34, 1
	s_cbranch_scc1 .Latt_slot1_6
	s_cmp_eq_u32 s34, 2
	s_cbranch_scc1 .Latt_slot2_6
	ds_read_b128 v[206:209], v195
	ds_read_b128 v[210:213], v196
	ds_read_b128 v[214:217], v197
	ds_read_b128 v[238:241], v198
	ds_read_b128 v[242:245], v199
	ds_read_b128 v[250:253], v200
	ds_read_b128 v[222:225], v201
	ds_read_b128 v[226:229], v202
	s_cmp_lg_u32 s72, 0
	s_cbranch_scc1 .Latt_vstep_6s0
	v_bfe_u32 v246, v204, 2, 2
	v_bfe_u32 v247, v204, 5, 1
	v_lshl_or_b32 v247, v247, 2, v246
	v_and_b32_e32 v249, 3, v204
	v_and_b32_e32 v254, 16, v204
	v_lshl_or_b32 v249, v249, 2, v254
	v_lshlrev_b32_e32 v249, 1, v249
	v_lshl_add_u32 v247, v247, 9, v249
	v_add_u32_e32 v247, 0xc000, v247
	v_lshlrev_b32_e32 v246, 6, v246
	v_add_u32_e32 v205, v247, v246
	v_xor_b32_e32 v249, 64, v246
	v_add_u32_e32 v218, v247, v249
	v_xor_b32_e32 v249, 0x80, v246
	v_add_u32_e32 v219, v247, v249
	v_xor_b32_e32 v249, 0xc0, v246
	v_add_u32_e32 v221, v247, v249
	s_branch .Latt_vdone_6s0

.Latt_nr0_6s0:
	s_waitcnt lgkmcnt(3)
	v_mfma_f32_32x32x16_bf16 v[222:237], v[214:217], v[152:155], v[222:237]
	ds_read_b128 v[214:217], v201 offset:8192
	v_sub_f32_e32 v128, v128, v190
	v_exp_f32_e32 v128, v128
	v_sub_f32_e32 v129, v129, v190
	v_exp_f32_e32 v129, v129
	v_sub_f32_e32 v130, v130, v190
	s_waitcnt lgkmcnt(3)
	v_mfma_f32_32x32x16_bf16 v[222:237], v[238:241], v[156:159], v[222:237]
	ds_read_b128 v[238:241], v202 offset:8192
	v_add_f32_e32 v254, 0, v128
	v_exp_f32_e32 v130, v130
	v_sub_f32_e32 v131, v131, v190
	v_add_f32_e32 v254, v129, v254
	v_exp_f32_e32 v131, v131
	s_waitcnt lgkmcnt(3)
	v_mfma_f32_32x32x16_bf16 v[222:237], v[206:209], v[160:163], v[222:237]
	ds_read_b64_tr_b16 v[206:207], v205
	ds_read_b64_tr_b16 v[208:209], v205 offset:4096
	v_sub_f32_e32 v132, v132, v190
	v_add_f32_e32 v254, v130, v254
	v_exp_f32_e32 v132, v132
	v_sub_f32_e32 v133, v133, v190
	v_add_f32_e32 v254, v131, v254
	s_waitcnt lgkmcnt(4)
	v_mfma_f32_32x32x16_bf16 v[222:237], v[210:213], v[164:167], v[222:237]
	ds_read_b64_tr_b16 v[210:211], v218
	ds_read_b64_tr_b16 v[212:213], v218 offset:4096
	v_exp_f32_e32 v133, v133
	v_sub_f32_e32 v134, v134, v190
	v_add_f32_e32 v254, v132, v254
	v_exp_f32_e32 v134, v134
	s_waitcnt lgkmcnt(5)
	v_mfma_f32_32x32x16_bf16 v[222:237], v[214:217], v[168:171], v[222:237]
	ds_read_b64_tr_b16 v[214:215], v219
	ds_read_b64_tr_b16 v[216:217], v219 offset:4096
	v_sub_f32_e32 v135, v135, v190
	v_add_f32_e32 v254, v133, v254
	v_exp_f32_e32 v135, v135
	s_nop 0
	s_waitcnt lgkmcnt(6)
	v_mfma_f32_32x32x16_bf16 v[222:237], v[238:241], v[172:175], v[222:237]
	ds_read_b64_tr_b16 v[238:239], v221
	ds_read_b64_tr_b16 v[240:241], v221 offset:4096
	v_cvt_pk_bf16_f32 v242, v128, v129
	v_cvt_pk_bf16_f32 v243, v130, v131
	v_cvt_pk_bf16_f32 v244, v132, v133
	v_cvt_pk_bf16_f32 v245, v134, v135
	s_nop 1
	s_waitcnt lgkmcnt(6)
	v_mfma_f32_32x32x16_bf16 v[112:127], v[206:209], v[242:245], v[112:127]
	ds_read_b64_tr_b16 v[206:207], v205 offset:256
	ds_read_b64_tr_b16 v[208:209], v205 offset:4352
	v_sub_f32_e32 v136, v136, v190
	v_add_f32_e32 v254, v134, v254
	v_exp_f32_e32 v136, v136
	v_sub_f32_e32 v137, v137, v190
	v_add_f32_e32 v254, v135, v254
	s_waitcnt lgkmcnt(6)
	v_mfma_f32_32x32x16_bf16 v[96:111], v[210:213], v[242:245], v[96:111]
	ds_read_b64_tr_b16 v[210:211], v218 offset:256
	ds_read_b64_tr_b16 v[212:213], v218 offset:4352
	v_exp_f32_e32 v137, v137
	v_sub_f32_e32 v138, v138, v190
	v_add_f32_e32 v254, v136, v254
	v_exp_f32_e32 v138, v138
	v_sub_f32_e32 v139, v139, v190
	s_waitcnt lgkmcnt(6)
	v_mfma_f32_32x32x16_bf16 v[80:95], v[214:217], v[242:245], v[80:95]
	ds_read_b64_tr_b16 v[214:215], v219 offset:256
	ds_read_b64_tr_b16 v[216:217], v219 offset:4352
	v_add_f32_e32 v254, v137, v254
	v_exp_f32_e32 v139, v139
	v_sub_f32_e32 v140, v140, v190
	v_add_f32_e32 v254, v138, v254
	s_waitcnt lgkmcnt(6)
	v_mfma_f32_32x32x16_bf16 v[64:79], v[238:241], v[242:245], v[64:79]
	ds_read_b64_tr_b16 v[238:239], v221 offset:256
	ds_read_b64_tr_b16 v[240:241], v221 offset:4352
	v_exp_f32_e32 v140, v140
	v_sub_f32_e32 v141, v141, v190
	v_add_f32_e32 v254, v139, v254
	v_exp_f32_e32 v141, v141
	s_waitcnt lgkmcnt(6)
	v_mfma_f32_32x32x16_bf16 v[48:63], v[206:209], v[242:245], v[48:63]
	ds_read_b64_tr_b16 v[206:207], v205 offset:8192
	ds_read_b64_tr_b16 v[208:209], v205 offset:12288
	v_sub_f32_e32 v142, v142, v190
	v_add_f32_e32 v254, v140, v254
	v_exp_f32_e32 v142, v142
	v_sub_f32_e32 v143, v143, v190
	s_waitcnt lgkmcnt(6)
	v_mfma_f32_32x32x16_bf16 v[32:47], v[210:213], v[242:245], v[32:47]
	ds_read_b64_tr_b16 v[210:211], v218 offset:8192
	ds_read_b64_tr_b16 v[212:213], v218 offset:12288
	v_add_f32_e32 v254, v141, v254
	v_exp_f32_e32 v143, v143
	v_add_f32_e32 v254, v142, v254
	v_add_f32_e32 v254, v143, v254
	s_waitcnt lgkmcnt(6)
	v_mfma_f32_32x32x16_bf16 v[16:31], v[214:217], v[242:245], v[16:31]
	ds_read_b64_tr_b16 v[214:215], v219 offset:8192
	ds_read_b64_tr_b16 v[216:217], v219 offset:12288
	v_cvt_pk_bf16_f32 v250, v136, v137
	v_cvt_pk_bf16_f32 v251, v138, v139
	v_cvt_pk_bf16_f32 v252, v140, v141
	v_cvt_pk_bf16_f32 v253, v142, v143
	v_add_f32_e32 v203, v203, v254
	s_waitcnt lgkmcnt(6)
	v_mfma_f32_32x32x16_bf16 v[0:15], v[238:241], v[242:245], v[0:15]
	ds_read_b64_tr_b16 v[238:239], v221 offset:8192
	ds_read_b64_tr_b16 v[240:241], v221 offset:12288
	ds_read_b64_tr_b16 v[128:129], v205 offset:8448
	ds_read_b64_tr_b16 v[130:131], v205 offset:12544
	s_waitcnt lgkmcnt(8)
	v_mfma_f32_32x32x16_bf16 v[112:127], v[206:209], v[250:253], v[112:127]
	ds_read_b64_tr_b16 v[206:207], v218 offset:8448
	ds_read_b64_tr_b16 v[208:209], v218 offset:12544
	v_max3_f32 v246, v222, v223, v224
	v_max3_f32 v247, v225, v226, v227
	v_max3_f32 v246, v246, v228, v229
	v_max3_f32 v247, v247, v230, v231
	v_max3_f32 v246, v246, v232, v233
	s_waitcnt lgkmcnt(8)
	v_mfma_f32_32x32x16_bf16 v[96:111], v[210:213], v[250:253], v[96:111]
	ds_read_b64_tr_b16 v[210:211], v219 offset:8448
	ds_read_b64_tr_b16 v[212:213], v219 offset:12544
	v_max3_f32 v247, v247, v234, v235
	v_max3_f32 v246, v246, v236, v237
	v_max_f32_e32 v246, v246, v247
	v_mov_b32_e32 v247, v246
	v_add_f32_e32 v249, 0x41000000, v190
	s_waitcnt lgkmcnt(8)
	v_mfma_f32_32x32x16_bf16 v[80:95], v[214:217], v[250:253], v[80:95]
	ds_read_b64_tr_b16 v[214:215], v221 offset:8448
	ds_read_b64_tr_b16 v[216:217], v221 offset:12544
	s_nop 1
	v_permlane32_swap_b32_e32 v246, v247
	v_max_f32_e32 v246, v246, v247
	v_cmp_gt_f32_e32 vcc, v246, v249
	s_cbranch_vccnz .Latt_rs1_6s0
	s_waitcnt lgkmcnt(8)
	v_mfma_f32_32x32x16_bf16 v[64:79], v[238:241], v[250:253], v[64:79]
	ds_read_b64_tr_b16 v[238:239], v205 offset:16384
	ds_read_b64_tr_b16 v[240:241], v205 offset:20480
	v_sub_f32_e32 v222, v222, v190
	v_exp_f32_e32 v222, v222
	v_sub_f32_e32 v223, v223, v190
	v_exp_f32_e32 v223, v223
	v_sub_f32_e32 v224, v224, v190
	v_add_f32_e32 v254, 0, v222
	s_waitcnt lgkmcnt(8)
	v_mfma_f32_32x32x16_bf16 v[48:63], v[128:131], v[250:253], v[48:63]
	ds_read_b64_tr_b16 v[128:129], v218 offset:16384
	ds_read_b64_tr_b16 v[130:131], v218 offset:20480
	v_exp_f32_e32 v224, v224
	v_sub_f32_e32 v225, v225, v190
	v_add_f32_e32 v254, v223, v254
	v_exp_f32_e32 v225, v225
	v_sub_f32_e32 v226, v226, v190
	v_add_f32_e32 v254, v224, v254
	s_waitcnt lgkmcnt(8)
	v_mfma_f32_32x32x16_bf16 v[32:47], v[206:209], v[250:253], v[32:47]
	ds_read_b64_tr_b16 v[206:207], v219 offset:16384
	ds_read_b64_tr_b16 v[208:209], v219 offset:20480
	v_exp_f32_e32 v226, v226
	v_sub_f32_e32 v227, v227, v190
	v_add_f32_e32 v254, v225, v254
	v_exp_f32_e32 v227, v227
	v_sub_f32_e32 v228, v228, v190
	s_waitcnt lgkmcnt(8)
	v_mfma_f32_32x32x16_bf16 v[16:31], v[210:213], v[250:253], v[16:31]
	ds_read_b64_tr_b16 v[210:211], v221 offset:16384
	ds_read_b64_tr_b16 v[212:213], v221 offset:20480
	v_add_f32_e32 v254, v226, v254
	v_exp_f32_e32 v228, v228
	v_sub_f32_e32 v229, v229, v190
	v_add_f32_e32 v254, v227, v254
	v_exp_f32_e32 v229, v229
	s_waitcnt lgkmcnt(8)
	v_mfma_f32_32x32x16_bf16 v[0:15], v[214:217], v[250:253], v[0:15]
	ds_read_b64_tr_b16 v[214:215], v205 offset:16640
	ds_read_b64_tr_b16 v[216:217], v205 offset:20736
	s_nop 0
	v_cvt_pk_bf16_f32 v242, v222, v223
	v_cvt_pk_bf16_f32 v243, v224, v225
	v_cvt_pk_bf16_f32 v244, v226, v227
	v_cvt_pk_bf16_f32 v245, v228, v229
	s_nop 1
	s_waitcnt lgkmcnt(8)
	v_mfma_f32_32x32x16_bf16 v[112:127], v[238:241], v[242:245], v[112:127]
	ds_read_b64_tr_b16 v[238:239], v218 offset:16640
	ds_read_b64_tr_b16 v[240:241], v218 offset:20736
	v_sub_f32_e32 v230, v230, v190
	v_add_f32_e32 v254, v228, v254
	v_exp_f32_e32 v230, v230
	v_sub_f32_e32 v231, v231, v190
	v_add_f32_e32 v254, v229, v254
	s_waitcnt lgkmcnt(8)
	v_mfma_f32_32x32x16_bf16 v[96:111], v[128:131], v[242:245], v[96:111]
	ds_read_b64_tr_b16 v[128:129], v219 offset:16640
	ds_read_b64_tr_b16 v[130:131], v219 offset:20736
	v_exp_f32_e32 v231, v231
	v_sub_f32_e32 v232, v232, v190
	v_add_f32_e32 v254, v230, v254
	v_exp_f32_e32 v232, v232
	v_sub_f32_e32 v233, v233, v190
	s_cmp_lg_u64 s[12:13], 0
	s_cbranch_scc1 .Latt_nd0_6s0
	s_sub_i32 s100, s34, 1
	s_cmp_eq_u32 s34, 0
	s_cselect_b32 s100, 2, s100
	s_lshl_b32 s101, s100, 14
	s_add_i32 m0, s36, s101
	s_nop 0
	global_load_lds_dwordx4 v178, s[20:21]

.Latt_nr0_6s1:
	s_waitcnt lgkmcnt(3)
	v_mfma_f32_32x32x16_bf16 v[222:237], v[214:217], v[152:155], v[222:237]
	ds_read_b128 v[214:217], v201 offset:24576
	v_sub_f32_e32 v128, v128, v190
	v_exp_f32_e32 v128, v128
	v_sub_f32_e32 v129, v129, v190
	v_exp_f32_e32 v129, v129
	v_sub_f32_e32 v130, v130, v190
	s_waitcnt lgkmcnt(3)
	v_mfma_f32_32x32x16_bf16 v[222:237], v[238:241], v[156:159], v[222:237]
	ds_read_b128 v[238:241], v202 offset:24576
	v_add_f32_e32 v254, 0, v128
	v_exp_f32_e32 v130, v130
	v_sub_f32_e32 v131, v131, v190
	v_add_f32_e32 v254, v129, v254
	v_exp_f32_e32 v131, v131
	s_waitcnt lgkmcnt(3)
	v_mfma_f32_32x32x16_bf16 v[222:237], v[206:209], v[160:163], v[222:237]
	ds_read_b64_tr_b16 v[206:207], v205
	ds_read_b64_tr_b16 v[208:209], v205 offset:4096
	v_sub_f32_e32 v132, v132, v190
	v_add_f32_e32 v254, v130, v254
	v_exp_f32_e32 v132, v132
	v_sub_f32_e32 v133, v133, v190
	v_add_f32_e32 v254, v131, v254
	s_waitcnt lgkmcnt(4)
	v_mfma_f32_32x32x16_bf16 v[222:237], v[210:213], v[164:167], v[222:237]
	ds_read_b64_tr_b16 v[210:211], v218
	ds_read_b64_tr_b16 v[212:213], v218 offset:4096
	v_exp_f32_e32 v133, v133
	v_sub_f32_e32 v134, v134, v190
	v_add_f32_e32 v254, v132, v254
	v_exp_f32_e32 v134, v134
	s_waitcnt lgkmcnt(5)
	v_mfma_f32_32x32x16_bf16 v[222:237], v[214:217], v[168:171], v[222:237]
	ds_read_b64_tr_b16 v[214:215], v219
	ds_read_b64_tr_b16 v[216:217], v219 offset:4096
	v_sub_f32_e32 v135, v135, v190
	v_add_f32_e32 v254, v133, v254
	v_exp_f32_e32 v135, v135
	s_nop 0
	s_waitcnt lgkmcnt(6)
	v_mfma_f32_32x32x16_bf16 v[222:237], v[238:241], v[172:175], v[222:237]
	ds_read_b64_tr_b16 v[238:239], v221
	ds_read_b64_tr_b16 v[240:241], v221 offset:4096
	v_cvt_pk_bf16_f32 v242, v128, v129
	v_cvt_pk_bf16_f32 v243, v130, v131
	v_cvt_pk_bf16_f32 v244, v132, v133
	v_cvt_pk_bf16_f32 v245, v134, v135
	s_nop 1
	s_waitcnt lgkmcnt(6)
	v_mfma_f32_32x32x16_bf16 v[112:127], v[206:209], v[242:245], v[112:127]
	ds_read_b64_tr_b16 v[206:207], v205 offset:256
	ds_read_b64_tr_b16 v[208:209], v205 offset:4352
	v_sub_f32_e32 v136, v136, v190
	v_add_f32_e32 v254, v134, v254
	v_exp_f32_e32 v136, v136
	v_sub_f32_e32 v137, v137, v190
	v_add_f32_e32 v254, v135, v254
	s_waitcnt lgkmcnt(6)
	v_mfma_f32_32x32x16_bf16 v[96:111], v[210:213], v[242:245], v[96:111]
	ds_read_b64_tr_b16 v[210:211], v218 offset:256
	ds_read_b64_tr_b16 v[212:213], v218 offset:4352
	v_exp_f32_e32 v137, v137
	v_sub_f32_e32 v138, v138, v190
	v_add_f32_e32 v254, v136, v254
	v_exp_f32_e32 v138, v138
	v_sub_f32_e32 v139, v139, v190
	s_waitcnt lgkmcnt(6)
	v_mfma_f32_32x32x16_bf16 v[80:95], v[214:217], v[242:245], v[80:95]
	ds_read_b64_tr_b16 v[214:215], v219 offset:256
	ds_read_b64_tr_b16 v[216:217], v219 offset:4352
	v_add_f32_e32 v254, v137, v254
	v_exp_f32_e32 v139, v139
	v_sub_f32_e32 v140, v140, v190
	v_add_f32_e32 v254, v138, v254
	s_waitcnt lgkmcnt(6)
	v_mfma_f32_32x32x16_bf16 v[64:79], v[238:241], v[242:245], v[64:79]
	ds_read_b64_tr_b16 v[238:239], v221 offset:256
	ds_read_b64_tr_b16 v[240:241], v221 offset:4352
	v_exp_f32_e32 v140, v140
	v_sub_f32_e32 v141, v141, v190
	v_add_f32_e32 v254, v139, v254
	v_exp_f32_e32 v141, v141
	s_waitcnt lgkmcnt(6)
	v_mfma_f32_32x32x16_bf16 v[48:63], v[206:209], v[242:245], v[48:63]
	ds_read_b64_tr_b16 v[206:207], v205 offset:8192
	ds_read_b64_tr_b16 v[208:209], v205 offset:12288
	v_sub_f32_e32 v142, v142, v190
	v_add_f32_e32 v254, v140, v254
	v_exp_f32_e32 v142, v142
	v_sub_f32_e32 v143, v143, v190
	s_waitcnt lgkmcnt(6)
	v_mfma_f32_32x32x16_bf16 v[32:47], v[210:213], v[242:245], v[32:47]
	ds_read_b64_tr_b16 v[210:211], v218 offset:8192
	ds_read_b64_tr_b16 v[212:213], v218 offset:12288
	v_add_f32_e32 v254, v141, v254
	v_exp_f32_e32 v143, v143
	v_add_f32_e32 v254, v142, v254
	v_add_f32_e32 v254, v143, v254
	s_waitcnt lgkmcnt(6)
	v_mfma_f32_32x32x16_bf16 v[16:31], v[214:217], v[242:245], v[16:31]
	ds_read_b64_tr_b16 v[214:215], v219 offset:8192
	ds_read_b64_tr_b16 v[216:217], v219 offset:12288
	v_cvt_pk_bf16_f32 v250, v136, v137
	v_cvt_pk_bf16_f32 v251, v138, v139
	v_cvt_pk_bf16_f32 v252, v140, v141
	v_cvt_pk_bf16_f32 v253, v142, v143
	v_add_f32_e32 v203, v203, v254
	s_waitcnt lgkmcnt(6)
	v_mfma_f32_32x32x16_bf16 v[0:15], v[238:241], v[242:245], v[0:15]
	ds_read_b64_tr_b16 v[238:239], v221 offset:8192
	ds_read_b64_tr_b16 v[240:241], v221 offset:12288
	ds_read_b64_tr_b16 v[128:129], v205 offset:8448
	ds_read_b64_tr_b16 v[130:131], v205 offset:12544
	s_waitcnt lgkmcnt(8)
	v_mfma_f32_32x32x16_bf16 v[112:127], v[206:209], v[250:253], v[112:127]
	ds_read_b64_tr_b16 v[206:207], v218 offset:8448
	ds_read_b64_tr_b16 v[208:209], v218 offset:12544
	v_max3_f32 v246, v222, v223, v224
	v_max3_f32 v247, v225, v226, v227
	v_max3_f32 v246, v246, v228, v229
	v_max3_f32 v247, v247, v230, v231
	v_max3_f32 v246, v246, v232, v233
	s_waitcnt lgkmcnt(8)
	v_mfma_f32_32x32x16_bf16 v[96:111], v[210:213], v[250:253], v[96:111]
	ds_read_b64_tr_b16 v[210:211], v219 offset:8448
	ds_read_b64_tr_b16 v[212:213], v219 offset:12544
	v_max3_f32 v247, v247, v234, v235
	v_max3_f32 v246, v246, v236, v237
	v_max_f32_e32 v246, v246, v247
	v_mov_b32_e32 v247, v246
	v_add_f32_e32 v249, 0x41000000, v190
	s_waitcnt lgkmcnt(8)
	v_mfma_f32_32x32x16_bf16 v[80:95], v[214:217], v[250:253], v[80:95]
	ds_read_b64_tr_b16 v[214:215], v221 offset:8448
	ds_read_b64_tr_b16 v[216:217], v221 offset:12544
	s_nop 1
	v_permlane32_swap_b32_e32 v246, v247
	v_max_f32_e32 v246, v246, v247
	v_cmp_gt_f32_e32 vcc, v246, v249
	s_cbranch_vccnz .Latt_rs1_6s1
	s_waitcnt lgkmcnt(8)
	v_mfma_f32_32x32x16_bf16 v[64:79], v[238:241], v[250:253], v[64:79]
	ds_read_b64_tr_b16 v[238:239], v205 offset:16384
	ds_read_b64_tr_b16 v[240:241], v205 offset:20480
	v_sub_f32_e32 v222, v222, v190
	v_exp_f32_e32 v222, v222
	v_sub_f32_e32 v223, v223, v190
	v_exp_f32_e32 v223, v223
	v_sub_f32_e32 v224, v224, v190
	v_add_f32_e32 v254, 0, v222
	s_waitcnt lgkmcnt(8)
	v_mfma_f32_32x32x16_bf16 v[48:63], v[128:131], v[250:253], v[48:63]
	ds_read_b64_tr_b16 v[128:129], v218 offset:16384
	ds_read_b64_tr_b16 v[130:131], v218 offset:20480
	v_exp_f32_e32 v224, v224
	v_sub_f32_e32 v225, v225, v190
	v_add_f32_e32 v254, v223, v254
	v_exp_f32_e32 v225, v225
	v_sub_f32_e32 v226, v226, v190
	v_add_f32_e32 v254, v224, v254
	s_waitcnt lgkmcnt(8)
	v_mfma_f32_32x32x16_bf16 v[32:47], v[206:209], v[250:253], v[32:47]
	ds_read_b64_tr_b16 v[206:207], v219 offset:16384
	ds_read_b64_tr_b16 v[208:209], v219 offset:20480
	v_exp_f32_e32 v226, v226
	v_sub_f32_e32 v227, v227, v190
	v_add_f32_e32 v254, v225, v254
	v_exp_f32_e32 v227, v227
	v_sub_f32_e32 v228, v228, v190
	s_waitcnt lgkmcnt(8)
	v_mfma_f32_32x32x16_bf16 v[16:31], v[210:213], v[250:253], v[16:31]
	ds_read_b64_tr_b16 v[210:211], v221 offset:16384
	ds_read_b64_tr_b16 v[212:213], v221 offset:20480
	v_add_f32_e32 v254, v226, v254
	v_exp_f32_e32 v228, v228
	v_sub_f32_e32 v229, v229, v190
	v_add_f32_e32 v254, v227, v254
	v_exp_f32_e32 v229, v229
	s_waitcnt lgkmcnt(8)
	v_mfma_f32_32x32x16_bf16 v[0:15], v[214:217], v[250:253], v[0:15]
	ds_read_b64_tr_b16 v[214:215], v205 offset:16640
	ds_read_b64_tr_b16 v[216:217], v205 offset:20736
	s_nop 0
	v_cvt_pk_bf16_f32 v242, v222, v223
	v_cvt_pk_bf16_f32 v243, v224, v225
	v_cvt_pk_bf16_f32 v244, v226, v227
	v_cvt_pk_bf16_f32 v245, v228, v229
	s_nop 1
	s_waitcnt lgkmcnt(8)
	v_mfma_f32_32x32x16_bf16 v[112:127], v[238:241], v[242:245], v[112:127]
	ds_read_b64_tr_b16 v[238:239], v218 offset:16640
	ds_read_b64_tr_b16 v[240:241], v218 offset:20736
	v_sub_f32_e32 v230, v230, v190
	v_add_f32_e32 v254, v228, v254
	v_exp_f32_e32 v230, v230
	v_sub_f32_e32 v231, v231, v190
	v_add_f32_e32 v254, v229, v254
	s_waitcnt lgkmcnt(8)
	v_mfma_f32_32x32x16_bf16 v[96:111], v[128:131], v[242:245], v[96:111]
	ds_read_b64_tr_b16 v[128:129], v219 offset:16640
	ds_read_b64_tr_b16 v[130:131], v219 offset:20736
	v_exp_f32_e32 v231, v231
	v_sub_f32_e32 v232, v232, v190
	v_add_f32_e32 v254, v230, v254
	v_exp_f32_e32 v232, v232
	v_sub_f32_e32 v233, v233, v190
	s_cmp_lg_u64 s[12:13], 0
	s_cbranch_scc1 .Latt_nd0_6s1
	s_sub_i32 s100, s34, 1
	s_cmp_eq_u32 s34, 0
	s_cselect_b32 s100, 2, s100
	s_lshl_b32 s101, s100, 14
	s_add_i32 m0, s36, s101
	s_nop 0
	global_load_lds_dwordx4 v178, s[20:21]

.Latt_nr0_6s2:
	s_waitcnt lgkmcnt(3)
	v_mfma_f32_32x32x16_bf16 v[222:237], v[214:217], v[152:155], v[222:237]
	ds_read_b128 v[214:217], v201 offset:40960
	v_sub_f32_e32 v128, v128, v190
	v_exp_f32_e32 v128, v128
	v_sub_f32_e32 v129, v129, v190
	v_exp_f32_e32 v129, v129
	v_sub_f32_e32 v130, v130, v190
	s_waitcnt lgkmcnt(3)
	v_mfma_f32_32x32x16_bf16 v[222:237], v[238:241], v[156:159], v[222:237]
	ds_read_b128 v[238:241], v202 offset:40960
	v_add_f32_e32 v254, 0, v128
	v_exp_f32_e32 v130, v130
	v_sub_f32_e32 v131, v131, v190
	v_add_f32_e32 v254, v129, v254
	v_exp_f32_e32 v131, v131
	s_waitcnt lgkmcnt(3)
	v_mfma_f32_32x32x16_bf16 v[222:237], v[206:209], v[160:163], v[222:237]
	ds_read_b64_tr_b16 v[206:207], v205
	ds_read_b64_tr_b16 v[208:209], v205 offset:4096
	v_sub_f32_e32 v132, v132, v190
	v_add_f32_e32 v254, v130, v254
	v_exp_f32_e32 v132, v132
	v_sub_f32_e32 v133, v133, v190
	v_add_f32_e32 v254, v131, v254
	s_waitcnt lgkmcnt(4)
	v_mfma_f32_32x32x16_bf16 v[222:237], v[210:213], v[164:167], v[222:237]
	ds_read_b64_tr_b16 v[210:211], v218
	ds_read_b64_tr_b16 v[212:213], v218 offset:4096
	v_exp_f32_e32 v133, v133
	v_sub_f32_e32 v134, v134, v190
	v_add_f32_e32 v254, v132, v254
	v_exp_f32_e32 v134, v134
	s_waitcnt lgkmcnt(5)
	v_mfma_f32_32x32x16_bf16 v[222:237], v[214:217], v[168:171], v[222:237]
	ds_read_b64_tr_b16 v[214:215], v219
	ds_read_b64_tr_b16 v[216:217], v219 offset:4096
	v_sub_f32_e32 v135, v135, v190
	v_add_f32_e32 v254, v133, v254
	v_exp_f32_e32 v135, v135
	s_nop 0
	s_waitcnt lgkmcnt(6)
	v_mfma_f32_32x32x16_bf16 v[222:237], v[238:241], v[172:175], v[222:237]
	ds_read_b64_tr_b16 v[238:239], v221
	ds_read_b64_tr_b16 v[240:241], v221 offset:4096
	v_cvt_pk_bf16_f32 v242, v128, v129
	v_cvt_pk_bf16_f32 v243, v130, v131
	v_cvt_pk_bf16_f32 v244, v132, v133
	v_cvt_pk_bf16_f32 v245, v134, v135
	s_nop 1
	s_waitcnt lgkmcnt(6)
	v_mfma_f32_32x32x16_bf16 v[112:127], v[206:209], v[242:245], v[112:127]
	ds_read_b64_tr_b16 v[206:207], v205 offset:256
	ds_read_b64_tr_b16 v[208:209], v205 offset:4352
	v_sub_f32_e32 v136, v136, v190
	v_add_f32_e32 v254, v134, v254
	v_exp_f32_e32 v136, v136
	v_sub_f32_e32 v137, v137, v190
	v_add_f32_e32 v254, v135, v254
	s_waitcnt lgkmcnt(6)
	v_mfma_f32_32x32x16_bf16 v[96:111], v[210:213], v[242:245], v[96:111]
	ds_read_b64_tr_b16 v[210:211], v218 offset:256
	ds_read_b64_tr_b16 v[212:213], v218 offset:4352
	v_exp_f32_e32 v137, v137
	v_sub_f32_e32 v138, v138, v190
	v_add_f32_e32 v254, v136, v254
	v_exp_f32_e32 v138, v138
	v_sub_f32_e32 v139, v139, v190
	s_waitcnt lgkmcnt(6)
	v_mfma_f32_32x32x16_bf16 v[80:95], v[214:217], v[242:245], v[80:95]
	ds_read_b64_tr_b16 v[214:215], v219 offset:256
	ds_read_b64_tr_b16 v[216:217], v219 offset:4352
	v_add_f32_e32 v254, v137, v254
	v_exp_f32_e32 v139, v139
	v_sub_f32_e32 v140, v140, v190
	v_add_f32_e32 v254, v138, v254
	s_waitcnt lgkmcnt(6)
	v_mfma_f32_32x32x16_bf16 v[64:79], v[238:241], v[242:245], v[64:79]
	ds_read_b64_tr_b16 v[238:239], v221 offset:256
	ds_read_b64_tr_b16 v[240:241], v221 offset:4352
	v_exp_f32_e32 v140, v140
	v_sub_f32_e32 v141, v141, v190
	v_add_f32_e32 v254, v139, v254
	v_exp_f32_e32 v141, v141
	s_waitcnt lgkmcnt(6)
	v_mfma_f32_32x32x16_bf16 v[48:63], v[206:209], v[242:245], v[48:63]
	ds_read_b64_tr_b16 v[206:207], v205 offset:8192
	ds_read_b64_tr_b16 v[208:209], v205 offset:12288
	v_sub_f32_e32 v142, v142, v190
	v_add_f32_e32 v254, v140, v254
	v_exp_f32_e32 v142, v142
	v_sub_f32_e32 v143, v143, v190
	s_waitcnt lgkmcnt(6)
	v_mfma_f32_32x32x16_bf16 v[32:47], v[210:213], v[242:245], v[32:47]
	ds_read_b64_tr_b16 v[210:211], v218 offset:8192
	ds_read_b64_tr_b16 v[212:213], v218 offset:12288
	v_add_f32_e32 v254, v141, v254
	v_exp_f32_e32 v143, v143
	v_add_f32_e32 v254, v142, v254
	v_add_f32_e32 v254, v143, v254
	s_waitcnt lgkmcnt(6)
	v_mfma_f32_32x32x16_bf16 v[16:31], v[214:217], v[242:245], v[16:31]
	ds_read_b64_tr_b16 v[214:215], v219 offset:8192
	ds_read_b64_tr_b16 v[216:217], v219 offset:12288
	v_cvt_pk_bf16_f32 v250, v136, v137
	v_cvt_pk_bf16_f32 v251, v138, v139
	v_cvt_pk_bf16_f32 v252, v140, v141
	v_cvt_pk_bf16_f32 v253, v142, v143
	v_add_f32_e32 v203, v203, v254
	s_waitcnt lgkmcnt(6)
	v_mfma_f32_32x32x16_bf16 v[0:15], v[238:241], v[242:245], v[0:15]
	ds_read_b64_tr_b16 v[238:239], v221 offset:8192
	ds_read_b64_tr_b16 v[240:241], v221 offset:12288
	ds_read_b64_tr_b16 v[128:129], v205 offset:8448
	ds_read_b64_tr_b16 v[130:131], v205 offset:12544
	s_waitcnt lgkmcnt(8)
	v_mfma_f32_32x32x16_bf16 v[112:127], v[206:209], v[250:253], v[112:127]
	ds_read_b64_tr_b16 v[206:207], v218 offset:8448
	ds_read_b64_tr_b16 v[208:209], v218 offset:12544
	v_max3_f32 v246, v222, v223, v224
	v_max3_f32 v247, v225, v226, v227
	v_max3_f32 v246, v246, v228, v229
	v_max3_f32 v247, v247, v230, v231
	v_max3_f32 v246, v246, v232, v233
	s_waitcnt lgkmcnt(8)
	v_mfma_f32_32x32x16_bf16 v[96:111], v[210:213], v[250:253], v[96:111]
	ds_read_b64_tr_b16 v[210:211], v219 offset:8448
	ds_read_b64_tr_b16 v[212:213], v219 offset:12544
	v_max3_f32 v247, v247, v234, v235
	v_max3_f32 v246, v246, v236, v237
	v_max_f32_e32 v246, v246, v247
	v_mov_b32_e32 v247, v246
	v_add_f32_e32 v249, 0x41000000, v190
	s_waitcnt lgkmcnt(8)
	v_mfma_f32_32x32x16_bf16 v[80:95], v[214:217], v[250:253], v[80:95]
	ds_read_b64_tr_b16 v[214:215], v221 offset:8448
	ds_read_b64_tr_b16 v[216:217], v221 offset:12544
	s_nop 1
	v_permlane32_swap_b32_e32 v246, v247
	v_max_f32_e32 v246, v246, v247
	v_cmp_gt_f32_e32 vcc, v246, v249
	s_cbranch_vccnz .Latt_rs1_6s2
	s_waitcnt lgkmcnt(8)
	v_mfma_f32_32x32x16_bf16 v[64:79], v[238:241], v[250:253], v[64:79]
	ds_read_b64_tr_b16 v[238:239], v205 offset:16384
	ds_read_b64_tr_b16 v[240:241], v205 offset:20480
	v_sub_f32_e32 v222, v222, v190
	v_exp_f32_e32 v222, v222
	v_sub_f32_e32 v223, v223, v190
	v_exp_f32_e32 v223, v223
	v_sub_f32_e32 v224, v224, v190
	v_add_f32_e32 v254, 0, v222
	s_waitcnt lgkmcnt(8)
	v_mfma_f32_32x32x16_bf16 v[48:63], v[128:131], v[250:253], v[48:63]
	ds_read_b64_tr_b16 v[128:129], v218 offset:16384
	ds_read_b64_tr_b16 v[130:131], v218 offset:20480
	v_exp_f32_e32 v224, v224
	v_sub_f32_e32 v225, v225, v190
	v_add_f32_e32 v254, v223, v254
	v_exp_f32_e32 v225, v225
	v_sub_f32_e32 v226, v226, v190
	v_add_f32_e32 v254, v224, v254
	s_waitcnt lgkmcnt(8)
	v_mfma_f32_32x32x16_bf16 v[32:47], v[206:209], v[250:253], v[32:47]
	ds_read_b64_tr_b16 v[206:207], v219 offset:16384
	ds_read_b64_tr_b16 v[208:209], v219 offset:20480
	v_exp_f32_e32 v226, v226
	v_sub_f32_e32 v227, v227, v190
	v_add_f32_e32 v254, v225, v254
	v_exp_f32_e32 v227, v227
	v_sub_f32_e32 v228, v228, v190
	s_waitcnt lgkmcnt(8)
	v_mfma_f32_32x32x16_bf16 v[16:31], v[210:213], v[250:253], v[16:31]
	ds_read_b64_tr_b16 v[210:211], v221 offset:16384
	ds_read_b64_tr_b16 v[212:213], v221 offset:20480
	v_add_f32_e32 v254, v226, v254
	v_exp_f32_e32 v228, v228
	v_sub_f32_e32 v229, v229, v190
	v_add_f32_e32 v254, v227, v254
	v_exp_f32_e32 v229, v229
	s_waitcnt lgkmcnt(8)
	v_mfma_f32_32x32x16_bf16 v[0:15], v[214:217], v[250:253], v[0:15]
	ds_read_b64_tr_b16 v[214:215], v205 offset:16640
	ds_read_b64_tr_b16 v[216:217], v205 offset:20736
	s_nop 0
	v_cvt_pk_bf16_f32 v242, v222, v223
	v_cvt_pk_bf16_f32 v243, v224, v225
	v_cvt_pk_bf16_f32 v244, v226, v227
	v_cvt_pk_bf16_f32 v245, v228, v229
	s_nop 1
	s_waitcnt lgkmcnt(8)
	v_mfma_f32_32x32x16_bf16 v[112:127], v[238:241], v[242:245], v[112:127]
	ds_read_b64_tr_b16 v[238:239], v218 offset:16640
	ds_read_b64_tr_b16 v[240:241], v218 offset:20736
	v_sub_f32_e32 v230, v230, v190
	v_add_f32_e32 v254, v228, v254
	v_exp_f32_e32 v230, v230
	v_sub_f32_e32 v231, v231, v190
	v_add_f32_e32 v254, v229, v254
	s_waitcnt lgkmcnt(8)
	v_mfma_f32_32x32x16_bf16 v[96:111], v[128:131], v[242:245], v[96:111]
	ds_read_b64_tr_b16 v[128:129], v219 offset:16640
	ds_read_b64_tr_b16 v[130:131], v219 offset:20736
	v_exp_f32_e32 v231, v231
	v_sub_f32_e32 v232, v232, v190
	v_add_f32_e32 v254, v230, v254
	v_exp_f32_e32 v232, v232
	v_sub_f32_e32 v233, v233, v190
	s_cmp_lg_u64 s[12:13], 0
	s_cbranch_scc1 .Latt_nd0_6s2
	s_sub_i32 s100, s34, 1
	s_cmp_eq_u32 s34, 0
	s_cselect_b32 s100, 2, s100
	s_lshl_b32 s101, s100, 14
	s_add_i32 m0, s36, s101
	s_nop 0
	global_load_lds_dwordx4 v178, s[20:21]

.Latt_slow_6s2:
.Latt_slow_6:
	s_lshl_b32 s14, s34, 14
	s_add_i32 s15, s14, 0
	v_add_u32_e32 v207, s15, v195
	ds_read_b128 v[128:131], v207
	v_add_u32_e32 v208, s15, v196
	ds_read_b128 v[210:213], v208
	v_add_u32_e32 v209, s15, v197
	v_lshrrev_b32_e32 v205, 3, v204
	s_add_i32 s35, s72, 31
	v_and_or_b32 v206, v204, 31, s68
	s_cmp_le_i32 s35, s68
	s_waitcnt lgkmcnt(1)
	v_mfma_f32_32x32x16_bf16 v[128:143], v[128:131], v[144:147], 0
	s_waitcnt lgkmcnt(0)
	v_mfma_f32_32x32x16_bf16 v[128:143], v[210:213], v[148:151], v[128:143]
	ds_read_b128 v[212:215], v209
	v_add_u32_e32 v210, s15, v198
	ds_read_b128 v[216:219], v210
	v_add_u32_e32 v211, s15, v199
	s_waitcnt lgkmcnt(1)
	v_mfma_f32_32x32x16_bf16 v[128:143], v[212:215], v[152:155], v[128:143]
	v_add_u32_e32 v213, s15, v200
	v_and_b32_e32 v212, 4, v205
	ds_read_b128 v[222:225], v213
	s_waitcnt lgkmcnt(1)
	v_mfma_f32_32x32x16_bf16 v[128:143], v[216:219], v[156:159], v[128:143]
	ds_read_b128 v[214:217], v211
	s_waitcnt lgkmcnt(0)
	v_mfma_f32_32x32x16_bf16 v[128:143], v[214:217], v[160:163], v[128:143]
	v_add_u32_e32 v214, s15, v201
	ds_read_b128 v[216:219], v214
	v_add_u32_e32 v215, s15, v202
	v_mfma_f32_32x32x16_bf16 v[128:143], v[222:225], v[164:167], v[128:143]
	ds_read_b128 v[222:225], v215
	s_waitcnt lgkmcnt(1)
	v_mfma_f32_32x32x16_bf16 v[128:143], v[216:219], v[168:171], v[128:143]
	s_waitcnt lgkmcnt(0)
	v_mfma_f32_32x32x16_bf16 v[128:143], v[222:225], v[172:175], v[128:143]
	s_cbranch_scc1 .LBB0_1842
	v_add_u32_e32 v205, s72, v212
	v_cmp_lt_i32_e32 vcc, v205, v206
	v_add_u32_e32 v216, 2, v205
	s_nop 7
	v_cndmask_b32_e32 v129, v192, v129, vcc
	v_cmp_le_i32_e32 vcc, v205, v206
	s_nop 1
	v_cndmask_b32_e32 v128, v192, v128, vcc
	v_cmp_le_i32_e32 vcc, v216, v206
	v_add_u32_e32 v216, 3, v205
	s_nop 0
	v_cndmask_b32_e32 v130, v192, v130, vcc
	v_cmp_le_i32_e32 vcc, v216, v206
	v_add_u32_e32 v216, 8, v205
	s_nop 0
	v_cndmask_b32_e32 v131, v192, v131, vcc
	v_cmp_le_i32_e32 vcc, v216, v206
	v_add_u32_e32 v216, 9, v205
	s_nop 0
	v_cndmask_b32_e32 v132, v192, v132, vcc
	v_cmp_le_i32_e32 vcc, v216, v206
	v_add_u32_e32 v216, 10, v205
	s_nop 0
	v_cndmask_b32_e32 v133, v192, v133, vcc
	v_cmp_le_i32_e32 vcc, v216, v206
	v_add_u32_e32 v216, 11, v205
	s_nop 0
	v_cndmask_b32_e32 v134, v192, v134, vcc
	v_cmp_le_i32_e32 vcc, v216, v206
	v_add_u32_e32 v216, 16, v205
	s_nop 0
	v_cndmask_b32_e32 v135, v192, v135, vcc
	v_cmp_le_i32_e32 vcc, v216, v206
	v_add_u32_e32 v216, 17, v205
	s_nop 0
	v_cndmask_b32_e32 v136, v192, v136, vcc
	v_cmp_le_i32_e32 vcc, v216, v206
	v_add_u32_e32 v216, 18, v205
	s_nop 0
	v_cndmask_b32_e32 v137, v192, v137, vcc
	v_cmp_le_i32_e32 vcc, v216, v206
	v_add_u32_e32 v216, 19, v205
	s_nop 0
	v_cndmask_b32_e32 v138, v192, v138, vcc
	v_cmp_le_i32_e32 vcc, v216, v206
	v_add_u32_e32 v216, 24, v205
	s_nop 0
	v_cndmask_b32_e32 v139, v192, v139, vcc
	v_cmp_le_i32_e32 vcc, v216, v206
	v_add_u32_e32 v216, 25, v205
	s_nop 0
	v_cndmask_b32_e32 v140, v192, v140, vcc
	v_cmp_le_i32_e32 vcc, v216, v206
	v_add_u32_e32 v216, 26, v205
	v_add_u32_e32 v205, 27, v205
	v_cndmask_b32_e32 v141, v192, v141, vcc
	v_cmp_le_i32_e32 vcc, v216, v206
	s_nop 1
	v_cndmask_b32_e32 v142, v192, v142, vcc
	v_cmp_le_i32_e32 vcc, v205, v206
	s_nop 1
	v_cndmask_b32_e32 v143, v192, v143, vcc

.LBB0_1858:
	s_cmp_gt_i32 s14, s69
	s_cbranch_scc1 .LBB0_1869
	s_add_i32 s100, s14, 63
	s_cmp_le_i32 s100, s68
	s_cbranch_scc0 .Latt_slow_7
	s_cmp_eq_u32 s11, 1
	s_cbranch_scc1 .Latt_slot1_7
	s_cmp_eq_u32 s11, 2
	s_cbranch_scc1 .Latt_slot2_7
	ds_read_b128 v[206:209], v196
	ds_read_b128 v[210:213], v197
	ds_read_b128 v[214:217], v198
	ds_read_b128 v[238:241], v199
	ds_read_b128 v[242:245], v200
	ds_read_b128 v[250:253], v201
	ds_read_b128 v[222:225], v202
	ds_read_b128 v[226:229], v203
	s_cmp_lg_u32 s14, 0
	s_cbranch_scc1 .Latt_vstep_7s0
	v_bfe_u32 v246, v204, 2, 2
	v_bfe_u32 v247, v204, 5, 1
	v_lshl_or_b32 v247, v247, 2, v246
	v_and_b32_e32 v249, 3, v204
	v_and_b32_e32 v254, 16, v204
	v_lshl_or_b32 v249, v249, 2, v254
	v_lshlrev_b32_e32 v249, 1, v249
	v_lshl_add_u32 v247, v247, 9, v249
	v_add_u32_e32 v247, 0xc000, v247
	v_lshlrev_b32_e32 v246, 6, v246
	v_add_u32_e32 v205, v247, v246
	v_xor_b32_e32 v249, 64, v246
	v_add_u32_e32 v218, v247, v249
	v_xor_b32_e32 v249, 0x80, v246
	v_add_u32_e32 v219, v247, v249
	v_xor_b32_e32 v249, 0xc0, v246
	v_add_u32_e32 v221, v247, v249
	s_branch .Latt_vdone_7s0

.Latt_nr0_7s0:
	s_waitcnt lgkmcnt(3)
	v_mfma_f32_32x32x16_bf16 v[222:237], v[214:217], v[152:155], v[222:237]
	ds_read_b128 v[214:217], v202 offset:8192
	v_sub_f32_e32 v128, v128, v190
	v_exp_f32_e32 v128, v128
	v_sub_f32_e32 v129, v129, v190
	v_exp_f32_e32 v129, v129
	v_sub_f32_e32 v130, v130, v190
	s_waitcnt lgkmcnt(3)
	v_mfma_f32_32x32x16_bf16 v[222:237], v[238:241], v[156:159], v[222:237]
	ds_read_b128 v[238:241], v203 offset:8192
	v_add_f32_e32 v254, 0, v128
	v_exp_f32_e32 v130, v130
	v_sub_f32_e32 v131, v131, v190
	v_add_f32_e32 v254, v129, v254
	v_exp_f32_e32 v131, v131
	s_waitcnt lgkmcnt(3)
	v_mfma_f32_32x32x16_bf16 v[222:237], v[206:209], v[160:163], v[222:237]
	ds_read_b64_tr_b16 v[206:207], v205
	ds_read_b64_tr_b16 v[208:209], v205 offset:4096
	v_sub_f32_e32 v132, v132, v190
	v_add_f32_e32 v254, v130, v254
	v_exp_f32_e32 v132, v132
	v_sub_f32_e32 v133, v133, v190
	v_add_f32_e32 v254, v131, v254
	s_waitcnt lgkmcnt(4)
	v_mfma_f32_32x32x16_bf16 v[222:237], v[210:213], v[164:167], v[222:237]
	ds_read_b64_tr_b16 v[210:211], v218
	ds_read_b64_tr_b16 v[212:213], v218 offset:4096
	v_exp_f32_e32 v133, v133
	v_sub_f32_e32 v134, v134, v190
	v_add_f32_e32 v254, v132, v254
	v_exp_f32_e32 v134, v134
	s_waitcnt lgkmcnt(5)
	v_mfma_f32_32x32x16_bf16 v[222:237], v[214:217], v[168:171], v[222:237]
	ds_read_b64_tr_b16 v[214:215], v219
	ds_read_b64_tr_b16 v[216:217], v219 offset:4096
	v_sub_f32_e32 v135, v135, v190
	v_add_f32_e32 v254, v133, v254
	v_exp_f32_e32 v135, v135
	s_nop 0
	s_waitcnt lgkmcnt(6)
	v_mfma_f32_32x32x16_bf16 v[222:237], v[238:241], v[172:175], v[222:237]
	ds_read_b64_tr_b16 v[238:239], v221
	ds_read_b64_tr_b16 v[240:241], v221 offset:4096
	v_cvt_pk_bf16_f32 v242, v128, v129
	v_cvt_pk_bf16_f32 v243, v130, v131
	v_cvt_pk_bf16_f32 v244, v132, v133
	v_cvt_pk_bf16_f32 v245, v134, v135
	s_nop 1
	s_waitcnt lgkmcnt(6)
	v_mfma_f32_32x32x16_bf16 v[112:127], v[206:209], v[242:245], v[112:127]
	ds_read_b64_tr_b16 v[206:207], v205 offset:256
	ds_read_b64_tr_b16 v[208:209], v205 offset:4352
	v_sub_f32_e32 v136, v136, v190
	v_add_f32_e32 v254, v134, v254
	v_exp_f32_e32 v136, v136
	v_sub_f32_e32 v137, v137, v190
	v_add_f32_e32 v254, v135, v254
	s_waitcnt lgkmcnt(6)
	v_mfma_f32_32x32x16_bf16 v[96:111], v[210:213], v[242:245], v[96:111]
	ds_read_b64_tr_b16 v[210:211], v218 offset:256
	ds_read_b64_tr_b16 v[212:213], v218 offset:4352
	v_exp_f32_e32 v137, v137
	v_sub_f32_e32 v138, v138, v190
	v_add_f32_e32 v254, v136, v254
	v_exp_f32_e32 v138, v138
	v_sub_f32_e32 v139, v139, v190
	s_waitcnt lgkmcnt(6)
	v_mfma_f32_32x32x16_bf16 v[80:95], v[214:217], v[242:245], v[80:95]
	ds_read_b64_tr_b16 v[214:215], v219 offset:256
	ds_read_b64_tr_b16 v[216:217], v219 offset:4352
	v_add_f32_e32 v254, v137, v254
	v_exp_f32_e32 v139, v139
	v_sub_f32_e32 v140, v140, v190
	v_add_f32_e32 v254, v138, v254
	s_waitcnt lgkmcnt(6)
	v_mfma_f32_32x32x16_bf16 v[64:79], v[238:241], v[242:245], v[64:79]
	ds_read_b64_tr_b16 v[238:239], v221 offset:256
	ds_read_b64_tr_b16 v[240:241], v221 offset:4352
	v_exp_f32_e32 v140, v140
	v_sub_f32_e32 v141, v141, v190
	v_add_f32_e32 v254, v139, v254
	v_exp_f32_e32 v141, v141
	s_waitcnt lgkmcnt(6)
	v_mfma_f32_32x32x16_bf16 v[48:63], v[206:209], v[242:245], v[48:63]
	ds_read_b64_tr_b16 v[206:207], v205 offset:8192
	ds_read_b64_tr_b16 v[208:209], v205 offset:12288
	v_sub_f32_e32 v142, v142, v190
	v_add_f32_e32 v254, v140, v254
	v_exp_f32_e32 v142, v142
	v_sub_f32_e32 v143, v143, v190
	s_waitcnt lgkmcnt(6)
	v_mfma_f32_32x32x16_bf16 v[32:47], v[210:213], v[242:245], v[32:47]
	ds_read_b64_tr_b16 v[210:211], v218 offset:8192
	ds_read_b64_tr_b16 v[212:213], v218 offset:12288
	v_add_f32_e32 v254, v141, v254
	v_exp_f32_e32 v143, v143
	v_add_f32_e32 v254, v142, v254
	v_add_f32_e32 v254, v143, v254
	s_waitcnt lgkmcnt(6)
	v_mfma_f32_32x32x16_bf16 v[16:31], v[214:217], v[242:245], v[16:31]
	ds_read_b64_tr_b16 v[214:215], v219 offset:8192
	ds_read_b64_tr_b16 v[216:217], v219 offset:12288
	v_cvt_pk_bf16_f32 v250, v136, v137
	v_cvt_pk_bf16_f32 v251, v138, v139
	v_cvt_pk_bf16_f32 v252, v140, v141
	v_cvt_pk_bf16_f32 v253, v142, v143
	v_add_f32_e32 v195, v195, v254
	s_waitcnt lgkmcnt(6)
	v_mfma_f32_32x32x16_bf16 v[0:15], v[238:241], v[242:245], v[0:15]
	ds_read_b64_tr_b16 v[238:239], v221 offset:8192
	ds_read_b64_tr_b16 v[240:241], v221 offset:12288
	ds_read_b64_tr_b16 v[128:129], v205 offset:8448
	ds_read_b64_tr_b16 v[130:131], v205 offset:12544
	s_waitcnt lgkmcnt(8)
	v_mfma_f32_32x32x16_bf16 v[112:127], v[206:209], v[250:253], v[112:127]
	ds_read_b64_tr_b16 v[206:207], v218 offset:8448
	ds_read_b64_tr_b16 v[208:209], v218 offset:12544
	v_max3_f32 v246, v222, v223, v224
	v_max3_f32 v247, v225, v226, v227
	v_max3_f32 v246, v246, v228, v229
	v_max3_f32 v247, v247, v230, v231
	v_max3_f32 v246, v246, v232, v233
	s_waitcnt lgkmcnt(8)
	v_mfma_f32_32x32x16_bf16 v[96:111], v[210:213], v[250:253], v[96:111]
	ds_read_b64_tr_b16 v[210:211], v219 offset:8448
	ds_read_b64_tr_b16 v[212:213], v219 offset:12544
	v_max3_f32 v247, v247, v234, v235
	v_max3_f32 v246, v246, v236, v237
	v_max_f32_e32 v246, v246, v247
	v_mov_b32_e32 v247, v246
	v_add_f32_e32 v249, 0x41000000, v190
	s_waitcnt lgkmcnt(8)
	v_mfma_f32_32x32x16_bf16 v[80:95], v[214:217], v[250:253], v[80:95]
	ds_read_b64_tr_b16 v[214:215], v221 offset:8448
	ds_read_b64_tr_b16 v[216:217], v221 offset:12544
	s_nop 1
	v_permlane32_swap_b32_e32 v246, v247
	v_max_f32_e32 v246, v246, v247
	v_cmp_gt_f32_e32 vcc, v246, v249
	s_cbranch_vccnz .Latt_rs1_7s0
	s_waitcnt lgkmcnt(8)
	v_mfma_f32_32x32x16_bf16 v[64:79], v[238:241], v[250:253], v[64:79]
	ds_read_b64_tr_b16 v[238:239], v205 offset:16384
	ds_read_b64_tr_b16 v[240:241], v205 offset:20480
	v_sub_f32_e32 v222, v222, v190
	v_exp_f32_e32 v222, v222
	v_sub_f32_e32 v223, v223, v190
	v_exp_f32_e32 v223, v223
	v_sub_f32_e32 v224, v224, v190
	v_add_f32_e32 v254, 0, v222
	s_waitcnt lgkmcnt(8)
	v_mfma_f32_32x32x16_bf16 v[48:63], v[128:131], v[250:253], v[48:63]
	ds_read_b64_tr_b16 v[128:129], v218 offset:16384
	ds_read_b64_tr_b16 v[130:131], v218 offset:20480
	v_exp_f32_e32 v224, v224
	v_sub_f32_e32 v225, v225, v190
	v_add_f32_e32 v254, v223, v254
	v_exp_f32_e32 v225, v225
	v_sub_f32_e32 v226, v226, v190
	v_add_f32_e32 v254, v224, v254
	s_waitcnt lgkmcnt(8)
	v_mfma_f32_32x32x16_bf16 v[32:47], v[206:209], v[250:253], v[32:47]
	ds_read_b64_tr_b16 v[206:207], v219 offset:16384
	ds_read_b64_tr_b16 v[208:209], v219 offset:20480
	v_exp_f32_e32 v226, v226
	v_sub_f32_e32 v227, v227, v190
	v_add_f32_e32 v254, v225, v254
	v_exp_f32_e32 v227, v227
	v_sub_f32_e32 v228, v228, v190
	s_waitcnt lgkmcnt(8)
	v_mfma_f32_32x32x16_bf16 v[16:31], v[210:213], v[250:253], v[16:31]
	ds_read_b64_tr_b16 v[210:211], v221 offset:16384
	ds_read_b64_tr_b16 v[212:213], v221 offset:20480
	v_add_f32_e32 v254, v226, v254
	v_exp_f32_e32 v228, v228
	v_sub_f32_e32 v229, v229, v190
	v_add_f32_e32 v254, v227, v254
	v_exp_f32_e32 v229, v229
	s_waitcnt lgkmcnt(8)
	v_mfma_f32_32x32x16_bf16 v[0:15], v[214:217], v[250:253], v[0:15]
	ds_read_b64_tr_b16 v[214:215], v205 offset:16640
	ds_read_b64_tr_b16 v[216:217], v205 offset:20736
	s_nop 0
	v_cvt_pk_bf16_f32 v242, v222, v223
	v_cvt_pk_bf16_f32 v243, v224, v225
	v_cvt_pk_bf16_f32 v244, v226, v227
	v_cvt_pk_bf16_f32 v245, v228, v229
	s_nop 1
	s_waitcnt lgkmcnt(8)
	v_mfma_f32_32x32x16_bf16 v[112:127], v[238:241], v[242:245], v[112:127]
	ds_read_b64_tr_b16 v[238:239], v218 offset:16640
	ds_read_b64_tr_b16 v[240:241], v218 offset:20736
	v_sub_f32_e32 v230, v230, v190
	v_add_f32_e32 v254, v228, v254
	v_exp_f32_e32 v230, v230
	v_sub_f32_e32 v231, v231, v190
	v_add_f32_e32 v254, v229, v254
	s_waitcnt lgkmcnt(8)
	v_mfma_f32_32x32x16_bf16 v[96:111], v[128:131], v[242:245], v[96:111]
	ds_read_b64_tr_b16 v[128:129], v219 offset:16640
	ds_read_b64_tr_b16 v[130:131], v219 offset:20736
	v_exp_f32_e32 v231, v231
	v_sub_f32_e32 v232, v232, v190
	v_add_f32_e32 v254, v230, v254
	v_exp_f32_e32 v232, v232
	v_sub_f32_e32 v233, v233, v190
	s_cmp_lg_u64 s[8:9], 0
	s_cbranch_scc1 .Latt_nd0_7s0
	s_sub_i32 s100, s11, 1
	s_cmp_eq_u32 s11, 0
	s_cselect_b32 s100, 2, s100
	s_lshl_b32 s101, s100, 14
	s_add_i32 m0, s36, s101
	s_nop 0
	global_load_lds_dwordx4 v178, s[22:23]

.Latt_nr0_7s1:
	s_waitcnt lgkmcnt(3)
	v_mfma_f32_32x32x16_bf16 v[222:237], v[214:217], v[152:155], v[222:237]
	ds_read_b128 v[214:217], v202 offset:24576
	v_sub_f32_e32 v128, v128, v190
	v_exp_f32_e32 v128, v128
	v_sub_f32_e32 v129, v129, v190
	v_exp_f32_e32 v129, v129
	v_sub_f32_e32 v130, v130, v190
	s_waitcnt lgkmcnt(3)
	v_mfma_f32_32x32x16_bf16 v[222:237], v[238:241], v[156:159], v[222:237]
	ds_read_b128 v[238:241], v203 offset:24576
	v_add_f32_e32 v254, 0, v128
	v_exp_f32_e32 v130, v130
	v_sub_f32_e32 v131, v131, v190
	v_add_f32_e32 v254, v129, v254
	v_exp_f32_e32 v131, v131
	s_waitcnt lgkmcnt(3)
	v_mfma_f32_32x32x16_bf16 v[222:237], v[206:209], v[160:163], v[222:237]
	ds_read_b64_tr_b16 v[206:207], v205
	ds_read_b64_tr_b16 v[208:209], v205 offset:4096
	v_sub_f32_e32 v132, v132, v190
	v_add_f32_e32 v254, v130, v254
	v_exp_f32_e32 v132, v132
	v_sub_f32_e32 v133, v133, v190
	v_add_f32_e32 v254, v131, v254
	s_waitcnt lgkmcnt(4)
	v_mfma_f32_32x32x16_bf16 v[222:237], v[210:213], v[164:167], v[222:237]
	ds_read_b64_tr_b16 v[210:211], v218
	ds_read_b64_tr_b16 v[212:213], v218 offset:4096
	v_exp_f32_e32 v133, v133
	v_sub_f32_e32 v134, v134, v190
	v_add_f32_e32 v254, v132, v254
	v_exp_f32_e32 v134, v134
	s_waitcnt lgkmcnt(5)
	v_mfma_f32_32x32x16_bf16 v[222:237], v[214:217], v[168:171], v[222:237]
	ds_read_b64_tr_b16 v[214:215], v219
	ds_read_b64_tr_b16 v[216:217], v219 offset:4096
	v_sub_f32_e32 v135, v135, v190
	v_add_f32_e32 v254, v133, v254
	v_exp_f32_e32 v135, v135
	s_nop 0
	s_waitcnt lgkmcnt(6)
	v_mfma_f32_32x32x16_bf16 v[222:237], v[238:241], v[172:175], v[222:237]
	ds_read_b64_tr_b16 v[238:239], v221
	ds_read_b64_tr_b16 v[240:241], v221 offset:4096
	v_cvt_pk_bf16_f32 v242, v128, v129
	v_cvt_pk_bf16_f32 v243, v130, v131
	v_cvt_pk_bf16_f32 v244, v132, v133
	v_cvt_pk_bf16_f32 v245, v134, v135
	s_nop 1
	s_waitcnt lgkmcnt(6)
	v_mfma_f32_32x32x16_bf16 v[112:127], v[206:209], v[242:245], v[112:127]
	ds_read_b64_tr_b16 v[206:207], v205 offset:256
	ds_read_b64_tr_b16 v[208:209], v205 offset:4352
	v_sub_f32_e32 v136, v136, v190
	v_add_f32_e32 v254, v134, v254
	v_exp_f32_e32 v136, v136
	v_sub_f32_e32 v137, v137, v190
	v_add_f32_e32 v254, v135, v254
	s_waitcnt lgkmcnt(6)
	v_mfma_f32_32x32x16_bf16 v[96:111], v[210:213], v[242:245], v[96:111]
	ds_read_b64_tr_b16 v[210:211], v218 offset:256
	ds_read_b64_tr_b16 v[212:213], v218 offset:4352
	v_exp_f32_e32 v137, v137
	v_sub_f32_e32 v138, v138, v190
	v_add_f32_e32 v254, v136, v254
	v_exp_f32_e32 v138, v138
	v_sub_f32_e32 v139, v139, v190
	s_waitcnt lgkmcnt(6)
	v_mfma_f32_32x32x16_bf16 v[80:95], v[214:217], v[242:245], v[80:95]
	ds_read_b64_tr_b16 v[214:215], v219 offset:256
	ds_read_b64_tr_b16 v[216:217], v219 offset:4352
	v_add_f32_e32 v254, v137, v254
	v_exp_f32_e32 v139, v139
	v_sub_f32_e32 v140, v140, v190
	v_add_f32_e32 v254, v138, v254
	s_waitcnt lgkmcnt(6)
	v_mfma_f32_32x32x16_bf16 v[64:79], v[238:241], v[242:245], v[64:79]
	ds_read_b64_tr_b16 v[238:239], v221 offset:256
	ds_read_b64_tr_b16 v[240:241], v221 offset:4352
	v_exp_f32_e32 v140, v140
	v_sub_f32_e32 v141, v141, v190
	v_add_f32_e32 v254, v139, v254
	v_exp_f32_e32 v141, v141
	s_waitcnt lgkmcnt(6)
	v_mfma_f32_32x32x16_bf16 v[48:63], v[206:209], v[242:245], v[48:63]
	ds_read_b64_tr_b16 v[206:207], v205 offset:8192
	ds_read_b64_tr_b16 v[208:209], v205 offset:12288
	v_sub_f32_e32 v142, v142, v190
	v_add_f32_e32 v254, v140, v254
	v_exp_f32_e32 v142, v142
	v_sub_f32_e32 v143, v143, v190
	s_waitcnt lgkmcnt(6)
	v_mfma_f32_32x32x16_bf16 v[32:47], v[210:213], v[242:245], v[32:47]
	ds_read_b64_tr_b16 v[210:211], v218 offset:8192
	ds_read_b64_tr_b16 v[212:213], v218 offset:12288
	v_add_f32_e32 v254, v141, v254
	v_exp_f32_e32 v143, v143
	v_add_f32_e32 v254, v142, v254
	v_add_f32_e32 v254, v143, v254
	s_waitcnt lgkmcnt(6)
	v_mfma_f32_32x32x16_bf16 v[16:31], v[214:217], v[242:245], v[16:31]
	ds_read_b64_tr_b16 v[214:215], v219 offset:8192
	ds_read_b64_tr_b16 v[216:217], v219 offset:12288
	v_cvt_pk_bf16_f32 v250, v136, v137
	v_cvt_pk_bf16_f32 v251, v138, v139
	v_cvt_pk_bf16_f32 v252, v140, v141
	v_cvt_pk_bf16_f32 v253, v142, v143
	v_add_f32_e32 v195, v195, v254
	s_waitcnt lgkmcnt(6)
	v_mfma_f32_32x32x16_bf16 v[0:15], v[238:241], v[242:245], v[0:15]
	ds_read_b64_tr_b16 v[238:239], v221 offset:8192
	ds_read_b64_tr_b16 v[240:241], v221 offset:12288
	ds_read_b64_tr_b16 v[128:129], v205 offset:8448
	ds_read_b64_tr_b16 v[130:131], v205 offset:12544
	s_waitcnt lgkmcnt(8)
	v_mfma_f32_32x32x16_bf16 v[112:127], v[206:209], v[250:253], v[112:127]
	ds_read_b64_tr_b16 v[206:207], v218 offset:8448
	ds_read_b64_tr_b16 v[208:209], v218 offset:12544
	v_max3_f32 v246, v222, v223, v224
	v_max3_f32 v247, v225, v226, v227
	v_max3_f32 v246, v246, v228, v229
	v_max3_f32 v247, v247, v230, v231
	v_max3_f32 v246, v246, v232, v233
	s_waitcnt lgkmcnt(8)
	v_mfma_f32_32x32x16_bf16 v[96:111], v[210:213], v[250:253], v[96:111]
	ds_read_b64_tr_b16 v[210:211], v219 offset:8448
	ds_read_b64_tr_b16 v[212:213], v219 offset:12544
	v_max3_f32 v247, v247, v234, v235
	v_max3_f32 v246, v246, v236, v237
	v_max_f32_e32 v246, v246, v247
	v_mov_b32_e32 v247, v246
	v_add_f32_e32 v249, 0x41000000, v190
	s_waitcnt lgkmcnt(8)
	v_mfma_f32_32x32x16_bf16 v[80:95], v[214:217], v[250:253], v[80:95]
	ds_read_b64_tr_b16 v[214:215], v221 offset:8448
	ds_read_b64_tr_b16 v[216:217], v221 offset:12544
	s_nop 1
	v_permlane32_swap_b32_e32 v246, v247
	v_max_f32_e32 v246, v246, v247
	v_cmp_gt_f32_e32 vcc, v246, v249
	s_cbranch_vccnz .Latt_rs1_7s1
	s_waitcnt lgkmcnt(8)
	v_mfma_f32_32x32x16_bf16 v[64:79], v[238:241], v[250:253], v[64:79]
	ds_read_b64_tr_b16 v[238:239], v205 offset:16384
	ds_read_b64_tr_b16 v[240:241], v205 offset:20480
	v_sub_f32_e32 v222, v222, v190
	v_exp_f32_e32 v222, v222
	v_sub_f32_e32 v223, v223, v190
	v_exp_f32_e32 v223, v223
	v_sub_f32_e32 v224, v224, v190
	v_add_f32_e32 v254, 0, v222
	s_waitcnt lgkmcnt(8)
	v_mfma_f32_32x32x16_bf16 v[48:63], v[128:131], v[250:253], v[48:63]
	ds_read_b64_tr_b16 v[128:129], v218 offset:16384
	ds_read_b64_tr_b16 v[130:131], v218 offset:20480
	v_exp_f32_e32 v224, v224
	v_sub_f32_e32 v225, v225, v190
	v_add_f32_e32 v254, v223, v254
	v_exp_f32_e32 v225, v225
	v_sub_f32_e32 v226, v226, v190
	v_add_f32_e32 v254, v224, v254
	s_waitcnt lgkmcnt(8)
	v_mfma_f32_32x32x16_bf16 v[32:47], v[206:209], v[250:253], v[32:47]
	ds_read_b64_tr_b16 v[206:207], v219 offset:16384
	ds_read_b64_tr_b16 v[208:209], v219 offset:20480
	v_exp_f32_e32 v226, v226
	v_sub_f32_e32 v227, v227, v190
	v_add_f32_e32 v254, v225, v254
	v_exp_f32_e32 v227, v227
	v_sub_f32_e32 v228, v228, v190
	s_waitcnt lgkmcnt(8)
	v_mfma_f32_32x32x16_bf16 v[16:31], v[210:213], v[250:253], v[16:31]
	ds_read_b64_tr_b16 v[210:211], v221 offset:16384
	ds_read_b64_tr_b16 v[212:213], v221 offset:20480
	v_add_f32_e32 v254, v226, v254
	v_exp_f32_e32 v228, v228
	v_sub_f32_e32 v229, v229, v190
	v_add_f32_e32 v254, v227, v254
	v_exp_f32_e32 v229, v229
	s_waitcnt lgkmcnt(8)
	v_mfma_f32_32x32x16_bf16 v[0:15], v[214:217], v[250:253], v[0:15]
	ds_read_b64_tr_b16 v[214:215], v205 offset:16640
	ds_read_b64_tr_b16 v[216:217], v205 offset:20736
	s_nop 0
	v_cvt_pk_bf16_f32 v242, v222, v223
	v_cvt_pk_bf16_f32 v243, v224, v225
	v_cvt_pk_bf16_f32 v244, v226, v227
	v_cvt_pk_bf16_f32 v245, v228, v229
	s_nop 1
	s_waitcnt lgkmcnt(8)
	v_mfma_f32_32x32x16_bf16 v[112:127], v[238:241], v[242:245], v[112:127]
	ds_read_b64_tr_b16 v[238:239], v218 offset:16640
	ds_read_b64_tr_b16 v[240:241], v218 offset:20736
	v_sub_f32_e32 v230, v230, v190
	v_add_f32_e32 v254, v228, v254
	v_exp_f32_e32 v230, v230
	v_sub_f32_e32 v231, v231, v190
	v_add_f32_e32 v254, v229, v254
	s_waitcnt lgkmcnt(8)
	v_mfma_f32_32x32x16_bf16 v[96:111], v[128:131], v[242:245], v[96:111]
	ds_read_b64_tr_b16 v[128:129], v219 offset:16640
	ds_read_b64_tr_b16 v[130:131], v219 offset:20736
	v_exp_f32_e32 v231, v231
	v_sub_f32_e32 v232, v232, v190
	v_add_f32_e32 v254, v230, v254
	v_exp_f32_e32 v232, v232
	v_sub_f32_e32 v233, v233, v190
	s_cmp_lg_u64 s[8:9], 0
	s_cbranch_scc1 .Latt_nd0_7s1
	s_sub_i32 s100, s11, 1
	s_cmp_eq_u32 s11, 0
	s_cselect_b32 s100, 2, s100
	s_lshl_b32 s101, s100, 14
	s_add_i32 m0, s36, s101
	s_nop 0
	global_load_lds_dwordx4 v178, s[22:23]

.Latt_nr0_7s2:
	s_waitcnt lgkmcnt(3)
	v_mfma_f32_32x32x16_bf16 v[222:237], v[214:217], v[152:155], v[222:237]
	ds_read_b128 v[214:217], v202 offset:40960
	v_sub_f32_e32 v128, v128, v190
	v_exp_f32_e32 v128, v128
	v_sub_f32_e32 v129, v129, v190
	v_exp_f32_e32 v129, v129
	v_sub_f32_e32 v130, v130, v190
	s_waitcnt lgkmcnt(3)
	v_mfma_f32_32x32x16_bf16 v[222:237], v[238:241], v[156:159], v[222:237]
	ds_read_b128 v[238:241], v203 offset:40960
	v_add_f32_e32 v254, 0, v128
	v_exp_f32_e32 v130, v130
	v_sub_f32_e32 v131, v131, v190
	v_add_f32_e32 v254, v129, v254
	v_exp_f32_e32 v131, v131
	s_waitcnt lgkmcnt(3)
	v_mfma_f32_32x32x16_bf16 v[222:237], v[206:209], v[160:163], v[222:237]
	ds_read_b64_tr_b16 v[206:207], v205
	ds_read_b64_tr_b16 v[208:209], v205 offset:4096
	v_sub_f32_e32 v132, v132, v190
	v_add_f32_e32 v254, v130, v254
	v_exp_f32_e32 v132, v132
	v_sub_f32_e32 v133, v133, v190
	v_add_f32_e32 v254, v131, v254
	s_waitcnt lgkmcnt(4)
	v_mfma_f32_32x32x16_bf16 v[222:237], v[210:213], v[164:167], v[222:237]
	ds_read_b64_tr_b16 v[210:211], v218
	ds_read_b64_tr_b16 v[212:213], v218 offset:4096
	v_exp_f32_e32 v133, v133
	v_sub_f32_e32 v134, v134, v190
	v_add_f32_e32 v254, v132, v254
	v_exp_f32_e32 v134, v134
	s_waitcnt lgkmcnt(5)
	v_mfma_f32_32x32x16_bf16 v[222:237], v[214:217], v[168:171], v[222:237]
	ds_read_b64_tr_b16 v[214:215], v219
	ds_read_b64_tr_b16 v[216:217], v219 offset:4096
	v_sub_f32_e32 v135, v135, v190
	v_add_f32_e32 v254, v133, v254
	v_exp_f32_e32 v135, v135
	s_nop 0
	s_waitcnt lgkmcnt(6)
	v_mfma_f32_32x32x16_bf16 v[222:237], v[238:241], v[172:175], v[222:237]
	ds_read_b64_tr_b16 v[238:239], v221
	ds_read_b64_tr_b16 v[240:241], v221 offset:4096
	v_cvt_pk_bf16_f32 v242, v128, v129
	v_cvt_pk_bf16_f32 v243, v130, v131
	v_cvt_pk_bf16_f32 v244, v132, v133
	v_cvt_pk_bf16_f32 v245, v134, v135
	s_nop 1
	s_waitcnt lgkmcnt(6)
	v_mfma_f32_32x32x16_bf16 v[112:127], v[206:209], v[242:245], v[112:127]
	ds_read_b64_tr_b16 v[206:207], v205 offset:256
	ds_read_b64_tr_b16 v[208:209], v205 offset:4352
	v_sub_f32_e32 v136, v136, v190
	v_add_f32_e32 v254, v134, v254
	v_exp_f32_e32 v136, v136
	v_sub_f32_e32 v137, v137, v190
	v_add_f32_e32 v254, v135, v254
	s_waitcnt lgkmcnt(6)
	v_mfma_f32_32x32x16_bf16 v[96:111], v[210:213], v[242:245], v[96:111]
	ds_read_b64_tr_b16 v[210:211], v218 offset:256
	ds_read_b64_tr_b16 v[212:213], v218 offset:4352
	v_exp_f32_e32 v137, v137
	v_sub_f32_e32 v138, v138, v190
	v_add_f32_e32 v254, v136, v254
	v_exp_f32_e32 v138, v138
	v_sub_f32_e32 v139, v139, v190
	s_waitcnt lgkmcnt(6)
	v_mfma_f32_32x32x16_bf16 v[80:95], v[214:217], v[242:245], v[80:95]
	ds_read_b64_tr_b16 v[214:215], v219 offset:256
	ds_read_b64_tr_b16 v[216:217], v219 offset:4352
	v_add_f32_e32 v254, v137, v254
	v_exp_f32_e32 v139, v139
	v_sub_f32_e32 v140, v140, v190
	v_add_f32_e32 v254, v138, v254
	s_waitcnt lgkmcnt(6)
	v_mfma_f32_32x32x16_bf16 v[64:79], v[238:241], v[242:245], v[64:79]
	ds_read_b64_tr_b16 v[238:239], v221 offset:256
	ds_read_b64_tr_b16 v[240:241], v221 offset:4352
	v_exp_f32_e32 v140, v140
	v_sub_f32_e32 v141, v141, v190
	v_add_f32_e32 v254, v139, v254
	v_exp_f32_e32 v141, v141
	s_waitcnt lgkmcnt(6)
	v_mfma_f32_32x32x16_bf16 v[48:63], v[206:209], v[242:245], v[48:63]
	ds_read_b64_tr_b16 v[206:207], v205 offset:8192
	ds_read_b64_tr_b16 v[208:209], v205 offset:12288
	v_sub_f32_e32 v142, v142, v190
	v_add_f32_e32 v254, v140, v254
	v_exp_f32_e32 v142, v142
	v_sub_f32_e32 v143, v143, v190
	s_waitcnt lgkmcnt(6)
	v_mfma_f32_32x32x16_bf16 v[32:47], v[210:213], v[242:245], v[32:47]
	ds_read_b64_tr_b16 v[210:211], v218 offset:8192
	ds_read_b64_tr_b16 v[212:213], v218 offset:12288
	v_add_f32_e32 v254, v141, v254
	v_exp_f32_e32 v143, v143
	v_add_f32_e32 v254, v142, v254
	v_add_f32_e32 v254, v143, v254
	s_waitcnt lgkmcnt(6)
	v_mfma_f32_32x32x16_bf16 v[16:31], v[214:217], v[242:245], v[16:31]
	ds_read_b64_tr_b16 v[214:215], v219 offset:8192
	ds_read_b64_tr_b16 v[216:217], v219 offset:12288
	v_cvt_pk_bf16_f32 v250, v136, v137
	v_cvt_pk_bf16_f32 v251, v138, v139
	v_cvt_pk_bf16_f32 v252, v140, v141
	v_cvt_pk_bf16_f32 v253, v142, v143
	v_add_f32_e32 v195, v195, v254
	s_waitcnt lgkmcnt(6)
	v_mfma_f32_32x32x16_bf16 v[0:15], v[238:241], v[242:245], v[0:15]
	ds_read_b64_tr_b16 v[238:239], v221 offset:8192
	ds_read_b64_tr_b16 v[240:241], v221 offset:12288
	ds_read_b64_tr_b16 v[128:129], v205 offset:8448
	ds_read_b64_tr_b16 v[130:131], v205 offset:12544
	s_waitcnt lgkmcnt(8)
	v_mfma_f32_32x32x16_bf16 v[112:127], v[206:209], v[250:253], v[112:127]
	ds_read_b64_tr_b16 v[206:207], v218 offset:8448
	ds_read_b64_tr_b16 v[208:209], v218 offset:12544
	v_max3_f32 v246, v222, v223, v224
	v_max3_f32 v247, v225, v226, v227
	v_max3_f32 v246, v246, v228, v229
	v_max3_f32 v247, v247, v230, v231
	v_max3_f32 v246, v246, v232, v233
	s_waitcnt lgkmcnt(8)
	v_mfma_f32_32x32x16_bf16 v[96:111], v[210:213], v[250:253], v[96:111]
	ds_read_b64_tr_b16 v[210:211], v219 offset:8448
	ds_read_b64_tr_b16 v[212:213], v219 offset:12544
	v_max3_f32 v247, v247, v234, v235
	v_max3_f32 v246, v246, v236, v237
	v_max_f32_e32 v246, v246, v247
	v_mov_b32_e32 v247, v246
	v_add_f32_e32 v249, 0x41000000, v190
	s_waitcnt lgkmcnt(8)
	v_mfma_f32_32x32x16_bf16 v[80:95], v[214:217], v[250:253], v[80:95]
	ds_read_b64_tr_b16 v[214:215], v221 offset:8448
	ds_read_b64_tr_b16 v[216:217], v221 offset:12544
	s_nop 1
	v_permlane32_swap_b32_e32 v246, v247
	v_max_f32_e32 v246, v246, v247
	v_cmp_gt_f32_e32 vcc, v246, v249
	s_cbranch_vccnz .Latt_rs1_7s2
	s_waitcnt lgkmcnt(8)
	v_mfma_f32_32x32x16_bf16 v[64:79], v[238:241], v[250:253], v[64:79]
	ds_read_b64_tr_b16 v[238:239], v205 offset:16384
	ds_read_b64_tr_b16 v[240:241], v205 offset:20480
	v_sub_f32_e32 v222, v222, v190
	v_exp_f32_e32 v222, v222
	v_sub_f32_e32 v223, v223, v190
	v_exp_f32_e32 v223, v223
	v_sub_f32_e32 v224, v224, v190
	v_add_f32_e32 v254, 0, v222
	s_waitcnt lgkmcnt(8)
	v_mfma_f32_32x32x16_bf16 v[48:63], v[128:131], v[250:253], v[48:63]
	ds_read_b64_tr_b16 v[128:129], v218 offset:16384
	ds_read_b64_tr_b16 v[130:131], v218 offset:20480
	v_exp_f32_e32 v224, v224
	v_sub_f32_e32 v225, v225, v190
	v_add_f32_e32 v254, v223, v254
	v_exp_f32_e32 v225, v225
	v_sub_f32_e32 v226, v226, v190
	v_add_f32_e32 v254, v224, v254
	s_waitcnt lgkmcnt(8)
	v_mfma_f32_32x32x16_bf16 v[32:47], v[206:209], v[250:253], v[32:47]
	ds_read_b64_tr_b16 v[206:207], v219 offset:16384
	ds_read_b64_tr_b16 v[208:209], v219 offset:20480
	v_exp_f32_e32 v226, v226
	v_sub_f32_e32 v227, v227, v190
	v_add_f32_e32 v254, v225, v254
	v_exp_f32_e32 v227, v227
	v_sub_f32_e32 v228, v228, v190
	s_waitcnt lgkmcnt(8)
	v_mfma_f32_32x32x16_bf16 v[16:31], v[210:213], v[250:253], v[16:31]
	ds_read_b64_tr_b16 v[210:211], v221 offset:16384
	ds_read_b64_tr_b16 v[212:213], v221 offset:20480
	v_add_f32_e32 v254, v226, v254
	v_exp_f32_e32 v228, v228
	v_sub_f32_e32 v229, v229, v190
	v_add_f32_e32 v254, v227, v254
	v_exp_f32_e32 v229, v229
	s_waitcnt lgkmcnt(8)
	v_mfma_f32_32x32x16_bf16 v[0:15], v[214:217], v[250:253], v[0:15]
	ds_read_b64_tr_b16 v[214:215], v205 offset:16640
	ds_read_b64_tr_b16 v[216:217], v205 offset:20736
	s_nop 0
	v_cvt_pk_bf16_f32 v242, v222, v223
	v_cvt_pk_bf16_f32 v243, v224, v225
	v_cvt_pk_bf16_f32 v244, v226, v227
	v_cvt_pk_bf16_f32 v245, v228, v229
	s_nop 1
	s_waitcnt lgkmcnt(8)
	v_mfma_f32_32x32x16_bf16 v[112:127], v[238:241], v[242:245], v[112:127]
	ds_read_b64_tr_b16 v[238:239], v218 offset:16640
	ds_read_b64_tr_b16 v[240:241], v218 offset:20736
	v_sub_f32_e32 v230, v230, v190
	v_add_f32_e32 v254, v228, v254
	v_exp_f32_e32 v230, v230
	v_sub_f32_e32 v231, v231, v190
	v_add_f32_e32 v254, v229, v254
	s_waitcnt lgkmcnt(8)
	v_mfma_f32_32x32x16_bf16 v[96:111], v[128:131], v[242:245], v[96:111]
	ds_read_b64_tr_b16 v[128:129], v219 offset:16640
	ds_read_b64_tr_b16 v[130:131], v219 offset:20736
	v_exp_f32_e32 v231, v231
	v_sub_f32_e32 v232, v232, v190
	v_add_f32_e32 v254, v230, v254
	v_exp_f32_e32 v232, v232
	v_sub_f32_e32 v233, v233, v190
	s_cmp_lg_u64 s[8:9], 0
	s_cbranch_scc1 .Latt_nd0_7s2
	s_sub_i32 s100, s11, 1
	s_cmp_eq_u32 s11, 0
	s_cselect_b32 s100, 2, s100
	s_lshl_b32 s101, s100, 14
	s_add_i32 m0, s36, s101
	s_nop 0
	global_load_lds_dwordx4 v178, s[22:23]

.Latt_slow_7s2:
.Latt_slow_7:
	s_lshl_b32 s15, s11, 14
	s_add_i32 s16, s15, 0
	v_add_u32_e32 v207, s16, v196
	ds_read_b128 v[128:131], v207
	v_add_u32_e32 v208, s16, v197
	ds_read_b128 v[210:213], v208
	v_add_u32_e32 v209, s16, v198
	v_lshrrev_b32_e32 v205, 3, v204
	s_add_i32 s17, s14, 31
	v_and_or_b32 v206, v204, 31, s68
	s_cmp_le_i32 s17, s68
	s_waitcnt lgkmcnt(1)
	v_mfma_f32_32x32x16_bf16 v[128:143], v[128:131], v[144:147], 0
	s_waitcnt lgkmcnt(0)
	v_mfma_f32_32x32x16_bf16 v[128:143], v[210:213], v[148:151], v[128:143]
	ds_read_b128 v[212:215], v209
	v_add_u32_e32 v210, s16, v199
	ds_read_b128 v[216:219], v210
	v_add_u32_e32 v211, s16, v200
	s_waitcnt lgkmcnt(1)
	v_mfma_f32_32x32x16_bf16 v[128:143], v[212:215], v[152:155], v[128:143]
	v_add_u32_e32 v213, s16, v201
	v_and_b32_e32 v212, 4, v205
	ds_read_b128 v[222:225], v213
	s_waitcnt lgkmcnt(1)
	v_mfma_f32_32x32x16_bf16 v[128:143], v[216:219], v[156:159], v[128:143]
	ds_read_b128 v[214:217], v211
	s_waitcnt lgkmcnt(0)
	v_mfma_f32_32x32x16_bf16 v[128:143], v[214:217], v[160:163], v[128:143]
	v_add_u32_e32 v214, s16, v202
	ds_read_b128 v[216:219], v214
	v_add_u32_e32 v215, s16, v203
	v_mfma_f32_32x32x16_bf16 v[128:143], v[222:225], v[164:167], v[128:143]
	ds_read_b128 v[222:225], v215
	s_waitcnt lgkmcnt(1)
	v_mfma_f32_32x32x16_bf16 v[128:143], v[216:219], v[168:171], v[128:143]
	s_waitcnt lgkmcnt(0)
	v_mfma_f32_32x32x16_bf16 v[128:143], v[222:225], v[172:175], v[128:143]
	s_cbranch_scc1 .LBB0_1861
	v_add_u32_e32 v205, s14, v212
	v_cmp_lt_i32_e32 vcc, v205, v206
	v_add_u32_e32 v216, 2, v205
	s_nop 7
	v_cndmask_b32_e32 v129, v192, v129, vcc
	v_cmp_le_i32_e32 vcc, v205, v206
	s_nop 1
	v_cndmask_b32_e32 v128, v192, v128, vcc
	v_cmp_le_i32_e32 vcc, v216, v206
	v_add_u32_e32 v216, 3, v205
	s_nop 0
	v_cndmask_b32_e32 v130, v192, v130, vcc
	v_cmp_le_i32_e32 vcc, v216, v206
	v_add_u32_e32 v216, 8, v205
	s_nop 0
	v_cndmask_b32_e32 v131, v192, v131, vcc
	v_cmp_le_i32_e32 vcc, v216, v206
	v_add_u32_e32 v216, 9, v205
	s_nop 0
	v_cndmask_b32_e32 v132, v192, v132, vcc
	v_cmp_le_i32_e32 vcc, v216, v206
	v_add_u32_e32 v216, 10, v205
	s_nop 0
	v_cndmask_b32_e32 v133, v192, v133, vcc
	v_cmp_le_i32_e32 vcc, v216, v206
	v_add_u32_e32 v216, 11, v205
	s_nop 0
	v_cndmask_b32_e32 v134, v192, v134, vcc
	v_cmp_le_i32_e32 vcc, v216, v206
	v_add_u32_e32 v216, 16, v205
	s_nop 0
	v_cndmask_b32_e32 v135, v192, v135, vcc
	v_cmp_le_i32_e32 vcc, v216, v206
	v_add_u32_e32 v216, 17, v205
	s_nop 0
	v_cndmask_b32_e32 v136, v192, v136, vcc
	v_cmp_le_i32_e32 vcc, v216, v206
	v_add_u32_e32 v216, 18, v205
	s_nop 0
	v_cndmask_b32_e32 v137, v192, v137, vcc
	v_cmp_le_i32_e32 vcc, v216, v206
	v_add_u32_e32 v216, 19, v205
	s_nop 0
	v_cndmask_b32_e32 v138, v192, v138, vcc
	v_cmp_le_i32_e32 vcc, v216, v206
	v_add_u32_e32 v216, 24, v205
	s_nop 0
	v_cndmask_b32_e32 v139, v192, v139, vcc
	v_cmp_le_i32_e32 vcc, v216, v206
	v_add_u32_e32 v216, 25, v205
	s_nop 0
	v_cndmask_b32_e32 v140, v192, v140, vcc
	v_cmp_le_i32_e32 vcc, v216, v206
	v_add_u32_e32 v216, 26, v205
	v_add_u32_e32 v205, 27, v205
	v_cndmask_b32_e32 v141, v192, v141, vcc
	v_cmp_le_i32_e32 vcc, v216, v206
	s_nop 1
	v_cndmask_b32_e32 v142, v192, v142, vcc
	v_cmp_le_i32_e32 vcc, v205, v206
	s_nop 1
	v_cndmask_b32_e32 v143, v192, v143, vcc
